# GEMM mainloops: per-cluster s_setprio flips removed (13 loops)
# speedup vs baseline: 1.0084x; 1.0036x over previous
; #define PG8_STAGE(bufoff, gbase, voff) do { _Pragma("unroll") for (int _i = 0; _i < 2; ++_i) \
;         __builtin_amdgcn_global_load_lds((const unsigned*)((const char*)(gbase) + (voff)[_i]), (LAS unsigned*)(lds + (bufoff) + ldsw + _i * 8192), 16, 0, 0); } while (0)
; #define PG8_LDA(dst, b, h) do { _Pragma("unroll") for (int m = 0; m < 4; ++m) _Pragma("unroll") for (int k = 0; k < 2; ++k) dst[m][k] = *(const LAS bf16x8*)(lds + PG8_SA(b, h) + aoff + m * 2048 + k * 1024); } while (0)
; #define PG8_LDB(dst, b, h) do { _Pragma("unroll") for (int n = 0; n < 2; ++n) _Pragma("unroll") for (int k = 0; k < 2; ++k) dst[n][k] = *(const LAS bf16x8*)(lds + PG8_SB(b, h) + boff + n * 2048 + k * 1024); } while (0)
; #define PG8_MMA(ai, bj, At, Bt) do { __builtin_amdgcn_s_setprio(1); _Pragma("unroll") for (int m = 0; m < 4; ++m) _Pragma("unroll") for (int n = 0; n < 2; ++n) _Pragma("unroll") for (int k = 0; k < 2; ++k) \
;         acc[ai][bj][m][n] = __builtin_amdgcn_mfma_f32_16x16x32_bf16(Bt[n][k], At[m][k], acc[ai][bj][m][n], 0, 0, 0); __builtin_amdgcn_s_setprio(0); } while (0)
; template <class Epi>
; DEVI void gemm_phase(LAS unsigned char* lds, const Gemm g, const Epi& E) {
;     ...
;         for (int t = 0; t < nt; t += 2) {
;             const bool last = (t == nt - 2);
;             const char* a1 = cA + (size_t)(t + 1) * kstep;
;             const char* a2 = last ? nA : cA + (size_t)(t + 2) * kstep; const char* b2 = last ? nB : cB + (size_t)(t + 2) * kstep;
;             const char* a3 = a2 + kstep; const char* b3 = b2 + kstep;
;             PG8_LDB(B0, 0, 0); PG8_SCHED; PG8_LDA(At, 0, 0); PG8_STAGE(PG8_SA(1, 1), a1 + hstepA, voffA);
;             PG8_WAIT_L(8); PG8_BAR; PG8_WAIT_L(0); PG8_MMA(0, 0, At, B0); PG8_BAR; PG8_SCHED;
;             PG8_LDB(B1, 0, 1); PG8_STAGE(PG8_SB(0, 0), b2, voffB);
;             PG8_BAR; PG8_WAIT_L(0); PG8_MMA(0, 1, At, B1); PG8_BAR;
;             PG8_LDA(At, 0, 1); PG8_STAGE(PG8_SA(0, 0), a2, voffA);
;             PG8_BAR; PG8_WAIT_L(0); PG8_MMA(1, 0, At, B0); PG8_BAR; PG8_SCHED;
;             PG8_STAGE(PG8_SB(0, 1), b2 + hstepB, voffB);
;             PG8_WAIT_V(6); PG8_BAR; PG8_MMA(1, 1, At, B1); PG8_BAR;
;             PG8_LDB(B0, 1, 0); PG8_SCHED; PG8_LDA(At, 1, 0); PG8_STAGE(PG8_SA(0, 1), a2 + hstepA, voffA);
;             PG8_WAIT_L(8); PG8_BAR; PG8_WAIT_L(0); PG8_MMA(0, 0, At, B0); PG8_BAR; PG8_SCHED;
.LBB0_187:
	ds_read_b128 v[156:159], v150
	ds_read_b128 v[160:163], v150 offset:1024
	ds_read_b128 v[164:167], v150 offset:2048
	ds_read_b128 v[168:171], v150 offset:3072
	s_add_u32 s26, s0, 0xfffc0080
	s_addc_u32 s27, s1, -1
	s_cmp_eq_u32 s50, 12
	s_cselect_b32 s29, s13, s27
	s_cselect_b32 s28, s15, s26
	s_cselect_b32 s27, s19, s49
	s_cselect_b32 s26, s18, s17
	v_lshl_add_u64 v[204:205], s[0:1], 0, v[138:139]
	s_add_i32 m0, s38, 0xc000
	ds_read_b128 v[172:175], v151
	ds_read_b128 v[176:179], v151 offset:1024
	ds_read_b128 v[180:183], v151 offset:2048
	ds_read_b128 v[184:187], v151 offset:3072
	ds_read_b128 v[188:191], v151 offset:4096
	ds_read_b128 v[192:195], v151 offset:5120
	ds_read_b128 v[196:199], v151 offset:6144
	ds_read_b128 v[200:203], v151 offset:7168
	global_load_lds_dwordx4 v[204:205], off
	v_lshl_add_u64 v[204:205], s[0:1], 0, v[140:141]
	s_add_i32 m0, s38, 0xe000
	s_nop 0
	global_load_lds_dwordx4 v[204:205], off
	s_waitcnt lgkmcnt(8)
	s_barrier
	s_waitcnt lgkmcnt(0)
	v_mfma_f32_16x16x32_bf16 v[124:127], v[156:159], v[172:175], v[124:127]
	v_mfma_f32_16x16x32_bf16 v[120:123], v[164:167], v[172:175], v[120:123]
	v_mfma_f32_16x16x32_bf16 v[116:119], v[156:159], v[180:183], v[116:119]
	v_mfma_f32_16x16x32_bf16 v[108:111], v[164:167], v[180:183], v[108:111]
	v_mfma_f32_16x16x32_bf16 v[100:103], v[156:159], v[188:191], v[100:103]
	v_mfma_f32_16x16x32_bf16 v[96:99], v[164:167], v[188:191], v[96:99]
	v_mfma_f32_16x16x32_bf16 v[84:87], v[156:159], v[196:199], v[84:87]
	v_mfma_f32_16x16x32_bf16 v[80:83], v[164:167], v[196:199], v[80:83]
	v_mfma_f32_16x16x32_bf16 v[124:127], v[160:163], v[176:179], v[124:127]
	v_mfma_f32_16x16x32_bf16 v[120:123], v[168:171], v[176:179], v[120:123]
	v_mfma_f32_16x16x32_bf16 v[116:119], v[160:163], v[184:187], v[116:119]
	v_mfma_f32_16x16x32_bf16 v[108:111], v[168:171], v[184:187], v[108:111]
	v_mfma_f32_16x16x32_bf16 v[100:103], v[160:163], v[192:195], v[100:103]
	v_mfma_f32_16x16x32_bf16 v[96:99], v[168:171], v[192:195], v[96:99]
	v_mfma_f32_16x16x32_bf16 v[84:87], v[160:163], v[200:203], v[84:87]
	v_mfma_f32_16x16x32_bf16 v[80:83], v[168:171], v[200:203], v[80:83]
	s_barrier
	s_add_i32 s51, s46, s35
	v_lshl_add_u64 v[220:221], s[26:27], 0, v[130:131]
	s_mov_b32 m0, s51
	ds_read_b128 v[204:207], v152
	ds_read_b128 v[208:211], v152 offset:1024
	ds_read_b128 v[212:215], v152 offset:2048
	ds_read_b128 v[216:219], v152 offset:3072
	global_load_lds_dwordx4 v[220:221], off
	v_lshl_add_u64 v[222:223], s[26:27], 0, v[134:135]
	s_add_i32 m0, s51, 0x2000
	s_nop 0
	global_load_lds_dwordx4 v[222:223], off
	s_barrier
	s_waitcnt lgkmcnt(0)
	v_mfma_f32_16x16x32_bf16 v[112:115], v[204:207], v[172:175], v[112:115]
	v_mfma_f32_16x16x32_bf16 v[104:107], v[212:215], v[172:175], v[104:107]
	v_mfma_f32_16x16x32_bf16 v[92:95], v[204:207], v[180:183], v[92:95]
	v_mfma_f32_16x16x32_bf16 v[88:91], v[212:215], v[180:183], v[88:91]
	v_mfma_f32_16x16x32_bf16 v[76:79], v[204:207], v[188:191], v[76:79]
	v_mfma_f32_16x16x32_bf16 v[72:75], v[212:215], v[188:191], v[72:75]
	v_mfma_f32_16x16x32_bf16 v[68:71], v[204:207], v[196:199], v[68:71]
	v_mfma_f32_16x16x32_bf16 v[64:67], v[212:215], v[196:199], v[64:67]
	v_mfma_f32_16x16x32_bf16 v[112:115], v[208:211], v[176:179], v[112:115]
	v_mfma_f32_16x16x32_bf16 v[104:107], v[216:219], v[176:179], v[104:107]
	v_mfma_f32_16x16x32_bf16 v[92:95], v[208:211], v[184:187], v[92:95]
	v_mfma_f32_16x16x32_bf16 v[88:91], v[216:219], v[184:187], v[88:91]
	v_mfma_f32_16x16x32_bf16 v[76:79], v[208:211], v[192:195], v[76:79]
	v_mfma_f32_16x16x32_bf16 v[72:75], v[216:219], v[192:195], v[72:75]
	v_mfma_f32_16x16x32_bf16 v[68:71], v[208:211], v[200:203], v[68:71]
	v_mfma_f32_16x16x32_bf16 v[64:67], v[216:219], v[200:203], v[64:67]
	s_mov_b32 m0, s38
	v_lshl_add_u64 v[224:225], s[28:29], 0, v[128:129]
	s_barrier
	ds_read_b128 v[172:175], v151 offset:16384
	ds_read_b128 v[176:179], v151 offset:17408
	ds_read_b128 v[180:183], v151 offset:18432
	ds_read_b128 v[184:187], v151 offset:19456
	ds_read_b128 v[188:191], v151 offset:20480
	ds_read_b128 v[192:195], v151 offset:21504
	ds_read_b128 v[196:199], v151 offset:22528
	ds_read_b128 v[200:203], v151 offset:23552
	global_load_lds_dwordx4 v[224:225], off
	v_lshl_add_u64 v[226:227], s[28:29], 0, v[132:133]
	s_mov_b32 m0, s39
	s_nop 0
	global_load_lds_dwordx4 v[226:227], off
	s_barrier
	s_waitcnt lgkmcnt(0)
	v_mfma_f32_16x16x32_bf16 v[60:63], v[156:159], v[172:175], v[60:63]
	v_mfma_f32_16x16x32_bf16 v[56:59], v[164:167], v[172:175], v[56:59]
	v_mfma_f32_16x16x32_bf16 v[52:55], v[156:159], v[180:183], v[52:55]
	v_mfma_f32_16x16x32_bf16 v[48:51], v[164:167], v[180:183], v[48:51]
	v_mfma_f32_16x16x32_bf16 v[36:39], v[156:159], v[188:191], v[36:39]
	v_mfma_f32_16x16x32_bf16 v[32:35], v[164:167], v[188:191], v[32:35]
	v_mfma_f32_16x16x32_bf16 v[20:23], v[156:159], v[196:199], v[20:23]
	v_mfma_f32_16x16x32_bf16 v[16:19], v[164:167], v[196:199], v[16:19]
	v_mfma_f32_16x16x32_bf16 v[60:63], v[160:163], v[176:179], v[60:63]
	v_mfma_f32_16x16x32_bf16 v[56:59], v[168:171], v[176:179], v[56:59]
	v_mfma_f32_16x16x32_bf16 v[52:55], v[160:163], v[184:187], v[52:55]
	v_mfma_f32_16x16x32_bf16 v[48:51], v[168:171], v[184:187], v[48:51]
	v_mfma_f32_16x16x32_bf16 v[36:39], v[160:163], v[192:195], v[36:39]
	v_mfma_f32_16x16x32_bf16 v[32:35], v[168:171], v[192:195], v[32:35]
	v_mfma_f32_16x16x32_bf16 v[20:23], v[160:163], v[200:203], v[20:23]
	v_mfma_f32_16x16x32_bf16 v[16:19], v[168:171], v[200:203], v[16:19]
	s_barrier
; #define PG8_STAGE(bufoff, gbase, voff) do { _Pragma("unroll") for (int _i = 0; _i < 2; ++_i) \
;         __builtin_amdgcn_global_load_lds((const unsigned*)((const char*)(gbase) + (voff)[_i]), (LAS unsigned*)(lds + (bufoff) + ldsw + _i * 8192), 16, 0, 0); } while (0)
; #define PG8_LDA(dst, b, h) do { _Pragma("unroll") for (int m = 0; m < 4; ++m) _Pragma("unroll") for (int k = 0; k < 2; ++k) dst[m][k] = *(const LAS bf16x8*)(lds + PG8_SA(b, h) + aoff + m * 2048 + k * 1024); } while (0)
; #define PG8_LDB(dst, b, h) do { _Pragma("unroll") for (int n = 0; n < 2; ++n) _Pragma("unroll") for (int k = 0; k < 2; ++k) dst[n][k] = *(const LAS bf16x8*)(lds + PG8_SB(b, h) + boff + n * 2048 + k * 1024); } while (0)
; #define PG8_MMA(ai, bj, At, Bt) do { __builtin_amdgcn_s_setprio(1); _Pragma("unroll") for (int m = 0; m < 4; ++m) _Pragma("unroll") for (int n = 0; n < 2; ++n) _Pragma("unroll") for (int k = 0; k < 2; ++k) \
;         acc[ai][bj][m][n] = __builtin_amdgcn_mfma_f32_16x16x32_bf16(Bt[n][k], At[m][k], acc[ai][bj][m][n], 0, 0, 0); __builtin_amdgcn_s_setprio(0); } while (0)
; #define PG8_WAIT_V(n) asm volatile("s_waitcnt vmcnt(" #n ")" ::: "memory")
; #define PG8_WAIT_L(n) asm volatile("s_waitcnt lgkmcnt(" #n ")" ::: "memory")
; #define PG8_BAR __builtin_amdgcn_s_barrier()
; #define PG8_SCHED __builtin_amdgcn_sched_barrier(0)
; template <class Epi>
; DEVI void gemm_phase(LAS unsigned char* lds, const Gemm g, const Epi& E) {
;     ...
;             PG8_WAIT_V(6); PG8_BAR; PG8_MMA(1, 1, At, B1); PG8_BAR;
;             PG8_LDB(B0, 1, 0); PG8_SCHED; PG8_LDA(At, 1, 0); PG8_STAGE(PG8_SA(0, 1), a2 + hstepA, voffA);
;             PG8_WAIT_L(8); PG8_BAR; PG8_WAIT_L(0); PG8_MMA(0, 0, At, B0); PG8_BAR; PG8_SCHED;
;             PG8_LDB(B1, 1, 1); PG8_STAGE(PG8_SB(1, 0), b3, voffB);
;             PG8_BAR; PG8_WAIT_L(0); PG8_MMA(0, 1, At, B1); PG8_BAR;
;             PG8_LDA(At, 1, 1); PG8_STAGE(PG8_SA(1, 0), a3, voffA);
;             PG8_BAR; PG8_WAIT_L(0); PG8_MMA(1, 0, At, B0); PG8_BAR; PG8_SCHED;
	s_add_u32 s52, s26, 0x40000
	s_addc_u32 s53, s27, 0
	s_add_i32 s51, s47, s35
	v_lshl_add_u64 v[156:157], s[52:53], 0, v[130:131]
	s_mov_b32 m0, s51
	s_nop 0
	global_load_lds_dwordx4 v[156:157], off
	v_lshl_add_u64 v[156:157], s[52:53], 0, v[134:135]
	s_add_i32 m0, s51, 0x2000
	s_nop 0
	global_load_lds_dwordx4 v[156:157], off
	s_waitcnt vmcnt(6)
	s_barrier
	v_mfma_f32_16x16x32_bf16 v[44:47], v[204:207], v[172:175], v[44:47]
	v_mfma_f32_16x16x32_bf16 v[40:43], v[212:215], v[172:175], v[40:43]
	v_mfma_f32_16x16x32_bf16 v[28:31], v[204:207], v[180:183], v[28:31]
	v_mfma_f32_16x16x32_bf16 v[24:27], v[212:215], v[180:183], v[24:27]
	v_mfma_f32_16x16x32_bf16 v[12:15], v[204:207], v[188:191], v[12:15]
	v_mfma_f32_16x16x32_bf16 v[8:11], v[212:215], v[188:191], v[8:11]
	v_mfma_f32_16x16x32_bf16 v[4:7], v[204:207], v[196:199], v[4:7]
	v_mfma_f32_16x16x32_bf16 v[0:3], v[212:215], v[196:199], v[0:3]
	v_mfma_f32_16x16x32_bf16 v[44:47], v[208:211], v[176:179], v[44:47]
	v_mfma_f32_16x16x32_bf16 v[40:43], v[216:219], v[176:179], v[40:43]
	v_mfma_f32_16x16x32_bf16 v[28:31], v[208:211], v[184:187], v[28:31]
	v_mfma_f32_16x16x32_bf16 v[24:27], v[216:219], v[184:187], v[24:27]
	v_mfma_f32_16x16x32_bf16 v[12:15], v[208:211], v[192:195], v[12:15]
	v_mfma_f32_16x16x32_bf16 v[8:11], v[216:219], v[192:195], v[8:11]
	v_mfma_f32_16x16x32_bf16 v[4:7], v[208:211], v[200:203], v[4:7]
	v_mfma_f32_16x16x32_bf16 v[0:3], v[216:219], v[200:203], v[0:3]
	s_add_i32 s51, 0, 0x18000
	v_add_u32_e32 v136, s51, v148
	s_barrier
	ds_read_b128 v[156:159], v136
	ds_read_b128 v[160:163], v136 offset:1024
	ds_read_b128 v[164:167], v136 offset:2048
	ds_read_b128 v[168:171], v136 offset:3072
	s_add_u32 s28, s28, 0x40000
	s_addc_u32 s29, s29, 0
	s_mov_b32 m0, s40
	v_lshl_add_u64 v[204:205], s[28:29], 0, v[128:129]
	ds_read_b128 v[172:175], v151 offset:32768
	ds_read_b128 v[176:179], v151 offset:33792
	ds_read_b128 v[180:183], v151 offset:34816
	ds_read_b128 v[184:187], v151 offset:35840
	ds_read_b128 v[188:191], v151 offset:36864
	ds_read_b128 v[192:195], v151 offset:37888
	ds_read_b128 v[196:199], v151 offset:38912
	ds_read_b128 v[200:203], v151 offset:39936
	global_load_lds_dwordx4 v[204:205], off
	v_lshl_add_u64 v[204:205], s[28:29], 0, v[132:133]
	s_mov_b32 m0, s41
	s_nop 0
	global_load_lds_dwordx4 v[204:205], off
	s_waitcnt lgkmcnt(8)
	s_barrier
	s_waitcnt lgkmcnt(0)
	v_mfma_f32_16x16x32_bf16 v[124:127], v[156:159], v[172:175], v[124:127]
	v_mfma_f32_16x16x32_bf16 v[120:123], v[164:167], v[172:175], v[120:123]
	v_mfma_f32_16x16x32_bf16 v[116:119], v[156:159], v[180:183], v[116:119]
	v_mfma_f32_16x16x32_bf16 v[108:111], v[164:167], v[180:183], v[108:111]
	v_mfma_f32_16x16x32_bf16 v[100:103], v[156:159], v[188:191], v[100:103]
	v_mfma_f32_16x16x32_bf16 v[96:99], v[164:167], v[188:191], v[96:99]
	v_mfma_f32_16x16x32_bf16 v[84:87], v[156:159], v[196:199], v[84:87]
	v_mfma_f32_16x16x32_bf16 v[80:83], v[164:167], v[196:199], v[80:83]
	v_mfma_f32_16x16x32_bf16 v[124:127], v[160:163], v[176:179], v[124:127]
	v_mfma_f32_16x16x32_bf16 v[120:123], v[168:171], v[176:179], v[120:123]
	v_mfma_f32_16x16x32_bf16 v[116:119], v[160:163], v[184:187], v[116:119]
	v_mfma_f32_16x16x32_bf16 v[108:111], v[168:171], v[184:187], v[108:111]
	v_mfma_f32_16x16x32_bf16 v[100:103], v[160:163], v[192:195], v[100:103]
	v_mfma_f32_16x16x32_bf16 v[96:99], v[168:171], v[192:195], v[96:99]
	v_mfma_f32_16x16x32_bf16 v[84:87], v[160:163], v[200:203], v[84:87]
	v_mfma_f32_16x16x32_bf16 v[80:83], v[168:171], v[200:203], v[80:83]
	s_barrier
	s_add_i32 s28, 0, 0x1c000
	s_add_i32 s29, s51, s35
	v_add_u32_e32 v136, s28, v148
	v_lshl_add_u64 v[220:221], v[220:221], 0, s[8:9]
	s_mov_b32 m0, s29
	ds_read_b128 v[204:207], v136
	ds_read_b128 v[208:211], v136 offset:1024
	ds_read_b128 v[212:215], v136 offset:2048
	ds_read_b128 v[216:219], v136 offset:3072
	global_load_lds_dwordx4 v[220:221], off
	v_lshl_add_u64 v[220:221], v[222:223], 0, s[8:9]
	s_add_i32 m0, s29, 0x2000
	s_nop 0
	global_load_lds_dwordx4 v[220:221], off
	s_barrier
	s_waitcnt lgkmcnt(0)
	v_mfma_f32_16x16x32_bf16 v[112:115], v[204:207], v[172:175], v[112:115]
	v_mfma_f32_16x16x32_bf16 v[104:107], v[212:215], v[172:175], v[104:107]
	v_mfma_f32_16x16x32_bf16 v[92:95], v[204:207], v[180:183], v[92:95]
	v_mfma_f32_16x16x32_bf16 v[88:91], v[212:215], v[180:183], v[88:91]
	v_mfma_f32_16x16x32_bf16 v[76:79], v[204:207], v[188:191], v[76:79]
	v_mfma_f32_16x16x32_bf16 v[72:75], v[212:215], v[188:191], v[72:75]
	v_mfma_f32_16x16x32_bf16 v[68:71], v[204:207], v[196:199], v[68:71]
	v_mfma_f32_16x16x32_bf16 v[64:67], v[212:215], v[196:199], v[64:67]
	v_mfma_f32_16x16x32_bf16 v[112:115], v[208:211], v[176:179], v[112:115]
	v_mfma_f32_16x16x32_bf16 v[104:107], v[216:219], v[176:179], v[104:107]
	v_mfma_f32_16x16x32_bf16 v[92:95], v[208:211], v[184:187], v[92:95]
	v_mfma_f32_16x16x32_bf16 v[88:91], v[216:219], v[184:187], v[88:91]
	v_mfma_f32_16x16x32_bf16 v[76:79], v[208:211], v[192:195], v[76:79]
	v_mfma_f32_16x16x32_bf16 v[72:75], v[216:219], v[192:195], v[72:75]
	v_mfma_f32_16x16x32_bf16 v[68:71], v[208:211], v[200:203], v[68:71]
	v_mfma_f32_16x16x32_bf16 v[64:67], v[216:219], v[200:203], v[64:67]
	s_mov_b32 m0, s44
	v_lshl_add_u64 v[220:221], v[224:225], 0, s[8:9]
	s_barrier
	ds_read_b128 v[172:175], v151 offset:49152
	ds_read_b128 v[176:179], v151 offset:50176
	ds_read_b128 v[180:183], v151 offset:51200
	ds_read_b128 v[184:187], v151 offset:52224
	ds_read_b128 v[188:191], v151 offset:53248
	ds_read_b128 v[192:195], v151 offset:54272
	ds_read_b128 v[196:199], v151 offset:55296
	ds_read_b128 v[200:203], v151 offset:56320
	global_load_lds_dwordx4 v[220:221], off
	v_lshl_add_u64 v[220:221], v[226:227], 0, s[8:9]
	s_mov_b32 m0, s45
	s_nop 0
	global_load_lds_dwordx4 v[220:221], off
	s_barrier
; #define PG8_STAGE(bufoff, gbase, voff) do { _Pragma("unroll") for (int _i = 0; _i < 2; ++_i) \
;         __builtin_amdgcn_global_load_lds((const unsigned*)((const char*)(gbase) + (voff)[_i]), (LAS unsigned*)(lds + (bufoff) + ldsw + _i * 8192), 16, 0, 0); } while (0)
; #define PG8_LDA(dst, b, h) do { _Pragma("unroll") for (int m = 0; m < 4; ++m) _Pragma("unroll") for (int k = 0; k < 2; ++k) dst[m][k] = *(const LAS bf16x8*)(lds + PG8_SA(b, h) + aoff + m * 2048 + k * 1024); } while (0)
; #define PG8_LDB(dst, b, h) do { _Pragma("unroll") for (int n = 0; n < 2; ++n) _Pragma("unroll") for (int k = 0; k < 2; ++k) dst[n][k] = *(const LAS bf16x8*)(lds + PG8_SB(b, h) + boff + n * 2048 + k * 1024); } while (0)
; #define PG8_MMA(ai, bj, At, Bt) do { __builtin_amdgcn_s_setprio(1); _Pragma("unroll") for (int m = 0; m < 4; ++m) _Pragma("unroll") for (int n = 0; n < 2; ++n) _Pragma("unroll") for (int k = 0; k < 2; ++k) \
;         acc[ai][bj][m][n] = __builtin_amdgcn_mfma_f32_16x16x32_bf16(Bt[n][k], At[m][k], acc[ai][bj][m][n], 0, 0, 0); __builtin_amdgcn_s_setprio(0); } while (0)
; #define PG8_WAIT_V(n) asm volatile("s_waitcnt vmcnt(" #n ")" ::: "memory")
; #define PG8_WAIT_L(n) asm volatile("s_waitcnt lgkmcnt(" #n ")" ::: "memory")
; #define PG8_BAR __builtin_amdgcn_s_barrier()
; #define PG8_SCHED __builtin_amdgcn_sched_barrier(0)
; template <class Epi>
; DEVI void gemm_phase(LAS unsigned char* lds, const Gemm g, const Epi& E) {
;     ...
;             PG8_WAIT_L(8); PG8_BAR; PG8_WAIT_L(0); PG8_MMA(0, 0, At, B0); PG8_BAR; PG8_SCHED;
;             PG8_LDB(B1, 1, 1); PG8_STAGE(PG8_SB(1, 0), b3, voffB);
;             PG8_BAR; PG8_WAIT_L(0); PG8_MMA(0, 1, At, B1); PG8_BAR;
;             PG8_LDA(At, 1, 1); PG8_STAGE(PG8_SA(1, 0), a3, voffA);
;             PG8_BAR; PG8_WAIT_L(0); PG8_MMA(1, 0, At, B0); PG8_BAR; PG8_SCHED;
;             PG8_STAGE(PG8_SB(1, 1), b3 + hstepB, voffB);
;             PG8_WAIT_V(6); PG8_BAR; PG8_MMA(1, 1, At, B1); PG8_BAR;
	s_waitcnt lgkmcnt(0)
	v_mfma_f32_16x16x32_bf16 v[60:63], v[156:159], v[172:175], v[60:63]
	v_mfma_f32_16x16x32_bf16 v[56:59], v[164:167], v[172:175], v[56:59]
	v_mfma_f32_16x16x32_bf16 v[52:55], v[156:159], v[180:183], v[52:55]
	v_mfma_f32_16x16x32_bf16 v[48:51], v[164:167], v[180:183], v[48:51]
	v_mfma_f32_16x16x32_bf16 v[36:39], v[156:159], v[188:191], v[36:39]
	v_mfma_f32_16x16x32_bf16 v[32:35], v[164:167], v[188:191], v[32:35]
	v_mfma_f32_16x16x32_bf16 v[20:23], v[156:159], v[196:199], v[20:23]
	v_mfma_f32_16x16x32_bf16 v[16:19], v[164:167], v[196:199], v[16:19]
	v_mfma_f32_16x16x32_bf16 v[60:63], v[160:163], v[176:179], v[60:63]
	v_mfma_f32_16x16x32_bf16 v[56:59], v[168:171], v[176:179], v[56:59]
	v_mfma_f32_16x16x32_bf16 v[52:55], v[160:163], v[184:187], v[52:55]
	v_mfma_f32_16x16x32_bf16 v[48:51], v[168:171], v[184:187], v[48:51]
	v_mfma_f32_16x16x32_bf16 v[36:39], v[160:163], v[192:195], v[36:39]
	v_mfma_f32_16x16x32_bf16 v[32:35], v[168:171], v[192:195], v[32:35]
	v_mfma_f32_16x16x32_bf16 v[20:23], v[160:163], v[200:203], v[20:23]
	v_mfma_f32_16x16x32_bf16 v[16:19], v[168:171], v[200:203], v[16:19]
	s_barrier
	s_add_u32 s26, s26, 0x40080
	s_addc_u32 s27, s27, 0
	s_add_i32 s28, s28, s35
	v_lshl_add_u64 v[156:157], s[26:27], 0, v[130:131]
	s_mov_b32 m0, s28
	s_nop 0
	global_load_lds_dwordx4 v[156:157], off
	v_lshl_add_u64 v[156:157], s[26:27], 0, v[134:135]
	s_add_i32 m0, s28, 0x2000
	s_nop 0
	global_load_lds_dwordx4 v[156:157], off
	s_waitcnt vmcnt(6)
	s_barrier
	v_mfma_f32_16x16x32_bf16 v[44:47], v[204:207], v[172:175], v[44:47]
	v_mfma_f32_16x16x32_bf16 v[40:43], v[212:215], v[172:175], v[40:43]
	v_mfma_f32_16x16x32_bf16 v[28:31], v[204:207], v[180:183], v[28:31]
	v_mfma_f32_16x16x32_bf16 v[24:27], v[212:215], v[180:183], v[24:27]
	v_mfma_f32_16x16x32_bf16 v[12:15], v[204:207], v[188:191], v[12:15]
	v_mfma_f32_16x16x32_bf16 v[8:11], v[212:215], v[188:191], v[8:11]
	v_mfma_f32_16x16x32_bf16 v[4:7], v[204:207], v[196:199], v[4:7]
	v_mfma_f32_16x16x32_bf16 v[0:3], v[212:215], v[196:199], v[0:3]
	v_mfma_f32_16x16x32_bf16 v[44:47], v[208:211], v[176:179], v[44:47]
	v_mfma_f32_16x16x32_bf16 v[40:43], v[216:219], v[176:179], v[40:43]
	v_mfma_f32_16x16x32_bf16 v[28:31], v[208:211], v[184:187], v[28:31]
	v_mfma_f32_16x16x32_bf16 v[24:27], v[216:219], v[184:187], v[24:27]
	v_mfma_f32_16x16x32_bf16 v[12:15], v[208:211], v[192:195], v[12:15]
	v_mfma_f32_16x16x32_bf16 v[8:11], v[216:219], v[192:195], v[8:11]
	v_mfma_f32_16x16x32_bf16 v[4:7], v[208:211], v[200:203], v[4:7]
	v_mfma_f32_16x16x32_bf16 v[0:3], v[216:219], v[200:203], v[0:3]
	s_add_i32 s50, s50, 2
	s_add_u32 s0, s0, 0x100
	s_addc_u32 s1, s1, 0
	s_add_u32 s17, s17, 0x100
	s_addc_u32 s49, s49, 0
	s_cmp_gt_u32 s50, 13
	s_barrier
	s_cbranch_scc0 .LBB0_187
; template <class Epi>
; DEVI void gemm_phase(LAS unsigned char* lds, const Gemm g, const Epi& E) {
;     ...
;                     if constexpr (Epi::PAIR) E.pair8(cur.b, r, cur.pn * HALF + wc * 32 + 8 * fq, acc[ai][0][m][0] * rs, acc[ai][0][m][1] * rs, acc[ai][1][m][0] * rs, acc[ai][1][m][1] * rs);
;                     else
; #pragma unroll
;                     for (int bj = 0; bj < 2; ++bj) {
;                         const int c = col0 + bj * HALF; f32x4 v0 = acc[ai][bj][m][0], v1 = acc[ai][bj][m][1];
;                         if constexpr (Epi::RS) { v0 = v0 * rs; v1 = v1 * rs; }
;                         if constexpr (Epi::PRE) part += E.frag_pre8(cur.b, r, c, v0, v1, pre[mm][bj][0], pre[mm][bj][1]);
;                         else if constexpr (Epi::PERM) E.frag8(cur.b, r, c, v0, v1);
;                         else { E.frag(cur.b, r, c, v0); E.frag(cur.b, r, c + 16, v1); }
	s_setprio 0
	v_lshl_add_u32 v156, s48, 8, v147
	v_ashrrev_i32_e32 v157, 31, v156
	v_readlane_b32 s2, v252, 39
	v_lshlrev_b64 v[158:159], 11, v[156:157]
	v_lshl_or_b32 v155, s11, 8, v149
	v_mov_b32_e32 v157, s2
	v_readlane_b32 s2, v252, 37
	s_ashr_i32 s11, s10, 31
	v_cmp_gt_i32_e32 vcc, s42, v155
	v_mov_b32_e32 v162, s2
	v_readlane_b32 s2, v252, 38
	s_lshl_b64 s[0:1], s[10:11], 21
	v_cndmask_b32_e32 v161, v157, v162, vcc
	v_mov_b32_e32 v163, s2
	v_readlane_b32 s2, v252, 36
	v_cvt_pk_bf16_f32 v124, v124, v125
	v_cvt_pk_bf16_f32 v125, v126, v127
	v_mov_b32_e32 v164, s2
	v_cndmask_b32_e32 v160, v163, v164, vcc
	v_cvt_pk_bf16_f32 v126, v120, v121
	v_lshl_add_u64 v[120:121], v[160:161], 0, s[0:1]
	v_and_b32_e32 v136, 0x378, v155
	v_cvt_pk_bf16_f32 v127, v122, v123
	v_lshl_add_u64 v[122:123], v[120:121], 0, v[158:159]
	v_lshlrev_b32_e32 v136, 1, v136
	v_lshl_add_u64 v[122:123], v[122:123], 0, v[136:137]
	global_store_dwordx4 v[122:123], v[124:127], off
	v_or_b32_e32 v122, 0x80, v155
	v_cmp_gt_i32_e32 vcc, s42, v122
	v_cvt_pk_bf16_f32 v112, v112, v113
	v_cvt_pk_bf16_f32 v113, v114, v115
	v_cndmask_b32_e32 v123, v157, v162, vcc
	v_cndmask_b32_e32 v122, v163, v164, vcc
	v_lshl_add_u64 v[122:123], v[122:123], 0, s[0:1]
	s_movk_i32 s0, 0x3f8
	v_cvt_pk_bf16_f32 v115, v106, v107
	v_bitop3_b32 v106, v155, s0, v153 bitop3:0xc8
	v_cvt_pk_bf16_f32 v114, v104, v105
	v_lshl_add_u64 v[104:105], v[122:123], 0, v[158:159]
	v_lshlrev_b32_e32 v124, 1, v106
	v_mov_b32_e32 v125, v137
	v_lshl_add_u64 v[104:105], v[104:105], 0, v[124:125]
	global_store_dwordx4 v[104:105], v[112:115], off
	v_or_b32_e32 v104, 16, v156
	v_ashrrev_i32_e32 v105, 31, v104
	v_lshlrev_b64 v[112:113], 11, v[104:105]
	v_cvt_pk_bf16_f32 v106, v108, v109
	v_lshl_add_u64 v[108:109], v[120:121], 0, v[112:113]
	v_cvt_pk_bf16_f32 v92, v92, v93
	v_cvt_pk_bf16_f32 v93, v94, v95
	v_cvt_pk_bf16_f32 v94, v88, v89
	v_lshl_add_u64 v[88:89], v[122:123], 0, v[112:113]
	v_cvt_pk_bf16_f32 v104, v116, v117
	v_cvt_pk_bf16_f32 v105, v118, v119
	v_cvt_pk_bf16_f32 v107, v110, v111
	v_lshl_add_u64 v[108:109], v[108:109], 0, v[136:137]
	v_cvt_pk_bf16_f32 v95, v90, v91
	v_lshl_add_u64 v[88:89], v[88:89], 0, v[124:125]
	global_store_dwordx4 v[108:109], v[104:107], off
	global_store_dwordx4 v[88:89], v[92:95], off
	v_or_b32_e32 v88, 32, v156
	v_ashrrev_i32_e32 v89, 31, v88
	v_lshlrev_b64 v[92:93], 11, v[88:89]
	v_lshl_add_u64 v[94:95], v[120:121], 0, v[92:93]
	v_cvt_pk_bf16_f32 v76, v76, v77
	v_cvt_pk_bf16_f32 v77, v78, v79
	v_cvt_pk_bf16_f32 v78, v72, v73
	v_lshl_add_u64 v[72:73], v[122:123], 0, v[92:93]
	v_cvt_pk_bf16_f32 v88, v100, v101
	v_cvt_pk_bf16_f32 v89, v102, v103
	v_cvt_pk_bf16_f32 v90, v96, v97
	v_cvt_pk_bf16_f32 v91, v98, v99
	v_lshl_add_u64 v[94:95], v[94:95], 0, v[136:137]
	v_cvt_pk_bf16_f32 v79, v74, v75
	v_lshl_add_u64 v[72:73], v[72:73], 0, v[124:125]
	global_store_dwordx4 v[94:95], v[88:91], off
	global_store_dwordx4 v[72:73], v[76:79], off
	v_or_b32_e32 v72, 48, v156
	v_ashrrev_i32_e32 v73, 31, v72
	v_lshlrev_b64 v[76:77], 11, v[72:73]
	v_lshl_add_u64 v[78:79], v[120:121], 0, v[76:77]
	v_cvt_pk_bf16_f32 v68, v68, v69
	v_cvt_pk_bf16_f32 v69, v70, v71
	v_cvt_pk_bf16_f32 v70, v64, v65
	v_lshl_add_u64 v[64:65], v[122:123], 0, v[76:77]
	v_cvt_pk_bf16_f32 v72, v84, v85
	v_cvt_pk_bf16_f32 v73, v86, v87
	v_cvt_pk_bf16_f32 v74, v80, v81
	v_cvt_pk_bf16_f32 v75, v82, v83
	v_lshl_add_u64 v[78:79], v[78:79], 0, v[136:137]
	v_cvt_pk_bf16_f32 v71, v66, v67
	v_lshl_add_u64 v[64:65], v[64:65], 0, v[124:125]
	s_mov_b64 s[0:1], 0x40000
	global_store_dwordx4 v[78:79], v[72:75], off
	global_store_dwordx4 v[64:65], v[68:71], off
	v_lshl_add_u64 v[64:65], v[158:159], 0, s[0:1]
	v_cvt_pk_bf16_f32 v60, v60, v61
	v_cvt_pk_bf16_f32 v61, v62, v63
	v_cvt_pk_bf16_f32 v62, v56, v57
	v_lshl_add_u64 v[56:57], v[120:121], 0, v[64:65]
	v_cvt_pk_bf16_f32 v44, v44, v45
	v_cvt_pk_bf16_f32 v45, v46, v47
	v_cvt_pk_bf16_f32 v46, v40, v41
	v_lshl_add_u64 v[40:41], v[122:123], 0, v[64:65]
	v_cvt_pk_bf16_f32 v63, v58, v59
	v_lshl_add_u64 v[56:57], v[56:57], 0, v[136:137]
	v_cvt_pk_bf16_f32 v47, v42, v43
	v_lshl_add_u64 v[40:41], v[40:41], 0, v[124:125]
	s_mov_b64 s[0:1], 0x48000
	global_store_dwordx4 v[56:57], v[60:63], off
	global_store_dwordx4 v[40:41], v[44:47], off
	v_cvt_pk_bf16_f32 v28, v28, v29
	v_cvt_pk_bf16_f32 v29, v30, v31
	v_lshl_add_u64 v[44:45], v[158:159], 0, s[0:1]
	v_lshl_add_u64 v[46:47], v[120:121], 0, v[44:45]
	v_cvt_pk_bf16_f32 v30, v24, v25
	v_lshl_add_u64 v[24:25], v[122:123], 0, v[44:45]
	v_cvt_pk_bf16_f32 v40, v52, v53
	v_cvt_pk_bf16_f32 v41, v54, v55
	v_cvt_pk_bf16_f32 v42, v48, v49
	v_cvt_pk_bf16_f32 v43, v50, v51
	v_lshl_add_u64 v[46:47], v[46:47], 0, v[136:137]
	v_cvt_pk_bf16_f32 v31, v26, v27
	v_lshl_add_u64 v[24:25], v[24:25], 0, v[124:125]
	s_mov_b64 s[0:1], 0x50000
	global_store_dwordx4 v[46:47], v[40:43], off
	global_store_dwordx4 v[24:25], v[28:31], off
	v_cvt_pk_bf16_f32 v12, v12, v13
	v_cvt_pk_bf16_f32 v13, v14, v15
	v_lshl_add_u64 v[28:29], v[158:159], 0, s[0:1]
	v_lshl_add_u64 v[30:31], v[120:121], 0, v[28:29]
	v_cvt_pk_bf16_f32 v14, v8, v9
	v_lshl_add_u64 v[8:9], v[122:123], 0, v[28:29]
	v_cvt_pk_bf16_f32 v24, v36, v37
	v_cvt_pk_bf16_f32 v25, v38, v39
	v_cvt_pk_bf16_f32 v26, v32, v33
	v_cvt_pk_bf16_f32 v27, v34, v35
	v_lshl_add_u64 v[30:31], v[30:31], 0, v[136:137]
	v_cvt_pk_bf16_f32 v15, v10, v11
	v_lshl_add_u64 v[8:9], v[8:9], 0, v[124:125]
	s_mov_b64 s[0:1], 0x58000
	global_store_dwordx4 v[30:31], v[24:27], off
	global_store_dwordx4 v[8:9], v[12:15], off
	v_cvt_pk_bf16_f32 v4, v4, v5
	v_cvt_pk_bf16_f32 v5, v6, v7
	v_lshl_add_u64 v[12:13], v[158:159], 0, s[0:1]
	v_lshl_add_u64 v[14:15], v[120:121], 0, v[12:13]
	v_cvt_pk_bf16_f32 v6, v0, v1
	v_lshl_add_u64 v[0:1], v[122:123], 0, v[12:13]
	v_cvt_pk_bf16_f32 v8, v20, v21
	v_cvt_pk_bf16_f32 v9, v22, v23
	v_cvt_pk_bf16_f32 v10, v16, v17
	v_cvt_pk_bf16_f32 v11, v18, v19
	v_lshl_add_u64 v[14:15], v[14:15], 0, v[136:137]
	v_cvt_pk_bf16_f32 v7, v2, v3
	v_lshl_add_u64 v[0:1], v[0:1], 0, v[124:125]
	s_and_b64 vcc, exec, s[4:5]
	s_mov_b32 s10, s12
	s_mov_b32 s11, s14
	s_mov_b32 s48, s16
	s_mov_b64 s[28:29], s[18:19]
	s_mov_b64 s[26:27], s[24:25]
	global_store_dwordx4 v[14:15], v[8:11], off
	global_store_dwordx4 v[0:1], v[4:7], off
	s_cbranch_vccz .LBB0_178
	s_waitcnt vmcnt(0)
	s_cmpk_gt_u32 s34, 0xff
	s_cbranch_scc1 .LBB0_191
	s_barrier

; #define PG8_STAGE(bufoff, gbase, voff) do { _Pragma("unroll") for (int _i = 0; _i < 2; ++_i) \
;         __builtin_amdgcn_global_load_lds((const unsigned*)((const char*)(gbase) + (voff)[_i]), (LAS unsigned*)(lds + (bufoff) + ldsw + _i * 8192), 16, 0, 0); } while (0)
; #define PG8_LDA(dst, b, h) do { _Pragma("unroll") for (int m = 0; m < 4; ++m) _Pragma("unroll") for (int k = 0; k < 2; ++k) dst[m][k] = *(const LAS bf16x8*)(lds + PG8_SA(b, h) + aoff + m * 2048 + k * 1024); } while (0)
; #define PG8_LDB(dst, b, h) do { _Pragma("unroll") for (int n = 0; n < 2; ++n) _Pragma("unroll") for (int k = 0; k < 2; ++k) dst[n][k] = *(const LAS bf16x8*)(lds + PG8_SB(b, h) + boff + n * 2048 + k * 1024); } while (0)
; #define PG8_MMA(ai, bj, At, Bt) do { __builtin_amdgcn_s_setprio(1); _Pragma("unroll") for (int m = 0; m < 4; ++m) _Pragma("unroll") for (int n = 0; n < 2; ++n) _Pragma("unroll") for (int k = 0; k < 2; ++k) \
;         acc[ai][bj][m][n] = __builtin_amdgcn_mfma_f32_16x16x32_bf16(Bt[n][k], At[m][k], acc[ai][bj][m][n], 0, 0, 0); __builtin_amdgcn_s_setprio(0); } while (0)
; template <class Epi>
; DEVI void gemm_phase(LAS unsigned char* lds, const Gemm g, const Epi& E) {
;     ...
;         for (int t = 0; t < nt; t += 2) {
;             const bool last = (t == nt - 2);
;             const char* a1 = cA + (size_t)(t + 1) * kstep;
;             const char* a2 = last ? nA : cA + (size_t)(t + 2) * kstep; const char* b2 = last ? nB : cB + (size_t)(t + 2) * kstep;
;             const char* a3 = a2 + kstep; const char* b3 = b2 + kstep;
;             PG8_LDB(B0, 0, 0); PG8_SCHED; PG8_LDA(At, 0, 0); PG8_STAGE(PG8_SA(1, 1), a1 + hstepA, voffA);
;             PG8_WAIT_L(8); PG8_BAR; PG8_WAIT_L(0); PG8_MMA(0, 0, At, B0); PG8_BAR; PG8_SCHED;
;             PG8_LDB(B1, 0, 1); PG8_STAGE(PG8_SB(0, 0), b2, voffB);
;             PG8_BAR; PG8_WAIT_L(0); PG8_MMA(0, 1, At, B1); PG8_BAR;
;             PG8_LDA(At, 0, 1); PG8_STAGE(PG8_SA(0, 0), a2, voffA);
;             PG8_BAR; PG8_WAIT_L(0); PG8_MMA(1, 0, At, B0); PG8_BAR; PG8_SCHED;
;             PG8_STAGE(PG8_SB(0, 1), b2 + hstepB, voffB);
;             PG8_WAIT_V(6); PG8_BAR; PG8_MMA(1, 1, At, B1); PG8_BAR;
;             PG8_LDB(B0, 1, 0); PG8_SCHED; PG8_LDA(At, 1, 0); PG8_STAGE(PG8_SA(0, 1), a2 + hstepA, voffA);
;             PG8_WAIT_L(8); PG8_BAR; PG8_WAIT_L(0); PG8_MMA(0, 0, At, B0); PG8_BAR; PG8_SCHED;
.LBB0_276:
	s_add_u32 s19, s8, 0xfffc0080
	s_addc_u32 s26, s9, -1
	s_add_i32 s27, 0, 0x10000
	v_add_u32_e32 v8, s27, v214
	ds_read_b128 v[130:133], v8
	ds_read_b128 v[134:137], v8 offset:1024
	ds_read_b128 v[138:141], v8 offset:2048
	ds_read_b128 v[142:145], v8 offset:3072
	s_cmp_eq_u32 s18, 12
	s_cselect_b32 s69, s0, s26
	s_cselect_b32 s68, s1, s19
	s_cselect_b32 s47, s5, s15
	s_cselect_b32 s46, s7, s13
	v_lshl_add_u64 v[208:209], s[8:9], 0, v[184:185]
	s_add_i32 m0, s81, 0xc000
	ds_read_b128 v[146:149], v216
	ds_read_b128 v[150:153], v216 offset:1024
	ds_read_b128 v[188:191], v216 offset:2048
	ds_read_b128 v[192:195], v216 offset:3072
	ds_read_b128 v[196:199], v216 offset:4096
	ds_read_b128 v[200:203], v216 offset:5120
	ds_read_b128 v[204:207], v216 offset:6144
	ds_read_b128 v[218:221], v216 offset:7168
	global_load_lds_dwordx4 v[208:209], off
	v_lshl_add_u64 v[208:209], s[8:9], 0, v[186:187]
	s_add_i32 m0, s81, 0xe000
	s_nop 0
	global_load_lds_dwordx4 v[208:209], off
	s_waitcnt lgkmcnt(8)
	s_barrier
	s_waitcnt lgkmcnt(0)
	s_waitcnt lgkmcnt(0)
	s_cmp_lg_u32 s101, 0
	s_cbranch_scc1 .Lip13_a_0
	v_mfma_f32_16x16x32_bf16 v[126:129], v[130:133], v[146:149], v[126:129]
	v_mfma_f32_16x16x32_bf16 v[122:125], v[138:141], v[146:149], v[122:125]
	v_mfma_f32_16x16x32_bf16 v[114:117], v[130:133], v[188:191], v[114:117]
	v_mfma_f32_16x16x32_bf16 v[106:109], v[138:141], v[188:191], v[106:109]
	v_mfma_f32_16x16x32_bf16 v[94:97], v[130:133], v[196:199], v[94:97]
	v_mfma_f32_16x16x32_bf16 v[90:93], v[138:141], v[196:199], v[90:93]
	v_mfma_f32_16x16x32_bf16 v[82:85], v[130:133], v[204:207], v[82:85]
	v_mfma_f32_16x16x32_bf16 v[74:77], v[138:141], v[204:207], v[74:77]
	v_mfma_f32_16x16x32_bf16 v[126:129], v[134:137], v[150:153], v[126:129]
	v_mfma_f32_16x16x32_bf16 v[122:125], v[142:145], v[150:153], v[122:125]
	v_mfma_f32_16x16x32_bf16 v[114:117], v[134:137], v[192:195], v[114:117]
	v_mfma_f32_16x16x32_bf16 v[106:109], v[142:145], v[192:195], v[106:109]
	v_mfma_f32_16x16x32_bf16 v[94:97], v[134:137], v[200:203], v[94:97]
	v_mfma_f32_16x16x32_bf16 v[90:93], v[142:145], v[200:203], v[90:93]
	v_mfma_f32_16x16x32_bf16 v[82:85], v[134:137], v[218:221], v[82:85]
	v_mfma_f32_16x16x32_bf16 v[74:77], v[142:145], v[218:221], v[74:77]
.Lip13_a_0:
	s_barrier
	s_add_i32 s19, 0, 0x14000
	s_add_i32 s26, s27, s80
	v_add_u32_e32 v8, s19, v214
	v_lshl_add_u64 v[208:209], s[46:47], 0, v[178:179]
	s_mov_b32 m0, s26
	ds_read_b128 v[222:225], v8
	ds_read_b128 v[226:229], v8 offset:1024
	ds_read_b128 v[230:233], v8 offset:2048
	ds_read_b128 v[234:237], v8 offset:3072
	global_load_lds_dwordx4 v[208:209], off
	v_lshl_add_u64 v[238:239], s[46:47], 0, v[182:183]
	s_add_i32 m0, s26, 0x2000
	s_nop 0
	global_load_lds_dwordx4 v[238:239], off
	s_barrier
	s_waitcnt lgkmcnt(0)
	s_waitcnt lgkmcnt(0)
	s_cmp_lg_u32 s100, 0
	s_cbranch_scc1 .Lip13_a_1
	v_mfma_f32_16x16x32_bf16 v[118:121], v[222:225], v[146:149], v[118:121]
	v_mfma_f32_16x16x32_bf16 v[110:113], v[230:233], v[146:149], v[110:113]
	v_mfma_f32_16x16x32_bf16 v[102:105], v[222:225], v[188:191], v[102:105]
	v_mfma_f32_16x16x32_bf16 v[98:101], v[230:233], v[188:191], v[98:101]
	v_mfma_f32_16x16x32_bf16 v[86:89], v[222:225], v[196:199], v[86:89]
	v_mfma_f32_16x16x32_bf16 v[78:81], v[230:233], v[196:199], v[78:81]
	v_mfma_f32_16x16x32_bf16 v[62:65], v[222:225], v[204:207], v[62:65]
	v_mfma_f32_16x16x32_bf16 v[58:61], v[230:233], v[204:207], v[58:61]
	v_mfma_f32_16x16x32_bf16 v[118:121], v[226:229], v[150:153], v[118:121]
	v_mfma_f32_16x16x32_bf16 v[110:113], v[234:237], v[150:153], v[110:113]
	v_mfma_f32_16x16x32_bf16 v[102:105], v[226:229], v[192:195], v[102:105]
	v_mfma_f32_16x16x32_bf16 v[98:101], v[234:237], v[192:195], v[98:101]
	v_mfma_f32_16x16x32_bf16 v[86:89], v[226:229], v[200:203], v[86:89]
	v_mfma_f32_16x16x32_bf16 v[78:81], v[234:237], v[200:203], v[78:81]
	v_mfma_f32_16x16x32_bf16 v[62:65], v[226:229], v[218:221], v[62:65]
	v_mfma_f32_16x16x32_bf16 v[58:61], v[234:237], v[218:221], v[58:61]
.Lip13_a_1:
	s_mov_b32 m0, s81
	v_lshl_add_u64 v[240:241], s[68:69], 0, v[176:177]
	s_barrier
	ds_read_b128 v[146:149], v216 offset:16384
	ds_read_b128 v[150:153], v216 offset:17408
	ds_read_b128 v[188:191], v216 offset:18432
	ds_read_b128 v[192:195], v216 offset:19456
	ds_read_b128 v[196:199], v216 offset:20480
	ds_read_b128 v[200:203], v216 offset:21504
	ds_read_b128 v[204:207], v216 offset:22528
	ds_read_b128 v[218:221], v216 offset:23552
	global_load_lds_dwordx4 v[240:241], off
	v_lshl_add_u64 v[242:243], s[68:69], 0, v[180:181]
	s_mov_b32 m0, s82
	s_nop 0
	global_load_lds_dwordx4 v[242:243], off
	s_barrier
	s_waitcnt lgkmcnt(0)
	s_waitcnt lgkmcnt(0)
	s_cmp_lg_u32 s101, 0
	s_cbranch_scc1 .Lip13_a_2
	v_mfma_f32_16x16x32_bf16 v[70:73], v[130:133], v[146:149], v[70:73]
	v_mfma_f32_16x16x32_bf16 v[66:69], v[138:141], v[146:149], v[66:69]
	v_mfma_f32_16x16x32_bf16 v[46:49], v[130:133], v[188:191], v[46:49]
	v_mfma_f32_16x16x32_bf16 v[42:45], v[138:141], v[188:191], v[42:45]
	v_mfma_f32_16x16x32_bf16 v[30:33], v[130:133], v[196:199], v[30:33]
	v_mfma_f32_16x16x32_bf16 v[26:29], v[138:141], v[196:199], v[26:29]
	v_mfma_f32_16x16x32_bf16 v[14:17], v[130:133], v[204:207], v[14:17]
	v_mfma_f32_16x16x32_bf16 v[10:13], v[138:141], v[204:207], v[10:13]
	v_mfma_f32_16x16x32_bf16 v[70:73], v[134:137], v[150:153], v[70:73]
	v_mfma_f32_16x16x32_bf16 v[66:69], v[142:145], v[150:153], v[66:69]
	v_mfma_f32_16x16x32_bf16 v[46:49], v[134:137], v[192:195], v[46:49]
	v_mfma_f32_16x16x32_bf16 v[42:45], v[142:145], v[192:195], v[42:45]
	v_mfma_f32_16x16x32_bf16 v[30:33], v[134:137], v[200:203], v[30:33]
	v_mfma_f32_16x16x32_bf16 v[26:29], v[142:145], v[200:203], v[26:29]
	v_mfma_f32_16x16x32_bf16 v[14:17], v[134:137], v[218:221], v[14:17]
	v_mfma_f32_16x16x32_bf16 v[10:13], v[142:145], v[218:221], v[10:13]
; #define PG8_STAGE(bufoff, gbase, voff) do { _Pragma("unroll") for (int _i = 0; _i < 2; ++_i) \
;         __builtin_amdgcn_global_load_lds((const unsigned*)((const char*)(gbase) + (voff)[_i]), (LAS unsigned*)(lds + (bufoff) + ldsw + _i * 8192), 16, 0, 0); } while (0)
; #define PG8_LDA(dst, b, h) do { _Pragma("unroll") for (int m = 0; m < 4; ++m) _Pragma("unroll") for (int k = 0; k < 2; ++k) dst[m][k] = *(const LAS bf16x8*)(lds + PG8_SA(b, h) + aoff + m * 2048 + k * 1024); } while (0)
; #define PG8_LDB(dst, b, h) do { _Pragma("unroll") for (int n = 0; n < 2; ++n) _Pragma("unroll") for (int k = 0; k < 2; ++k) dst[n][k] = *(const LAS bf16x8*)(lds + PG8_SB(b, h) + boff + n * 2048 + k * 1024); } while (0)
; #define PG8_MMA(ai, bj, At, Bt) do { __builtin_amdgcn_s_setprio(1); _Pragma("unroll") for (int m = 0; m < 4; ++m) _Pragma("unroll") for (int n = 0; n < 2; ++n) _Pragma("unroll") for (int k = 0; k < 2; ++k) \
;         acc[ai][bj][m][n] = __builtin_amdgcn_mfma_f32_16x16x32_bf16(Bt[n][k], At[m][k], acc[ai][bj][m][n], 0, 0, 0); __builtin_amdgcn_s_setprio(0); } while (0)
; #define PG8_WAIT_V(n) asm volatile("s_waitcnt vmcnt(" #n ")" ::: "memory")
; #define PG8_WAIT_L(n) asm volatile("s_waitcnt lgkmcnt(" #n ")" ::: "memory")
; #define PG8_BAR __builtin_amdgcn_s_barrier()
; #define PG8_SCHED __builtin_amdgcn_sched_barrier(0)
; template <class Epi>
; DEVI void gemm_phase(LAS unsigned char* lds, const Gemm g, const Epi& E) {
;     ...
;             PG8_WAIT_V(6); PG8_BAR; PG8_MMA(1, 1, At, B1); PG8_BAR;
;             PG8_LDB(B0, 1, 0); PG8_SCHED; PG8_LDA(At, 1, 0); PG8_STAGE(PG8_SA(0, 1), a2 + hstepA, voffA);
;             PG8_WAIT_L(8); PG8_BAR; PG8_WAIT_L(0); PG8_MMA(0, 0, At, B0); PG8_BAR; PG8_SCHED;
;             PG8_LDB(B1, 1, 1); PG8_STAGE(PG8_SB(1, 0), b3, voffB);
;             PG8_BAR; PG8_WAIT_L(0); PG8_MMA(0, 1, At, B1); PG8_BAR;
;             PG8_LDA(At, 1, 1); PG8_STAGE(PG8_SA(1, 0), a3, voffA);
;             PG8_BAR; PG8_WAIT_L(0); PG8_MMA(1, 0, At, B0); PG8_BAR; PG8_SCHED;
.Lip13_a_2:
	s_barrier
	s_add_u32 s26, s46, 0x40000
	s_addc_u32 s27, s47, 0
	s_add_i32 s19, s19, s80
	v_lshl_add_u64 v[130:131], s[26:27], 0, v[178:179]
	s_mov_b32 m0, s19
	s_nop 0
	global_load_lds_dwordx4 v[130:131], off
	v_lshl_add_u64 v[130:131], s[26:27], 0, v[182:183]
	s_add_i32 m0, s19, 0x2000
	s_nop 0
	global_load_lds_dwordx4 v[130:131], off
	s_waitcnt vmcnt(6)
	s_barrier
	s_cmp_lg_u32 s100, 0
	s_cbranch_scc1 .Lip13_a_3
	v_mfma_f32_16x16x32_bf16 v[50:53], v[222:225], v[146:149], v[50:53]
	v_mfma_f32_16x16x32_bf16 v[54:57], v[230:233], v[146:149], v[54:57]
	v_mfma_f32_16x16x32_bf16 v[34:37], v[222:225], v[188:191], v[34:37]
	v_mfma_f32_16x16x32_bf16 v[38:41], v[230:233], v[188:191], v[38:41]
	v_mfma_f32_16x16x32_bf16 v[18:21], v[222:225], v[196:199], v[18:21]
	v_mfma_f32_16x16x32_bf16 v[22:25], v[230:233], v[196:199], v[22:25]
	v_mfma_f32_16x16x32_bf16 v[0:3], v[222:225], v[204:207], v[0:3]
	v_mfma_f32_16x16x32_bf16 v[4:7], v[230:233], v[204:207], v[4:7]
	v_mfma_f32_16x16x32_bf16 v[50:53], v[226:229], v[150:153], v[50:53]
	v_mfma_f32_16x16x32_bf16 v[54:57], v[234:237], v[150:153], v[54:57]
	v_mfma_f32_16x16x32_bf16 v[34:37], v[226:229], v[192:195], v[34:37]
	v_mfma_f32_16x16x32_bf16 v[38:41], v[234:237], v[192:195], v[38:41]
	v_mfma_f32_16x16x32_bf16 v[18:21], v[226:229], v[200:203], v[18:21]
	v_mfma_f32_16x16x32_bf16 v[22:25], v[234:237], v[200:203], v[22:25]
	v_mfma_f32_16x16x32_bf16 v[0:3], v[226:229], v[218:221], v[0:3]
	v_mfma_f32_16x16x32_bf16 v[4:7], v[234:237], v[218:221], v[4:7]
.Lip13_a_3:
	s_add_i32 s19, 0, 0x18000
	v_add_u32_e32 v8, s19, v214
	s_barrier
	ds_read_b128 v[130:133], v8
	ds_read_b128 v[134:137], v8 offset:1024
	ds_read_b128 v[138:141], v8 offset:2048
	ds_read_b128 v[142:145], v8 offset:3072
	s_add_u32 s26, s68, 0x40000
	s_addc_u32 s27, s69, 0
	s_mov_b32 m0, s83
	v_lshl_add_u64 v[222:223], s[26:27], 0, v[176:177]
	ds_read_b128 v[146:149], v216 offset:32768
	ds_read_b128 v[150:153], v216 offset:33792
	ds_read_b128 v[188:191], v216 offset:34816
	ds_read_b128 v[192:195], v216 offset:35840
	ds_read_b128 v[196:199], v216 offset:36864
	ds_read_b128 v[200:203], v216 offset:37888
	ds_read_b128 v[204:207], v216 offset:38912
	ds_read_b128 v[218:221], v216 offset:39936
	global_load_lds_dwordx4 v[222:223], off
	v_lshl_add_u64 v[222:223], s[26:27], 0, v[180:181]
	s_mov_b32 m0, s84
	s_nop 0
	global_load_lds_dwordx4 v[222:223], off
	s_waitcnt lgkmcnt(8)
	s_barrier
	s_waitcnt lgkmcnt(0)
	s_waitcnt lgkmcnt(0)
	s_cmp_lg_u32 s101, 0
	s_cbranch_scc1 .Lip13_a_4
	v_mfma_f32_16x16x32_bf16 v[126:129], v[130:133], v[146:149], v[126:129]
	v_mfma_f32_16x16x32_bf16 v[122:125], v[138:141], v[146:149], v[122:125]
	v_mfma_f32_16x16x32_bf16 v[114:117], v[130:133], v[188:191], v[114:117]
	v_mfma_f32_16x16x32_bf16 v[106:109], v[138:141], v[188:191], v[106:109]
	v_mfma_f32_16x16x32_bf16 v[94:97], v[130:133], v[196:199], v[94:97]
	v_mfma_f32_16x16x32_bf16 v[90:93], v[138:141], v[196:199], v[90:93]
	v_mfma_f32_16x16x32_bf16 v[82:85], v[130:133], v[204:207], v[82:85]
	v_mfma_f32_16x16x32_bf16 v[74:77], v[138:141], v[204:207], v[74:77]
	v_mfma_f32_16x16x32_bf16 v[126:129], v[134:137], v[150:153], v[126:129]
	v_mfma_f32_16x16x32_bf16 v[122:125], v[142:145], v[150:153], v[122:125]
	v_mfma_f32_16x16x32_bf16 v[114:117], v[134:137], v[192:195], v[114:117]
	v_mfma_f32_16x16x32_bf16 v[106:109], v[142:145], v[192:195], v[106:109]
	v_mfma_f32_16x16x32_bf16 v[94:97], v[134:137], v[200:203], v[94:97]
	v_mfma_f32_16x16x32_bf16 v[90:93], v[142:145], v[200:203], v[90:93]
	v_mfma_f32_16x16x32_bf16 v[82:85], v[134:137], v[218:221], v[82:85]
	v_mfma_f32_16x16x32_bf16 v[74:77], v[142:145], v[218:221], v[74:77]
.Lip13_a_4:
	s_barrier
	s_add_i32 s38, 0, 0x1c000
	s_add_i32 s19, s19, s80
	v_add_u32_e32 v8, s38, v214
	v_lshl_add_u64 v[208:209], v[208:209], 0, s[70:71]
	s_mov_b32 m0, s19
	ds_read_b128 v[222:225], v8
	ds_read_b128 v[226:229], v8 offset:1024
	ds_read_b128 v[230:233], v8 offset:2048
	ds_read_b128 v[234:237], v8 offset:3072
	global_load_lds_dwordx4 v[208:209], off
	v_lshl_add_u64 v[208:209], v[238:239], 0, s[70:71]
	s_add_i32 m0, s19, 0x2000
	s_nop 0
	global_load_lds_dwordx4 v[208:209], off
	s_barrier
	s_waitcnt lgkmcnt(0)
	s_waitcnt lgkmcnt(0)
	s_cmp_lg_u32 s100, 0
	s_cbranch_scc1 .Lip13_a_5
	v_mfma_f32_16x16x32_bf16 v[118:121], v[222:225], v[146:149], v[118:121]
	v_mfma_f32_16x16x32_bf16 v[110:113], v[230:233], v[146:149], v[110:113]
	v_mfma_f32_16x16x32_bf16 v[102:105], v[222:225], v[188:191], v[102:105]
	v_mfma_f32_16x16x32_bf16 v[98:101], v[230:233], v[188:191], v[98:101]
	v_mfma_f32_16x16x32_bf16 v[86:89], v[222:225], v[196:199], v[86:89]
	v_mfma_f32_16x16x32_bf16 v[78:81], v[230:233], v[196:199], v[78:81]
	v_mfma_f32_16x16x32_bf16 v[62:65], v[222:225], v[204:207], v[62:65]
	v_mfma_f32_16x16x32_bf16 v[58:61], v[230:233], v[204:207], v[58:61]
	v_mfma_f32_16x16x32_bf16 v[118:121], v[226:229], v[150:153], v[118:121]
	v_mfma_f32_16x16x32_bf16 v[110:113], v[234:237], v[150:153], v[110:113]
	v_mfma_f32_16x16x32_bf16 v[102:105], v[226:229], v[192:195], v[102:105]
	v_mfma_f32_16x16x32_bf16 v[98:101], v[234:237], v[192:195], v[98:101]
	v_mfma_f32_16x16x32_bf16 v[86:89], v[226:229], v[200:203], v[86:89]
	v_mfma_f32_16x16x32_bf16 v[78:81], v[234:237], v[200:203], v[78:81]
	v_mfma_f32_16x16x32_bf16 v[62:65], v[226:229], v[218:221], v[62:65]
	v_mfma_f32_16x16x32_bf16 v[58:61], v[234:237], v[218:221], v[58:61]
; template <class Epi>
; DEVI void gemm_phase(LAS unsigned char* lds, const Gemm g, const Epi& E) {
;     ...
;         {
;             const int row0 = cur.pm * BM + wr * 64 + fr, col0 = cur.pn * BM + wc * 32 + (Epi::PERM ? 8 : 4) * fq; constexpr int NST = Epi::PERM ? 4 : 16;
;             float rsv[8];
;             if constexpr (Epi::RS) { f32x4 q4[8];
; #pragma unroll
;                 for (int i = 0; i < 8; ++i) q4[i] = *(const f32x4*)(E.ssq_in + (size_t)(row0 + (i >> 2) * HALF + (i & 3) * 16) * 4);
; #pragma unroll
;                 for (int i = 0; i < 8; ++i) rsv[i] = rsqrtf((((q4[i][0] + q4[i][1]) + q4[i][2]) + q4[i][3]) * (1.f / DM) + 1e-6f); }
.Lip13_a_5:
	s_mov_b32 m0, s85
	v_lshl_add_u64 v[208:209], v[240:241], 0, s[70:71]
	s_barrier
	ds_read_b128 v[146:149], v216 offset:49152
	ds_read_b128 v[150:153], v216 offset:50176
	ds_read_b128 v[188:191], v216 offset:51200
	ds_read_b128 v[192:195], v216 offset:52224
	ds_read_b128 v[196:199], v216 offset:53248
	ds_read_b128 v[200:203], v216 offset:54272
	ds_read_b128 v[204:207], v216 offset:55296
	ds_read_b128 v[218:221], v216 offset:56320
	global_load_lds_dwordx4 v[208:209], off
	v_lshl_add_u64 v[208:209], v[242:243], 0, s[70:71]
	s_mov_b32 m0, s86
	s_nop 0
	global_load_lds_dwordx4 v[208:209], off
	s_barrier
	s_waitcnt lgkmcnt(0)
	s_waitcnt lgkmcnt(0)
	s_cmp_lg_u32 s101, 0
	s_cbranch_scc1 .Lip13_a_6
	v_mfma_f32_16x16x32_bf16 v[70:73], v[130:133], v[146:149], v[70:73]
	v_mfma_f32_16x16x32_bf16 v[66:69], v[138:141], v[146:149], v[66:69]
	v_mfma_f32_16x16x32_bf16 v[46:49], v[130:133], v[188:191], v[46:49]
	v_mfma_f32_16x16x32_bf16 v[42:45], v[138:141], v[188:191], v[42:45]
	v_mfma_f32_16x16x32_bf16 v[30:33], v[130:133], v[196:199], v[30:33]
	v_mfma_f32_16x16x32_bf16 v[26:29], v[138:141], v[196:199], v[26:29]
	v_mfma_f32_16x16x32_bf16 v[14:17], v[130:133], v[204:207], v[14:17]
	v_mfma_f32_16x16x32_bf16 v[10:13], v[138:141], v[204:207], v[10:13]
	v_mfma_f32_16x16x32_bf16 v[70:73], v[134:137], v[150:153], v[70:73]
	v_mfma_f32_16x16x32_bf16 v[66:69], v[142:145], v[150:153], v[66:69]
	v_mfma_f32_16x16x32_bf16 v[46:49], v[134:137], v[192:195], v[46:49]
	v_mfma_f32_16x16x32_bf16 v[42:45], v[142:145], v[192:195], v[42:45]
	v_mfma_f32_16x16x32_bf16 v[30:33], v[134:137], v[200:203], v[30:33]
	v_mfma_f32_16x16x32_bf16 v[26:29], v[142:145], v[200:203], v[26:29]
	v_mfma_f32_16x16x32_bf16 v[14:17], v[134:137], v[218:221], v[14:17]
	v_mfma_f32_16x16x32_bf16 v[10:13], v[142:145], v[218:221], v[10:13]
.Lip13_a_6:
	s_barrier
	s_add_u32 s26, s46, 0x40080
	s_addc_u32 s27, s47, 0
	s_add_i32 s19, s38, s80
	v_lshl_add_u64 v[130:131], s[26:27], 0, v[178:179]
	s_mov_b32 m0, s19
	s_nop 0
	global_load_lds_dwordx4 v[130:131], off
	v_lshl_add_u64 v[130:131], s[26:27], 0, v[182:183]
	s_add_i32 m0, s19, 0x2000
	s_nop 0
	global_load_lds_dwordx4 v[130:131], off
	s_waitcnt vmcnt(6)
	s_barrier
	s_cmp_lg_u32 s100, 0
	s_cbranch_scc1 .Lip13_a_7
	v_mfma_f32_16x16x32_bf16 v[50:53], v[222:225], v[146:149], v[50:53]
	v_mfma_f32_16x16x32_bf16 v[54:57], v[230:233], v[146:149], v[54:57]
	v_mfma_f32_16x16x32_bf16 v[34:37], v[222:225], v[188:191], v[34:37]
	v_mfma_f32_16x16x32_bf16 v[38:41], v[230:233], v[188:191], v[38:41]
	v_mfma_f32_16x16x32_bf16 v[18:21], v[222:225], v[196:199], v[18:21]
	v_mfma_f32_16x16x32_bf16 v[22:25], v[230:233], v[196:199], v[22:25]
	v_mfma_f32_16x16x32_bf16 v[0:3], v[222:225], v[204:207], v[0:3]
	v_mfma_f32_16x16x32_bf16 v[4:7], v[230:233], v[204:207], v[4:7]
	v_mfma_f32_16x16x32_bf16 v[50:53], v[226:229], v[150:153], v[50:53]
	v_mfma_f32_16x16x32_bf16 v[54:57], v[234:237], v[150:153], v[54:57]
	v_mfma_f32_16x16x32_bf16 v[34:37], v[226:229], v[192:195], v[34:37]
	v_mfma_f32_16x16x32_bf16 v[38:41], v[234:237], v[192:195], v[38:41]
	v_mfma_f32_16x16x32_bf16 v[18:21], v[226:229], v[200:203], v[18:21]
	v_mfma_f32_16x16x32_bf16 v[22:25], v[234:237], v[200:203], v[22:25]
	v_mfma_f32_16x16x32_bf16 v[0:3], v[226:229], v[218:221], v[0:3]
	v_mfma_f32_16x16x32_bf16 v[4:7], v[234:237], v[218:221], v[4:7]
.Lip13_a_7:
	s_add_i32 s18, s18, 2
	s_add_u32 s8, s8, 0x100
	s_addc_u32 s9, s9, 0
	s_add_u32 s13, s13, 0x100
	s_addc_u32 s15, s15, 0
	s_cmp_gt_u32 s18, 13
	s_barrier
	s_cbranch_scc0 .LBB0_276
	s_setprio 0
	v_lshl_add_u32 v204, s6, 8, v213
	v_add_u32_e32 v188, 0xb0, v204
	v_ashrrev_i32_e32 v205, 31, v204
	v_or_b32_e32 v202, 16, v204
	v_ashrrev_i32_e32 v189, 31, v188
	v_lshl_add_u64 v[130:131], v[204:205], 4, s[76:77]
	v_ashrrev_i32_e32 v203, 31, v202
	v_lshl_add_u64 v[134:135], v[188:189], 4, s[76:77]
	global_load_dwordx4 v[206:209], v[130:131], off
	v_or_b32_e32 v200, 32, v204
	global_load_dwordx4 v[134:137], v[134:135], off
	v_lshl_add_u64 v[130:131], v[202:203], 4, s[76:77]
	global_load_dwordx4 v[218:221], v[130:131], off
	v_ashrrev_i32_e32 v201, 31, v200
	v_or_b32_e32 v198, 48, v204
	v_lshl_add_u64 v[130:131], v[200:201], 4, s[76:77]
	v_ashrrev_i32_e32 v199, 31, v198
	v_add_u32_e32 v196, 0x80, v204
	global_load_dwordx4 v[146:149], v[130:131], off
	v_lshl_add_u64 v[130:131], v[198:199], 4, s[76:77]
	v_ashrrev_i32_e32 v197, 31, v196
	v_add_u32_e32 v194, 0x90, v204
	global_load_dwordx4 v[150:153], v[130:131], off
	v_lshl_add_u64 v[130:131], v[196:197], 4, s[76:77]
	v_ashrrev_i32_e32 v195, 31, v194
	v_add_u32_e32 v192, 0xa0, v204
	global_load_dwordx4 v[138:141], v[130:131], off
	v_lshl_add_u64 v[130:131], v[194:195], 4, s[76:77]
	v_ashrrev_i32_e32 v193, 31, v192
	global_load_dwordx4 v[142:145], v[130:131], off
	v_lshl_add_u64 v[130:131], v[192:193], 4, s[76:77]
	global_load_dwordx4 v[130:133], v[130:131], off
	s_waitcnt vmcnt(0)
	v_mov_b32_e32 v191, v206
	v_mov_b32_e32 v190, v218
	v_mov_b32_e32 v206, v219
	v_pk_add_f32 v[190:191], v[190:191], v[206:207]
	v_mov_b32_e32 v206, v220
	v_mov_b32_e32 v207, v208
	v_pk_add_f32 v[190:191], v[206:207], v[190:191]
	v_mov_b32_e32 v208, v221
	v_pk_add_f32 v[190:191], v[208:209], v[190:191]
	s_nop 0
	v_pk_fma_f32 v[206:207], v[190:191], s[72:73], v[160:161] op_sel_hi:[1,0,0]
	v_lshl_or_b32 v190, s4, 8, v215
	v_mul_f32_e32 v8, 0x4b800000, v207
	v_cmp_gt_f32_e32 vcc, s94, v207
	v_cmp_gt_f32_e64 s[6:7], s94, v206
	s_nop 0
	v_cndmask_b32_e32 v8, v207, v8, vcc
	v_rsq_f32_e32 v8, v8
	s_nop 0
	v_mul_f32_e32 v162, 0x45800000, v8
	v_cndmask_b32_e32 v208, v8, v162, vcc
	v_pk_mul_f32 v[128:129], v[128:129], v[208:209] op_sel_hi:[1,0]
	v_pk_mul_f32 v[126:127], v[126:127], v[208:209] op_sel_hi:[1,0]
	v_pk_mul_f32 v[124:125], v[124:125], v[208:209] op_sel_hi:[1,0]
	v_pk_mul_f32 v[122:123], v[122:123], v[208:209] op_sel_hi:[1,0]
	v_cmp_lt_i32_e32 vcc, s39, v190
	v_add_u32_e32 v8, 0xfffff400, v190
	s_and_saveexec_b64 s[0:1], vcc
	s_xor_b64 s[8:9], exec, s[0:1]
	s_cbranch_execz .LBB0_281
	v_cmp_gt_u32_e64 s[4:5], 16, v8
	s_and_saveexec_b64 s[46:47], s[4:5]
	s_cbranch_execz .LBB0_280
	v_lshlrev_b64 v[218:219], 6, v[204:205]
	v_lshl_add_u64 v[218:219], s[58:59], 0, v[218:219]
	v_lshl_add_u64 v[218:219], v[8:9], 2, v[218:219]
	global_store_dwordx4 v[218:219], v[126:129], off
	global_store_dwordx4 v[218:219], v[122:125], off offset:16

; #define PG8_STAGE(bufoff, gbase, voff) do { _Pragma("unroll") for (int _i = 0; _i < 2; ++_i) \
;         __builtin_amdgcn_global_load_lds((const unsigned*)((const char*)(gbase) + (voff)[_i]), (LAS unsigned*)(lds + (bufoff) + ldsw + _i * 8192), 16, 0, 0); } while (0)
; #define PG8_LDA(dst, b, h) do { _Pragma("unroll") for (int m = 0; m < 4; ++m) _Pragma("unroll") for (int k = 0; k < 2; ++k) dst[m][k] = *(const LAS bf16x8*)(lds + PG8_SA(b, h) + aoff + m * 2048 + k * 1024); } while (0)
; #define PG8_LDB(dst, b, h) do { _Pragma("unroll") for (int n = 0; n < 2; ++n) _Pragma("unroll") for (int k = 0; k < 2; ++k) dst[n][k] = *(const LAS bf16x8*)(lds + PG8_SB(b, h) + boff + n * 2048 + k * 1024); } while (0)
; #define PG8_MMA(ai, bj, At, Bt) do { __builtin_amdgcn_s_setprio(1); _Pragma("unroll") for (int m = 0; m < 4; ++m) _Pragma("unroll") for (int n = 0; n < 2; ++n) _Pragma("unroll") for (int k = 0; k < 2; ++k) \
;         acc[ai][bj][m][n] = __builtin_amdgcn_mfma_f32_16x16x32_bf16(Bt[n][k], At[m][k], acc[ai][bj][m][n], 0, 0, 0); __builtin_amdgcn_s_setprio(0); } while (0)
; template <class Epi>
; DEVI void gemm_phase(LAS unsigned char* lds, const Gemm g, const Epi& E) {
;     ...
;         for (int t = 0; t < nt; t += 2) {
;             const bool last = (t == nt - 2);
;             const char* a1 = cA + (size_t)(t + 1) * kstep;
;             const char* a2 = last ? nA : cA + (size_t)(t + 2) * kstep; const char* b2 = last ? nB : cB + (size_t)(t + 2) * kstep;
;             const char* a3 = a2 + kstep; const char* b3 = b2 + kstep;
;             PG8_LDB(B0, 0, 0); PG8_SCHED; PG8_LDA(At, 0, 0); PG8_STAGE(PG8_SA(1, 1), a1 + hstepA, voffA);
;             PG8_WAIT_L(8); PG8_BAR; PG8_WAIT_L(0); PG8_MMA(0, 0, At, B0); PG8_BAR; PG8_SCHED;
;             PG8_LDB(B1, 0, 1); PG8_STAGE(PG8_SB(0, 0), b2, voffB);
;             PG8_BAR; PG8_WAIT_L(0); PG8_MMA(0, 1, At, B1); PG8_BAR;
;             PG8_LDA(At, 0, 1); PG8_STAGE(PG8_SA(0, 0), a2, voffA);
;             PG8_BAR; PG8_WAIT_L(0); PG8_MMA(1, 0, At, B0); PG8_BAR; PG8_SCHED;
;             PG8_STAGE(PG8_SB(0, 1), b2 + hstepB, voffB);
;             PG8_WAIT_V(6); PG8_BAR; PG8_MMA(1, 1, At, B1); PG8_BAR;
;             PG8_LDB(B0, 1, 0); PG8_SCHED; PG8_LDA(At, 1, 0); PG8_STAGE(PG8_SA(0, 1), a2 + hstepA, voffA);
;             PG8_WAIT_L(8); PG8_BAR; PG8_WAIT_L(0); PG8_MMA(0, 0, At, B0); PG8_BAR; PG8_SCHED;
.LBB0_356:
	s_add_u32 s19, s8, 0xfffc0080
	s_addc_u32 s26, s9, -1
	s_add_i32 s27, 0, 0x10000
	v_add_u32_e32 v142, s27, v209
	ds_read_b128 v[130:133], v142
	ds_read_b128 v[134:137], v142 offset:1024
	ds_read_b128 v[138:141], v142 offset:2048
	ds_read_b128 v[142:145], v142 offset:3072
	s_cmp_eq_u32 s18, 12
	s_cselect_b32 s69, s0, s26
	s_cselect_b32 s68, s1, s19
	s_cselect_b32 s47, s5, s13
	s_cselect_b32 s46, s7, s11
	v_lshl_add_u64 v[206:207], s[8:9], 0, v[182:183]
	s_add_i32 m0, s85, 0xc000
	ds_read_b128 v[146:149], v214
	ds_read_b128 v[150:153], v214 offset:1024
	ds_read_b128 v[186:189], v214 offset:2048
	ds_read_b128 v[190:193], v214 offset:3072
	ds_read_b128 v[194:197], v214 offset:4096
	ds_read_b128 v[198:201], v214 offset:5120
	ds_read_b128 v[202:205], v214 offset:6144
	ds_read_b128 v[216:219], v214 offset:7168
	global_load_lds_dwordx4 v[206:207], off
	v_lshl_add_u64 v[206:207], s[8:9], 0, v[184:185]
	s_add_i32 m0, s85, 0xe000
	s_nop 0
	global_load_lds_dwordx4 v[206:207], off
	s_waitcnt lgkmcnt(8)
	s_barrier
	s_waitcnt lgkmcnt(0)
	s_waitcnt lgkmcnt(0)
	s_cmp_lg_u32 s101, 0
	s_cbranch_scc1 .Lip13_b_0
	v_mfma_f32_16x16x32_bf16 v[126:129], v[130:133], v[146:149], v[126:129]
	v_mfma_f32_16x16x32_bf16 v[122:125], v[138:141], v[146:149], v[122:125]
	v_mfma_f32_16x16x32_bf16 v[114:117], v[130:133], v[186:189], v[114:117]
	v_mfma_f32_16x16x32_bf16 v[106:109], v[138:141], v[186:189], v[106:109]
	v_mfma_f32_16x16x32_bf16 v[94:97], v[130:133], v[194:197], v[94:97]
	v_mfma_f32_16x16x32_bf16 v[90:93], v[138:141], v[194:197], v[90:93]
	v_mfma_f32_16x16x32_bf16 v[82:85], v[130:133], v[202:205], v[82:85]
	v_mfma_f32_16x16x32_bf16 v[74:77], v[138:141], v[202:205], v[74:77]
	v_mfma_f32_16x16x32_bf16 v[126:129], v[134:137], v[150:153], v[126:129]
	v_mfma_f32_16x16x32_bf16 v[122:125], v[142:145], v[150:153], v[122:125]
	v_mfma_f32_16x16x32_bf16 v[114:117], v[134:137], v[190:193], v[114:117]
	v_mfma_f32_16x16x32_bf16 v[106:109], v[142:145], v[190:193], v[106:109]
	v_mfma_f32_16x16x32_bf16 v[94:97], v[134:137], v[198:201], v[94:97]
	v_mfma_f32_16x16x32_bf16 v[90:93], v[142:145], v[198:201], v[90:93]
	v_mfma_f32_16x16x32_bf16 v[82:85], v[134:137], v[216:219], v[82:85]
	v_mfma_f32_16x16x32_bf16 v[74:77], v[142:145], v[216:219], v[74:77]
.Lip13_b_0:
	s_barrier
	s_add_i32 s19, 0, 0x14000
	s_add_i32 s26, s27, s84
	v_add_u32_e32 v162, s19, v209
	v_lshl_add_u64 v[206:207], s[46:47], 0, v[8:9]
	s_mov_b32 m0, s26
	ds_read_b128 v[220:223], v162
	ds_read_b128 v[224:227], v162 offset:1024
	ds_read_b128 v[228:231], v162 offset:2048
	ds_read_b128 v[232:235], v162 offset:3072
	global_load_lds_dwordx4 v[206:207], off
	v_lshl_add_u64 v[236:237], s[46:47], 0, v[180:181]
	s_add_i32 m0, s26, 0x2000
	s_nop 0
	global_load_lds_dwordx4 v[236:237], off
	s_barrier
	s_waitcnt lgkmcnt(0)
	s_waitcnt lgkmcnt(0)
	s_cmp_lg_u32 s100, 0
	s_cbranch_scc1 .Lip13_b_1
	v_mfma_f32_16x16x32_bf16 v[118:121], v[220:223], v[146:149], v[118:121]
	v_mfma_f32_16x16x32_bf16 v[110:113], v[228:231], v[146:149], v[110:113]
	v_mfma_f32_16x16x32_bf16 v[102:105], v[220:223], v[186:189], v[102:105]
	v_mfma_f32_16x16x32_bf16 v[98:101], v[228:231], v[186:189], v[98:101]
	v_mfma_f32_16x16x32_bf16 v[86:89], v[220:223], v[194:197], v[86:89]
	v_mfma_f32_16x16x32_bf16 v[78:81], v[228:231], v[194:197], v[78:81]
	v_mfma_f32_16x16x32_bf16 v[62:65], v[220:223], v[202:205], v[62:65]
	v_mfma_f32_16x16x32_bf16 v[58:61], v[228:231], v[202:205], v[58:61]
	v_mfma_f32_16x16x32_bf16 v[118:121], v[224:227], v[150:153], v[118:121]
	v_mfma_f32_16x16x32_bf16 v[110:113], v[232:235], v[150:153], v[110:113]
	v_mfma_f32_16x16x32_bf16 v[102:105], v[224:227], v[190:193], v[102:105]
	v_mfma_f32_16x16x32_bf16 v[98:101], v[232:235], v[190:193], v[98:101]
	v_mfma_f32_16x16x32_bf16 v[86:89], v[224:227], v[198:201], v[86:89]
	v_mfma_f32_16x16x32_bf16 v[78:81], v[232:235], v[198:201], v[78:81]
	v_mfma_f32_16x16x32_bf16 v[62:65], v[224:227], v[216:219], v[62:65]
	v_mfma_f32_16x16x32_bf16 v[58:61], v[232:235], v[216:219], v[58:61]
.Lip13_b_1:
	s_mov_b32 m0, s85
	v_lshl_add_u64 v[238:239], s[68:69], 0, v[176:177]
	s_barrier
	ds_read_b128 v[146:149], v214 offset:16384
	ds_read_b128 v[150:153], v214 offset:17408
	ds_read_b128 v[186:189], v214 offset:18432
	ds_read_b128 v[190:193], v214 offset:19456
	ds_read_b128 v[194:197], v214 offset:20480
	ds_read_b128 v[198:201], v214 offset:21504
	ds_read_b128 v[202:205], v214 offset:22528
	ds_read_b128 v[216:219], v214 offset:23552
	global_load_lds_dwordx4 v[238:239], off
	v_lshl_add_u64 v[240:241], s[68:69], 0, v[178:179]
	s_mov_b32 m0, s86
	s_nop 0
	global_load_lds_dwordx4 v[240:241], off
	s_barrier
	s_waitcnt lgkmcnt(0)
	s_waitcnt lgkmcnt(0)
	s_cmp_lg_u32 s101, 0
	s_cbranch_scc1 .Lip13_b_2
	v_mfma_f32_16x16x32_bf16 v[70:73], v[130:133], v[146:149], v[70:73]
	v_mfma_f32_16x16x32_bf16 v[66:69], v[138:141], v[146:149], v[66:69]
	v_mfma_f32_16x16x32_bf16 v[46:49], v[130:133], v[186:189], v[46:49]
	v_mfma_f32_16x16x32_bf16 v[42:45], v[138:141], v[186:189], v[42:45]
	v_mfma_f32_16x16x32_bf16 v[30:33], v[130:133], v[194:197], v[30:33]
	v_mfma_f32_16x16x32_bf16 v[26:29], v[138:141], v[194:197], v[26:29]
	v_mfma_f32_16x16x32_bf16 v[14:17], v[130:133], v[202:205], v[14:17]
	v_mfma_f32_16x16x32_bf16 v[10:13], v[138:141], v[202:205], v[10:13]
	v_mfma_f32_16x16x32_bf16 v[70:73], v[134:137], v[150:153], v[70:73]
	v_mfma_f32_16x16x32_bf16 v[66:69], v[142:145], v[150:153], v[66:69]
	v_mfma_f32_16x16x32_bf16 v[46:49], v[134:137], v[190:193], v[46:49]
	v_mfma_f32_16x16x32_bf16 v[42:45], v[142:145], v[190:193], v[42:45]
	v_mfma_f32_16x16x32_bf16 v[30:33], v[134:137], v[198:201], v[30:33]
	v_mfma_f32_16x16x32_bf16 v[26:29], v[142:145], v[198:201], v[26:29]
	v_mfma_f32_16x16x32_bf16 v[14:17], v[134:137], v[216:219], v[14:17]
	v_mfma_f32_16x16x32_bf16 v[10:13], v[142:145], v[216:219], v[10:13]
; #define PG8_STAGE(bufoff, gbase, voff) do { _Pragma("unroll") for (int _i = 0; _i < 2; ++_i) \
;         __builtin_amdgcn_global_load_lds((const unsigned*)((const char*)(gbase) + (voff)[_i]), (LAS unsigned*)(lds + (bufoff) + ldsw + _i * 8192), 16, 0, 0); } while (0)
; #define PG8_LDA(dst, b, h) do { _Pragma("unroll") for (int m = 0; m < 4; ++m) _Pragma("unroll") for (int k = 0; k < 2; ++k) dst[m][k] = *(const LAS bf16x8*)(lds + PG8_SA(b, h) + aoff + m * 2048 + k * 1024); } while (0)
; #define PG8_LDB(dst, b, h) do { _Pragma("unroll") for (int n = 0; n < 2; ++n) _Pragma("unroll") for (int k = 0; k < 2; ++k) dst[n][k] = *(const LAS bf16x8*)(lds + PG8_SB(b, h) + boff + n * 2048 + k * 1024); } while (0)
; #define PG8_MMA(ai, bj, At, Bt) do { __builtin_amdgcn_s_setprio(1); _Pragma("unroll") for (int m = 0; m < 4; ++m) _Pragma("unroll") for (int n = 0; n < 2; ++n) _Pragma("unroll") for (int k = 0; k < 2; ++k) \
;         acc[ai][bj][m][n] = __builtin_amdgcn_mfma_f32_16x16x32_bf16(Bt[n][k], At[m][k], acc[ai][bj][m][n], 0, 0, 0); __builtin_amdgcn_s_setprio(0); } while (0)
; #define PG8_WAIT_V(n) asm volatile("s_waitcnt vmcnt(" #n ")" ::: "memory")
; #define PG8_WAIT_L(n) asm volatile("s_waitcnt lgkmcnt(" #n ")" ::: "memory")
; #define PG8_BAR __builtin_amdgcn_s_barrier()
; #define PG8_SCHED __builtin_amdgcn_sched_barrier(0)
; template <class Epi>
; DEVI void gemm_phase(LAS unsigned char* lds, const Gemm g, const Epi& E) {
;     ...
;             PG8_WAIT_V(6); PG8_BAR; PG8_MMA(1, 1, At, B1); PG8_BAR;
;             PG8_LDB(B0, 1, 0); PG8_SCHED; PG8_LDA(At, 1, 0); PG8_STAGE(PG8_SA(0, 1), a2 + hstepA, voffA);
;             PG8_WAIT_L(8); PG8_BAR; PG8_WAIT_L(0); PG8_MMA(0, 0, At, B0); PG8_BAR; PG8_SCHED;
;             PG8_LDB(B1, 1, 1); PG8_STAGE(PG8_SB(1, 0), b3, voffB);
;             PG8_BAR; PG8_WAIT_L(0); PG8_MMA(0, 1, At, B1); PG8_BAR;
;             PG8_LDA(At, 1, 1); PG8_STAGE(PG8_SA(1, 0), a3, voffA);
;             PG8_BAR; PG8_WAIT_L(0); PG8_MMA(1, 0, At, B0); PG8_BAR; PG8_SCHED;
.Lip13_b_2:
	s_barrier
	s_add_u32 s26, s46, 0x40000
	s_addc_u32 s27, s47, 0
	s_add_i32 s19, s19, s84
	v_lshl_add_u64 v[130:131], s[26:27], 0, v[8:9]
	s_mov_b32 m0, s19
	s_nop 0
	global_load_lds_dwordx4 v[130:131], off
	v_lshl_add_u64 v[130:131], s[26:27], 0, v[180:181]
	s_add_i32 m0, s19, 0x2000
	s_nop 0
	global_load_lds_dwordx4 v[130:131], off
	s_waitcnt vmcnt(6)
	s_barrier
	s_cmp_lg_u32 s100, 0
	s_cbranch_scc1 .Lip13_b_3
	v_mfma_f32_16x16x32_bf16 v[50:53], v[220:223], v[146:149], v[50:53]
	v_mfma_f32_16x16x32_bf16 v[54:57], v[228:231], v[146:149], v[54:57]
	v_mfma_f32_16x16x32_bf16 v[34:37], v[220:223], v[186:189], v[34:37]
	v_mfma_f32_16x16x32_bf16 v[38:41], v[228:231], v[186:189], v[38:41]
	v_mfma_f32_16x16x32_bf16 v[18:21], v[220:223], v[194:197], v[18:21]
	v_mfma_f32_16x16x32_bf16 v[22:25], v[228:231], v[194:197], v[22:25]
	v_mfma_f32_16x16x32_bf16 v[0:3], v[220:223], v[202:205], v[0:3]
	v_mfma_f32_16x16x32_bf16 v[4:7], v[228:231], v[202:205], v[4:7]
	v_mfma_f32_16x16x32_bf16 v[50:53], v[224:227], v[150:153], v[50:53]
	v_mfma_f32_16x16x32_bf16 v[54:57], v[232:235], v[150:153], v[54:57]
	v_mfma_f32_16x16x32_bf16 v[34:37], v[224:227], v[190:193], v[34:37]
	v_mfma_f32_16x16x32_bf16 v[38:41], v[232:235], v[190:193], v[38:41]
	v_mfma_f32_16x16x32_bf16 v[18:21], v[224:227], v[198:201], v[18:21]
	v_mfma_f32_16x16x32_bf16 v[22:25], v[232:235], v[198:201], v[22:25]
	v_mfma_f32_16x16x32_bf16 v[0:3], v[224:227], v[216:219], v[0:3]
	v_mfma_f32_16x16x32_bf16 v[4:7], v[232:235], v[216:219], v[4:7]
.Lip13_b_3:
	s_add_i32 s19, 0, 0x18000
	v_add_u32_e32 v142, s19, v209
	s_barrier
	ds_read_b128 v[130:133], v142
	ds_read_b128 v[134:137], v142 offset:1024
	ds_read_b128 v[138:141], v142 offset:2048
	ds_read_b128 v[142:145], v142 offset:3072
	s_add_u32 s26, s68, 0x40000
	s_addc_u32 s27, s69, 0
	s_mov_b32 m0, s87
	v_lshl_add_u64 v[220:221], s[26:27], 0, v[176:177]
	ds_read_b128 v[146:149], v214 offset:32768
	ds_read_b128 v[150:153], v214 offset:33792
	ds_read_b128 v[186:189], v214 offset:34816
	ds_read_b128 v[190:193], v214 offset:35840
	ds_read_b128 v[194:197], v214 offset:36864
	ds_read_b128 v[198:201], v214 offset:37888
	ds_read_b128 v[202:205], v214 offset:38912
	ds_read_b128 v[216:219], v214 offset:39936
	global_load_lds_dwordx4 v[220:221], off
	v_lshl_add_u64 v[220:221], s[26:27], 0, v[178:179]
	s_mov_b32 m0, s88
	s_nop 0
	global_load_lds_dwordx4 v[220:221], off
	s_waitcnt lgkmcnt(8)
	s_barrier
	s_waitcnt lgkmcnt(0)
	s_waitcnt lgkmcnt(0)
	s_cmp_lg_u32 s101, 0
	s_cbranch_scc1 .Lip13_b_4
	v_mfma_f32_16x16x32_bf16 v[126:129], v[130:133], v[146:149], v[126:129]
	v_mfma_f32_16x16x32_bf16 v[122:125], v[138:141], v[146:149], v[122:125]
	v_mfma_f32_16x16x32_bf16 v[114:117], v[130:133], v[186:189], v[114:117]
	v_mfma_f32_16x16x32_bf16 v[106:109], v[138:141], v[186:189], v[106:109]
	v_mfma_f32_16x16x32_bf16 v[94:97], v[130:133], v[194:197], v[94:97]
	v_mfma_f32_16x16x32_bf16 v[90:93], v[138:141], v[194:197], v[90:93]
	v_mfma_f32_16x16x32_bf16 v[82:85], v[130:133], v[202:205], v[82:85]
	v_mfma_f32_16x16x32_bf16 v[74:77], v[138:141], v[202:205], v[74:77]
	v_mfma_f32_16x16x32_bf16 v[126:129], v[134:137], v[150:153], v[126:129]
	v_mfma_f32_16x16x32_bf16 v[122:125], v[142:145], v[150:153], v[122:125]
	v_mfma_f32_16x16x32_bf16 v[114:117], v[134:137], v[190:193], v[114:117]
	v_mfma_f32_16x16x32_bf16 v[106:109], v[142:145], v[190:193], v[106:109]
	v_mfma_f32_16x16x32_bf16 v[94:97], v[134:137], v[198:201], v[94:97]
	v_mfma_f32_16x16x32_bf16 v[90:93], v[142:145], v[198:201], v[90:93]
	v_mfma_f32_16x16x32_bf16 v[82:85], v[134:137], v[216:219], v[82:85]
	v_mfma_f32_16x16x32_bf16 v[74:77], v[142:145], v[216:219], v[74:77]
.Lip13_b_4:
	s_barrier
	s_add_i32 s38, 0, 0x1c000
	s_add_i32 s19, s19, s84
	v_add_u32_e32 v162, s38, v209
	v_lshl_add_u64 v[206:207], v[206:207], 0, s[70:71]
	s_mov_b32 m0, s19
	ds_read_b128 v[220:223], v162
	ds_read_b128 v[224:227], v162 offset:1024
	ds_read_b128 v[228:231], v162 offset:2048
	ds_read_b128 v[232:235], v162 offset:3072
	global_load_lds_dwordx4 v[206:207], off
	v_lshl_add_u64 v[206:207], v[236:237], 0, s[70:71]
	s_add_i32 m0, s19, 0x2000
	s_nop 0
	global_load_lds_dwordx4 v[206:207], off
	s_barrier
	s_waitcnt lgkmcnt(0)
	s_waitcnt lgkmcnt(0)
	s_cmp_lg_u32 s100, 0
	s_cbranch_scc1 .Lip13_b_5
	v_mfma_f32_16x16x32_bf16 v[118:121], v[220:223], v[146:149], v[118:121]
	v_mfma_f32_16x16x32_bf16 v[110:113], v[228:231], v[146:149], v[110:113]
	v_mfma_f32_16x16x32_bf16 v[102:105], v[220:223], v[186:189], v[102:105]
	v_mfma_f32_16x16x32_bf16 v[98:101], v[228:231], v[186:189], v[98:101]
	v_mfma_f32_16x16x32_bf16 v[86:89], v[220:223], v[194:197], v[86:89]
	v_mfma_f32_16x16x32_bf16 v[78:81], v[228:231], v[194:197], v[78:81]
	v_mfma_f32_16x16x32_bf16 v[62:65], v[220:223], v[202:205], v[62:65]
	v_mfma_f32_16x16x32_bf16 v[58:61], v[228:231], v[202:205], v[58:61]
	v_mfma_f32_16x16x32_bf16 v[118:121], v[224:227], v[150:153], v[118:121]
	v_mfma_f32_16x16x32_bf16 v[110:113], v[232:235], v[150:153], v[110:113]
	v_mfma_f32_16x16x32_bf16 v[102:105], v[224:227], v[190:193], v[102:105]
	v_mfma_f32_16x16x32_bf16 v[98:101], v[232:235], v[190:193], v[98:101]
	v_mfma_f32_16x16x32_bf16 v[86:89], v[224:227], v[198:201], v[86:89]
	v_mfma_f32_16x16x32_bf16 v[78:81], v[232:235], v[198:201], v[78:81]
	v_mfma_f32_16x16x32_bf16 v[62:65], v[224:227], v[216:219], v[62:65]
	v_mfma_f32_16x16x32_bf16 v[58:61], v[232:235], v[216:219], v[58:61]
; #define PG8_STAGE(bufoff, gbase, voff) do { _Pragma("unroll") for (int _i = 0; _i < 2; ++_i) \
;         __builtin_amdgcn_global_load_lds((const unsigned*)((const char*)(gbase) + (voff)[_i]), (LAS unsigned*)(lds + (bufoff) + ldsw + _i * 8192), 16, 0, 0); } while (0)
; #define PG8_LDA(dst, b, h) do { _Pragma("unroll") for (int m = 0; m < 4; ++m) _Pragma("unroll") for (int k = 0; k < 2; ++k) dst[m][k] = *(const LAS bf16x8*)(lds + PG8_SA(b, h) + aoff + m * 2048 + k * 1024); } while (0)
; #define PG8_LDB(dst, b, h) do { _Pragma("unroll") for (int n = 0; n < 2; ++n) _Pragma("unroll") for (int k = 0; k < 2; ++k) dst[n][k] = *(const LAS bf16x8*)(lds + PG8_SB(b, h) + boff + n * 2048 + k * 1024); } while (0)
; #define PG8_MMA(ai, bj, At, Bt) do { __builtin_amdgcn_s_setprio(1); _Pragma("unroll") for (int m = 0; m < 4; ++m) _Pragma("unroll") for (int n = 0; n < 2; ++n) _Pragma("unroll") for (int k = 0; k < 2; ++k) \
;         acc[ai][bj][m][n] = __builtin_amdgcn_mfma_f32_16x16x32_bf16(Bt[n][k], At[m][k], acc[ai][bj][m][n], 0, 0, 0); __builtin_amdgcn_s_setprio(0); } while (0)
; template <class Epi>
; DEVI void gemm_phase(LAS unsigned char* lds, const Gemm g, const Epi& E) {
;     ...
;             PG8_LDB(B0, 1, 0); PG8_SCHED; PG8_LDA(At, 1, 0); PG8_STAGE(PG8_SA(0, 1), a2 + hstepA, voffA);
;             PG8_WAIT_L(8); PG8_BAR; PG8_WAIT_L(0); PG8_MMA(0, 0, At, B0); PG8_BAR; PG8_SCHED;
;             PG8_LDB(B1, 1, 1); PG8_STAGE(PG8_SB(1, 0), b3, voffB);
;             PG8_BAR; PG8_WAIT_L(0); PG8_MMA(0, 1, At, B1); PG8_BAR;
;             PG8_LDA(At, 1, 1); PG8_STAGE(PG8_SA(1, 0), a3, voffA);
;             PG8_BAR; PG8_WAIT_L(0); PG8_MMA(1, 0, At, B0); PG8_BAR; PG8_SCHED;
;             PG8_STAGE(PG8_SB(1, 1), b3 + hstepB, voffB);
;             PG8_WAIT_V(6); PG8_BAR; PG8_MMA(1, 1, At, B1); PG8_BAR;
;         }
;         {
;             const int row0 = cur.pm * BM + wr * 64 + fr, col0 = cur.pn * BM + wc * 32 + (Epi::PERM ? 8 : 4) * fq; constexpr int NST = Epi::PERM ? 4 : 16;
;             float rsv[8];
;             if constexpr (Epi::RS) { f32x4 q4[8];
; #pragma unroll
;                 for (int i = 0; i < 8; ++i) q4[i] = *(const f32x4*)(E.ssq_in + (size_t)(row0 + (i >> 2) * HALF + (i & 3) * 16) * 4);
; #pragma unroll
;                 for (int i = 0; i < 8; ++i) rsv[i] = rsqrtf((((q4[i][0] + q4[i][1]) + q4[i][2]) + q4[i][3]) * (1.f / DM) + 1e-6f); }
.Lip13_b_5:
	s_mov_b32 m0, s89
	v_lshl_add_u64 v[206:207], v[238:239], 0, s[70:71]
	s_barrier
	ds_read_b128 v[146:149], v214 offset:49152
	ds_read_b128 v[150:153], v214 offset:50176
	ds_read_b128 v[186:189], v214 offset:51200
	ds_read_b128 v[190:193], v214 offset:52224
	ds_read_b128 v[194:197], v214 offset:53248
	ds_read_b128 v[198:201], v214 offset:54272
	ds_read_b128 v[202:205], v214 offset:55296
	ds_read_b128 v[216:219], v214 offset:56320
	global_load_lds_dwordx4 v[206:207], off
	v_lshl_add_u64 v[206:207], v[240:241], 0, s[70:71]
	s_mov_b32 m0, s90
	s_nop 0
	global_load_lds_dwordx4 v[206:207], off
	s_barrier
	s_waitcnt lgkmcnt(0)
	s_waitcnt lgkmcnt(0)
	s_cmp_lg_u32 s101, 0
	s_cbranch_scc1 .Lip13_b_6
	v_mfma_f32_16x16x32_bf16 v[70:73], v[130:133], v[146:149], v[70:73]
	v_mfma_f32_16x16x32_bf16 v[66:69], v[138:141], v[146:149], v[66:69]
	v_mfma_f32_16x16x32_bf16 v[46:49], v[130:133], v[186:189], v[46:49]
	v_mfma_f32_16x16x32_bf16 v[42:45], v[138:141], v[186:189], v[42:45]
	v_mfma_f32_16x16x32_bf16 v[30:33], v[130:133], v[194:197], v[30:33]
	v_mfma_f32_16x16x32_bf16 v[26:29], v[138:141], v[194:197], v[26:29]
	v_mfma_f32_16x16x32_bf16 v[14:17], v[130:133], v[202:205], v[14:17]
	v_mfma_f32_16x16x32_bf16 v[10:13], v[138:141], v[202:205], v[10:13]
	v_mfma_f32_16x16x32_bf16 v[70:73], v[134:137], v[150:153], v[70:73]
	v_mfma_f32_16x16x32_bf16 v[66:69], v[142:145], v[150:153], v[66:69]
	v_mfma_f32_16x16x32_bf16 v[46:49], v[134:137], v[190:193], v[46:49]
	v_mfma_f32_16x16x32_bf16 v[42:45], v[142:145], v[190:193], v[42:45]
	v_mfma_f32_16x16x32_bf16 v[30:33], v[134:137], v[198:201], v[30:33]
	v_mfma_f32_16x16x32_bf16 v[26:29], v[142:145], v[198:201], v[26:29]
	v_mfma_f32_16x16x32_bf16 v[14:17], v[134:137], v[216:219], v[14:17]
	v_mfma_f32_16x16x32_bf16 v[10:13], v[142:145], v[216:219], v[10:13]
.Lip13_b_6:
	s_barrier
	s_add_u32 s26, s46, 0x40080
	s_addc_u32 s27, s47, 0
	s_add_i32 s19, s38, s84
	v_lshl_add_u64 v[130:131], s[26:27], 0, v[8:9]
	s_mov_b32 m0, s19
	s_nop 0
	global_load_lds_dwordx4 v[130:131], off
	v_lshl_add_u64 v[130:131], s[26:27], 0, v[180:181]
	s_add_i32 m0, s19, 0x2000
	s_nop 0
	global_load_lds_dwordx4 v[130:131], off
	s_waitcnt vmcnt(6)
	s_barrier
	s_cmp_lg_u32 s100, 0
	s_cbranch_scc1 .Lip13_b_7
	v_mfma_f32_16x16x32_bf16 v[50:53], v[220:223], v[146:149], v[50:53]
	v_mfma_f32_16x16x32_bf16 v[54:57], v[228:231], v[146:149], v[54:57]
	v_mfma_f32_16x16x32_bf16 v[34:37], v[220:223], v[186:189], v[34:37]
	v_mfma_f32_16x16x32_bf16 v[38:41], v[228:231], v[186:189], v[38:41]
	v_mfma_f32_16x16x32_bf16 v[18:21], v[220:223], v[194:197], v[18:21]
	v_mfma_f32_16x16x32_bf16 v[22:25], v[228:231], v[194:197], v[22:25]
	v_mfma_f32_16x16x32_bf16 v[0:3], v[220:223], v[202:205], v[0:3]
	v_mfma_f32_16x16x32_bf16 v[4:7], v[228:231], v[202:205], v[4:7]
	v_mfma_f32_16x16x32_bf16 v[50:53], v[224:227], v[150:153], v[50:53]
	v_mfma_f32_16x16x32_bf16 v[54:57], v[232:235], v[150:153], v[54:57]
	v_mfma_f32_16x16x32_bf16 v[34:37], v[224:227], v[190:193], v[34:37]
	v_mfma_f32_16x16x32_bf16 v[38:41], v[232:235], v[190:193], v[38:41]
	v_mfma_f32_16x16x32_bf16 v[18:21], v[224:227], v[198:201], v[18:21]
	v_mfma_f32_16x16x32_bf16 v[22:25], v[232:235], v[198:201], v[22:25]
	v_mfma_f32_16x16x32_bf16 v[0:3], v[224:227], v[216:219], v[0:3]
	v_mfma_f32_16x16x32_bf16 v[4:7], v[232:235], v[216:219], v[4:7]
.Lip13_b_7:
	s_add_i32 s18, s18, 2
	s_add_u32 s8, s8, 0x100
	s_addc_u32 s9, s9, 0
	s_add_u32 s11, s11, 0x100
	s_addc_u32 s13, s13, 0
	s_cmp_gt_u32 s18, 13
	s_barrier
	s_cbranch_scc0 .LBB0_356
	s_setprio 0
	v_lshl_add_u32 v202, s6, 8, v208
	v_ashrrev_i32_e32 v203, 31, v202
	v_or_b32_e32 v200, 16, v202
	v_lshl_add_u64 v[130:131], v[202:203], 4, s[76:77]
	v_ashrrev_i32_e32 v201, 31, v200
	v_lshl_add_u64 v[132:133], v[200:201], 4, s[76:77]
	global_load_dwordx4 v[204:207], v[130:131], off
	global_load_dwordx4 v[216:219], v[132:133], off
	v_or_b32_e32 v198, 32, v202
	v_ashrrev_i32_e32 v199, 31, v198
	v_or_b32_e32 v196, 48, v202
	v_add_u32_e32 v194, 0x80, v202
	v_lshl_add_u64 v[130:131], v[198:199], 4, s[76:77]
	v_ashrrev_i32_e32 v197, 31, v196
	v_ashrrev_i32_e32 v195, 31, v194
	v_add_u32_e32 v192, 0x90, v202
	v_add_u32_e32 v190, 0xa0, v202
	v_add_u32_e32 v188, 0xb0, v202
	v_lshl_add_u64 v[132:133], v[196:197], 4, s[76:77]
	global_load_dwordx4 v[146:149], v[130:131], off
	global_load_dwordx4 v[150:153], v[132:133], off
	v_lshl_add_u64 v[130:131], v[194:195], 4, s[76:77]
	v_ashrrev_i32_e32 v193, 31, v192
	v_ashrrev_i32_e32 v191, 31, v190
	v_ashrrev_i32_e32 v189, 31, v188
	v_lshl_add_u64 v[132:133], v[192:193], 4, s[76:77]
	global_load_dwordx4 v[138:141], v[130:131], off
	global_load_dwordx4 v[142:145], v[132:133], off
	v_lshl_add_u64 v[130:131], v[190:191], 4, s[76:77]
	v_lshl_add_u64 v[134:135], v[188:189], 4, s[76:77]
	global_load_dwordx4 v[130:133], v[130:131], off
	s_nop 0
	global_load_dwordx4 v[134:137], v[134:135], off
	s_waitcnt vmcnt(0)
	v_mov_b32_e32 v187, v204
	v_mov_b32_e32 v186, v216
	v_mov_b32_e32 v204, v217
	v_mov_b32_e32 v221, v206
	v_mov_b32_e32 v220, v218
	v_pk_add_f32 v[186:187], v[186:187], v[204:205]
	v_mov_b32_e32 v206, v219
	v_pk_add_f32 v[186:187], v[220:221], v[186:187]
	s_nop 0
	v_pk_add_f32 v[186:187], v[206:207], v[186:187]
	s_nop 0
	v_pk_fma_f32 v[204:205], v[186:187], s[72:73], v[160:161] op_sel_hi:[1,0,0]
	v_lshl_or_b32 v186, s4, 8, v213
	v_mul_f32_e32 v162, 0x4b800000, v205
	v_cmp_gt_f32_e32 vcc, s94, v205
	v_cmp_gt_f32_e64 s[6:7], s94, v204
	s_nop 0
	v_cndmask_b32_e32 v162, v205, v162, vcc
	v_rsq_f32_e32 v162, v162
	s_nop 0
	v_mul_f32_e32 v163, 0x45800000, v162
	v_cndmask_b32_e32 v206, v162, v163, vcc
	v_pk_mul_f32 v[128:129], v[128:129], v[206:207] op_sel_hi:[1,0]
	v_pk_mul_f32 v[126:127], v[126:127], v[206:207] op_sel_hi:[1,0]
	v_pk_mul_f32 v[124:125], v[124:125], v[206:207] op_sel_hi:[1,0]
	v_pk_mul_f32 v[122:123], v[122:123], v[206:207] op_sel_hi:[1,0]
	v_cmp_lt_i32_e32 vcc, s52, v186
	s_and_saveexec_b64 s[0:1], vcc
	s_xor_b64 s[8:9], exec, s[0:1]
	s_cbranch_execz .LBB0_361
	v_cmp_eq_u32_e64 s[4:5], s53, v186
	s_and_saveexec_b64 s[46:47], s[4:5]
	s_cbranch_execz .LBB0_360
	v_lshlrev_b64 v[216:217], 6, v[202:203]
	v_lshl_add_u64 v[216:217], s[58:59], 0, v[216:217]
	global_store_dwordx4 v[216:217], v[126:129], off
	global_store_dwordx4 v[216:217], v[122:125], off offset:16

; #define PG8_STAGE(bufoff, gbase, voff) do { _Pragma("unroll") for (int _i = 0; _i < 2; ++_i) \
;         __builtin_amdgcn_global_load_lds((const unsigned*)((const char*)(gbase) + (voff)[_i]), (LAS unsigned*)(lds + (bufoff) + ldsw + _i * 8192), 16, 0, 0); } while (0)
; #define PG8_LDA(dst, b, h) do { _Pragma("unroll") for (int m = 0; m < 4; ++m) _Pragma("unroll") for (int k = 0; k < 2; ++k) dst[m][k] = *(const LAS bf16x8*)(lds + PG8_SA(b, h) + aoff + m * 2048 + k * 1024); } while (0)
; #define PG8_LDB(dst, b, h) do { _Pragma("unroll") for (int n = 0; n < 2; ++n) _Pragma("unroll") for (int k = 0; k < 2; ++k) dst[n][k] = *(const LAS bf16x8*)(lds + PG8_SB(b, h) + boff + n * 2048 + k * 1024); } while (0)
; #define PG8_MMA(ai, bj, At, Bt) do { __builtin_amdgcn_s_setprio(1); _Pragma("unroll") for (int m = 0; m < 4; ++m) _Pragma("unroll") for (int n = 0; n < 2; ++n) _Pragma("unroll") for (int k = 0; k < 2; ++k) \
;         acc[ai][bj][m][n] = __builtin_amdgcn_mfma_f32_16x16x32_bf16(Bt[n][k], At[m][k], acc[ai][bj][m][n], 0, 0, 0); __builtin_amdgcn_s_setprio(0); } while (0)
; #define PG8_WAIT_L(n) asm volatile("s_waitcnt lgkmcnt(" #n ")" ::: "memory")
; #define PG8_BAR __builtin_amdgcn_s_barrier()
; #define PG8_SCHED __builtin_amdgcn_sched_barrier(0)
; template <class Epi>
; DEVI void gemm_phase(LAS unsigned char* lds, const Gemm g, const Epi& E) {
;     ...
;             PG8_LDB(B0, 0, 0); PG8_SCHED; PG8_LDA(At, 0, 0); PG8_STAGE(PG8_SA(1, 1), a1 + hstepA, voffA);
;             PG8_WAIT_L(8); PG8_BAR; PG8_WAIT_L(0); PG8_MMA(0, 0, At, B0); PG8_BAR; PG8_SCHED;
;             PG8_LDB(B1, 0, 1); PG8_STAGE(PG8_SB(0, 0), b2, voffB);
;             PG8_BAR; PG8_WAIT_L(0); PG8_MMA(0, 1, At, B1); PG8_BAR;
;             PG8_LDA(At, 0, 1); PG8_STAGE(PG8_SA(0, 0), a2, voffA);
;             PG8_BAR; PG8_WAIT_L(0); PG8_MMA(1, 0, At, B0); PG8_BAR; PG8_SCHED;
;             PG8_STAGE(PG8_SB(0, 1), b2 + hstepB, voffB);
.LBB0_968:
	s_add_u32 s26, s68, 0xfffc0080
	s_addc_u32 s27, s69, -1
	s_add_i32 s38, 0, 0x10000
	v_add_u32_e32 v142, s38, v193
	ds_read_b128 v[130:133], v142
	ds_read_b128 v[134:137], v142 offset:1024
	ds_read_b128 v[138:141], v142 offset:2048
	ds_read_b128 v[142:145], v142 offset:3072
	s_cmp_eq_u32 s19, 12
	s_cselect_b32 s83, s0, s27
	s_cselect_b32 s82, s1, s26
	s_cselect_b32 s81, s9, s18
	s_cselect_b32 s80, s13, s15
	v_lshl_add_u64 v[162:163], s[68:69], 0, v[178:179]
	s_add_i32 m0, s85, 0xc000
	ds_read_b128 v[146:149], v198
	ds_read_b128 v[182:185], v198 offset:1024
	ds_read_b128 v[186:189], v198 offset:2048
	ds_read_b128 v[200:203], v198 offset:3072
	ds_read_b128 v[204:207], v198 offset:4096
	ds_read_b128 v[214:217], v198 offset:5120
	ds_read_b128 v[218:221], v198 offset:6144
	ds_read_b128 v[222:225], v198 offset:7168
	global_load_lds_dwordx4 v[162:163], off
	v_lshl_add_u64 v[162:163], s[68:69], 0, v[180:181]
	s_add_i32 m0, s85, 0xe000
	s_nop 0
	global_load_lds_dwordx4 v[162:163], off
	s_waitcnt lgkmcnt(8)
	s_barrier
	s_waitcnt lgkmcnt(0)
	v_mfma_f32_16x16x32_bf16 v[126:129], v[130:133], v[146:149], v[126:129]
	v_mfma_f32_16x16x32_bf16 v[122:125], v[138:141], v[146:149], v[122:125]
	v_mfma_f32_16x16x32_bf16 v[110:113], v[130:133], v[186:189], v[110:113]
	v_mfma_f32_16x16x32_bf16 v[106:109], v[138:141], v[186:189], v[106:109]
	v_mfma_f32_16x16x32_bf16 v[94:97], v[130:133], v[204:207], v[94:97]
	v_mfma_f32_16x16x32_bf16 v[90:93], v[138:141], v[204:207], v[90:93]
	v_mfma_f32_16x16x32_bf16 v[78:81], v[130:133], v[218:221], v[78:81]
	v_mfma_f32_16x16x32_bf16 v[74:77], v[138:141], v[218:221], v[74:77]
	v_mfma_f32_16x16x32_bf16 v[126:129], v[134:137], v[182:185], v[126:129]
	v_mfma_f32_16x16x32_bf16 v[122:125], v[142:145], v[182:185], v[122:125]
	v_mfma_f32_16x16x32_bf16 v[110:113], v[134:137], v[200:203], v[110:113]
	v_mfma_f32_16x16x32_bf16 v[106:109], v[142:145], v[200:203], v[106:109]
	v_mfma_f32_16x16x32_bf16 v[94:97], v[134:137], v[214:217], v[94:97]
	v_mfma_f32_16x16x32_bf16 v[90:93], v[142:145], v[214:217], v[90:93]
	v_mfma_f32_16x16x32_bf16 v[78:81], v[134:137], v[222:225], v[78:81]
	v_mfma_f32_16x16x32_bf16 v[74:77], v[142:145], v[222:225], v[74:77]
	s_barrier
	s_add_i32 s39, 0, 0x14000
	v_add_u32_e32 v162, s39, v193
	s_add_i32 s26, s38, s84
	ds_read_b128 v[226:229], v162
	ds_read_b128 v[230:233], v162 offset:1024
	ds_read_b128 v[234:237], v162 offset:2048
	ds_read_b128 v[238:241], v162 offset:3072
	v_lshl_add_u64 v[162:163], s[80:81], 0, v[8:9]
	s_mov_b32 m0, s26
	v_lshl_add_u64 v[164:165], s[80:81], 0, v[176:177]
	global_load_lds_dwordx4 v[162:163], off
	s_add_i32 m0, s26, 0x2000
	s_nop 0
	global_load_lds_dwordx4 v[164:165], off
	s_barrier
	s_waitcnt lgkmcnt(0)
	v_mfma_f32_16x16x32_bf16 v[118:121], v[226:229], v[146:149], v[118:121]
	v_mfma_f32_16x16x32_bf16 v[114:117], v[234:237], v[146:149], v[114:117]
	v_mfma_f32_16x16x32_bf16 v[102:105], v[226:229], v[186:189], v[102:105]
	v_mfma_f32_16x16x32_bf16 v[98:101], v[234:237], v[186:189], v[98:101]
	v_mfma_f32_16x16x32_bf16 v[86:89], v[226:229], v[204:207], v[86:89]
	v_mfma_f32_16x16x32_bf16 v[82:85], v[234:237], v[204:207], v[82:85]
	v_mfma_f32_16x16x32_bf16 v[70:73], v[226:229], v[218:221], v[70:73]
	v_mfma_f32_16x16x32_bf16 v[66:69], v[234:237], v[218:221], v[66:69]
	v_mfma_f32_16x16x32_bf16 v[118:121], v[230:233], v[182:185], v[118:121]
	v_mfma_f32_16x16x32_bf16 v[114:117], v[238:241], v[182:185], v[114:117]
	v_mfma_f32_16x16x32_bf16 v[102:105], v[230:233], v[200:203], v[102:105]
	v_mfma_f32_16x16x32_bf16 v[98:101], v[238:241], v[200:203], v[98:101]
	v_mfma_f32_16x16x32_bf16 v[86:89], v[230:233], v[214:217], v[86:89]
	v_mfma_f32_16x16x32_bf16 v[82:85], v[238:241], v[214:217], v[82:85]
	v_mfma_f32_16x16x32_bf16 v[70:73], v[230:233], v[222:225], v[70:73]
	v_mfma_f32_16x16x32_bf16 v[66:69], v[238:241], v[222:225], v[66:69]
	s_mov_b32 m0, s85
	v_lshl_add_u64 v[190:191], s[82:83], 0, v[150:151]
	s_barrier
	ds_read_b128 v[146:149], v198 offset:16384
	ds_read_b128 v[182:185], v198 offset:17408
	ds_read_b128 v[186:189], v198 offset:18432
	ds_read_b128 v[200:203], v198 offset:19456
	ds_read_b128 v[204:207], v198 offset:20480
	ds_read_b128 v[214:217], v198 offset:21504
	ds_read_b128 v[218:221], v198 offset:22528
	ds_read_b128 v[222:225], v198 offset:23552
	global_load_lds_dwordx4 v[190:191], off
	v_lshl_add_u64 v[208:209], s[82:83], 0, v[152:153]
	s_mov_b32 m0, s86
	s_nop 0
	global_load_lds_dwordx4 v[208:209], off
	s_barrier
	s_waitcnt lgkmcnt(0)
	v_mfma_f32_16x16x32_bf16 v[62:65], v[130:133], v[146:149], v[62:65]
	v_mfma_f32_16x16x32_bf16 v[58:61], v[138:141], v[146:149], v[58:61]
	v_mfma_f32_16x16x32_bf16 v[46:49], v[130:133], v[186:189], v[46:49]
	v_mfma_f32_16x16x32_bf16 v[42:45], v[138:141], v[186:189], v[42:45]
	v_mfma_f32_16x16x32_bf16 v[30:33], v[130:133], v[204:207], v[30:33]
	v_mfma_f32_16x16x32_bf16 v[26:29], v[138:141], v[204:207], v[26:29]
	v_mfma_f32_16x16x32_bf16 v[14:17], v[130:133], v[218:221], v[14:17]
	v_mfma_f32_16x16x32_bf16 v[10:13], v[138:141], v[218:221], v[10:13]
	v_mfma_f32_16x16x32_bf16 v[62:65], v[134:137], v[182:185], v[62:65]
	v_mfma_f32_16x16x32_bf16 v[58:61], v[142:145], v[182:185], v[58:61]
	v_mfma_f32_16x16x32_bf16 v[46:49], v[134:137], v[200:203], v[46:49]
	v_mfma_f32_16x16x32_bf16 v[42:45], v[142:145], v[200:203], v[42:45]
	v_mfma_f32_16x16x32_bf16 v[30:33], v[134:137], v[214:217], v[30:33]
	v_mfma_f32_16x16x32_bf16 v[26:29], v[142:145], v[214:217], v[26:29]
	v_mfma_f32_16x16x32_bf16 v[14:17], v[134:137], v[222:225], v[14:17]
	v_mfma_f32_16x16x32_bf16 v[10:13], v[142:145], v[222:225], v[10:13]
	s_barrier
; #define PG8_STAGE(bufoff, gbase, voff) do { _Pragma("unroll") for (int _i = 0; _i < 2; ++_i) \
;         __builtin_amdgcn_global_load_lds((const unsigned*)((const char*)(gbase) + (voff)[_i]), (LAS unsigned*)(lds + (bufoff) + ldsw + _i * 8192), 16, 0, 0); } while (0)
; #define PG8_LDA(dst, b, h) do { _Pragma("unroll") for (int m = 0; m < 4; ++m) _Pragma("unroll") for (int k = 0; k < 2; ++k) dst[m][k] = *(const LAS bf16x8*)(lds + PG8_SA(b, h) + aoff + m * 2048 + k * 1024); } while (0)
; #define PG8_LDB(dst, b, h) do { _Pragma("unroll") for (int n = 0; n < 2; ++n) _Pragma("unroll") for (int k = 0; k < 2; ++k) dst[n][k] = *(const LAS bf16x8*)(lds + PG8_SB(b, h) + boff + n * 2048 + k * 1024); } while (0)
; #define PG8_MMA(ai, bj, At, Bt) do { __builtin_amdgcn_s_setprio(1); _Pragma("unroll") for (int m = 0; m < 4; ++m) _Pragma("unroll") for (int n = 0; n < 2; ++n) _Pragma("unroll") for (int k = 0; k < 2; ++k) \
;         acc[ai][bj][m][n] = __builtin_amdgcn_mfma_f32_16x16x32_bf16(Bt[n][k], At[m][k], acc[ai][bj][m][n], 0, 0, 0); __builtin_amdgcn_s_setprio(0); } while (0)
; #define PG8_WAIT_V(n) asm volatile("s_waitcnt vmcnt(" #n ")" ::: "memory")
; #define PG8_WAIT_L(n) asm volatile("s_waitcnt lgkmcnt(" #n ")" ::: "memory")
; #define PG8_BAR __builtin_amdgcn_s_barrier()
; #define PG8_SCHED __builtin_amdgcn_sched_barrier(0)
; template <class Epi>
; DEVI void gemm_phase(LAS unsigned char* lds, const Gemm g, const Epi& E) {
;     ...
;             PG8_STAGE(PG8_SB(0, 1), b2 + hstepB, voffB);
;             PG8_WAIT_V(6); PG8_BAR; PG8_MMA(1, 1, At, B1); PG8_BAR;
;             PG8_LDB(B0, 1, 0); PG8_SCHED; PG8_LDA(At, 1, 0); PG8_STAGE(PG8_SA(0, 1), a2 + hstepA, voffA);
;             PG8_WAIT_L(8); PG8_BAR; PG8_WAIT_L(0); PG8_MMA(0, 0, At, B0); PG8_BAR; PG8_SCHED;
;             PG8_LDB(B1, 1, 1); PG8_STAGE(PG8_SB(1, 0), b3, voffB);
;             PG8_BAR; PG8_WAIT_L(0); PG8_MMA(0, 1, At, B1); PG8_BAR;
;             PG8_LDA(At, 1, 1); PG8_STAGE(PG8_SA(1, 0), a3, voffA);
	s_add_u32 s26, s80, 0x40000
	s_addc_u32 s27, s81, 0
	s_add_i32 s38, s39, s84
	v_lshl_add_u64 v[130:131], s[26:27], 0, v[8:9]
	s_mov_b32 m0, s38
	s_nop 0
	global_load_lds_dwordx4 v[130:131], off
	v_lshl_add_u64 v[130:131], s[26:27], 0, v[176:177]
	s_add_i32 m0, s38, 0x2000
	s_nop 0
	global_load_lds_dwordx4 v[130:131], off
	s_waitcnt vmcnt(6)
	s_barrier
	v_mfma_f32_16x16x32_bf16 v[54:57], v[226:229], v[146:149], v[54:57]
	v_mfma_f32_16x16x32_bf16 v[50:53], v[234:237], v[146:149], v[50:53]
	v_mfma_f32_16x16x32_bf16 v[38:41], v[226:229], v[186:189], v[38:41]
	v_mfma_f32_16x16x32_bf16 v[34:37], v[234:237], v[186:189], v[34:37]
	v_mfma_f32_16x16x32_bf16 v[22:25], v[226:229], v[204:207], v[22:25]
	v_mfma_f32_16x16x32_bf16 v[18:21], v[234:237], v[204:207], v[18:21]
	v_mfma_f32_16x16x32_bf16 v[4:7], v[226:229], v[218:221], v[4:7]
	v_mfma_f32_16x16x32_bf16 v[0:3], v[234:237], v[218:221], v[0:3]
	v_mfma_f32_16x16x32_bf16 v[54:57], v[230:233], v[182:185], v[54:57]
	v_mfma_f32_16x16x32_bf16 v[50:53], v[238:241], v[182:185], v[50:53]
	v_mfma_f32_16x16x32_bf16 v[38:41], v[230:233], v[200:203], v[38:41]
	v_mfma_f32_16x16x32_bf16 v[34:37], v[238:241], v[200:203], v[34:37]
	v_mfma_f32_16x16x32_bf16 v[22:25], v[230:233], v[214:217], v[22:25]
	v_mfma_f32_16x16x32_bf16 v[18:21], v[238:241], v[214:217], v[18:21]
	v_mfma_f32_16x16x32_bf16 v[4:7], v[230:233], v[222:225], v[4:7]
	v_mfma_f32_16x16x32_bf16 v[0:3], v[238:241], v[222:225], v[0:3]
	s_add_i32 s38, 0, 0x18000
	v_add_u32_e32 v142, s38, v193
	s_barrier
	ds_read_b128 v[130:133], v142
	ds_read_b128 v[134:137], v142 offset:1024
	ds_read_b128 v[138:141], v142 offset:2048
	ds_read_b128 v[142:145], v142 offset:3072
	s_add_u32 s26, s82, 0x40000
	s_addc_u32 s27, s83, 0
	s_mov_b32 m0, s87
	v_lshl_add_u64 v[226:227], s[26:27], 0, v[150:151]
	ds_read_b128 v[146:149], v198 offset:32768
	ds_read_b128 v[182:185], v198 offset:33792
	ds_read_b128 v[186:189], v198 offset:34816
	ds_read_b128 v[200:203], v198 offset:35840
	ds_read_b128 v[204:207], v198 offset:36864
	ds_read_b128 v[214:217], v198 offset:37888
	ds_read_b128 v[218:221], v198 offset:38912
	ds_read_b128 v[222:225], v198 offset:39936
	global_load_lds_dwordx4 v[226:227], off
	v_lshl_add_u64 v[226:227], s[26:27], 0, v[152:153]
	s_mov_b32 m0, s88
	s_nop 0
	global_load_lds_dwordx4 v[226:227], off
	s_waitcnt lgkmcnt(8)
	s_barrier
	s_waitcnt lgkmcnt(0)
	v_mfma_f32_16x16x32_bf16 v[126:129], v[130:133], v[146:149], v[126:129]
	v_mfma_f32_16x16x32_bf16 v[122:125], v[138:141], v[146:149], v[122:125]
	v_mfma_f32_16x16x32_bf16 v[110:113], v[130:133], v[186:189], v[110:113]
	v_mfma_f32_16x16x32_bf16 v[106:109], v[138:141], v[186:189], v[106:109]
	v_mfma_f32_16x16x32_bf16 v[94:97], v[130:133], v[204:207], v[94:97]
	v_mfma_f32_16x16x32_bf16 v[90:93], v[138:141], v[204:207], v[90:93]
	v_mfma_f32_16x16x32_bf16 v[78:81], v[130:133], v[218:221], v[78:81]
	v_mfma_f32_16x16x32_bf16 v[74:77], v[138:141], v[218:221], v[74:77]
	v_mfma_f32_16x16x32_bf16 v[126:129], v[134:137], v[182:185], v[126:129]
	v_mfma_f32_16x16x32_bf16 v[122:125], v[142:145], v[182:185], v[122:125]
	v_mfma_f32_16x16x32_bf16 v[110:113], v[134:137], v[200:203], v[110:113]
	v_mfma_f32_16x16x32_bf16 v[106:109], v[142:145], v[200:203], v[106:109]
	v_mfma_f32_16x16x32_bf16 v[94:97], v[134:137], v[214:217], v[94:97]
	v_mfma_f32_16x16x32_bf16 v[90:93], v[142:145], v[214:217], v[90:93]
	v_mfma_f32_16x16x32_bf16 v[78:81], v[134:137], v[222:225], v[78:81]
	v_mfma_f32_16x16x32_bf16 v[74:77], v[142:145], v[222:225], v[74:77]
	s_barrier
	s_add_i32 s39, 0, 0x1c000
	s_add_i32 s26, s38, s84
	v_add_u32_e32 v199, s39, v193
	v_lshl_add_u64 v[162:163], v[162:163], 0, s[70:71]
	s_mov_b32 m0, s26
	ds_read_b128 v[226:229], v199
	ds_read_b128 v[230:233], v199 offset:1024
	ds_read_b128 v[234:237], v199 offset:2048
	ds_read_b128 v[238:241], v199 offset:3072
	global_load_lds_dwordx4 v[162:163], off
	v_lshl_add_u64 v[162:163], v[164:165], 0, s[70:71]
	s_add_i32 m0, s26, 0x2000
	s_nop 0
	global_load_lds_dwordx4 v[162:163], off
	s_barrier
	s_waitcnt lgkmcnt(0)
	v_mfma_f32_16x16x32_bf16 v[118:121], v[226:229], v[146:149], v[118:121]
	v_mfma_f32_16x16x32_bf16 v[114:117], v[234:237], v[146:149], v[114:117]
	v_mfma_f32_16x16x32_bf16 v[102:105], v[226:229], v[186:189], v[102:105]
	v_mfma_f32_16x16x32_bf16 v[98:101], v[234:237], v[186:189], v[98:101]
	v_mfma_f32_16x16x32_bf16 v[86:89], v[226:229], v[204:207], v[86:89]
	v_mfma_f32_16x16x32_bf16 v[82:85], v[234:237], v[204:207], v[82:85]
	v_mfma_f32_16x16x32_bf16 v[70:73], v[226:229], v[218:221], v[70:73]
	v_mfma_f32_16x16x32_bf16 v[66:69], v[234:237], v[218:221], v[66:69]
	v_mfma_f32_16x16x32_bf16 v[118:121], v[230:233], v[182:185], v[118:121]
	v_mfma_f32_16x16x32_bf16 v[114:117], v[238:241], v[182:185], v[114:117]
	v_mfma_f32_16x16x32_bf16 v[102:105], v[230:233], v[200:203], v[102:105]
	v_mfma_f32_16x16x32_bf16 v[98:101], v[238:241], v[200:203], v[98:101]
	v_mfma_f32_16x16x32_bf16 v[86:89], v[230:233], v[214:217], v[86:89]
	v_mfma_f32_16x16x32_bf16 v[82:85], v[238:241], v[214:217], v[82:85]
	v_mfma_f32_16x16x32_bf16 v[70:73], v[230:233], v[222:225], v[70:73]
	v_mfma_f32_16x16x32_bf16 v[66:69], v[238:241], v[222:225], v[66:69]
	s_mov_b32 m0, s89
	v_lshl_add_u64 v[162:163], v[190:191], 0, s[70:71]
	s_barrier
	ds_read_b128 v[146:149], v198 offset:49152
	ds_read_b128 v[182:185], v198 offset:50176
	ds_read_b128 v[186:189], v198 offset:51200
	ds_read_b128 v[200:203], v198 offset:52224
	ds_read_b128 v[204:207], v198 offset:53248
	ds_read_b128 v[214:217], v198 offset:54272
	ds_read_b128 v[218:221], v198 offset:55296
	ds_read_b128 v[222:225], v198 offset:56320
	global_load_lds_dwordx4 v[162:163], off
	v_lshl_add_u64 v[162:163], v[208:209], 0, s[70:71]
	s_mov_b32 m0, s90
	s_nop 0
	global_load_lds_dwordx4 v[162:163], off
	s_barrier
; #define LAS __attribute__((address_space(3)))
; #define PG8_STAGE(bufoff, gbase, voff) do { _Pragma("unroll") for (int _i = 0; _i < 2; ++_i) \
;         __builtin_amdgcn_global_load_lds((const unsigned*)((const char*)(gbase) + (voff)[_i]), (LAS unsigned*)(lds + (bufoff) + ldsw + _i * 8192), 16, 0, 0); } while (0)
; #define PG8_WAIT_V(n) asm volatile("s_waitcnt vmcnt(" #n ")" ::: "memory")
; #define PG8_WAIT_L(n) asm volatile("s_waitcnt lgkmcnt(" #n ")" ::: "memory")
; #define PG8_BAR __builtin_amdgcn_s_barrier()
; #define PG8_SCHED __builtin_amdgcn_sched_barrier(0)
; template <class Epi>
; DEVI void gemm_phase(LAS unsigned char* lds, const Gemm g, const Epi& E) {
;     ...
;             PG8_BAR; PG8_WAIT_L(0); PG8_MMA(1, 0, At, B0); PG8_BAR; PG8_SCHED;
;             PG8_STAGE(PG8_SB(1, 1), b3 + hstepB, voffB);
;             PG8_WAIT_V(6); PG8_BAR; PG8_MMA(1, 1, At, B1); PG8_BAR;
;     ...
;                             for (int n = 0; n < 2; ++n) pre[m][bj][n] = E.load(row0 + ai * HALF + (m0 + m) * 16, col0 + bj * HALF + n * NST);
;                 }
; #pragma unroll
;                 for (int mm = 0; mm < 2; ++mm) {
;                     const int m = m0 + mm;
;                     const int r = row0 + ai * HALF + m * 16; float rs = 1.f, part = 0.f;
;                     if constexpr (Epi::RS) rs = rsv[ai * 4 + m];
;                     if constexpr (Epi::PAIR) E.pair8(cur.b, r, cur.pn * HALF + wc * 32 + 8 * fq, acc[ai][0][m][0] * rs, acc[ai][0][m][1] * rs, acc[ai][1][m][0] * rs, acc[ai][1][m][1] * rs);
;                     else
; #pragma unroll
;                     for (int bj = 0; bj < 2; ++bj) {
;                         const int c = col0 + bj * HALF; f32x4 v0 = acc[ai][bj][m][0], v1 = acc[ai][bj][m][1];
;                         if constexpr (Epi::RS) { v0 = v0 * rs; v1 = v1 * rs; }
;                         if constexpr (Epi::PRE) part += E.frag_pre8(cur.b, r, c, v0, v1, pre[mm][bj][0], pre[mm][bj][1]);
;                         else if constexpr (Epi::PERM) E.frag8(cur.b, r, c, v0, v1);
;                         else { E.frag(cur.b, r, c, v0); E.frag(cur.b, r, c + 16, v1); }
;                     }
;                     if constexpr (Epi::SSQ) { part += __shfl_xor(part, 16); part += __shfl_xor(part, 32); if (fq == 0) ((LAS float*)(lds + 131072))[(wr * 4 + wc) * 128 + ai * 64 + m * 16 + fr] = part; }
	s_waitcnt lgkmcnt(0)
	v_mfma_f32_16x16x32_bf16 v[62:65], v[130:133], v[146:149], v[62:65]
	v_mfma_f32_16x16x32_bf16 v[58:61], v[138:141], v[146:149], v[58:61]
	v_mfma_f32_16x16x32_bf16 v[46:49], v[130:133], v[186:189], v[46:49]
	v_mfma_f32_16x16x32_bf16 v[42:45], v[138:141], v[186:189], v[42:45]
	v_mfma_f32_16x16x32_bf16 v[30:33], v[130:133], v[204:207], v[30:33]
	v_mfma_f32_16x16x32_bf16 v[26:29], v[138:141], v[204:207], v[26:29]
	v_mfma_f32_16x16x32_bf16 v[14:17], v[130:133], v[218:221], v[14:17]
	v_mfma_f32_16x16x32_bf16 v[10:13], v[138:141], v[218:221], v[10:13]
	v_mfma_f32_16x16x32_bf16 v[62:65], v[134:137], v[182:185], v[62:65]
	v_mfma_f32_16x16x32_bf16 v[58:61], v[142:145], v[182:185], v[58:61]
	v_mfma_f32_16x16x32_bf16 v[46:49], v[134:137], v[200:203], v[46:49]
	v_mfma_f32_16x16x32_bf16 v[42:45], v[142:145], v[200:203], v[42:45]
	v_mfma_f32_16x16x32_bf16 v[30:33], v[134:137], v[214:217], v[30:33]
	v_mfma_f32_16x16x32_bf16 v[26:29], v[142:145], v[214:217], v[26:29]
	v_mfma_f32_16x16x32_bf16 v[14:17], v[134:137], v[222:225], v[14:17]
	v_mfma_f32_16x16x32_bf16 v[10:13], v[142:145], v[222:225], v[10:13]
	s_barrier
	s_add_u32 s26, s80, 0x40080
	s_addc_u32 s27, s81, 0
	s_add_i32 s38, s39, s84
	v_lshl_add_u64 v[130:131], s[26:27], 0, v[8:9]
	s_mov_b32 m0, s38
	s_nop 0
	global_load_lds_dwordx4 v[130:131], off
	v_lshl_add_u64 v[130:131], s[26:27], 0, v[176:177]
	s_add_i32 m0, s38, 0x2000
	s_nop 0
	global_load_lds_dwordx4 v[130:131], off
	s_waitcnt vmcnt(6)
	s_barrier
	v_mfma_f32_16x16x32_bf16 v[54:57], v[226:229], v[146:149], v[54:57]
	v_mfma_f32_16x16x32_bf16 v[50:53], v[234:237], v[146:149], v[50:53]
	v_mfma_f32_16x16x32_bf16 v[38:41], v[226:229], v[186:189], v[38:41]
	v_mfma_f32_16x16x32_bf16 v[34:37], v[234:237], v[186:189], v[34:37]
	v_mfma_f32_16x16x32_bf16 v[22:25], v[226:229], v[204:207], v[22:25]
	v_mfma_f32_16x16x32_bf16 v[18:21], v[234:237], v[204:207], v[18:21]
	v_mfma_f32_16x16x32_bf16 v[4:7], v[226:229], v[218:221], v[4:7]
	v_mfma_f32_16x16x32_bf16 v[0:3], v[234:237], v[218:221], v[0:3]
	v_mfma_f32_16x16x32_bf16 v[54:57], v[230:233], v[182:185], v[54:57]
	v_mfma_f32_16x16x32_bf16 v[50:53], v[238:241], v[182:185], v[50:53]
	v_mfma_f32_16x16x32_bf16 v[38:41], v[230:233], v[200:203], v[38:41]
	v_mfma_f32_16x16x32_bf16 v[34:37], v[238:241], v[200:203], v[34:37]
	v_mfma_f32_16x16x32_bf16 v[22:25], v[230:233], v[214:217], v[22:25]
	v_mfma_f32_16x16x32_bf16 v[18:21], v[238:241], v[214:217], v[18:21]
	v_mfma_f32_16x16x32_bf16 v[4:7], v[230:233], v[222:225], v[4:7]
	v_mfma_f32_16x16x32_bf16 v[0:3], v[238:241], v[222:225], v[0:3]
	s_add_i32 s19, s19, 2
	s_add_u32 s68, s68, 0x100
	s_addc_u32 s69, s69, 0
	s_add_u32 s15, s15, 0x100
	s_addc_u32 s18, s18, 0
	s_cmp_gt_u32 s19, 13
	s_barrier
	s_cbranch_scc0 .LBB0_968
	s_setprio 0
	v_and_b32_e32 v131, 64, v155
	v_xor_b32_e32 v130, 16, v155
	v_add_u32_e32 v131, 64, v131
	v_cmp_lt_i32_e32 vcc, v130, v131
	s_lshl_b32 s9, s46, 8
	v_add_u32_e32 v186, s9, v192
	v_cndmask_b32_e32 v130, v155, v130, vcc
	v_lshlrev_b32_e32 v200, 2, v130
	v_xor_b32_e32 v130, 32, v155
	v_cmp_lt_i32_e32 vcc, v130, v131
	v_lshl_or_b32 v184, s8, 8, v197
	v_ashrrev_i32_e32 v187, 31, v186
	v_cndmask_b32_e32 v130, v155, v130, vcc
	v_lshlrev_b32_e32 v199, 2, v130
	v_lshlrev_b64 v[130:131], 12, v[186:187]
	v_ashrrev_i32_e32 v185, 31, v184
	v_lshl_add_u64 v[130:131], s[78:79], 0, v[130:131]
	v_lshlrev_b64 v[188:189], 2, v[184:185]
	v_lshl_add_u64 v[130:131], v[130:131], 0, v[188:189]
	global_load_dwordx4 v[202:205], v[130:131], off offset:16
	global_load_dwordx4 v[206:209], v[130:131], off
	global_load_dwordx4 v[146:149], v[130:131], off offset:528
	global_load_dwordx4 v[214:217], v[130:131], off offset:512
	v_or_b32_e32 v190, 16, v186
	v_ashrrev_i32_e32 v191, 31, v190
	v_lshlrev_b64 v[130:131], 12, v[190:191]
	v_lshl_add_u64 v[130:131], s[78:79], 0, v[130:131]
	v_lshl_add_u64 v[134:135], v[130:131], 0, v[188:189]
	global_load_dwordx4 v[138:141], v[134:135], off offset:16
	global_load_dwordx4 v[142:145], v[134:135], off
	global_load_dwordx4 v[130:133], v[134:135], off offset:528
	s_nop 0
	global_load_dwordx4 v[134:137], v[134:135], off offset:512
	v_lshlrev_b64 v[162:163], 10, v[186:187]
	v_lshl_add_u64 v[164:165], v[162:163], 0, v[184:185]
	v_or_b32_e32 v182, 0x80, v184
	v_ashrrev_i32_e32 v183, 31, v182
	s_waitcnt vmcnt(0)
	v_pk_add_f32 v[122:123], v[122:123], v[202:203]
	v_pk_add_f32 v[128:129], v[128:129], v[208:209]
	v_pk_add_f32 v[126:127], v[126:127], v[206:207]
	v_lshl_add_u64 v[206:207], v[164:165], 2, s[30:31]
	v_pk_add_f32 v[124:125], v[124:125], v[204:205]
	global_store_dwordx4 v[206:207], v[126:129], off
	global_store_dwordx4 v[206:207], v[122:125], off offset:16
	v_cvt_pk_bf16_f32 v202, v126, v127
	v_cvt_pk_bf16_f32 v204, v122, v123
	v_mul_f32_e32 v127, v127, v127
	v_mul_f32_e32 v123, v123, v123
	v_fmac_f32_e32 v127, v126, v126
	v_mul_f32_e32 v126, v129, v129
	v_fmac_f32_e32 v123, v122, v122
	v_mul_f32_e32 v122, v125, v125
	v_fmac_f32_e32 v126, v128, v128
	v_fmac_f32_e32 v122, v124, v124
	v_cvt_pk_bf16_f32 v203, v128, v129
	v_cvt_pk_bf16_f32 v205, v124, v125
	v_lshl_add_u64 v[164:165], v[164:165], 1, s[28:29]
	v_add_f32_e32 v126, v127, v126
	v_add_f32_e32 v122, v123, v122
	v_pk_add_f32 v[120:121], v[120:121], v[216:217]
	v_pk_add_f32 v[118:119], v[118:119], v[214:215]
	v_pk_add_f32 v[114:115], v[114:115], v[146:147]
	global_store_dwordx4 v[164:165], v[202:205], off
	v_add_f32_e32 v128, v126, v122
	v_pk_add_f32 v[116:117], v[116:117], v[148:149]
	global_store_dwordx4 v[206:207], v[118:121], off offset:512
	global_store_dwordx4 v[206:207], v[114:117], off offset:528
	v_cvt_pk_bf16_f32 v122, v118, v119
	v_cvt_pk_bf16_f32 v124, v114, v115
	v_mul_f32_e32 v119, v119, v119
	v_mul_f32_e32 v115, v115, v115
	v_fmac_f32_e32 v119, v118, v118
	v_mul_f32_e32 v118, v121, v121
	v_fmac_f32_e32 v115, v114, v114
	v_mul_f32_e32 v114, v117, v117
	v_fmac_f32_e32 v118, v120, v120
	v_fmac_f32_e32 v114, v116, v116
	v_add_f32_e32 v118, v119, v118
	v_add_f32_e32 v114, v115, v114
	v_add_f32_e32 v114, v118, v114
	v_add_f32_e32 v114, v128, v114
	ds_bpermute_b32 v115, v200, v114
	v_lshl_add_u64 v[126:127], v[162:163], 0, v[182:183]
	v_cvt_pk_bf16_f32 v123, v120, v121
	v_cvt_pk_bf16_f32 v125, v116, v117
	v_lshl_add_u64 v[126:127], v[126:127], 1, s[28:29]
	s_waitcnt lgkmcnt(0)
	v_add_f32_e32 v114, v114, v115
	ds_bpermute_b32 v115, v199, v114
	global_store_dwordx4 v[126:127], v[122:125], off
	s_and_saveexec_b64 s[46:47], s[2:3]
	s_cbranch_execz .LBB0_971
	s_waitcnt lgkmcnt(0)
	v_add_f32_e32 v114, v114, v115
	ds_write_b32 v194, v114

; #define PG8_STAGE(bufoff, gbase, voff) do { _Pragma("unroll") for (int _i = 0; _i < 2; ++_i) \
;         __builtin_amdgcn_global_load_lds((const unsigned*)((const char*)(gbase) + (voff)[_i]), (LAS unsigned*)(lds + (bufoff) + ldsw + _i * 8192), 16, 0, 0); } while (0)
; #define PG8_LDA(dst, b, h) do { _Pragma("unroll") for (int m = 0; m < 4; ++m) _Pragma("unroll") for (int k = 0; k < 2; ++k) dst[m][k] = *(const LAS bf16x8*)(lds + PG8_SA(b, h) + aoff + m * 2048 + k * 1024); } while (0)
; #define PG8_LDB(dst, b, h) do { _Pragma("unroll") for (int n = 0; n < 2; ++n) _Pragma("unroll") for (int k = 0; k < 2; ++k) dst[n][k] = *(const LAS bf16x8*)(lds + PG8_SB(b, h) + boff + n * 2048 + k * 1024); } while (0)
; #define PG8_MMA(ai, bj, At, Bt) do { __builtin_amdgcn_s_setprio(1); _Pragma("unroll") for (int m = 0; m < 4; ++m) _Pragma("unroll") for (int n = 0; n < 2; ++n) _Pragma("unroll") for (int k = 0; k < 2; ++k) \
;         acc[ai][bj][m][n] = __builtin_amdgcn_mfma_f32_16x16x32_bf16(Bt[n][k], At[m][k], acc[ai][bj][m][n], 0, 0, 0); __builtin_amdgcn_s_setprio(0); } while (0)
; #define PG8_WAIT_L(n) asm volatile("s_waitcnt lgkmcnt(" #n ")" ::: "memory")
; #define PG8_BAR __builtin_amdgcn_s_barrier()
; #define PG8_SCHED __builtin_amdgcn_sched_barrier(0)
; template <class Epi>
; DEVI void gemm_phase(LAS unsigned char* lds, const Gemm g, const Epi& E) {
;     ...
;             PG8_LDB(B0, 0, 0); PG8_SCHED; PG8_LDA(At, 0, 0); PG8_STAGE(PG8_SA(1, 1), a1 + hstepA, voffA);
;             PG8_WAIT_L(8); PG8_BAR; PG8_WAIT_L(0); PG8_MMA(0, 0, At, B0); PG8_BAR; PG8_SCHED;
;             PG8_LDB(B1, 0, 1); PG8_STAGE(PG8_SB(0, 0), b2, voffB);
;             PG8_BAR; PG8_WAIT_L(0); PG8_MMA(0, 1, At, B1); PG8_BAR;
;             PG8_LDA(At, 0, 1); PG8_STAGE(PG8_SA(0, 0), a2, voffA);
;             PG8_BAR; PG8_WAIT_L(0); PG8_MMA(1, 0, At, B0); PG8_BAR; PG8_SCHED;
;             PG8_STAGE(PG8_SB(0, 1), b2 + hstepB, voffB);
.LBB0_1007:
	s_add_u32 s16, s14, 0xfffc0080
	s_addc_u32 s17, s15, -1
	s_add_i32 s26, 0, 0x10000
	v_add_u32_e32 v8, s26, v199
	ds_read_b128 v[130:133], v8
	ds_read_b128 v[134:137], v8 offset:1024
	ds_read_b128 v[138:141], v8 offset:2048
	ds_read_b128 v[142:145], v8 offset:3072
	s_cmp_eq_u32 s19, 12
	s_cselect_b32 s37, s0, s17
	s_cselect_b32 s36, s1, s16
	s_cselect_b32 s17, s5, s18
	s_cselect_b32 s16, s7, s9
	v_lshl_add_u64 v[162:163], s[14:15], 0, v[180:181]
	s_add_i32 m0, s66, 0xc000
	ds_read_b128 v[184:187], v204
	ds_read_b128 v[188:191], v204 offset:1024
	ds_read_b128 v[192:195], v204 offset:2048
	ds_read_b128 v[206:209], v204 offset:3072
	ds_read_b128 v[214:217], v204 offset:4096
	ds_read_b128 v[218:221], v204 offset:5120
	ds_read_b128 v[222:225], v204 offset:6144
	ds_read_b128 v[226:229], v204 offset:7168
	global_load_lds_dwordx4 v[162:163], off
	v_lshl_add_u64 v[162:163], s[14:15], 0, v[182:183]
	s_add_i32 m0, s66, 0xe000
	s_nop 0
	global_load_lds_dwordx4 v[162:163], off
	s_waitcnt lgkmcnt(8)
	s_barrier
	s_waitcnt lgkmcnt(0)
	v_mfma_f32_16x16x32_bf16 v[126:129], v[130:133], v[184:187], v[126:129]
	v_mfma_f32_16x16x32_bf16 v[122:125], v[138:141], v[184:187], v[122:125]
	v_mfma_f32_16x16x32_bf16 v[114:117], v[130:133], v[192:195], v[114:117]
	v_mfma_f32_16x16x32_bf16 v[106:109], v[138:141], v[192:195], v[106:109]
	v_mfma_f32_16x16x32_bf16 v[102:105], v[130:133], v[214:217], v[102:105]
	v_mfma_f32_16x16x32_bf16 v[94:97], v[138:141], v[214:217], v[94:97]
	v_mfma_f32_16x16x32_bf16 v[82:85], v[130:133], v[222:225], v[82:85]
	v_mfma_f32_16x16x32_bf16 v[74:77], v[138:141], v[222:225], v[74:77]
	v_mfma_f32_16x16x32_bf16 v[126:129], v[134:137], v[188:191], v[126:129]
	v_mfma_f32_16x16x32_bf16 v[122:125], v[142:145], v[188:191], v[122:125]
	v_mfma_f32_16x16x32_bf16 v[114:117], v[134:137], v[206:209], v[114:117]
	v_mfma_f32_16x16x32_bf16 v[106:109], v[142:145], v[206:209], v[106:109]
	v_mfma_f32_16x16x32_bf16 v[102:105], v[134:137], v[218:221], v[102:105]
	v_mfma_f32_16x16x32_bf16 v[94:97], v[142:145], v[218:221], v[94:97]
	v_mfma_f32_16x16x32_bf16 v[82:85], v[134:137], v[226:229], v[82:85]
	v_mfma_f32_16x16x32_bf16 v[74:77], v[142:145], v[226:229], v[74:77]
	s_barrier
	s_add_i32 s38, 0, 0x14000
	s_add_i32 s26, s26, s47
	v_add_u32_e32 v8, s38, v199
	v_lshl_add_u64 v[162:163], s[16:17], 0, v[148:149]
	s_mov_b32 m0, s26
	ds_read_b128 v[230:233], v8
	ds_read_b128 v[234:237], v8 offset:1024
	ds_read_b128 v[238:241], v8 offset:2048
	ds_read_b128 v[242:245], v8 offset:3072
	global_load_lds_dwordx4 v[162:163], off
	v_lshl_add_u64 v[164:165], s[16:17], 0, v[152:153]
	s_add_i32 m0, s26, 0x2000
	s_nop 0
	global_load_lds_dwordx4 v[164:165], off
	s_barrier
	s_waitcnt lgkmcnt(0)
	v_mfma_f32_16x16x32_bf16 v[118:121], v[230:233], v[184:187], v[118:121]
	v_mfma_f32_16x16x32_bf16 v[110:113], v[238:241], v[184:187], v[110:113]
	v_mfma_f32_16x16x32_bf16 v[98:101], v[230:233], v[192:195], v[98:101]
	v_mfma_f32_16x16x32_bf16 v[90:93], v[238:241], v[192:195], v[90:93]
	v_mfma_f32_16x16x32_bf16 v[86:89], v[230:233], v[214:217], v[86:89]
	v_mfma_f32_16x16x32_bf16 v[78:81], v[238:241], v[214:217], v[78:81]
	v_mfma_f32_16x16x32_bf16 v[54:57], v[230:233], v[222:225], v[54:57]
	v_mfma_f32_16x16x32_bf16 v[34:37], v[238:241], v[222:225], v[34:37]
	v_mfma_f32_16x16x32_bf16 v[118:121], v[234:237], v[188:191], v[118:121]
	v_mfma_f32_16x16x32_bf16 v[110:113], v[242:245], v[188:191], v[110:113]
	v_mfma_f32_16x16x32_bf16 v[98:101], v[234:237], v[206:209], v[98:101]
	v_mfma_f32_16x16x32_bf16 v[90:93], v[242:245], v[206:209], v[90:93]
	v_mfma_f32_16x16x32_bf16 v[86:89], v[234:237], v[218:221], v[86:89]
	v_mfma_f32_16x16x32_bf16 v[78:81], v[242:245], v[218:221], v[78:81]
	v_mfma_f32_16x16x32_bf16 v[54:57], v[234:237], v[226:229], v[54:57]
	v_mfma_f32_16x16x32_bf16 v[34:37], v[242:245], v[226:229], v[34:37]
	s_mov_b32 m0, s66
	v_lshl_add_u64 v[202:203], s[36:37], 0, v[146:147]
	s_barrier
	ds_read_b128 v[184:187], v204 offset:16384
	ds_read_b128 v[188:191], v204 offset:17408
	ds_read_b128 v[192:195], v204 offset:18432
	ds_read_b128 v[206:209], v204 offset:19456
	ds_read_b128 v[214:217], v204 offset:20480
	ds_read_b128 v[218:221], v204 offset:21504
	ds_read_b128 v[222:225], v204 offset:22528
	ds_read_b128 v[226:229], v204 offset:23552
	global_load_lds_dwordx4 v[202:203], off
	v_lshl_add_u64 v[246:247], s[36:37], 0, v[150:151]
	s_mov_b32 m0, s68
	s_nop 0
	global_load_lds_dwordx4 v[246:247], off
	s_barrier
	s_waitcnt lgkmcnt(0)
	v_mfma_f32_16x16x32_bf16 v[58:61], v[130:133], v[184:187], v[58:61]
	v_mfma_f32_16x16x32_bf16 v[62:65], v[138:141], v[184:187], v[62:65]
	v_mfma_f32_16x16x32_bf16 v[38:41], v[130:133], v[192:195], v[38:41]
	v_mfma_f32_16x16x32_bf16 v[42:45], v[138:141], v[192:195], v[42:45]
	v_mfma_f32_16x16x32_bf16 v[18:21], v[130:133], v[214:217], v[18:21]
	v_mfma_f32_16x16x32_bf16 v[22:25], v[138:141], v[214:217], v[22:25]
	v_mfma_f32_16x16x32_bf16 v[0:3], v[130:133], v[222:225], v[0:3]
	v_mfma_f32_16x16x32_bf16 v[4:7], v[138:141], v[222:225], v[4:7]
	v_mfma_f32_16x16x32_bf16 v[58:61], v[134:137], v[188:191], v[58:61]
	v_mfma_f32_16x16x32_bf16 v[62:65], v[142:145], v[188:191], v[62:65]
	v_mfma_f32_16x16x32_bf16 v[38:41], v[134:137], v[206:209], v[38:41]
	v_mfma_f32_16x16x32_bf16 v[42:45], v[142:145], v[206:209], v[42:45]
	v_mfma_f32_16x16x32_bf16 v[18:21], v[134:137], v[218:221], v[18:21]
	v_mfma_f32_16x16x32_bf16 v[22:25], v[142:145], v[218:221], v[22:25]
	v_mfma_f32_16x16x32_bf16 v[0:3], v[134:137], v[226:229], v[0:3]
	v_mfma_f32_16x16x32_bf16 v[4:7], v[142:145], v[226:229], v[4:7]
	s_barrier
; #define PG8_STAGE(bufoff, gbase, voff) do { _Pragma("unroll") for (int _i = 0; _i < 2; ++_i) \
;         __builtin_amdgcn_global_load_lds((const unsigned*)((const char*)(gbase) + (voff)[_i]), (LAS unsigned*)(lds + (bufoff) + ldsw + _i * 8192), 16, 0, 0); } while (0)
; #define PG8_LDA(dst, b, h) do { _Pragma("unroll") for (int m = 0; m < 4; ++m) _Pragma("unroll") for (int k = 0; k < 2; ++k) dst[m][k] = *(const LAS bf16x8*)(lds + PG8_SA(b, h) + aoff + m * 2048 + k * 1024); } while (0)
; #define PG8_LDB(dst, b, h) do { _Pragma("unroll") for (int n = 0; n < 2; ++n) _Pragma("unroll") for (int k = 0; k < 2; ++k) dst[n][k] = *(const LAS bf16x8*)(lds + PG8_SB(b, h) + boff + n * 2048 + k * 1024); } while (0)
; #define PG8_MMA(ai, bj, At, Bt) do { __builtin_amdgcn_s_setprio(1); _Pragma("unroll") for (int m = 0; m < 4; ++m) _Pragma("unroll") for (int n = 0; n < 2; ++n) _Pragma("unroll") for (int k = 0; k < 2; ++k) \
;         acc[ai][bj][m][n] = __builtin_amdgcn_mfma_f32_16x16x32_bf16(Bt[n][k], At[m][k], acc[ai][bj][m][n], 0, 0, 0); __builtin_amdgcn_s_setprio(0); } while (0)
; #define PG8_WAIT_V(n) asm volatile("s_waitcnt vmcnt(" #n ")" ::: "memory")
; #define PG8_WAIT_L(n) asm volatile("s_waitcnt lgkmcnt(" #n ")" ::: "memory")
; #define PG8_BAR __builtin_amdgcn_s_barrier()
; #define PG8_SCHED __builtin_amdgcn_sched_barrier(0)
; template <class Epi>
; DEVI void gemm_phase(LAS unsigned char* lds, const Gemm g, const Epi& E) {
;     ...
;             PG8_STAGE(PG8_SB(0, 1), b2 + hstepB, voffB);
;             PG8_WAIT_V(6); PG8_BAR; PG8_MMA(1, 1, At, B1); PG8_BAR;
;             PG8_LDB(B0, 1, 0); PG8_SCHED; PG8_LDA(At, 1, 0); PG8_STAGE(PG8_SA(0, 1), a2 + hstepA, voffA);
;             PG8_WAIT_L(8); PG8_BAR; PG8_WAIT_L(0); PG8_MMA(0, 0, At, B0); PG8_BAR; PG8_SCHED;
;             PG8_LDB(B1, 1, 1); PG8_STAGE(PG8_SB(1, 0), b3, voffB);
;             PG8_BAR; PG8_WAIT_L(0); PG8_MMA(0, 1, At, B1); PG8_BAR;
;             PG8_LDA(At, 1, 1); PG8_STAGE(PG8_SA(1, 0), a3, voffA);
	s_add_u32 s26, s16, 0x40000
	s_addc_u32 s27, s17, 0
	s_add_i32 s38, s38, s47
	v_lshl_add_u64 v[130:131], s[26:27], 0, v[148:149]
	s_mov_b32 m0, s38
	s_nop 0
	global_load_lds_dwordx4 v[130:131], off
	v_lshl_add_u64 v[130:131], s[26:27], 0, v[152:153]
	s_add_i32 m0, s38, 0x2000
	s_nop 0
	global_load_lds_dwordx4 v[130:131], off
	s_waitcnt vmcnt(6)
	s_barrier
	v_mfma_f32_16x16x32_bf16 v[66:69], v[230:233], v[184:187], v[66:69]
	v_mfma_f32_16x16x32_bf16 v[70:73], v[238:241], v[184:187], v[70:73]
	v_mfma_f32_16x16x32_bf16 v[46:49], v[230:233], v[192:195], v[46:49]
	v_mfma_f32_16x16x32_bf16 v[50:53], v[238:241], v[192:195], v[50:53]
	v_mfma_f32_16x16x32_bf16 v[26:29], v[230:233], v[214:217], v[26:29]
	v_mfma_f32_16x16x32_bf16 v[30:33], v[238:241], v[214:217], v[30:33]
	v_mfma_f32_16x16x32_bf16 v[10:13], v[230:233], v[222:225], v[10:13]
	v_mfma_f32_16x16x32_bf16 v[14:17], v[238:241], v[222:225], v[14:17]
	v_mfma_f32_16x16x32_bf16 v[66:69], v[234:237], v[188:191], v[66:69]
	v_mfma_f32_16x16x32_bf16 v[70:73], v[242:245], v[188:191], v[70:73]
	v_mfma_f32_16x16x32_bf16 v[46:49], v[234:237], v[206:209], v[46:49]
	v_mfma_f32_16x16x32_bf16 v[50:53], v[242:245], v[206:209], v[50:53]
	v_mfma_f32_16x16x32_bf16 v[26:29], v[234:237], v[218:221], v[26:29]
	v_mfma_f32_16x16x32_bf16 v[30:33], v[242:245], v[218:221], v[30:33]
	v_mfma_f32_16x16x32_bf16 v[10:13], v[234:237], v[226:229], v[10:13]
	v_mfma_f32_16x16x32_bf16 v[14:17], v[242:245], v[226:229], v[14:17]
	s_add_i32 s38, 0, 0x18000
	v_add_u32_e32 v8, s38, v199
	s_barrier
	ds_read_b128 v[130:133], v8
	ds_read_b128 v[134:137], v8 offset:1024
	ds_read_b128 v[138:141], v8 offset:2048
	ds_read_b128 v[142:145], v8 offset:3072
	s_add_u32 s26, s36, 0x40000
	s_addc_u32 s27, s37, 0
	s_mov_b32 m0, s69
	v_lshl_add_u64 v[230:231], s[26:27], 0, v[146:147]
	ds_read_b128 v[184:187], v204 offset:32768
	ds_read_b128 v[188:191], v204 offset:33792
	ds_read_b128 v[192:195], v204 offset:34816
	ds_read_b128 v[206:209], v204 offset:35840
	ds_read_b128 v[214:217], v204 offset:36864
	ds_read_b128 v[218:221], v204 offset:37888
	ds_read_b128 v[222:225], v204 offset:38912
	ds_read_b128 v[226:229], v204 offset:39936
	global_load_lds_dwordx4 v[230:231], off
	v_lshl_add_u64 v[230:231], s[26:27], 0, v[150:151]
	s_mov_b32 m0, s80
	s_nop 0
	global_load_lds_dwordx4 v[230:231], off
	s_waitcnt lgkmcnt(8)
	s_barrier
	s_waitcnt lgkmcnt(0)
	v_mfma_f32_16x16x32_bf16 v[126:129], v[130:133], v[184:187], v[126:129]
	v_mfma_f32_16x16x32_bf16 v[122:125], v[138:141], v[184:187], v[122:125]
	v_mfma_f32_16x16x32_bf16 v[114:117], v[130:133], v[192:195], v[114:117]
	v_mfma_f32_16x16x32_bf16 v[106:109], v[138:141], v[192:195], v[106:109]
	v_mfma_f32_16x16x32_bf16 v[102:105], v[130:133], v[214:217], v[102:105]
	v_mfma_f32_16x16x32_bf16 v[94:97], v[138:141], v[214:217], v[94:97]
	v_mfma_f32_16x16x32_bf16 v[82:85], v[130:133], v[222:225], v[82:85]
	v_mfma_f32_16x16x32_bf16 v[74:77], v[138:141], v[222:225], v[74:77]
	v_mfma_f32_16x16x32_bf16 v[126:129], v[134:137], v[188:191], v[126:129]
	v_mfma_f32_16x16x32_bf16 v[122:125], v[142:145], v[188:191], v[122:125]
	v_mfma_f32_16x16x32_bf16 v[114:117], v[134:137], v[206:209], v[114:117]
	v_mfma_f32_16x16x32_bf16 v[106:109], v[142:145], v[206:209], v[106:109]
	v_mfma_f32_16x16x32_bf16 v[102:105], v[134:137], v[218:221], v[102:105]
	v_mfma_f32_16x16x32_bf16 v[94:97], v[142:145], v[218:221], v[94:97]
	v_mfma_f32_16x16x32_bf16 v[82:85], v[134:137], v[226:229], v[82:85]
	v_mfma_f32_16x16x32_bf16 v[74:77], v[142:145], v[226:229], v[74:77]
	s_barrier
	s_add_i32 s26, 0, 0x1c000
	s_add_i32 s27, s38, s47
	v_add_u32_e32 v8, s26, v199
	v_lshl_add_u64 v[162:163], v[162:163], 0, s[70:71]
	s_mov_b32 m0, s27
	ds_read_b128 v[230:233], v8
	ds_read_b128 v[234:237], v8 offset:1024
	ds_read_b128 v[238:241], v8 offset:2048
	ds_read_b128 v[242:245], v8 offset:3072
	global_load_lds_dwordx4 v[162:163], off
	v_lshl_add_u64 v[162:163], v[164:165], 0, s[70:71]
	s_add_i32 m0, s27, 0x2000
	s_nop 0
	global_load_lds_dwordx4 v[162:163], off
	s_barrier
	s_waitcnt lgkmcnt(0)
	v_mfma_f32_16x16x32_bf16 v[118:121], v[230:233], v[184:187], v[118:121]
	v_mfma_f32_16x16x32_bf16 v[110:113], v[238:241], v[184:187], v[110:113]
	v_mfma_f32_16x16x32_bf16 v[98:101], v[230:233], v[192:195], v[98:101]
	v_mfma_f32_16x16x32_bf16 v[90:93], v[238:241], v[192:195], v[90:93]
	v_mfma_f32_16x16x32_bf16 v[86:89], v[230:233], v[214:217], v[86:89]
	v_mfma_f32_16x16x32_bf16 v[78:81], v[238:241], v[214:217], v[78:81]
	v_mfma_f32_16x16x32_bf16 v[54:57], v[230:233], v[222:225], v[54:57]
	v_mfma_f32_16x16x32_bf16 v[34:37], v[238:241], v[222:225], v[34:37]
	v_mfma_f32_16x16x32_bf16 v[118:121], v[234:237], v[188:191], v[118:121]
	v_mfma_f32_16x16x32_bf16 v[110:113], v[242:245], v[188:191], v[110:113]
	v_mfma_f32_16x16x32_bf16 v[98:101], v[234:237], v[206:209], v[98:101]
	v_mfma_f32_16x16x32_bf16 v[90:93], v[242:245], v[206:209], v[90:93]
	v_mfma_f32_16x16x32_bf16 v[86:89], v[234:237], v[218:221], v[86:89]
	v_mfma_f32_16x16x32_bf16 v[78:81], v[242:245], v[218:221], v[78:81]
	v_mfma_f32_16x16x32_bf16 v[54:57], v[234:237], v[226:229], v[54:57]
	v_mfma_f32_16x16x32_bf16 v[34:37], v[242:245], v[226:229], v[34:37]
	s_mov_b32 m0, s81
	v_lshl_add_u64 v[162:163], v[202:203], 0, s[70:71]
	s_barrier
	ds_read_b128 v[184:187], v204 offset:49152
	ds_read_b128 v[188:191], v204 offset:50176
	ds_read_b128 v[192:195], v204 offset:51200
	ds_read_b128 v[206:209], v204 offset:52224
	ds_read_b128 v[214:217], v204 offset:53248
	ds_read_b128 v[218:221], v204 offset:54272
	ds_read_b128 v[222:225], v204 offset:55296
	ds_read_b128 v[226:229], v204 offset:56320
	global_load_lds_dwordx4 v[162:163], off
	v_lshl_add_u64 v[162:163], v[246:247], 0, s[70:71]
	s_mov_b32 m0, s82
	s_nop 0
	global_load_lds_dwordx4 v[162:163], off
	s_barrier
; #define PG8_STAGE(bufoff, gbase, voff) do { _Pragma("unroll") for (int _i = 0; _i < 2; ++_i) \
;         __builtin_amdgcn_global_load_lds((const unsigned*)((const char*)(gbase) + (voff)[_i]), (LAS unsigned*)(lds + (bufoff) + ldsw + _i * 8192), 16, 0, 0); } while (0)
; #define PG8_MMA(ai, bj, At, Bt) do { __builtin_amdgcn_s_setprio(1); _Pragma("unroll") for (int m = 0; m < 4; ++m) _Pragma("unroll") for (int n = 0; n < 2; ++n) _Pragma("unroll") for (int k = 0; k < 2; ++k) \
;         acc[ai][bj][m][n] = __builtin_amdgcn_mfma_f32_16x16x32_bf16(Bt[n][k], At[m][k], acc[ai][bj][m][n], 0, 0, 0); __builtin_amdgcn_s_setprio(0); } while (0)
; #define PG8_WAIT_V(n) asm volatile("s_waitcnt vmcnt(" #n ")" ::: "memory")
; #define PG8_WAIT_L(n) asm volatile("s_waitcnt lgkmcnt(" #n ")" ::: "memory")
; #define PG8_BAR __builtin_amdgcn_s_barrier()
; #define PG8_SCHED __builtin_amdgcn_sched_barrier(0)
; template <class Epi>
; DEVI void gemm_phase(LAS unsigned char* lds, const Gemm g, const Epi& E) {
;     ...
;             PG8_BAR; PG8_WAIT_L(0); PG8_MMA(1, 0, At, B0); PG8_BAR; PG8_SCHED;
;             PG8_STAGE(PG8_SB(1, 1), b3 + hstepB, voffB);
;             PG8_WAIT_V(6); PG8_BAR; PG8_MMA(1, 1, At, B1); PG8_BAR;
;         }
;         {
;             const int row0 = cur.pm * BM + wr * 64 + fr, col0 = cur.pn * BM + wc * 32 + (Epi::PERM ? 8 : 4) * fq; constexpr int NST = Epi::PERM ? 4 : 16;
;             float rsv[8];
;             if constexpr (Epi::RS) { f32x4 q4[8];
; #pragma unroll
;                 for (int i = 0; i < 8; ++i) q4[i] = *(const f32x4*)(E.ssq_in + (size_t)(row0 + (i >> 2) * HALF + (i & 3) * 16) * 4);
; #pragma unroll
;                 for (int i = 0; i < 8; ++i) rsv[i] = rsqrtf((((q4[i][0] + q4[i][1]) + q4[i][2]) + q4[i][3]) * (1.f / DM) + 1e-6f); }
	s_waitcnt lgkmcnt(0)
	v_mfma_f32_16x16x32_bf16 v[58:61], v[130:133], v[184:187], v[58:61]
	v_mfma_f32_16x16x32_bf16 v[62:65], v[138:141], v[184:187], v[62:65]
	v_mfma_f32_16x16x32_bf16 v[38:41], v[130:133], v[192:195], v[38:41]
	v_mfma_f32_16x16x32_bf16 v[42:45], v[138:141], v[192:195], v[42:45]
	v_mfma_f32_16x16x32_bf16 v[18:21], v[130:133], v[214:217], v[18:21]
	v_mfma_f32_16x16x32_bf16 v[22:25], v[138:141], v[214:217], v[22:25]
	v_mfma_f32_16x16x32_bf16 v[0:3], v[130:133], v[222:225], v[0:3]
	v_mfma_f32_16x16x32_bf16 v[4:7], v[138:141], v[222:225], v[4:7]
	v_mfma_f32_16x16x32_bf16 v[58:61], v[134:137], v[188:191], v[58:61]
	v_mfma_f32_16x16x32_bf16 v[62:65], v[142:145], v[188:191], v[62:65]
	v_mfma_f32_16x16x32_bf16 v[38:41], v[134:137], v[206:209], v[38:41]
	v_mfma_f32_16x16x32_bf16 v[42:45], v[142:145], v[206:209], v[42:45]
	v_mfma_f32_16x16x32_bf16 v[18:21], v[134:137], v[218:221], v[18:21]
	v_mfma_f32_16x16x32_bf16 v[22:25], v[142:145], v[218:221], v[22:25]
	v_mfma_f32_16x16x32_bf16 v[0:3], v[134:137], v[226:229], v[0:3]
	v_mfma_f32_16x16x32_bf16 v[4:7], v[142:145], v[226:229], v[4:7]
	s_barrier
	s_add_u32 s16, s16, 0x40080
	s_addc_u32 s17, s17, 0
	s_add_i32 s26, s26, s47
	v_lshl_add_u64 v[130:131], s[16:17], 0, v[148:149]
	s_mov_b32 m0, s26
	s_nop 0
	global_load_lds_dwordx4 v[130:131], off
	v_lshl_add_u64 v[130:131], s[16:17], 0, v[152:153]
	s_add_i32 m0, s26, 0x2000
	s_nop 0
	global_load_lds_dwordx4 v[130:131], off
	s_waitcnt vmcnt(6)
	s_barrier
	v_mfma_f32_16x16x32_bf16 v[66:69], v[230:233], v[184:187], v[66:69]
	v_mfma_f32_16x16x32_bf16 v[70:73], v[238:241], v[184:187], v[70:73]
	v_mfma_f32_16x16x32_bf16 v[46:49], v[230:233], v[192:195], v[46:49]
	v_mfma_f32_16x16x32_bf16 v[50:53], v[238:241], v[192:195], v[50:53]
	v_mfma_f32_16x16x32_bf16 v[26:29], v[230:233], v[214:217], v[26:29]
	v_mfma_f32_16x16x32_bf16 v[30:33], v[238:241], v[214:217], v[30:33]
	v_mfma_f32_16x16x32_bf16 v[10:13], v[230:233], v[222:225], v[10:13]
	v_mfma_f32_16x16x32_bf16 v[14:17], v[238:241], v[222:225], v[14:17]
	v_mfma_f32_16x16x32_bf16 v[66:69], v[234:237], v[188:191], v[66:69]
	v_mfma_f32_16x16x32_bf16 v[70:73], v[242:245], v[188:191], v[70:73]
	v_mfma_f32_16x16x32_bf16 v[46:49], v[234:237], v[206:209], v[46:49]
	v_mfma_f32_16x16x32_bf16 v[50:53], v[242:245], v[206:209], v[50:53]
	v_mfma_f32_16x16x32_bf16 v[26:29], v[234:237], v[218:221], v[26:29]
	v_mfma_f32_16x16x32_bf16 v[30:33], v[242:245], v[218:221], v[30:33]
	v_mfma_f32_16x16x32_bf16 v[10:13], v[234:237], v[226:229], v[10:13]
	v_mfma_f32_16x16x32_bf16 v[14:17], v[242:245], v[226:229], v[14:17]
	s_add_i32 s19, s19, 2
	s_add_u32 s14, s14, 0x100
	s_addc_u32 s15, s15, 0
	s_add_u32 s9, s9, 0x100
	s_addc_u32 s18, s18, 0
	s_cmp_gt_u32 s19, 13
	s_barrier
	s_cbranch_scc0 .LBB0_1007
	s_setprio 0
	v_lshl_add_u32 v194, s4, 8, v197
	v_add_u32_e32 v184, 0xb0, v194
	v_ashrrev_i32_e32 v195, 31, v194
	v_ashrrev_i32_e32 v185, 31, v184
	v_lshl_add_u64 v[130:131], v[194:195], 4, s[76:77]
	v_lshl_add_u64 v[134:135], v[184:185], 4, s[76:77]
	global_load_dwordx4 v[206:209], v[130:131], off
	v_or_b32_e32 v192, 48, v194
	global_load_dwordx4 v[134:137], v[134:135], off
	v_or_b32_e32 v130, 16, v194
	v_ashrrev_i32_e32 v131, 31, v130
	v_lshl_add_u64 v[130:131], v[130:131], 4, s[76:77]
	global_load_dwordx4 v[214:217], v[130:131], off
	v_or_b32_e32 v130, 32, v194
	v_ashrrev_i32_e32 v131, 31, v130
	v_lshl_add_u64 v[130:131], v[130:131], 4, s[76:77]
	v_ashrrev_i32_e32 v193, 31, v192
	global_load_dwordx4 v[218:221], v[130:131], off
	v_lshl_add_u64 v[130:131], v[192:193], 4, s[76:77]
	global_load_dwordx4 v[222:225], v[130:131], off
	v_add_u32_e32 v190, 0x80, v194
	v_ashrrev_i32_e32 v191, 31, v190
	v_add_u32_e32 v188, 0x90, v194
	v_lshl_add_u64 v[130:131], v[190:191], 4, s[76:77]
	v_ashrrev_i32_e32 v189, 31, v188
	global_load_dwordx4 v[138:141], v[130:131], off
	v_lshl_add_u64 v[130:131], v[188:189], 4, s[76:77]
	global_load_dwordx4 v[142:145], v[130:131], off
	v_add_u32_e32 v186, 0xa0, v194
	v_ashrrev_i32_e32 v187, 31, v186
	v_lshl_add_u64 v[130:131], v[186:187], 4, s[76:77]
	global_load_dwordx4 v[130:133], v[130:131], off
	s_mov_b32 s0, 0x358637bd
	v_mov_b64_e32 v[202:203], s[0:1]
	s_mov_b64 s[16:17], s[12:13]
	s_mov_b64 s[14:15], s[10:11]
	s_waitcnt vmcnt(0)
; template <class Epi>
; DEVI void gemm_phase(LAS unsigned char* lds, const Gemm g, const Epi& E) {
;     ...
;             if constexpr (Epi::RS) { f32x4 q4[8];
; #pragma unroll
;                 for (int i = 0; i < 8; ++i) q4[i] = *(const f32x4*)(E.ssq_in + (size_t)(row0 + (i >> 2) * HALF + (i & 3) * 16) * 4);
; #pragma unroll
;                 for (int i = 0; i < 8; ++i) rsv[i] = rsqrtf((((q4[i][0] + q4[i][1]) + q4[i][2]) + q4[i][3]) * (1.f / DM) + 1e-6f); }
	v_mov_b32_e32 v163, v206
	v_mov_b32_e32 v165, v208
	v_mov_b32_e32 v162, v214
	v_mov_b32_e32 v206, v215
	v_pk_add_f32 v[162:163], v[162:163], v[206:207]
	v_mov_b32_e32 v164, v216
	v_pk_add_f32 v[162:163], v[164:165], v[162:163]
	v_mov_b32_e32 v208, v217
	v_pk_add_f32 v[162:163], v[208:209], v[162:163]
	v_mov_b32_e32 v164, v224
	v_pk_fma_f32 v[162:163], v[162:163], s[72:73], v[202:203] op_sel_hi:[1,0,0]
	v_mov_b32_e32 v165, v220
	v_mul_f32_e32 v8, 0x4b800000, v163
	v_cmp_gt_f32_e64 s[4:5], s94, v163
	v_cmp_gt_f32_e32 vcc, s94, v162
	v_mov_b32_e32 v220, v225
	v_cndmask_b32_e64 v8, v163, v8, s[4:5]
	v_rsq_f32_e32 v8, v8
	s_nop 0
	v_mul_f32_e32 v163, 0x45800000, v8
	v_cndmask_b32_e64 v198, v8, v163, s[4:5]
	v_mul_f32_e32 v8, 0x4b800000, v162
	v_cndmask_b32_e32 v8, v162, v8, vcc
	v_rsq_f32_e32 v8, v8
	v_mov_b32_e32 v163, v218
	v_mov_b32_e32 v218, v223
	v_pk_mul_f32 v[128:129], v[128:129], v[198:199] op_sel_hi:[1,0]
	v_mul_f32_e32 v162, 0x45800000, v8
	v_cndmask_b32_e32 v8, v8, v162, vcc
	v_mov_b32_e32 v162, v222
	v_pk_add_f32 v[162:163], v[162:163], v[218:219]
	v_pk_mul_f32 v[126:127], v[126:127], v[198:199] op_sel_hi:[1,0]
	v_pk_add_f32 v[162:163], v[164:165], v[162:163]
	v_pk_mul_f32 v[122:123], v[122:123], v[198:199] op_sel_hi:[1,0]
	v_pk_add_f32 v[162:163], v[220:221], v[162:163]
	v_pk_mul_f32 v[120:121], v[120:121], v[198:199] op_sel_hi:[1,0]
	v_pk_fma_f32 v[162:163], v[162:163], s[72:73], v[202:203] op_sel_hi:[1,0,0]
	v_pk_mul_f32 v[118:119], v[118:119], v[198:199] op_sel_hi:[1,0]
	v_mul_f32_e32 v164, 0x4b800000, v163
	v_cmp_gt_f32_e64 s[4:5], s94, v163
	v_cmp_gt_f32_e32 vcc, s94, v162
	v_pk_mul_f32 v[110:111], v[110:111], v[198:199] op_sel_hi:[1,0]
	v_cndmask_b32_e64 v163, v163, v164, s[4:5]
	v_rsq_f32_e32 v163, v163
	v_cvt_pk_bf16_f32 v118, v118, v119
	v_cvt_pk_bf16_f32 v119, v120, v121
	v_cvt_pk_bf16_f32 v120, v110, v111
	v_mul_f32_e32 v164, 0x45800000, v163
	v_cndmask_b32_e64 v200, v163, v164, s[4:5]
	v_mul_f32_e32 v163, 0x4b800000, v162
	v_cndmask_b32_e32 v162, v162, v163, vcc
	v_rsq_f32_e32 v162, v162
	v_pk_mul_f32 v[112:113], v[112:113], v[198:199] op_sel_hi:[1,0]
	v_pk_mul_f32 v[114:115], v[114:115], v[8:9] op_sel_hi:[1,0]
	v_cvt_pk_bf16_f32 v121, v112, v113
	v_mul_f32_e32 v163, 0x45800000, v162
	v_cndmask_b32_e32 v196, v162, v163, vcc
	v_mov_b32_e32 v162, v142
	v_mov_b32_e32 v163, v138
	v_mov_b32_e32 v138, v143
	v_pk_add_f32 v[138:139], v[162:163], v[138:139]
	v_mov_b32_e32 v142, v144
	v_mov_b32_e32 v143, v140
	v_pk_add_f32 v[138:139], v[142:143], v[138:139]
	v_mov_b32_e32 v140, v145
	v_pk_add_f32 v[138:139], v[140:141], v[138:139]
	v_mov_b32_e32 v142, v134
	v_pk_fma_f32 v[140:141], v[138:139], s[72:73], v[202:203] op_sel_hi:[1,0,0]
	v_mov_b32_e32 v143, v130
	v_mul_f32_e32 v138, 0x4b800000, v141
	v_cmp_gt_f32_e64 s[4:5], s94, v141
	v_mov_b32_e32 v130, v135
	v_pk_add_f32 v[130:131], v[142:143], v[130:131]
	v_cndmask_b32_e64 v138, v141, v138, s[4:5]
	v_rsq_f32_e32 v138, v138
	v_mov_b32_e32 v134, v136
	v_mov_b32_e32 v135, v132
	v_pk_add_f32 v[130:131], v[134:135], v[130:131]
	v_mov_b32_e32 v132, v137
	v_pk_add_f32 v[130:131], v[132:133], v[130:131]
	v_mul_f32_e32 v139, 0x45800000, v138
	v_pk_fma_f32 v[130:131], v[130:131], s[72:73], v[202:203] op_sel_hi:[1,0,0]
	v_cmp_gt_f32_e32 vcc, s94, v140
	v_cndmask_b32_e64 v138, v138, v139, s[4:5]
	v_mul_f32_e32 v139, 0x4b800000, v140
	v_mul_f32_e32 v132, 0x4b800000, v131
	v_cmp_gt_f32_e64 s[4:5], s94, v131
	v_cndmask_b32_e32 v139, v140, v139, vcc
	v_rsq_f32_e32 v139, v139
	v_cndmask_b32_e64 v131, v131, v132, s[4:5]
	v_rsq_f32_e32 v131, v131
	v_pk_mul_f32 v[136:137], v[124:125], v[198:199] op_sel_hi:[1,0]
	v_mul_f32_e32 v140, 0x45800000, v139
	v_cndmask_b32_e32 v140, v139, v140, vcc
	v_mul_f32_e32 v132, 0x45800000, v131
	v_cmp_gt_f32_e32 vcc, s94, v130
	v_cndmask_b32_e64 v132, v131, v132, s[4:5]
	v_mul_f32_e32 v131, 0x4b800000, v130
	v_cndmask_b32_e32 v130, v130, v131, vcc
	v_rsq_f32_e32 v130, v130
	v_cvt_pk_bf16_f32 v125, v128, v129
	v_ashrrev_i32_e32 v134, 5, v194
	v_ashrrev_i32_e32 v135, 31, v134
	v_mul_f32_e32 v131, 0x45800000, v130
	v_cndmask_b32_e32 v130, v130, v131, vcc
	v_lshl_or_b32 v131, s84, 8, v201
	v_ashrrev_i32_e32 v128, 4, v131
	v_ashrrev_i32_e32 v129, 31, v128
	v_cvt_pk_bf16_f32 v124, v126, v127
	v_cvt_pk_bf16_f32 v126, v122, v123
	v_lshlrev_b64 v[122:123], 10, v[128:129]
	v_or_b32_e32 v110, 8, v128
	v_cvt_pk_bf16_f32 v127, v136, v137
	v_lshl_add_u64 v[136:137], v[122:123], 0, v[134:135]
	v_ashrrev_i32_e32 v111, 31, v110
	v_mad_u64_u32 v[142:143], s[0:1], v136, s34, v[178:179]
	v_lshlrev_b64 v[110:111], 10, v[110:111]
	v_mad_i32_i24 v143, v137, s34, v143
	v_lshl_add_u64 v[112:113], v[110:111], 0, v[134:135]
	global_store_dwordx4 v[142:143], v[124:127], off
	v_pk_mul_f32 v[100:101], v[100:101], v[8:9] op_sel_hi:[1,0]
	v_pk_mul_f32 v[98:99], v[98:99], v[8:9] op_sel_hi:[1,0]
	v_mad_u64_u32 v[124:125], s[0:1], v112, s34, v[178:179]
	v_mad_i32_i24 v125, v113, s34, v125
	v_pk_mul_f32 v[112:113], v[116:117], v[8:9] op_sel_hi:[1,0]
	v_pk_mul_f32 v[116:117], v[108:109], v[8:9] op_sel_hi:[1,0]
	v_pk_mul_f32 v[108:109], v[106:107], v[8:9] op_sel_hi:[1,0]
	v_cvt_pk_bf16_f32 v106, v114, v115
	v_cvt_pk_bf16_f32 v107, v112, v113
	v_cvt_pk_bf16_f32 v108, v108, v109
	v_cvt_pk_bf16_f32 v109, v116, v117
	global_store_dwordx4 v[142:143], v[106:109], off offset:512
	v_pk_mul_f32 v[94:95], v[94:95], v[200:201] op_sel_hi:[1,0]
	v_pk_mul_f32 v[96:97], v[96:97], v[200:201] op_sel_hi:[1,0]
	v_pk_mul_f32 v[106:107], v[92:93], v[8:9] op_sel_hi:[1,0]
	v_pk_mul_f32 v[92:93], v[90:91], v[8:9] op_sel_hi:[1,0]
	v_cvt_pk_bf16_f32 v90, v98, v99
	v_cvt_pk_bf16_f32 v91, v100, v101
	v_cvt_pk_bf16_f32 v92, v92, v93
; template <class Epi>
; DEVI void gemm_phase(LAS unsigned char* lds, const Gemm g, const Epi& E) {
;     ...
;                         const int c = col0 + bj * HALF; f32x4 v0 = acc[ai][bj][m][0], v1 = acc[ai][bj][m][1];
;                         if constexpr (Epi::RS) { v0 = v0 * rs; v1 = v1 * rs; }
;                         if constexpr (Epi::PRE) part += E.frag_pre8(cur.b, r, c, v0, v1, pre[mm][bj][0], pre[mm][bj][1]);
;                         else if constexpr (Epi::PERM) E.frag8(cur.b, r, c, v0, v1);
	v_cvt_pk_bf16_f32 v93, v106, v107
	v_or_b32_e32 v98, 1, v134
	global_store_dwordx4 v[124:125], v[90:93], off offset:512
	v_ashrrev_i32_e32 v99, 31, v98
	v_pk_mul_f32 v[86:87], v[86:87], v[200:201] op_sel_hi:[1,0]
	v_pk_mul_f32 v[92:93], v[104:105], v[200:201] op_sel_hi:[1,0]
	v_pk_mul_f32 v[90:91], v[102:103], v[200:201] op_sel_hi:[1,0]
	v_pk_mul_f32 v[88:89], v[88:89], v[200:201] op_sel_hi:[1,0]
	v_cvt_pk_bf16_f32 v90, v90, v91
	v_cvt_pk_bf16_f32 v91, v92, v93
	v_cvt_pk_bf16_f32 v92, v94, v95
	v_lshl_add_u64 v[94:95], v[122:123], 0, v[98:99]
	v_cvt_pk_bf16_f32 v93, v96, v97
	v_mad_u64_u32 v[96:97], s[0:1], v94, s34, v[178:179]
	v_mad_i32_i24 v97, v95, s34, v97
	global_store_dwordx4 v[96:97], v[90:93], off
	v_lshlrev_b32_e32 v8, 5, v192
	v_and_b32_e32 v8, 0x3e0, v8
	v_pk_mul_f32 v[90:91], v[80:81], v[200:201] op_sel_hi:[1,0]
	v_pk_mul_f32 v[80:81], v[78:79], v[200:201] op_sel_hi:[1,0]
	v_cvt_pk_bf16_f32 v78, v86, v87
	v_lshl_add_u64 v[86:87], v[110:111], 0, v[98:99]
	v_cvt_pk_bf16_f32 v79, v88, v89
	v_mad_u64_u32 v[88:89], s[0:1], v86, s34, v[178:179]
	v_cvt_pk_bf16_f32 v80, v80, v81
	v_cvt_pk_bf16_f32 v81, v90, v91
	v_mad_i32_i24 v89, v87, s34, v89
	global_store_dwordx4 v[88:89], v[78:81], off
	v_pk_mul_f32 v[82:83], v[82:83], v[196:197] op_sel_hi:[1,0]
	v_pk_mul_f32 v[84:85], v[84:85], v[196:197] op_sel_hi:[1,0]
	v_ashrrev_i32_e32 v78, 5, v192
	v_ashrrev_i32_e32 v79, 31, v78
	v_lshl_add_u64 v[80:81], v[176:177], 0, v[8:9]
	v_pk_mul_f32 v[86:87], v[76:77], v[196:197] op_sel_hi:[1,0]
	v_pk_mul_f32 v[76:77], v[74:75], v[196:197] op_sel_hi:[1,0]
	v_cvt_pk_bf16_f32 v74, v82, v83
	v_lshl_add_u64 v[82:83], v[122:123], 0, v[78:79]
	v_cvt_pk_bf16_f32 v75, v84, v85
	v_mad_u64_u32 v[84:85], s[0:1], v82, s34, v[80:81]
	v_cvt_pk_bf16_f32 v76, v76, v77
	v_cvt_pk_bf16_f32 v77, v86, v87
	v_mad_i32_i24 v85, v83, s34, v85
	v_pk_mul_f32 v[54:55], v[54:55], v[196:197] op_sel_hi:[1,0]
	global_store_dwordx4 v[124:125], v[118:121], off
	global_store_dwordx4 v[84:85], v[74:77], off
	v_pk_mul_f32 v[56:57], v[56:57], v[196:197] op_sel_hi:[1,0]
	v_lshlrev_b32_e32 v8, 5, v188
	v_pk_mul_f32 v[74:75], v[36:37], v[196:197] op_sel_hi:[1,0]
	v_pk_mul_f32 v[36:37], v[34:35], v[196:197] op_sel_hi:[1,0]
	v_cvt_pk_bf16_f32 v34, v54, v55
	v_lshl_add_u64 v[54:55], v[110:111], 0, v[78:79]
	v_cvt_pk_bf16_f32 v35, v56, v57
	v_mad_u64_u32 v[56:57], s[0:1], v54, s34, v[80:81]
	v_cvt_pk_bf16_f32 v36, v36, v37
	v_cvt_pk_bf16_f32 v37, v74, v75
	v_mad_i32_i24 v57, v55, s34, v57
	v_ashrrev_i32_e32 v54, 5, v190
	global_store_dwordx4 v[56:57], v[34:37], off
	v_ashrrev_i32_e32 v55, 31, v54
	v_pk_mul_f32 v[56:57], v[64:65], v[138:139] op_sel_hi:[1,0]
	v_pk_mul_f32 v[36:37], v[60:61], v[138:139] op_sel_hi:[1,0]
	v_pk_mul_f32 v[34:35], v[58:59], v[138:139] op_sel_hi:[1,0]
	v_pk_mul_f32 v[58:59], v[62:63], v[138:139] op_sel_hi:[1,0]
	v_cvt_pk_bf16_f32 v34, v34, v35
	v_cvt_pk_bf16_f32 v35, v36, v37
	v_cvt_pk_bf16_f32 v37, v56, v57
	v_lshl_add_u64 v[56:57], v[122:123], 0, v[54:55]
	v_cvt_pk_bf16_f32 v36, v58, v59
	v_mad_u64_u32 v[58:59], s[0:1], v56, s34, v[178:179]
	v_mad_i32_i24 v59, v57, s34, v59
	global_store_dwordx4 v[58:59], v[34:37], off
	v_pk_mul_f32 v[56:57], v[72:73], v[138:139] op_sel_hi:[1,0]
	v_lshl_add_u64 v[54:55], v[110:111], 0, v[54:55]
	v_pk_mul_f32 v[36:37], v[68:69], v[138:139] op_sel_hi:[1,0]
	v_pk_mul_f32 v[34:35], v[66:67], v[138:139] op_sel_hi:[1,0]
	v_pk_mul_f32 v[58:59], v[70:71], v[138:139] op_sel_hi:[1,0]
	v_cvt_pk_bf16_f32 v34, v34, v35
	v_cvt_pk_bf16_f32 v35, v36, v37
	v_cvt_pk_bf16_f32 v37, v56, v57
	v_mad_u64_u32 v[56:57], s[0:1], v54, s34, v[178:179]
	v_cvt_pk_bf16_f32 v36, v58, v59
	v_mad_i32_i24 v57, v55, s34, v57
	v_ashrrev_i32_e32 v54, 5, v188
	global_store_dwordx4 v[56:57], v[34:37], off
	v_ashrrev_i32_e32 v55, 31, v54
; #define PG8_WAIT_V(n) asm volatile("s_waitcnt vmcnt(" #n ")" ::: "memory")
; #define PG8_BAR __builtin_amdgcn_s_barrier()
; template <class Epi>
; DEVI void gemm_phase(LAS unsigned char* lds, const Gemm g, const Epi& E) {
;     ...
;                     for (int bj = 0; bj < 2; ++bj) {
;                         const int c = col0 + bj * HALF; f32x4 v0 = acc[ai][bj][m][0], v1 = acc[ai][bj][m][1];
;                         if constexpr (Epi::RS) { v0 = v0 * rs; v1 = v1 * rs; }
;                         if constexpr (Epi::PRE) part += E.frag_pre8(cur.b, r, c, v0, v1, pre[mm][bj][0], pre[mm][bj][1]);
;                         else if constexpr (Epi::PERM) E.frag8(cur.b, r, c, v0, v1);
;     ...
;         if (!has_next) break;
; #pragma unroll
;         for (int a = 0; a < 2; ++a)
; #pragma unroll
;             for (int b = 0; b < 2; ++b)
; #pragma unroll
;                 for (int m = 0; m < 4; ++m)
; #pragma unroll
;                     for (int n = 0; n < 2; ++n) acc[a][b][m][n] = (f32x4){0.f, 0.f, 0.f, 0.f};
;         cur = nxt; cA = nA; cB = nB; ++ui;
;     }
;     PG8_WAIT_V(0);
;     if (wr == 0) PG8_BAR;
;     PG8_BAR;
	v_and_b32_e32 v8, 0x3e0, v8
	v_pk_mul_f32 v[36:37], v[40:41], v[140:141] op_sel_hi:[1,0]
	v_pk_mul_f32 v[34:35], v[38:39], v[140:141] op_sel_hi:[1,0]
	v_pk_mul_f32 v[38:39], v[44:45], v[140:141] op_sel_hi:[1,0]
	v_lshl_add_u64 v[56:57], v[176:177], 0, v[8:9]
	v_pk_mul_f32 v[40:41], v[42:43], v[140:141] op_sel_hi:[1,0]
	v_cvt_pk_bf16_f32 v34, v34, v35
	v_cvt_pk_bf16_f32 v35, v36, v37
	v_cvt_pk_bf16_f32 v37, v38, v39
	v_lshl_add_u64 v[38:39], v[122:123], 0, v[54:55]
	v_cvt_pk_bf16_f32 v36, v40, v41
	v_mad_u64_u32 v[40:41], s[0:1], v38, s34, v[56:57]
	v_mad_i32_i24 v41, v39, s34, v41
	global_store_dwordx4 v[40:41], v[34:37], off
	v_pk_mul_f32 v[38:39], v[52:53], v[140:141] op_sel_hi:[1,0]
	v_pk_mul_f32 v[40:41], v[50:51], v[140:141] op_sel_hi:[1,0]
	v_pk_mul_f32 v[36:37], v[48:49], v[140:141] op_sel_hi:[1,0]
	v_pk_mul_f32 v[34:35], v[46:47], v[140:141] op_sel_hi:[1,0]
	v_pk_mul_f32 v[20:21], v[20:21], v[132:133] op_sel_hi:[1,0]
	v_cvt_pk_bf16_f32 v34, v34, v35
	v_cvt_pk_bf16_f32 v35, v36, v37
	v_cvt_pk_bf16_f32 v37, v38, v39
	v_lshl_add_u64 v[38:39], v[110:111], 0, v[54:55]
	v_cvt_pk_bf16_f32 v36, v40, v41
	v_mad_u64_u32 v[40:41], s[0:1], v38, s34, v[56:57]
	v_mad_i32_i24 v41, v39, s34, v41
	global_store_dwordx4 v[40:41], v[34:37], off
	v_pk_mul_f32 v[18:19], v[18:19], v[132:133] op_sel_hi:[1,0]
	v_pk_mul_f32 v[22:23], v[22:23], v[132:133] op_sel_hi:[1,0]
	v_ashrrev_i32_e32 v34, 5, v186
	v_ashrrev_i32_e32 v35, 31, v34
	v_pk_mul_f32 v[24:25], v[24:25], v[132:133] op_sel_hi:[1,0]
	v_cvt_pk_bf16_f32 v18, v18, v19
	v_cvt_pk_bf16_f32 v19, v20, v21
	v_cvt_pk_bf16_f32 v20, v22, v23
	v_lshl_add_u64 v[22:23], v[122:123], 0, v[34:35]
	v_cvt_pk_bf16_f32 v21, v24, v25
	v_mad_u64_u32 v[24:25], s[0:1], v22, s34, v[178:179]
	v_mad_i32_i24 v25, v23, s34, v25
	global_store_dwordx4 v[24:25], v[18:21], off
	v_pk_mul_f32 v[22:23], v[32:33], v[132:133] op_sel_hi:[1,0]
	v_pk_mul_f32 v[24:25], v[30:31], v[132:133] op_sel_hi:[1,0]
	v_pk_mul_f32 v[20:21], v[28:29], v[132:133] op_sel_hi:[1,0]
	v_pk_mul_f32 v[18:19], v[26:27], v[132:133] op_sel_hi:[1,0]
	v_lshlrev_b32_e32 v8, 5, v184
	v_cvt_pk_bf16_f32 v18, v18, v19
	v_cvt_pk_bf16_f32 v19, v20, v21
	v_cvt_pk_bf16_f32 v21, v22, v23
	v_lshl_add_u64 v[22:23], v[110:111], 0, v[34:35]
	v_cvt_pk_bf16_f32 v20, v24, v25
	v_mad_u64_u32 v[24:25], s[0:1], v22, s34, v[178:179]
	v_mad_i32_i24 v25, v23, s34, v25
	global_store_dwordx4 v[24:25], v[18:21], off
	v_and_b32_e32 v8, 0x3e0, v8
	v_pk_mul_f32 v[2:3], v[2:3], v[130:131] op_sel_hi:[1,0]
	v_ashrrev_i32_e32 v18, 5, v184
	v_ashrrev_i32_e32 v19, 31, v18
	v_pk_mul_f32 v[0:1], v[0:1], v[130:131] op_sel_hi:[1,0]
	v_pk_mul_f32 v[4:5], v[4:5], v[130:131] op_sel_hi:[1,0]
	v_lshl_add_u64 v[20:21], v[176:177], 0, v[8:9]
	v_pk_mul_f32 v[6:7], v[6:7], v[130:131] op_sel_hi:[1,0]
	v_cvt_pk_bf16_f32 v0, v0, v1
	v_cvt_pk_bf16_f32 v1, v2, v3
	v_cvt_pk_bf16_f32 v2, v4, v5
	v_lshl_add_u64 v[4:5], v[122:123], 0, v[18:19]
	v_cvt_pk_bf16_f32 v3, v6, v7
	v_mad_u64_u32 v[6:7], s[0:1], v4, s34, v[20:21]
	v_mad_i32_i24 v7, v5, s34, v7
	global_store_dwordx4 v[6:7], v[0:3], off
	v_pk_mul_f32 v[4:5], v[16:17], v[130:131] op_sel_hi:[1,0]
	v_pk_mul_f32 v[6:7], v[14:15], v[130:131] op_sel_hi:[1,0]
	v_pk_mul_f32 v[2:3], v[12:13], v[130:131] op_sel_hi:[1,0]
	v_pk_mul_f32 v[0:1], v[10:11], v[130:131] op_sel_hi:[1,0]
	s_and_b64 vcc, exec, s[2:3]
	v_cvt_pk_bf16_f32 v0, v0, v1
	v_cvt_pk_bf16_f32 v1, v2, v3
	v_cvt_pk_bf16_f32 v3, v4, v5
	v_lshl_add_u64 v[4:5], v[110:111], 0, v[18:19]
	v_cvt_pk_bf16_f32 v2, v6, v7
	v_mad_u64_u32 v[6:7], s[0:1], v4, s34, v[20:21]
	v_mad_i32_i24 v7, v5, s34, v7
	s_mov_b32 s84, s8
	s_mov_b32 s4, s6
	global_store_dwordx4 v[6:7], v[0:3], off
	s_cbranch_vccz .LBB0_1000
	s_waitcnt vmcnt(0)
	s_cmpk_gt_u32 s46, 0xff
	s_cbranch_scc1 .LBB0_1011
	s_barrier

; #define PG8_STAGE(bufoff, gbase, voff) do { _Pragma("unroll") for (int _i = 0; _i < 2; ++_i) \
;         __builtin_amdgcn_global_load_lds((const unsigned*)((const char*)(gbase) + (voff)[_i]), (LAS unsigned*)(lds + (bufoff) + ldsw + _i * 8192), 16, 0, 0); } while (0)
; #define PG8_LDA(dst, b, h) do { _Pragma("unroll") for (int m = 0; m < 4; ++m) _Pragma("unroll") for (int k = 0; k < 2; ++k) dst[m][k] = *(const LAS bf16x8*)(lds + PG8_SA(b, h) + aoff + m * 2048 + k * 1024); } while (0)
; #define PG8_LDB(dst, b, h) do { _Pragma("unroll") for (int n = 0; n < 2; ++n) _Pragma("unroll") for (int k = 0; k < 2; ++k) dst[n][k] = *(const LAS bf16x8*)(lds + PG8_SB(b, h) + boff + n * 2048 + k * 1024); } while (0)
; #define PG8_MMA(ai, bj, At, Bt) do { __builtin_amdgcn_s_setprio(1); _Pragma("unroll") for (int m = 0; m < 4; ++m) _Pragma("unroll") for (int n = 0; n < 2; ++n) _Pragma("unroll") for (int k = 0; k < 2; ++k) \
;         acc[ai][bj][m][n] = __builtin_amdgcn_mfma_f32_16x16x32_bf16(Bt[n][k], At[m][k], acc[ai][bj][m][n], 0, 0, 0); __builtin_amdgcn_s_setprio(0); } while (0)
; #define PG8_WAIT_V(n) asm volatile("s_waitcnt vmcnt(" #n ")" ::: "memory")
; #define PG8_WAIT_L(n) asm volatile("s_waitcnt lgkmcnt(" #n ")" ::: "memory")
; template <class Epi>
; DEVI void gemm_phase(LAS unsigned char* lds, const Gemm g, const Epi& E) {
;     ...
;             PG8_LDB(B0, 0, 0); PG8_SCHED; PG8_LDA(At, 0, 0); PG8_STAGE(PG8_SA(1, 1), a1 + hstepA, voffA);
;             PG8_WAIT_L(8); PG8_BAR; PG8_WAIT_L(0); PG8_MMA(0, 0, At, B0); PG8_BAR; PG8_SCHED;
;             PG8_LDB(B1, 0, 1); PG8_STAGE(PG8_SB(0, 0), b2, voffB);
;             PG8_BAR; PG8_WAIT_L(0); PG8_MMA(0, 1, At, B1); PG8_BAR;
;             PG8_LDA(At, 0, 1); PG8_STAGE(PG8_SA(0, 0), a2, voffA);
;             PG8_BAR; PG8_WAIT_L(0); PG8_MMA(1, 0, At, B0); PG8_BAR; PG8_SCHED;
;             PG8_STAGE(PG8_SB(0, 1), b2 + hstepB, voffB);
;             PG8_WAIT_V(6); PG8_BAR; PG8_MMA(1, 1, At, B1); PG8_BAR;
;             PG8_LDB(B0, 1, 0); PG8_SCHED; PG8_LDA(At, 1, 0); PG8_STAGE(PG8_SA(0, 1), a2 + hstepA, voffA);
;             PG8_WAIT_L(8); PG8_BAR; PG8_WAIT_L(0); PG8_MMA(0, 0, At, B0); PG8_BAR; PG8_SCHED;
;             PG8_LDB(B1, 1, 1); PG8_STAGE(PG8_SB(1, 0), b3, voffB);
;             PG8_BAR; PG8_WAIT_L(0); PG8_MMA(0, 1, At, B1); PG8_BAR;
;             PG8_LDA(At, 1, 1); PG8_STAGE(PG8_SA(1, 0), a3, voffA);
.LBB0_1127:
	s_add_u32 s14, s12, 0x100
	s_addc_u32 s15, s13, 0
	s_add_i32 s48, 0, 0x10000
	v_add_u32_e32 v81, s48, v79
	ds_read_b128 v[82:85], v81
	ds_read_b128 v[86:89], v81 offset:1024
	ds_read_b128 v[90:93], v81 offset:2048
	ds_read_b128 v[94:97], v81 offset:3072
	s_cmp_eq_u32 s47, 4
	s_cselect_b32 s37, s9, s15
	s_cselect_b32 s36, s8, s14
	s_cselect_b32 s17, s11, s7
	s_cselect_b32 s16, s10, s5
	v_lshl_add_u64 v[130:131], s[12:13], 0, v[74:75]
	s_add_i32 m0, s18, 0xc000
	ds_read_b128 v[98:101], v80
	ds_read_b128 v[102:105], v80 offset:1024
	ds_read_b128 v[106:109], v80 offset:2048
	ds_read_b128 v[110:113], v80 offset:3072
	ds_read_b128 v[114:117], v80 offset:4096
	ds_read_b128 v[118:121], v80 offset:5120
	ds_read_b128 v[122:125], v80 offset:6144
	ds_read_b128 v[126:129], v80 offset:7168
	global_load_lds_dwordx4 v[130:131], off
	v_lshl_add_u64 v[130:131], s[12:13], 0, v[76:77]
	s_add_i32 m0, s18, 0xe000
	s_nop 0
	global_load_lds_dwordx4 v[130:131], off
	s_waitcnt lgkmcnt(8)
	s_barrier
	s_waitcnt lgkmcnt(0)
	v_mfma_f32_16x16x32_bf16 v[62:65], v[82:85], v[98:101], v[62:65]
	v_mfma_f32_16x16x32_bf16 v[58:61], v[90:93], v[98:101], v[58:61]
	v_mfma_f32_16x16x32_bf16 v[54:57], v[82:85], v[106:109], v[54:57]
	v_mfma_f32_16x16x32_bf16 v[50:53], v[90:93], v[106:109], v[50:53]
	v_mfma_f32_16x16x32_bf16 v[46:49], v[82:85], v[114:117], v[46:49]
	v_mfma_f32_16x16x32_bf16 v[42:45], v[90:93], v[114:117], v[42:45]
	v_mfma_f32_16x16x32_bf16 v[38:41], v[82:85], v[122:125], v[38:41]
	v_mfma_f32_16x16x32_bf16 v[34:37], v[90:93], v[122:125], v[34:37]
	v_mfma_f32_16x16x32_bf16 v[62:65], v[86:89], v[102:105], v[62:65]
	v_mfma_f32_16x16x32_bf16 v[58:61], v[94:97], v[102:105], v[58:61]
	v_mfma_f32_16x16x32_bf16 v[54:57], v[86:89], v[110:113], v[54:57]
	v_mfma_f32_16x16x32_bf16 v[50:53], v[94:97], v[110:113], v[50:53]
	v_mfma_f32_16x16x32_bf16 v[46:49], v[86:89], v[118:121], v[46:49]
	v_mfma_f32_16x16x32_bf16 v[42:45], v[94:97], v[118:121], v[42:45]
	v_mfma_f32_16x16x32_bf16 v[38:41], v[86:89], v[126:129], v[38:41]
	v_mfma_f32_16x16x32_bf16 v[34:37], v[94:97], v[126:129], v[34:37]
	s_barrier
	s_add_i32 s12, s48, s1
	v_lshl_add_u64 v[130:131], s[16:17], 0, v[70:71]
	s_mov_b32 m0, s12
	v_lshl_add_u64 v[132:133], s[16:17], 0, v[66:67]
	global_load_lds_dwordx4 v[130:131], off
	s_add_i32 m0, s12, 0x2000
	s_nop 0
	global_load_lds_dwordx4 v[132:133], off
	s_barrier
	s_waitcnt lgkmcnt(0)
	s_mov_b32 m0, s18
	v_lshl_add_u64 v[134:135], s[36:37], 0, v[72:73]
	s_barrier
	ds_read_b128 v[98:101], v80 offset:16384
	ds_read_b128 v[102:105], v80 offset:17408
	ds_read_b128 v[106:109], v80 offset:18432
	ds_read_b128 v[110:113], v80 offset:19456
	ds_read_b128 v[114:117], v80 offset:20480
	ds_read_b128 v[118:121], v80 offset:21504
	ds_read_b128 v[122:125], v80 offset:22528
	ds_read_b128 v[126:129], v80 offset:23552
	global_load_lds_dwordx4 v[134:135], off
	v_lshl_add_u64 v[136:137], s[36:37], 0, v[68:69]
	s_mov_b32 m0, s19
	s_nop 0
	global_load_lds_dwordx4 v[136:137], off
	s_barrier
	s_waitcnt lgkmcnt(0)
	v_mfma_f32_16x16x32_bf16 v[30:33], v[82:85], v[98:101], v[30:33]
	v_mfma_f32_16x16x32_bf16 v[26:29], v[90:93], v[98:101], v[26:29]
	v_mfma_f32_16x16x32_bf16 v[22:25], v[82:85], v[106:109], v[22:25]
	v_mfma_f32_16x16x32_bf16 v[18:21], v[90:93], v[106:109], v[18:21]
	v_mfma_f32_16x16x32_bf16 v[14:17], v[82:85], v[114:117], v[14:17]
	v_mfma_f32_16x16x32_bf16 v[10:13], v[90:93], v[114:117], v[10:13]
	v_mfma_f32_16x16x32_bf16 v[4:7], v[82:85], v[122:125], v[4:7]
	v_mfma_f32_16x16x32_bf16 v[0:3], v[90:93], v[122:125], v[0:3]
	v_mfma_f32_16x16x32_bf16 v[30:33], v[86:89], v[102:105], v[30:33]
	v_mfma_f32_16x16x32_bf16 v[26:29], v[94:97], v[102:105], v[26:29]
	v_mfma_f32_16x16x32_bf16 v[22:25], v[86:89], v[110:113], v[22:25]
	v_mfma_f32_16x16x32_bf16 v[18:21], v[94:97], v[110:113], v[18:21]
	v_mfma_f32_16x16x32_bf16 v[14:17], v[86:89], v[118:121], v[14:17]
	v_mfma_f32_16x16x32_bf16 v[10:13], v[94:97], v[118:121], v[10:13]
	v_mfma_f32_16x16x32_bf16 v[4:7], v[86:89], v[126:129], v[4:7]
	v_mfma_f32_16x16x32_bf16 v[0:3], v[94:97], v[126:129], v[0:3]
	s_barrier
	s_add_u32 s12, s16, 0x20000
	s_addc_u32 s13, s17, 0
	s_mov_b32 m0, s26
	v_lshl_add_u64 v[82:83], s[12:13], 0, v[70:71]
	global_load_lds_dwordx4 v[82:83], off
	v_lshl_add_u64 v[82:83], s[12:13], 0, v[66:67]
	s_mov_b32 m0, s27
	s_nop 0
	global_load_lds_dwordx4 v[82:83], off
	s_waitcnt vmcnt(6)
	s_barrier
	s_add_i32 s48, 0, 0x18000
	v_add_u32_e32 v81, s48, v79
	s_barrier
	ds_read_b128 v[82:85], v81
	ds_read_b128 v[86:89], v81 offset:1024
	ds_read_b128 v[90:93], v81 offset:2048
	ds_read_b128 v[94:97], v81 offset:3072
	s_add_u32 s12, s36, 0x28000
	s_addc_u32 s13, s37, 0
	s_mov_b32 m0, s38
	v_lshl_add_u64 v[138:139], s[12:13], 0, v[72:73]
	ds_read_b128 v[98:101], v80 offset:32768
	ds_read_b128 v[102:105], v80 offset:33792
	ds_read_b128 v[106:109], v80 offset:34816
	ds_read_b128 v[110:113], v80 offset:35840
	ds_read_b128 v[114:117], v80 offset:36864
	ds_read_b128 v[118:121], v80 offset:37888
	ds_read_b128 v[122:125], v80 offset:38912
	ds_read_b128 v[126:129], v80 offset:39936
	global_load_lds_dwordx4 v[138:139], off
	v_lshl_add_u64 v[138:139], s[12:13], 0, v[68:69]
	s_mov_b32 m0, s39
	s_nop 0
	global_load_lds_dwordx4 v[138:139], off
	s_waitcnt lgkmcnt(8)
	s_barrier
; #define PG8_STAGE(bufoff, gbase, voff) do { _Pragma("unroll") for (int _i = 0; _i < 2; ++_i) \
;         __builtin_amdgcn_global_load_lds((const unsigned*)((const char*)(gbase) + (voff)[_i]), (LAS unsigned*)(lds + (bufoff) + ldsw + _i * 8192), 16, 0, 0); } while (0)
; #define PG8_LDA(dst, b, h) do { _Pragma("unroll") for (int m = 0; m < 4; ++m) _Pragma("unroll") for (int k = 0; k < 2; ++k) dst[m][k] = *(const LAS bf16x8*)(lds + PG8_SA(b, h) + aoff + m * 2048 + k * 1024); } while (0)
; #define PG8_MMA(ai, bj, At, Bt) do { __builtin_amdgcn_s_setprio(1); _Pragma("unroll") for (int m = 0; m < 4; ++m) _Pragma("unroll") for (int n = 0; n < 2; ++n) _Pragma("unroll") for (int k = 0; k < 2; ++k) \
;         acc[ai][bj][m][n] = __builtin_amdgcn_mfma_f32_16x16x32_bf16(Bt[n][k], At[m][k], acc[ai][bj][m][n], 0, 0, 0); __builtin_amdgcn_s_setprio(0); } while (0)
; #define PG8_WAIT_V(n) asm volatile("s_waitcnt vmcnt(" #n ")" ::: "memory")
; #define PG8_WAIT_L(n) asm volatile("s_waitcnt lgkmcnt(" #n ")" ::: "memory")
; #define PG8_BAR __builtin_amdgcn_s_barrier()
; #define PG8_SCHED __builtin_amdgcn_sched_barrier(0)
; template <class Epi>
; DEVI void gemm_phase(LAS unsigned char* lds, const Gemm g, const Epi& E) {
;     ...
;             PG8_LDA(At, 1, 1); PG8_STAGE(PG8_SA(1, 0), a3, voffA);
;             PG8_BAR; PG8_WAIT_L(0); PG8_MMA(1, 0, At, B0); PG8_BAR; PG8_SCHED;
;             PG8_STAGE(PG8_SB(1, 1), b3 + hstepB, voffB);
;             PG8_WAIT_V(6); PG8_BAR; PG8_MMA(1, 1, At, B1); PG8_BAR;
	s_waitcnt lgkmcnt(0)
	v_mfma_f32_16x16x32_bf16 v[62:65], v[82:85], v[98:101], v[62:65]
	v_mfma_f32_16x16x32_bf16 v[58:61], v[90:93], v[98:101], v[58:61]
	v_mfma_f32_16x16x32_bf16 v[54:57], v[82:85], v[106:109], v[54:57]
	v_mfma_f32_16x16x32_bf16 v[50:53], v[90:93], v[106:109], v[50:53]
	v_mfma_f32_16x16x32_bf16 v[46:49], v[82:85], v[114:117], v[46:49]
	v_mfma_f32_16x16x32_bf16 v[42:45], v[90:93], v[114:117], v[42:45]
	v_mfma_f32_16x16x32_bf16 v[38:41], v[82:85], v[122:125], v[38:41]
	v_mfma_f32_16x16x32_bf16 v[34:37], v[90:93], v[122:125], v[34:37]
	v_mfma_f32_16x16x32_bf16 v[62:65], v[86:89], v[102:105], v[62:65]
	v_mfma_f32_16x16x32_bf16 v[58:61], v[94:97], v[102:105], v[58:61]
	v_mfma_f32_16x16x32_bf16 v[54:57], v[86:89], v[110:113], v[54:57]
	v_mfma_f32_16x16x32_bf16 v[50:53], v[94:97], v[110:113], v[50:53]
	v_mfma_f32_16x16x32_bf16 v[46:49], v[86:89], v[118:121], v[46:49]
	v_mfma_f32_16x16x32_bf16 v[42:45], v[94:97], v[118:121], v[42:45]
	v_mfma_f32_16x16x32_bf16 v[38:41], v[86:89], v[126:129], v[38:41]
	v_mfma_f32_16x16x32_bf16 v[34:37], v[94:97], v[126:129], v[34:37]
	s_barrier
	s_add_i32 s12, s48, s1
	v_lshl_add_u64 v[98:99], v[130:131], 0, s[70:71]
	s_mov_b32 m0, s12
	s_nop 0
	global_load_lds_dwordx4 v[98:99], off
	v_lshl_add_u64 v[98:99], v[132:133], 0, s[70:71]
	s_add_i32 m0, s12, 0x2000
	s_nop 0
	global_load_lds_dwordx4 v[98:99], off
	s_barrier
	s_waitcnt lgkmcnt(0)
	s_mov_b32 m0, s41
	v_lshl_add_u64 v[130:131], v[134:135], 0, s[70:71]
	s_barrier
	ds_read_b128 v[98:101], v80 offset:49152
	ds_read_b128 v[102:105], v80 offset:50176
	ds_read_b128 v[106:109], v80 offset:51200
	ds_read_b128 v[110:113], v80 offset:52224
	ds_read_b128 v[114:117], v80 offset:53248
	ds_read_b128 v[118:121], v80 offset:54272
	ds_read_b128 v[122:125], v80 offset:55296
	ds_read_b128 v[126:129], v80 offset:56320
	global_load_lds_dwordx4 v[130:131], off
	v_lshl_add_u64 v[130:131], v[136:137], 0, s[70:71]
	s_mov_b32 m0, s42
	s_nop 0
	global_load_lds_dwordx4 v[130:131], off
	s_barrier
	s_waitcnt lgkmcnt(0)
	v_mfma_f32_16x16x32_bf16 v[30:33], v[82:85], v[98:101], v[30:33]
	v_mfma_f32_16x16x32_bf16 v[26:29], v[90:93], v[98:101], v[26:29]
	v_mfma_f32_16x16x32_bf16 v[22:25], v[82:85], v[106:109], v[22:25]
	v_mfma_f32_16x16x32_bf16 v[18:21], v[90:93], v[106:109], v[18:21]
	v_mfma_f32_16x16x32_bf16 v[14:17], v[82:85], v[114:117], v[14:17]
	v_mfma_f32_16x16x32_bf16 v[10:13], v[90:93], v[114:117], v[10:13]
	v_mfma_f32_16x16x32_bf16 v[4:7], v[82:85], v[122:125], v[4:7]
	v_mfma_f32_16x16x32_bf16 v[0:3], v[90:93], v[122:125], v[0:3]
	v_mfma_f32_16x16x32_bf16 v[30:33], v[86:89], v[102:105], v[30:33]
	v_mfma_f32_16x16x32_bf16 v[26:29], v[94:97], v[102:105], v[26:29]
	v_mfma_f32_16x16x32_bf16 v[22:25], v[86:89], v[110:113], v[22:25]
	v_mfma_f32_16x16x32_bf16 v[18:21], v[94:97], v[110:113], v[18:21]
	v_mfma_f32_16x16x32_bf16 v[14:17], v[86:89], v[118:121], v[14:17]
	v_mfma_f32_16x16x32_bf16 v[10:13], v[94:97], v[118:121], v[10:13]
	v_mfma_f32_16x16x32_bf16 v[4:7], v[86:89], v[126:129], v[4:7]
	v_mfma_f32_16x16x32_bf16 v[0:3], v[94:97], v[126:129], v[0:3]
	s_barrier
	s_add_u32 s12, s16, 0x20080
	s_addc_u32 s13, s17, 0
	s_mov_b32 m0, s43
	v_lshl_add_u64 v[82:83], s[12:13], 0, v[70:71]
	global_load_lds_dwordx4 v[82:83], off
	v_lshl_add_u64 v[82:83], s[12:13], 0, v[66:67]
	s_mov_b32 m0, s44
	s_nop 0
	global_load_lds_dwordx4 v[82:83], off
	s_waitcnt vmcnt(6)
	s_barrier
	s_add_i32 s47, s47, 2
	s_add_u32 s5, s5, 0x100
	s_addc_u32 s7, s7, 0
	s_cmp_gt_u32 s47, 5
	s_mov_b64 s[12:13], s[14:15]
	s_barrier
	s_cbranch_scc0 .LBB0_1127
	s_setprio 0
	s_ashr_i32 s5, s4, 31
	v_lshl_add_u32 v82, s40, 8, v78
	s_lshl_b64 s[4:5], s[4:5], 19
	v_readlane_b32 s7, v253, 50
	s_add_u32 s4, s7, s4
	v_readlane_b32 s7, v253, 51
	v_ashrrev_i32_e32 v83, 31, v82
	s_addc_u32 s5, s7, s5
	v_lshlrev_b64 v[84:85], 9, v[82:83]
	v_lshl_add_u64 v[84:85], s[4:5], 0, v[84:85]
	v_lshl_add_u64 v[84:85], v[84:85], 0, v[8:9]
	global_store_dwordx4 v[84:85], v[62:65], off
	global_store_dwordx4 v[84:85], v[58:61], off offset:64
	s_mov_b32 s40, s46
	s_mov_b64 s[14:15], s[10:11]
	v_or_b32_e32 v58, 16, v82
	v_ashrrev_i32_e32 v59, 31, v58
	v_lshlrev_b64 v[58:59], 9, v[58:59]
	v_lshl_add_u64 v[58:59], s[4:5], 0, v[58:59]
	v_lshl_add_u64 v[58:59], v[58:59], 0, v[8:9]
	global_store_dwordx4 v[58:59], v[54:57], off
	global_store_dwordx4 v[58:59], v[50:53], off offset:64
	s_mov_b64 s[12:13], s[8:9]
	s_nop 0
	v_or_b32_e32 v50, 32, v82
	v_ashrrev_i32_e32 v51, 31, v50
	v_lshlrev_b64 v[50:51], 9, v[50:51]
	v_lshl_add_u64 v[50:51], s[4:5], 0, v[50:51]
	v_lshl_add_u64 v[50:51], v[50:51], 0, v[8:9]
	global_store_dwordx4 v[50:51], v[46:49], off
	global_store_dwordx4 v[50:51], v[42:45], off offset:64
	s_nop 1
	v_or_b32_e32 v42, 48, v82
	v_ashrrev_i32_e32 v43, 31, v42
	v_lshlrev_b64 v[42:43], 9, v[42:43]
	v_lshl_add_u64 v[42:43], s[4:5], 0, v[42:43]
	v_lshl_add_u64 v[42:43], v[42:43], 0, v[8:9]
	s_mov_b64 s[4:5], 0x10000
	global_store_dwordx4 v[42:43], v[38:41], off
	global_store_dwordx4 v[42:43], v[34:37], off offset:64
	s_nop 1
	v_lshl_add_u64 v[34:35], v[84:85], 0, s[4:5]
	s_mov_b32 s4, 0x10000
	v_add_co_u32_e32 v36, vcc, s4, v84
	s_mov_b64 s[4:5], 0x12000
	s_nop 0
	v_addc_co_u32_e32 v37, vcc, 0, v85, vcc
	global_store_dwordx4 v[36:37], v[30:33], off
	global_store_dwordx4 v[34:35], v[26:29], off offset:64
	s_nop 1
	v_lshl_add_u64 v[26:27], v[84:85], 0, s[4:5]
	s_mov_b32 s4, 0x12000
	v_add_co_u32_e32 v28, vcc, s4, v84
	s_mov_b64 s[4:5], 0x14000
	s_nop 0
	v_addc_co_u32_e32 v29, vcc, 0, v85, vcc
	global_store_dwordx4 v[28:29], v[22:25], off
	global_store_dwordx4 v[26:27], v[18:21], off offset:64
	s_nop 1
	v_add_co_u32_e32 v20, vcc, 0x14000, v84
	v_lshl_add_u64 v[18:19], v[84:85], 0, s[4:5]
	s_nop 0
	v_addc_co_u32_e32 v21, vcc, 0, v85, vcc
	global_store_dwordx4 v[20:21], v[14:17], off
	global_store_dwordx4 v[18:19], v[10:13], off offset:64
	s_mov_b64 s[4:5], 0x16000
	s_nop 0
	v_add_co_u32_e32 v12, vcc, 0x16000, v84
	v_lshl_add_u64 v[10:11], v[84:85], 0, s[4:5]
	s_nop 0
	v_addc_co_u32_e32 v13, vcc, 0, v85, vcc
	s_and_b64 vcc, exec, s[2:3]
	s_mov_b32 s4, s6
	global_store_dwordx4 v[12:13], v[4:7], off
	global_store_dwordx4 v[10:11], v[0:3], off offset:64
	s_cbranch_vccz .LBB0_1122
	s_branch .LBB0_1131

; #define PG8_STAGE(bufoff, gbase, voff) do { _Pragma("unroll") for (int _i = 0; _i < 2; ++_i) \
;         __builtin_amdgcn_global_load_lds((const unsigned*)((const char*)(gbase) + (voff)[_i]), (LAS unsigned*)(lds + (bufoff) + ldsw + _i * 8192), 16, 0, 0); } while (0)
; #define PG8_LDA(dst, b, h) do { _Pragma("unroll") for (int m = 0; m < 4; ++m) _Pragma("unroll") for (int k = 0; k < 2; ++k) dst[m][k] = *(const LAS bf16x8*)(lds + PG8_SA(b, h) + aoff + m * 2048 + k * 1024); } while (0)
; #define PG8_LDB(dst, b, h) do { _Pragma("unroll") for (int n = 0; n < 2; ++n) _Pragma("unroll") for (int k = 0; k < 2; ++k) dst[n][k] = *(const LAS bf16x8*)(lds + PG8_SB(b, h) + boff + n * 2048 + k * 1024); } while (0)
; #define PG8_MMA(ai, bj, At, Bt) do { __builtin_amdgcn_s_setprio(1); _Pragma("unroll") for (int m = 0; m < 4; ++m) _Pragma("unroll") for (int n = 0; n < 2; ++n) _Pragma("unroll") for (int k = 0; k < 2; ++k) \
;         acc[ai][bj][m][n] = __builtin_amdgcn_mfma_f32_16x16x32_bf16(Bt[n][k], At[m][k], acc[ai][bj][m][n], 0, 0, 0); __builtin_amdgcn_s_setprio(0); } while (0)
; #define PG8_WAIT_L(n) asm volatile("s_waitcnt lgkmcnt(" #n ")" ::: "memory")
; #define PG8_BAR __builtin_amdgcn_s_barrier()
; #define PG8_SCHED __builtin_amdgcn_sched_barrier(0)
; template <class Epi>
; DEVI void gemm_phase(LAS unsigned char* lds, const Gemm g, const Epi& E) {
;     ...
;             PG8_LDB(B0, 0, 0); PG8_SCHED; PG8_LDA(At, 0, 0); PG8_STAGE(PG8_SA(1, 1), a1 + hstepA, voffA);
;             PG8_WAIT_L(8); PG8_BAR; PG8_WAIT_L(0); PG8_MMA(0, 0, At, B0); PG8_BAR; PG8_SCHED;
;             PG8_LDB(B1, 0, 1); PG8_STAGE(PG8_SB(0, 0), b2, voffB);
;             PG8_BAR; PG8_WAIT_L(0); PG8_MMA(0, 1, At, B1); PG8_BAR;
;             PG8_LDA(At, 0, 1); PG8_STAGE(PG8_SA(0, 0), a2, voffA);
;             PG8_BAR; PG8_WAIT_L(0); PG8_MMA(1, 0, At, B0); PG8_BAR; PG8_SCHED;
;             PG8_STAGE(PG8_SB(0, 1), b2 + hstepB, voffB);
.LBB0_1278:
	s_add_u32 s12, s10, 0x100
	s_addc_u32 s13, s11, 0
	s_add_i32 s38, 0, 0x10000
	v_add_u32_e32 v146, s38, v149
	ds_read_b128 v[142:145], v146
	ds_read_b128 v[176:179], v146 offset:1024
	ds_read_b128 v[180:183], v146 offset:2048
	ds_read_b128 v[184:187], v146 offset:3072
	s_cmp_eq_u32 s27, 6
	s_cselect_b32 s17, s5, s13
	s_cselect_b32 s16, s4, s12
	s_cselect_b32 s15, s7, s26
	s_cselect_b32 s14, s6, s19
	v_lshl_add_u64 v[146:147], s[10:11], 0, v[138:139]
	s_add_i32 m0, s46, 0xc000
	ds_read_b128 v[188:191], v151
	ds_read_b128 v[192:195], v151 offset:1024
	ds_read_b128 v[196:199], v151 offset:2048
	ds_read_b128 v[200:203], v151 offset:3072
	ds_read_b128 v[204:207], v151 offset:4096
	ds_read_b128 v[214:217], v151 offset:5120
	ds_read_b128 v[218:221], v151 offset:6144
	ds_read_b128 v[222:225], v151 offset:7168
	global_load_lds_dwordx4 v[146:147], off
	v_lshl_add_u64 v[146:147], s[10:11], 0, v[140:141]
	s_add_i32 m0, s46, 0xe000
	s_nop 0
	global_load_lds_dwordx4 v[146:147], off
	s_waitcnt lgkmcnt(8)
	s_barrier
	s_waitcnt lgkmcnt(0)
	v_mfma_f32_16x16x32_bf16 v[126:129], v[142:145], v[188:191], v[126:129]
	v_mfma_f32_16x16x32_bf16 v[122:125], v[180:183], v[188:191], v[122:125]
	v_mfma_f32_16x16x32_bf16 v[110:113], v[142:145], v[196:199], v[110:113]
	v_mfma_f32_16x16x32_bf16 v[106:109], v[180:183], v[196:199], v[106:109]
	v_mfma_f32_16x16x32_bf16 v[94:97], v[142:145], v[204:207], v[94:97]
	v_mfma_f32_16x16x32_bf16 v[90:93], v[180:183], v[204:207], v[90:93]
	v_mfma_f32_16x16x32_bf16 v[78:81], v[142:145], v[218:221], v[78:81]
	v_mfma_f32_16x16x32_bf16 v[74:77], v[180:183], v[218:221], v[74:77]
	v_mfma_f32_16x16x32_bf16 v[126:129], v[176:179], v[192:195], v[126:129]
	v_mfma_f32_16x16x32_bf16 v[122:125], v[184:187], v[192:195], v[122:125]
	v_mfma_f32_16x16x32_bf16 v[110:113], v[176:179], v[200:203], v[110:113]
	v_mfma_f32_16x16x32_bf16 v[106:109], v[184:187], v[200:203], v[106:109]
	v_mfma_f32_16x16x32_bf16 v[94:97], v[176:179], v[214:217], v[94:97]
	v_mfma_f32_16x16x32_bf16 v[90:93], v[184:187], v[214:217], v[90:93]
	v_mfma_f32_16x16x32_bf16 v[78:81], v[176:179], v[222:225], v[78:81]
	v_mfma_f32_16x16x32_bf16 v[74:77], v[184:187], v[222:225], v[74:77]
	s_barrier
	s_add_i32 s39, 0, 0x14000
	v_add_u32_e32 v146, s39, v149
	s_add_i32 s10, s38, s37
	ds_read_b128 v[226:229], v146
	ds_read_b128 v[230:233], v146 offset:1024
	ds_read_b128 v[234:237], v146 offset:2048
	ds_read_b128 v[238:241], v146 offset:3072
	v_lshl_add_u64 v[146:147], s[14:15], 0, v[8:9]
	s_mov_b32 m0, s10
	v_lshl_add_u64 v[152:153], s[14:15], 0, v[130:131]
	global_load_lds_dwordx4 v[146:147], off
	s_add_i32 m0, s10, 0x2000
	s_nop 0
	global_load_lds_dwordx4 v[152:153], off
	s_barrier
	s_waitcnt lgkmcnt(0)
	v_mfma_f32_16x16x32_bf16 v[118:121], v[226:229], v[188:191], v[118:121]
	v_mfma_f32_16x16x32_bf16 v[114:117], v[234:237], v[188:191], v[114:117]
	v_mfma_f32_16x16x32_bf16 v[102:105], v[226:229], v[196:199], v[102:105]
	v_mfma_f32_16x16x32_bf16 v[98:101], v[234:237], v[196:199], v[98:101]
	v_mfma_f32_16x16x32_bf16 v[86:89], v[226:229], v[204:207], v[86:89]
	v_mfma_f32_16x16x32_bf16 v[82:85], v[234:237], v[204:207], v[82:85]
	v_mfma_f32_16x16x32_bf16 v[70:73], v[226:229], v[218:221], v[70:73]
	v_mfma_f32_16x16x32_bf16 v[66:69], v[234:237], v[218:221], v[66:69]
	v_mfma_f32_16x16x32_bf16 v[118:121], v[230:233], v[192:195], v[118:121]
	v_mfma_f32_16x16x32_bf16 v[114:117], v[238:241], v[192:195], v[114:117]
	v_mfma_f32_16x16x32_bf16 v[102:105], v[230:233], v[200:203], v[102:105]
	v_mfma_f32_16x16x32_bf16 v[98:101], v[238:241], v[200:203], v[98:101]
	v_mfma_f32_16x16x32_bf16 v[86:89], v[230:233], v[214:217], v[86:89]
	v_mfma_f32_16x16x32_bf16 v[82:85], v[238:241], v[214:217], v[82:85]
	v_mfma_f32_16x16x32_bf16 v[70:73], v[230:233], v[222:225], v[70:73]
	v_mfma_f32_16x16x32_bf16 v[66:69], v[238:241], v[222:225], v[66:69]
	s_mov_b32 m0, s46
	v_lshl_add_u64 v[162:163], s[16:17], 0, v[134:135]
	s_barrier
	ds_read_b128 v[188:191], v151 offset:16384
	ds_read_b128 v[192:195], v151 offset:17408
	ds_read_b128 v[196:199], v151 offset:18432
	ds_read_b128 v[200:203], v151 offset:19456
	ds_read_b128 v[204:207], v151 offset:20480
	ds_read_b128 v[214:217], v151 offset:21504
	ds_read_b128 v[218:221], v151 offset:22528
	ds_read_b128 v[222:225], v151 offset:23552
	global_load_lds_dwordx4 v[162:163], off
	v_lshl_add_u64 v[164:165], s[16:17], 0, v[132:133]
	s_mov_b32 m0, s47
	s_nop 0
	global_load_lds_dwordx4 v[164:165], off
	s_barrier
	s_waitcnt lgkmcnt(0)
	v_mfma_f32_16x16x32_bf16 v[62:65], v[142:145], v[188:191], v[62:65]
	v_mfma_f32_16x16x32_bf16 v[58:61], v[180:183], v[188:191], v[58:61]
	v_mfma_f32_16x16x32_bf16 v[46:49], v[142:145], v[196:199], v[46:49]
	v_mfma_f32_16x16x32_bf16 v[42:45], v[180:183], v[196:199], v[42:45]
	v_mfma_f32_16x16x32_bf16 v[30:33], v[142:145], v[204:207], v[30:33]
	v_mfma_f32_16x16x32_bf16 v[26:29], v[180:183], v[204:207], v[26:29]
	v_mfma_f32_16x16x32_bf16 v[14:17], v[142:145], v[218:221], v[14:17]
	v_mfma_f32_16x16x32_bf16 v[10:13], v[180:183], v[218:221], v[10:13]
	v_mfma_f32_16x16x32_bf16 v[62:65], v[176:179], v[192:195], v[62:65]
	v_mfma_f32_16x16x32_bf16 v[58:61], v[184:187], v[192:195], v[58:61]
	v_mfma_f32_16x16x32_bf16 v[46:49], v[176:179], v[200:203], v[46:49]
	v_mfma_f32_16x16x32_bf16 v[42:45], v[184:187], v[200:203], v[42:45]
	v_mfma_f32_16x16x32_bf16 v[30:33], v[176:179], v[214:217], v[30:33]
	v_mfma_f32_16x16x32_bf16 v[26:29], v[184:187], v[214:217], v[26:29]
	v_mfma_f32_16x16x32_bf16 v[14:17], v[176:179], v[222:225], v[14:17]
	v_mfma_f32_16x16x32_bf16 v[10:13], v[184:187], v[222:225], v[10:13]
	s_barrier
; #define PG8_STAGE(bufoff, gbase, voff) do { _Pragma("unroll") for (int _i = 0; _i < 2; ++_i) \
;         __builtin_amdgcn_global_load_lds((const unsigned*)((const char*)(gbase) + (voff)[_i]), (LAS unsigned*)(lds + (bufoff) + ldsw + _i * 8192), 16, 0, 0); } while (0)
; #define PG8_LDA(dst, b, h) do { _Pragma("unroll") for (int m = 0; m < 4; ++m) _Pragma("unroll") for (int k = 0; k < 2; ++k) dst[m][k] = *(const LAS bf16x8*)(lds + PG8_SA(b, h) + aoff + m * 2048 + k * 1024); } while (0)
; #define PG8_LDB(dst, b, h) do { _Pragma("unroll") for (int n = 0; n < 2; ++n) _Pragma("unroll") for (int k = 0; k < 2; ++k) dst[n][k] = *(const LAS bf16x8*)(lds + PG8_SB(b, h) + boff + n * 2048 + k * 1024); } while (0)
; #define PG8_MMA(ai, bj, At, Bt) do { __builtin_amdgcn_s_setprio(1); _Pragma("unroll") for (int m = 0; m < 4; ++m) _Pragma("unroll") for (int n = 0; n < 2; ++n) _Pragma("unroll") for (int k = 0; k < 2; ++k) \
;         acc[ai][bj][m][n] = __builtin_amdgcn_mfma_f32_16x16x32_bf16(Bt[n][k], At[m][k], acc[ai][bj][m][n], 0, 0, 0); __builtin_amdgcn_s_setprio(0); } while (0)
; #define PG8_WAIT_V(n) asm volatile("s_waitcnt vmcnt(" #n ")" ::: "memory")
; #define PG8_WAIT_L(n) asm volatile("s_waitcnt lgkmcnt(" #n ")" ::: "memory")
; #define PG8_BAR __builtin_amdgcn_s_barrier()
; #define PG8_SCHED __builtin_amdgcn_sched_barrier(0)
; template <class Epi>
; DEVI void gemm_phase(LAS unsigned char* lds, const Gemm g, const Epi& E) {
;     ...
;             PG8_STAGE(PG8_SB(0, 1), b2 + hstepB, voffB);
;             PG8_WAIT_V(6); PG8_BAR; PG8_MMA(1, 1, At, B1); PG8_BAR;
;             PG8_LDB(B0, 1, 0); PG8_SCHED; PG8_LDA(At, 1, 0); PG8_STAGE(PG8_SA(0, 1), a2 + hstepA, voffA);
;             PG8_WAIT_L(8); PG8_BAR; PG8_WAIT_L(0); PG8_MMA(0, 0, At, B0); PG8_BAR; PG8_SCHED;
;             PG8_LDB(B1, 1, 1); PG8_STAGE(PG8_SB(1, 0), b3, voffB);
;             PG8_BAR; PG8_WAIT_L(0); PG8_MMA(0, 1, At, B1); PG8_BAR;
;             PG8_LDA(At, 1, 1); PG8_STAGE(PG8_SA(1, 0), a3, voffA);
	s_add_u32 s10, s14, 0x28000
	s_addc_u32 s11, s15, 0
	s_add_i32 s38, s39, s37
	v_lshl_add_u64 v[142:143], s[10:11], 0, v[8:9]
	s_mov_b32 m0, s38
	s_nop 0
	global_load_lds_dwordx4 v[142:143], off
	v_lshl_add_u64 v[142:143], s[10:11], 0, v[130:131]
	s_add_i32 m0, s38, 0x2000
	s_nop 0
	global_load_lds_dwordx4 v[142:143], off
	s_waitcnt vmcnt(6)
	s_barrier
	v_mfma_f32_16x16x32_bf16 v[54:57], v[226:229], v[188:191], v[54:57]
	v_mfma_f32_16x16x32_bf16 v[50:53], v[234:237], v[188:191], v[50:53]
	v_mfma_f32_16x16x32_bf16 v[38:41], v[226:229], v[196:199], v[38:41]
	v_mfma_f32_16x16x32_bf16 v[34:37], v[234:237], v[196:199], v[34:37]
	v_mfma_f32_16x16x32_bf16 v[22:25], v[226:229], v[204:207], v[22:25]
	v_mfma_f32_16x16x32_bf16 v[18:21], v[234:237], v[204:207], v[18:21]
	v_mfma_f32_16x16x32_bf16 v[4:7], v[226:229], v[218:221], v[4:7]
	v_mfma_f32_16x16x32_bf16 v[0:3], v[234:237], v[218:221], v[0:3]
	v_mfma_f32_16x16x32_bf16 v[54:57], v[230:233], v[192:195], v[54:57]
	v_mfma_f32_16x16x32_bf16 v[50:53], v[238:241], v[192:195], v[50:53]
	v_mfma_f32_16x16x32_bf16 v[38:41], v[230:233], v[200:203], v[38:41]
	v_mfma_f32_16x16x32_bf16 v[34:37], v[238:241], v[200:203], v[34:37]
	v_mfma_f32_16x16x32_bf16 v[22:25], v[230:233], v[214:217], v[22:25]
	v_mfma_f32_16x16x32_bf16 v[18:21], v[238:241], v[214:217], v[18:21]
	v_mfma_f32_16x16x32_bf16 v[4:7], v[230:233], v[222:225], v[4:7]
	v_mfma_f32_16x16x32_bf16 v[0:3], v[238:241], v[222:225], v[0:3]
	s_add_i32 s38, 0, 0x18000
	v_add_u32_e32 v184, s38, v149
	s_barrier
	ds_read_b128 v[142:145], v184
	ds_read_b128 v[176:179], v184 offset:1024
	ds_read_b128 v[180:183], v184 offset:2048
	ds_read_b128 v[184:187], v184 offset:3072
	s_add_u32 s10, s16, 0x28000
	s_addc_u32 s11, s17, 0
	s_mov_b32 m0, s66
	v_lshl_add_u64 v[208:209], s[10:11], 0, v[134:135]
	ds_read_b128 v[188:191], v151 offset:32768
	ds_read_b128 v[192:195], v151 offset:33792
	ds_read_b128 v[196:199], v151 offset:34816
	ds_read_b128 v[200:203], v151 offset:35840
	ds_read_b128 v[204:207], v151 offset:36864
	ds_read_b128 v[214:217], v151 offset:37888
	ds_read_b128 v[218:221], v151 offset:38912
	ds_read_b128 v[222:225], v151 offset:39936
	global_load_lds_dwordx4 v[208:209], off
	v_lshl_add_u64 v[208:209], s[10:11], 0, v[132:133]
	s_mov_b32 m0, s68
	s_nop 0
	global_load_lds_dwordx4 v[208:209], off
	s_waitcnt lgkmcnt(8)
	s_barrier
	s_waitcnt lgkmcnt(0)
	v_mfma_f32_16x16x32_bf16 v[126:129], v[142:145], v[188:191], v[126:129]
	v_mfma_f32_16x16x32_bf16 v[122:125], v[180:183], v[188:191], v[122:125]
	v_mfma_f32_16x16x32_bf16 v[110:113], v[142:145], v[196:199], v[110:113]
	v_mfma_f32_16x16x32_bf16 v[106:109], v[180:183], v[196:199], v[106:109]
	v_mfma_f32_16x16x32_bf16 v[94:97], v[142:145], v[204:207], v[94:97]
	v_mfma_f32_16x16x32_bf16 v[90:93], v[180:183], v[204:207], v[90:93]
	v_mfma_f32_16x16x32_bf16 v[78:81], v[142:145], v[218:221], v[78:81]
	v_mfma_f32_16x16x32_bf16 v[74:77], v[180:183], v[218:221], v[74:77]
	v_mfma_f32_16x16x32_bf16 v[126:129], v[176:179], v[192:195], v[126:129]
	v_mfma_f32_16x16x32_bf16 v[122:125], v[184:187], v[192:195], v[122:125]
	v_mfma_f32_16x16x32_bf16 v[110:113], v[176:179], v[200:203], v[110:113]
	v_mfma_f32_16x16x32_bf16 v[106:109], v[184:187], v[200:203], v[106:109]
	v_mfma_f32_16x16x32_bf16 v[94:97], v[176:179], v[214:217], v[94:97]
	v_mfma_f32_16x16x32_bf16 v[90:93], v[184:187], v[214:217], v[90:93]
	v_mfma_f32_16x16x32_bf16 v[78:81], v[176:179], v[222:225], v[78:81]
	v_mfma_f32_16x16x32_bf16 v[74:77], v[184:187], v[222:225], v[74:77]
	s_barrier
	s_add_i32 s16, 0, 0x1c000
	s_add_i32 s10, s38, s37
	v_add_u32_e32 v208, s16, v149
	v_lshl_add_u64 v[146:147], v[146:147], 0, s[70:71]
	s_mov_b32 m0, s10
	ds_read_b128 v[226:229], v208
	ds_read_b128 v[230:233], v208 offset:1024
	ds_read_b128 v[234:237], v208 offset:2048
	ds_read_b128 v[238:241], v208 offset:3072
	global_load_lds_dwordx4 v[146:147], off
	v_lshl_add_u64 v[146:147], v[152:153], 0, s[70:71]
	s_add_i32 m0, s10, 0x2000
	s_nop 0
	global_load_lds_dwordx4 v[146:147], off
	s_barrier
	s_waitcnt lgkmcnt(0)
	v_mfma_f32_16x16x32_bf16 v[118:121], v[226:229], v[188:191], v[118:121]
	v_mfma_f32_16x16x32_bf16 v[114:117], v[234:237], v[188:191], v[114:117]
	v_mfma_f32_16x16x32_bf16 v[102:105], v[226:229], v[196:199], v[102:105]
	v_mfma_f32_16x16x32_bf16 v[98:101], v[234:237], v[196:199], v[98:101]
	v_mfma_f32_16x16x32_bf16 v[86:89], v[226:229], v[204:207], v[86:89]
	v_mfma_f32_16x16x32_bf16 v[82:85], v[234:237], v[204:207], v[82:85]
	v_mfma_f32_16x16x32_bf16 v[70:73], v[226:229], v[218:221], v[70:73]
	v_mfma_f32_16x16x32_bf16 v[66:69], v[234:237], v[218:221], v[66:69]
	v_mfma_f32_16x16x32_bf16 v[118:121], v[230:233], v[192:195], v[118:121]
	v_mfma_f32_16x16x32_bf16 v[114:117], v[238:241], v[192:195], v[114:117]
	v_mfma_f32_16x16x32_bf16 v[102:105], v[230:233], v[200:203], v[102:105]
	v_mfma_f32_16x16x32_bf16 v[98:101], v[238:241], v[200:203], v[98:101]
	v_mfma_f32_16x16x32_bf16 v[86:89], v[230:233], v[214:217], v[86:89]
	v_mfma_f32_16x16x32_bf16 v[82:85], v[238:241], v[214:217], v[82:85]
	v_mfma_f32_16x16x32_bf16 v[70:73], v[230:233], v[222:225], v[70:73]
	v_mfma_f32_16x16x32_bf16 v[66:69], v[238:241], v[222:225], v[66:69]
	s_mov_b32 m0, s69
	v_lshl_add_u64 v[146:147], v[162:163], 0, s[70:71]
	s_barrier
	ds_read_b128 v[188:191], v151 offset:49152
	ds_read_b128 v[192:195], v151 offset:50176
	ds_read_b128 v[196:199], v151 offset:51200
	ds_read_b128 v[200:203], v151 offset:52224
	ds_read_b128 v[204:207], v151 offset:53248
	ds_read_b128 v[214:217], v151 offset:54272
	ds_read_b128 v[218:221], v151 offset:55296
	ds_read_b128 v[222:225], v151 offset:56320
	global_load_lds_dwordx4 v[146:147], off
	v_lshl_add_u64 v[146:147], v[164:165], 0, s[70:71]
	s_mov_b32 m0, s80
	s_nop 0
	global_load_lds_dwordx4 v[146:147], off
	s_barrier
; #define PG8_STAGE(bufoff, gbase, voff) do { _Pragma("unroll") for (int _i = 0; _i < 2; ++_i) \
;         __builtin_amdgcn_global_load_lds((const unsigned*)((const char*)(gbase) + (voff)[_i]), (LAS unsigned*)(lds + (bufoff) + ldsw + _i * 8192), 16, 0, 0); } while (0)
; #define PG8_MMA(ai, bj, At, Bt) do { __builtin_amdgcn_s_setprio(1); _Pragma("unroll") for (int m = 0; m < 4; ++m) _Pragma("unroll") for (int n = 0; n < 2; ++n) _Pragma("unroll") for (int k = 0; k < 2; ++k) \
;         acc[ai][bj][m][n] = __builtin_amdgcn_mfma_f32_16x16x32_bf16(Bt[n][k], At[m][k], acc[ai][bj][m][n], 0, 0, 0); __builtin_amdgcn_s_setprio(0); } while (0)
; #define PG8_WAIT_V(n) asm volatile("s_waitcnt vmcnt(" #n ")" ::: "memory")
; #define PG8_WAIT_L(n) asm volatile("s_waitcnt lgkmcnt(" #n ")" ::: "memory")
; #define PG8_BAR __builtin_amdgcn_s_barrier()
; #define PG8_SCHED __builtin_amdgcn_sched_barrier(0)
; template <class Epi>
; DEVI void gemm_phase(LAS unsigned char* lds, const Gemm g, const Epi& E) {
;     ...
;             PG8_BAR; PG8_WAIT_L(0); PG8_MMA(1, 0, At, B0); PG8_BAR; PG8_SCHED;
;             PG8_STAGE(PG8_SB(1, 1), b3 + hstepB, voffB);
;             PG8_WAIT_V(6); PG8_BAR; PG8_MMA(1, 1, At, B1); PG8_BAR;
	s_waitcnt lgkmcnt(0)
	v_mfma_f32_16x16x32_bf16 v[62:65], v[142:145], v[188:191], v[62:65]
	v_mfma_f32_16x16x32_bf16 v[58:61], v[180:183], v[188:191], v[58:61]
	v_mfma_f32_16x16x32_bf16 v[46:49], v[142:145], v[196:199], v[46:49]
	v_mfma_f32_16x16x32_bf16 v[42:45], v[180:183], v[196:199], v[42:45]
	v_mfma_f32_16x16x32_bf16 v[30:33], v[142:145], v[204:207], v[30:33]
	v_mfma_f32_16x16x32_bf16 v[26:29], v[180:183], v[204:207], v[26:29]
	v_mfma_f32_16x16x32_bf16 v[14:17], v[142:145], v[218:221], v[14:17]
	v_mfma_f32_16x16x32_bf16 v[10:13], v[180:183], v[218:221], v[10:13]
	v_mfma_f32_16x16x32_bf16 v[62:65], v[176:179], v[192:195], v[62:65]
	v_mfma_f32_16x16x32_bf16 v[58:61], v[184:187], v[192:195], v[58:61]
	v_mfma_f32_16x16x32_bf16 v[46:49], v[176:179], v[200:203], v[46:49]
	v_mfma_f32_16x16x32_bf16 v[42:45], v[184:187], v[200:203], v[42:45]
	v_mfma_f32_16x16x32_bf16 v[30:33], v[176:179], v[214:217], v[30:33]
	v_mfma_f32_16x16x32_bf16 v[26:29], v[184:187], v[214:217], v[26:29]
	v_mfma_f32_16x16x32_bf16 v[14:17], v[176:179], v[222:225], v[14:17]
	v_mfma_f32_16x16x32_bf16 v[10:13], v[184:187], v[222:225], v[10:13]
	s_barrier
	s_add_u32 s10, s14, 0x28080
	s_addc_u32 s11, s15, 0
	s_add_i32 s14, s16, s37
	v_lshl_add_u64 v[142:143], s[10:11], 0, v[8:9]
	s_mov_b32 m0, s14
	s_nop 0
	global_load_lds_dwordx4 v[142:143], off
	v_lshl_add_u64 v[142:143], s[10:11], 0, v[130:131]
	s_add_i32 m0, s14, 0x2000
	s_nop 0
	global_load_lds_dwordx4 v[142:143], off
	s_waitcnt vmcnt(6)
	s_barrier
	v_mfma_f32_16x16x32_bf16 v[54:57], v[226:229], v[188:191], v[54:57]
	v_mfma_f32_16x16x32_bf16 v[50:53], v[234:237], v[188:191], v[50:53]
	v_mfma_f32_16x16x32_bf16 v[38:41], v[226:229], v[196:199], v[38:41]
	v_mfma_f32_16x16x32_bf16 v[34:37], v[234:237], v[196:199], v[34:37]
	v_mfma_f32_16x16x32_bf16 v[22:25], v[226:229], v[204:207], v[22:25]
	v_mfma_f32_16x16x32_bf16 v[18:21], v[234:237], v[204:207], v[18:21]
	v_mfma_f32_16x16x32_bf16 v[4:7], v[226:229], v[218:221], v[4:7]
	v_mfma_f32_16x16x32_bf16 v[0:3], v[234:237], v[218:221], v[0:3]
	v_mfma_f32_16x16x32_bf16 v[54:57], v[230:233], v[192:195], v[54:57]
	v_mfma_f32_16x16x32_bf16 v[50:53], v[238:241], v[192:195], v[50:53]
	v_mfma_f32_16x16x32_bf16 v[38:41], v[230:233], v[200:203], v[38:41]
	v_mfma_f32_16x16x32_bf16 v[34:37], v[238:241], v[200:203], v[34:37]
	v_mfma_f32_16x16x32_bf16 v[22:25], v[230:233], v[214:217], v[22:25]
	v_mfma_f32_16x16x32_bf16 v[18:21], v[238:241], v[214:217], v[18:21]
	v_mfma_f32_16x16x32_bf16 v[4:7], v[230:233], v[222:225], v[4:7]
	v_mfma_f32_16x16x32_bf16 v[0:3], v[238:241], v[222:225], v[0:3]
	s_add_i32 s27, s27, 2
	s_add_u32 s19, s19, 0x100
	s_addc_u32 s26, s26, 0
	s_cmp_gt_u32 s27, 7
	s_mov_b64 s[10:11], s[12:13]
	s_barrier
	s_cbranch_scc0 .LBB0_1278
	s_setprio 0
	v_lshl_add_u32 v144, s18, 8, v148
	v_ashrrev_i32_e32 v145, 31, v144
	v_lshlrev_b64 v[142:143], 16, v[144:145]
	v_mul_f32_e32 v145, 0x3d372713, v126
	v_mul_f32_e32 v145, v126, v145
	v_fma_f32 v145, v126, v145, v126
	v_mul_f32_e32 v145, 0x3f4c422a, v145
	v_add_f32_e32 v145, v145, v145
	v_mul_f32_e32 v145, 0xbfb8aa3b, v145
	v_exp_f32_e32 v145, v145
	v_lshl_or_b32 v164, s1, 8, v150
	s_lshl_b32 s0, s0, 4
	s_ashr_i32 s1, s0, 31
	v_add_f32_e32 v145, 1.0, v145
	v_rcp_f32_e32 v152, v145
	v_mul_f32_e32 v145, 0x3d372713, v122
	v_mul_f32_e32 v145, v122, v145
	v_fma_f32 v145, v122, v145, v122
	v_mul_f32_e32 v145, 0x3f4c422a, v145
	v_add_f32_e32 v145, v145, v145
	v_mul_f32_e32 v145, 0xbfb8aa3b, v145
	v_exp_f32_e32 v145, v145
	v_lshl_add_u64 v[146:147], s[0:1], 1, v[136:137]
	v_lshl_add_u64 v[142:143], v[146:147], 0, v[142:143]
	s_mov_b64 s[0:1], 0x800000
	v_add_f32_e32 v145, 1.0, v145
	v_rcp_f32_e32 v162, v145
	v_mul_f32_e32 v145, 0x3d372713, v127
	v_mul_f32_e32 v145, v127, v145
	v_fma_f32 v145, v127, v145, v127
	v_mul_f32_e32 v145, 0x3f4c422a, v145
	v_add_f32_e32 v145, v145, v145
	v_mul_f32_e32 v145, 0xbfb8aa3b, v145
	v_exp_f32_e32 v145, v145
	s_and_b64 vcc, exec, s[2:3]
	s_mov_b32 s18, s82
	s_mov_b64 s[12:13], s[6:7]
	v_add_f32_e32 v145, 1.0, v145
	v_rcp_f32_e32 v153, v145
	v_mul_f32_e32 v145, 0x3d372713, v123
	v_mul_f32_e32 v145, v123, v145
	v_fma_f32 v145, v123, v145, v123
	v_mul_f32_e32 v145, 0x3f4c422a, v145
	v_add_f32_e32 v145, v145, v145
	v_mul_f32_e32 v145, 0xbfb8aa3b, v145
	v_exp_f32_e32 v145, v145
	v_pk_mul_f32 v[126:127], v[126:127], v[152:153]
	s_mov_b64 s[10:11], s[4:5]
	v_add_f32_e32 v145, 1.0, v145
	v_rcp_f32_e32 v163, v145
	v_mul_f32_e32 v145, 0x3d372713, v128
	v_mul_f32_e32 v145, v128, v145
	v_fma_f32 v145, v128, v145, v128
	v_mul_f32_e32 v145, 0x3f4c422a, v145
	v_add_f32_e32 v145, v145, v145
	v_mul_f32_e32 v145, 0xbfb8aa3b, v145
	v_exp_f32_e32 v145, v145
	v_pk_mul_f32 v[122:123], v[122:123], v[162:163]
	v_add_f32_e32 v145, 1.0, v145
	v_rcp_f32_e32 v152, v145
	v_mul_f32_e32 v145, 0x3d372713, v124
	v_mul_f32_e32 v145, v124, v145
	v_fma_f32 v145, v124, v145, v124
	v_mul_f32_e32 v145, 0x3f4c422a, v145
	v_add_f32_e32 v145, v145, v145
	v_mul_f32_e32 v145, 0xbfb8aa3b, v145
	v_exp_f32_e32 v145, v145
	s_nop 0
	v_add_f32_e32 v145, 1.0, v145
	v_rcp_f32_e32 v162, v145
	v_mul_f32_e32 v145, 0x3d372713, v129
	v_mul_f32_e32 v145, v129, v145
	v_fma_f32 v145, v129, v145, v129
	v_mul_f32_e32 v145, 0x3f4c422a, v145
	v_add_f32_e32 v145, v145, v145
	v_mul_f32_e32 v145, 0xbfb8aa3b, v145
	v_exp_f32_e32 v145, v145
	s_nop 0
	v_add_f32_e32 v145, 1.0, v145
	v_rcp_f32_e32 v153, v145
	v_mul_f32_e32 v145, 0x3d372713, v125
	v_mul_f32_e32 v145, v125, v145
	v_fma_f32 v145, v125, v145, v125
	v_mul_f32_e32 v145, 0x3f4c422a, v145
	v_add_f32_e32 v145, v145, v145
	v_mul_f32_e32 v145, 0xbfb8aa3b, v145
	v_exp_f32_e32 v145, v145
	v_pk_mul_f32 v[128:129], v[128:129], v[152:153]
; DEVI float sigmoidf_(float x) { return __builtin_amdgcn_rcpf(1.f + __expf(-x)); }
; DEVI float siluf_(float x) { return x * __builtin_amdgcn_rcpf(1.f + __expf(-x)); }
; DEVI float logsigf_(float x) { return fminf(x, 0.f) - __logf(1.f + __expf(-fabsf(x))); }
	v_add_f32_e32 v145, 1.0, v145
	v_rcp_f32_e32 v163, v145
	s_nop 0
	v_pk_mul_f32 v[152:153], v[124:125], v[162:163]
	v_cvt_pk_bf16_f32 v125, v128, v129
	v_ashrrev_i32_e32 v128, 4, v164
	v_ashrrev_i32_e32 v129, 31, v128
	v_cvt_pk_bf16_f32 v124, v126, v127
	v_cvt_pk_bf16_f32 v126, v122, v123
	v_lshlrev_b64 v[122:123], 11, v[128:129]
	v_cvt_pk_bf16_f32 v127, v152, v153
	v_lshl_add_u64 v[152:153], v[142:143], 0, v[122:123]
	global_store_dwordx4 v[152:153], v[124:127], off
	s_nop 1
	v_mul_f32_e32 v125, 0x3d372713, v114
	v_mul_f32_e32 v125, v114, v125
	v_fma_f32 v125, v114, v125, v114
	v_mul_f32_e32 v125, 0x3f4c422a, v125
	v_add_f32_e32 v125, v125, v125
	v_mul_f32_e32 v125, 0xbfb8aa3b, v125
	v_exp_f32_e32 v125, v125
	v_mul_f32_e32 v124, 0x3d372713, v118
	v_mul_f32_e32 v124, v118, v124
	v_fma_f32 v124, v118, v124, v118
	v_add_f32_e32 v125, 1.0, v125
	v_rcp_f32_e32 v126, v125
	v_mul_f32_e32 v125, 0x3d372713, v119
	v_mul_f32_e32 v125, v119, v125
	v_fma_f32 v125, v119, v125, v119
	v_mul_f32_e32 v124, 0x3f4c422a, v124
	v_mul_f32_e32 v125, 0x3f4c422a, v125
	v_add_f32_e32 v124, v124, v124
	v_add_f32_e32 v125, v125, v125
	v_mul_f32_e32 v124, 0xbfb8aa3b, v124
	v_mul_f32_e32 v125, 0xbfb8aa3b, v125
	v_exp_f32_e32 v124, v124
	v_exp_f32_e32 v125, v125
	v_add_f32_e32 v124, 1.0, v124
	v_add_f32_e32 v125, 1.0, v125
	v_rcp_f32_e32 v124, v124
	v_rcp_f32_e32 v125, v125
	s_nop 0
	v_pk_mul_f32 v[118:119], v[118:119], v[124:125]
	v_mul_f32_e32 v124, 0x3d372713, v115
	v_mul_f32_e32 v124, v115, v124
	v_fma_f32 v124, v115, v124, v115
	v_mul_f32_e32 v124, 0x3f4c422a, v124
	v_add_f32_e32 v124, v124, v124
	v_mul_f32_e32 v125, 0x3d372713, v116
	v_mul_f32_e32 v124, 0xbfb8aa3b, v124
	v_mul_f32_e32 v125, v116, v125
	v_exp_f32_e32 v124, v124
	v_fma_f32 v125, v116, v125, v116
	v_mul_f32_e32 v125, 0x3f4c422a, v125
	v_add_f32_e32 v125, v125, v125
	v_mul_f32_e32 v125, 0xbfb8aa3b, v125
	v_add_f32_e32 v124, 1.0, v124
	v_exp_f32_e32 v125, v125
	v_rcp_f32_e32 v127, v124
	v_mul_f32_e32 v124, 0x3d372713, v120
	v_mul_f32_e32 v124, v120, v124
	v_add_f32_e32 v125, 1.0, v125
	v_pk_mul_f32 v[114:115], v[114:115], v[126:127]
	v_rcp_f32_e32 v126, v125
	v_mul_f32_e32 v125, 0x3d372713, v121
	v_mul_f32_e32 v125, v121, v125
	v_fma_f32 v124, v120, v124, v120
	v_fma_f32 v125, v121, v125, v121
	v_mul_f32_e32 v124, 0x3f4c422a, v124
	v_mul_f32_e32 v125, 0x3f4c422a, v125
	v_add_f32_e32 v124, v124, v124
	v_add_f32_e32 v125, v125, v125
	v_mul_f32_e32 v124, 0xbfb8aa3b, v124
	v_mul_f32_e32 v125, 0xbfb8aa3b, v125
	v_exp_f32_e32 v124, v124
	v_exp_f32_e32 v125, v125
	v_add_f32_e32 v124, 1.0, v124
	v_add_f32_e32 v125, 1.0, v125
	v_rcp_f32_e32 v124, v124
	v_rcp_f32_e32 v125, v125
	s_nop 0
	v_pk_mul_f32 v[120:121], v[120:121], v[124:125]
	v_mul_f32_e32 v124, 0x3d372713, v117
	v_mul_f32_e32 v124, v117, v124
	v_fma_f32 v124, v117, v124, v117
	v_mul_f32_e32 v124, 0x3f4c422a, v124
	v_add_f32_e32 v124, v124, v124
	v_mul_f32_e32 v124, 0xbfb8aa3b, v124
	v_exp_f32_e32 v124, v124
	s_nop 0
	v_add_f32_e32 v124, 1.0, v124
	v_rcp_f32_e32 v127, v124
	s_nop 0
	v_pk_mul_f32 v[124:125], v[116:117], v[126:127]
	v_cvt_pk_bf16_f32 v116, v118, v119
	v_cvt_pk_bf16_f32 v118, v114, v115
	v_or_b32_e32 v114, 8, v128
	v_ashrrev_i32_e32 v115, 31, v114
	v_lshlrev_b64 v[114:115], 11, v[114:115]
	v_cvt_pk_bf16_f32 v117, v120, v121
	v_cvt_pk_bf16_f32 v119, v124, v125
	v_lshl_add_u64 v[120:121], v[142:143], 0, v[114:115]
	global_store_dwordx4 v[120:121], v[116:119], off
	s_nop 1
	v_mul_f32_e32 v119, 0x3d372713, v106
	v_mul_f32_e32 v119, v106, v119
	v_fma_f32 v119, v106, v119, v106
	v_mul_f32_e32 v119, 0x3f4c422a, v119
	v_add_f32_e32 v119, v119, v119
	v_mul_f32_e32 v119, 0xbfb8aa3b, v119
	v_exp_f32_e32 v119, v119
	v_mul_f32_e32 v118, 0x3d372713, v110
	v_mul_f32_e32 v118, v110, v118
	v_fma_f32 v118, v110, v118, v110
	v_add_f32_e32 v119, 1.0, v119
	v_rcp_f32_e32 v120, v119
	v_mul_f32_e32 v119, 0x3d372713, v111
	v_mul_f32_e32 v119, v111, v119
	v_fma_f32 v119, v111, v119, v111
	v_mul_f32_e32 v118, 0x3f4c422a, v118
	v_mul_f32_e32 v119, 0x3f4c422a, v119
	v_add_f32_e32 v118, v118, v118
	v_add_f32_e32 v119, v119, v119
	v_mul_f32_e32 v118, 0xbfb8aa3b, v118
	v_mul_f32_e32 v119, 0xbfb8aa3b, v119
	v_exp_f32_e32 v118, v118
	v_exp_f32_e32 v119, v119
	v_or_b32_e32 v116, 16, v144
	v_ashrrev_i32_e32 v117, 31, v116
	v_add_f32_e32 v118, 1.0, v118
	v_add_f32_e32 v119, 1.0, v119
	v_rcp_f32_e32 v118, v118
	v_rcp_f32_e32 v119, v119
	v_lshlrev_b64 v[116:117], 16, v[116:117]
	v_lshl_add_u64 v[116:117], v[146:147], 0, v[116:117]
	v_pk_mul_f32 v[110:111], v[110:111], v[118:119]
	v_mul_f32_e32 v118, 0x3d372713, v107
	v_mul_f32_e32 v118, v107, v118
	v_fma_f32 v118, v107, v118, v107
	v_mul_f32_e32 v118, 0x3f4c422a, v118
	v_add_f32_e32 v118, v118, v118
	v_mul_f32_e32 v118, 0xbfb8aa3b, v118
	v_exp_f32_e32 v118, v118
	s_nop 0
	v_add_f32_e32 v118, 1.0, v118
	v_rcp_f32_e32 v121, v118
	s_nop 0
	v_pk_mul_f32 v[118:119], v[106:107], v[120:121]
	v_mul_f32_e32 v107, 0x3d372713, v108
	v_mul_f32_e32 v107, v108, v107
	v_fma_f32 v107, v108, v107, v108
	v_mul_f32_e32 v107, 0x3f4c422a, v107
	v_add_f32_e32 v107, v107, v107
	v_mul_f32_e32 v107, 0xbfb8aa3b, v107
	v_exp_f32_e32 v107, v107
	v_mul_f32_e32 v106, 0x3d372713, v112
	v_mul_f32_e32 v106, v112, v106
	v_fma_f32 v106, v112, v106, v112
	v_add_f32_e32 v107, 1.0, v107
	v_rcp_f32_e32 v120, v107
	v_mul_f32_e32 v107, 0x3d372713, v113
	v_mul_f32_e32 v107, v113, v107
	v_fma_f32 v107, v113, v107, v113
	v_mul_f32_e32 v106, 0x3f4c422a, v106
	v_mul_f32_e32 v107, 0x3f4c422a, v107
	v_add_f32_e32 v106, v106, v106
	v_add_f32_e32 v107, v107, v107
	v_mul_f32_e32 v106, 0xbfb8aa3b, v106
	v_mul_f32_e32 v107, 0xbfb8aa3b, v107
	v_exp_f32_e32 v106, v106
; DEVI float sigmoidf_(float x) { return __builtin_amdgcn_rcpf(1.f + __expf(-x)); }
; DEVI float siluf_(float x) { return x * __builtin_amdgcn_rcpf(1.f + __expf(-x)); }
; DEVI float logsigf_(float x) { return fminf(x, 0.f) - __logf(1.f + __expf(-fabsf(x))); }
	v_exp_f32_e32 v107, v107
	v_add_f32_e32 v106, 1.0, v106
	v_add_f32_e32 v107, 1.0, v107
	v_rcp_f32_e32 v106, v106
	v_rcp_f32_e32 v107, v107
	s_nop 0
	v_pk_mul_f32 v[112:113], v[112:113], v[106:107]
	v_mul_f32_e32 v106, 0x3d372713, v109
	v_mul_f32_e32 v106, v109, v106
	v_fma_f32 v106, v109, v106, v109
	v_mul_f32_e32 v106, 0x3f4c422a, v106
	v_add_f32_e32 v106, v106, v106
	v_mul_f32_e32 v106, 0xbfb8aa3b, v106
	v_exp_f32_e32 v106, v106
	v_cvt_pk_bf16_f32 v107, v112, v113
	v_add_f32_e32 v106, 1.0, v106
	v_rcp_f32_e32 v121, v106
	v_cvt_pk_bf16_f32 v106, v110, v111
	v_lshl_add_u64 v[110:111], v[116:117], 0, v[122:123]
	v_pk_mul_f32 v[120:121], v[108:109], v[120:121]
	v_cvt_pk_bf16_f32 v108, v118, v119
	v_cvt_pk_bf16_f32 v109, v120, v121
	global_store_dwordx4 v[110:111], v[106:109], off
	s_nop 1
	v_mul_f32_e32 v107, 0x3d372713, v98
	v_mul_f32_e32 v107, v98, v107
	v_fma_f32 v107, v98, v107, v98
	v_mul_f32_e32 v107, 0x3f4c422a, v107
	v_add_f32_e32 v107, v107, v107
	v_mul_f32_e32 v107, 0xbfb8aa3b, v107
	v_exp_f32_e32 v107, v107
	v_mul_f32_e32 v106, 0x3d372713, v102
	v_mul_f32_e32 v106, v102, v106
	v_fma_f32 v106, v102, v106, v102
	v_add_f32_e32 v107, 1.0, v107
	v_rcp_f32_e32 v108, v107
	v_mul_f32_e32 v107, 0x3d372713, v103
	v_mul_f32_e32 v107, v103, v107
	v_fma_f32 v107, v103, v107, v103
	v_mul_f32_e32 v106, 0x3f4c422a, v106
	v_mul_f32_e32 v107, 0x3f4c422a, v107
	v_add_f32_e32 v106, v106, v106
	v_add_f32_e32 v107, v107, v107
	v_mul_f32_e32 v106, 0xbfb8aa3b, v106
	v_mul_f32_e32 v107, 0xbfb8aa3b, v107
	v_exp_f32_e32 v106, v106
	v_exp_f32_e32 v107, v107
	v_add_f32_e32 v106, 1.0, v106
	v_add_f32_e32 v107, 1.0, v107
	v_rcp_f32_e32 v106, v106
	v_rcp_f32_e32 v107, v107
	s_nop 0
	v_pk_mul_f32 v[102:103], v[102:103], v[106:107]
	v_mul_f32_e32 v106, 0x3d372713, v99
	v_mul_f32_e32 v106, v99, v106
	v_fma_f32 v106, v99, v106, v99
	v_mul_f32_e32 v106, 0x3f4c422a, v106
	v_add_f32_e32 v106, v106, v106
	v_mul_f32_e32 v106, 0xbfb8aa3b, v106
	v_exp_f32_e32 v106, v106
	s_nop 0
	v_add_f32_e32 v106, 1.0, v106
	v_rcp_f32_e32 v109, v106
	s_nop 0
	v_pk_mul_f32 v[106:107], v[98:99], v[108:109]
	v_mul_f32_e32 v99, 0x3d372713, v100
	v_mul_f32_e32 v99, v100, v99
	v_fma_f32 v99, v100, v99, v100
	v_mul_f32_e32 v99, 0x3f4c422a, v99
	v_add_f32_e32 v99, v99, v99
	v_mul_f32_e32 v99, 0xbfb8aa3b, v99
	v_exp_f32_e32 v99, v99
	v_mul_f32_e32 v98, 0x3d372713, v104
	v_mul_f32_e32 v98, v104, v98
	v_fma_f32 v98, v104, v98, v104
	v_add_f32_e32 v99, 1.0, v99
	v_rcp_f32_e32 v108, v99
	v_mul_f32_e32 v99, 0x3d372713, v105
	v_mul_f32_e32 v99, v105, v99
	v_fma_f32 v99, v105, v99, v105
	v_mul_f32_e32 v98, 0x3f4c422a, v98
	v_mul_f32_e32 v99, 0x3f4c422a, v99
	v_add_f32_e32 v98, v98, v98
	v_add_f32_e32 v99, v99, v99
	v_mul_f32_e32 v98, 0xbfb8aa3b, v98
	v_mul_f32_e32 v99, 0xbfb8aa3b, v99
	v_exp_f32_e32 v98, v98
	v_exp_f32_e32 v99, v99
	v_add_f32_e32 v98, 1.0, v98
	v_add_f32_e32 v99, 1.0, v99
	v_rcp_f32_e32 v98, v98
	v_rcp_f32_e32 v99, v99
	s_nop 0
	v_pk_mul_f32 v[104:105], v[104:105], v[98:99]
	v_mul_f32_e32 v98, 0x3d372713, v101
	v_mul_f32_e32 v98, v101, v98
	v_fma_f32 v98, v101, v98, v101
	v_mul_f32_e32 v98, 0x3f4c422a, v98
	v_add_f32_e32 v98, v98, v98
	v_mul_f32_e32 v98, 0xbfb8aa3b, v98
	v_exp_f32_e32 v98, v98
	v_cvt_pk_bf16_f32 v99, v104, v105
	v_add_f32_e32 v98, 1.0, v98
	v_rcp_f32_e32 v109, v98
	v_cvt_pk_bf16_f32 v98, v102, v103
	v_lshl_add_u64 v[102:103], v[116:117], 0, v[114:115]
	v_pk_mul_f32 v[108:109], v[100:101], v[108:109]
	v_cvt_pk_bf16_f32 v100, v106, v107
	v_cvt_pk_bf16_f32 v101, v108, v109
	global_store_dwordx4 v[102:103], v[98:101], off
	s_nop 1
	v_mul_f32_e32 v101, 0x3d372713, v90
	v_mul_f32_e32 v101, v90, v101
	v_fma_f32 v101, v90, v101, v90
	v_mul_f32_e32 v101, 0x3f4c422a, v101
	v_add_f32_e32 v101, v101, v101
	v_mul_f32_e32 v101, 0xbfb8aa3b, v101
	v_exp_f32_e32 v101, v101
	v_mul_f32_e32 v100, 0x3d372713, v94
	v_mul_f32_e32 v100, v94, v100
	v_fma_f32 v100, v94, v100, v94
	v_add_f32_e32 v101, 1.0, v101
	v_rcp_f32_e32 v102, v101
	v_mul_f32_e32 v101, 0x3d372713, v95
	v_mul_f32_e32 v101, v95, v101
	v_fma_f32 v101, v95, v101, v95
	v_mul_f32_e32 v100, 0x3f4c422a, v100
	v_mul_f32_e32 v101, 0x3f4c422a, v101
	v_add_f32_e32 v100, v100, v100
	v_add_f32_e32 v101, v101, v101
	v_mul_f32_e32 v100, 0xbfb8aa3b, v100
	v_mul_f32_e32 v101, 0xbfb8aa3b, v101
	v_exp_f32_e32 v100, v100
	v_exp_f32_e32 v101, v101
	v_or_b32_e32 v98, 32, v144
	v_ashrrev_i32_e32 v99, 31, v98
	v_add_f32_e32 v100, 1.0, v100
	v_add_f32_e32 v101, 1.0, v101
	v_rcp_f32_e32 v100, v100
	v_rcp_f32_e32 v101, v101
	v_lshlrev_b64 v[98:99], 16, v[98:99]
	v_lshl_add_u64 v[98:99], v[146:147], 0, v[98:99]
	v_pk_mul_f32 v[94:95], v[94:95], v[100:101]
	v_mul_f32_e32 v100, 0x3d372713, v91
	v_mul_f32_e32 v100, v91, v100
	v_fma_f32 v100, v91, v100, v91
	v_mul_f32_e32 v100, 0x3f4c422a, v100
	v_add_f32_e32 v100, v100, v100
	v_mul_f32_e32 v100, 0xbfb8aa3b, v100
	v_exp_f32_e32 v100, v100
	s_nop 0
	v_add_f32_e32 v100, 1.0, v100
	v_rcp_f32_e32 v103, v100
	s_nop 0
	v_pk_mul_f32 v[100:101], v[90:91], v[102:103]
	v_mul_f32_e32 v91, 0x3d372713, v92
	v_mul_f32_e32 v91, v92, v91
	v_fma_f32 v91, v92, v91, v92
	v_mul_f32_e32 v91, 0x3f4c422a, v91
	v_add_f32_e32 v91, v91, v91
	v_mul_f32_e32 v91, 0xbfb8aa3b, v91
	v_exp_f32_e32 v91, v91
	v_mul_f32_e32 v90, 0x3d372713, v96
	v_mul_f32_e32 v90, v96, v90
	v_fma_f32 v90, v96, v90, v96
	v_add_f32_e32 v91, 1.0, v91
	v_rcp_f32_e32 v102, v91
	v_mul_f32_e32 v91, 0x3d372713, v97
	v_mul_f32_e32 v91, v97, v91
	v_fma_f32 v91, v97, v91, v97
	v_mul_f32_e32 v90, 0x3f4c422a, v90
	v_mul_f32_e32 v91, 0x3f4c422a, v91
	v_add_f32_e32 v90, v90, v90
	v_add_f32_e32 v91, v91, v91
	v_mul_f32_e32 v90, 0xbfb8aa3b, v90
	v_mul_f32_e32 v91, 0xbfb8aa3b, v91
; DEVI float sigmoidf_(float x) { return __builtin_amdgcn_rcpf(1.f + __expf(-x)); }
; DEVI float siluf_(float x) { return x * __builtin_amdgcn_rcpf(1.f + __expf(-x)); }
; DEVI float logsigf_(float x) { return fminf(x, 0.f) - __logf(1.f + __expf(-fabsf(x))); }
	v_exp_f32_e32 v90, v90
	v_exp_f32_e32 v91, v91
	v_add_f32_e32 v90, 1.0, v90
	v_add_f32_e32 v91, 1.0, v91
	v_rcp_f32_e32 v90, v90
	v_rcp_f32_e32 v91, v91
	s_nop 0
	v_pk_mul_f32 v[96:97], v[96:97], v[90:91]
	v_mul_f32_e32 v90, 0x3d372713, v93
	v_mul_f32_e32 v90, v93, v90
	v_fma_f32 v90, v93, v90, v93
	v_mul_f32_e32 v90, 0x3f4c422a, v90
	v_add_f32_e32 v90, v90, v90
	v_mul_f32_e32 v90, 0xbfb8aa3b, v90
	v_exp_f32_e32 v90, v90
	v_cvt_pk_bf16_f32 v91, v96, v97
	v_add_f32_e32 v90, 1.0, v90
	v_rcp_f32_e32 v103, v90
	v_cvt_pk_bf16_f32 v90, v94, v95
	v_lshl_add_u64 v[94:95], v[98:99], 0, v[122:123]
	v_pk_mul_f32 v[102:103], v[92:93], v[102:103]
	v_cvt_pk_bf16_f32 v92, v100, v101
	v_cvt_pk_bf16_f32 v93, v102, v103
	global_store_dwordx4 v[94:95], v[90:93], off
	s_nop 1
	v_mul_f32_e32 v91, 0x3d372713, v82
	v_mul_f32_e32 v91, v82, v91
	v_fma_f32 v91, v82, v91, v82
	v_mul_f32_e32 v91, 0x3f4c422a, v91
	v_add_f32_e32 v91, v91, v91
	v_mul_f32_e32 v91, 0xbfb8aa3b, v91
	v_exp_f32_e32 v91, v91
	v_mul_f32_e32 v90, 0x3d372713, v86
	v_mul_f32_e32 v90, v86, v90
	v_fma_f32 v90, v86, v90, v86
	v_add_f32_e32 v91, 1.0, v91
	v_rcp_f32_e32 v92, v91
	v_mul_f32_e32 v91, 0x3d372713, v87
	v_mul_f32_e32 v91, v87, v91
	v_fma_f32 v91, v87, v91, v87
	v_mul_f32_e32 v90, 0x3f4c422a, v90
	v_mul_f32_e32 v91, 0x3f4c422a, v91
	v_add_f32_e32 v90, v90, v90
	v_add_f32_e32 v91, v91, v91
	v_mul_f32_e32 v90, 0xbfb8aa3b, v90
	v_mul_f32_e32 v91, 0xbfb8aa3b, v91
	v_exp_f32_e32 v90, v90
	v_exp_f32_e32 v91, v91
	v_add_f32_e32 v90, 1.0, v90
	v_add_f32_e32 v91, 1.0, v91
	v_rcp_f32_e32 v90, v90
	v_rcp_f32_e32 v91, v91
	s_nop 0
	v_pk_mul_f32 v[86:87], v[86:87], v[90:91]
	v_mul_f32_e32 v90, 0x3d372713, v83
	v_mul_f32_e32 v90, v83, v90
	v_fma_f32 v90, v83, v90, v83
	v_mul_f32_e32 v90, 0x3f4c422a, v90
	v_add_f32_e32 v90, v90, v90
	v_mul_f32_e32 v90, 0xbfb8aa3b, v90
	v_exp_f32_e32 v90, v90
	s_nop 0
	v_add_f32_e32 v90, 1.0, v90
	v_rcp_f32_e32 v93, v90
	s_nop 0
	v_pk_mul_f32 v[90:91], v[82:83], v[92:93]
	v_mul_f32_e32 v83, 0x3d372713, v84
	v_mul_f32_e32 v83, v84, v83
	v_fma_f32 v83, v84, v83, v84
	v_mul_f32_e32 v83, 0x3f4c422a, v83
	v_add_f32_e32 v83, v83, v83
	v_mul_f32_e32 v83, 0xbfb8aa3b, v83
	v_exp_f32_e32 v83, v83
	v_mul_f32_e32 v82, 0x3d372713, v88
	v_mul_f32_e32 v82, v88, v82
	v_fma_f32 v82, v88, v82, v88
	v_add_f32_e32 v83, 1.0, v83
	v_rcp_f32_e32 v92, v83
	v_mul_f32_e32 v83, 0x3d372713, v89
	v_mul_f32_e32 v83, v89, v83
	v_fma_f32 v83, v89, v83, v89
	v_mul_f32_e32 v82, 0x3f4c422a, v82
	v_mul_f32_e32 v83, 0x3f4c422a, v83
	v_add_f32_e32 v82, v82, v82
	v_add_f32_e32 v83, v83, v83
	v_mul_f32_e32 v82, 0xbfb8aa3b, v82
	v_mul_f32_e32 v83, 0xbfb8aa3b, v83
	v_exp_f32_e32 v82, v82
	v_exp_f32_e32 v83, v83
	v_add_f32_e32 v82, 1.0, v82
	v_add_f32_e32 v83, 1.0, v83
	v_rcp_f32_e32 v82, v82
	v_rcp_f32_e32 v83, v83
	s_nop 0
	v_pk_mul_f32 v[88:89], v[88:89], v[82:83]
	v_mul_f32_e32 v82, 0x3d372713, v85
	v_mul_f32_e32 v82, v85, v82
	v_fma_f32 v82, v85, v82, v85
	v_mul_f32_e32 v82, 0x3f4c422a, v82
	v_add_f32_e32 v82, v82, v82
	v_mul_f32_e32 v82, 0xbfb8aa3b, v82
	v_exp_f32_e32 v82, v82
	v_cvt_pk_bf16_f32 v83, v88, v89
	v_add_f32_e32 v82, 1.0, v82
	v_rcp_f32_e32 v93, v82
	v_cvt_pk_bf16_f32 v82, v86, v87
	v_lshl_add_u64 v[86:87], v[98:99], 0, v[114:115]
	v_pk_mul_f32 v[92:93], v[84:85], v[92:93]
	v_cvt_pk_bf16_f32 v84, v90, v91
	v_cvt_pk_bf16_f32 v85, v92, v93
	global_store_dwordx4 v[86:87], v[82:85], off
	s_nop 1
	v_mul_f32_e32 v85, 0x3d372713, v74
	v_mul_f32_e32 v85, v74, v85
	v_fma_f32 v85, v74, v85, v74
	v_mul_f32_e32 v85, 0x3f4c422a, v85
	v_add_f32_e32 v85, v85, v85
	v_mul_f32_e32 v85, 0xbfb8aa3b, v85
	v_exp_f32_e32 v85, v85
	v_mul_f32_e32 v84, 0x3d372713, v78
	v_mul_f32_e32 v84, v78, v84
	v_fma_f32 v84, v78, v84, v78
	v_add_f32_e32 v85, 1.0, v85
	v_rcp_f32_e32 v86, v85
	v_mul_f32_e32 v85, 0x3d372713, v79
	v_mul_f32_e32 v85, v79, v85
	v_fma_f32 v85, v79, v85, v79
	v_mul_f32_e32 v84, 0x3f4c422a, v84
	v_mul_f32_e32 v85, 0x3f4c422a, v85
	v_add_f32_e32 v84, v84, v84
	v_add_f32_e32 v85, v85, v85
	v_mul_f32_e32 v84, 0xbfb8aa3b, v84
	v_mul_f32_e32 v85, 0xbfb8aa3b, v85
	v_exp_f32_e32 v84, v84
	v_exp_f32_e32 v85, v85
	v_or_b32_e32 v82, 48, v144
	v_ashrrev_i32_e32 v83, 31, v82
	v_add_f32_e32 v84, 1.0, v84
	v_add_f32_e32 v85, 1.0, v85
	v_rcp_f32_e32 v84, v84
	v_rcp_f32_e32 v85, v85
	v_lshlrev_b64 v[82:83], 16, v[82:83]
	v_lshl_add_u64 v[82:83], v[146:147], 0, v[82:83]
	v_pk_mul_f32 v[78:79], v[78:79], v[84:85]
	v_mul_f32_e32 v84, 0x3d372713, v75
	v_mul_f32_e32 v84, v75, v84
	v_fma_f32 v84, v75, v84, v75
	v_mul_f32_e32 v84, 0x3f4c422a, v84
	v_add_f32_e32 v84, v84, v84
	v_mul_f32_e32 v84, 0xbfb8aa3b, v84
	v_exp_f32_e32 v84, v84
	s_nop 0
	v_add_f32_e32 v84, 1.0, v84
	v_rcp_f32_e32 v87, v84
	s_nop 0
	v_pk_mul_f32 v[84:85], v[74:75], v[86:87]
	v_mul_f32_e32 v75, 0x3d372713, v76
	v_mul_f32_e32 v75, v76, v75
	v_fma_f32 v75, v76, v75, v76
	v_mul_f32_e32 v75, 0x3f4c422a, v75
	v_add_f32_e32 v75, v75, v75
	v_mul_f32_e32 v75, 0xbfb8aa3b, v75
	v_exp_f32_e32 v75, v75
	v_mul_f32_e32 v74, 0x3d372713, v80
	v_mul_f32_e32 v74, v80, v74
	v_fma_f32 v74, v80, v74, v80
	v_add_f32_e32 v75, 1.0, v75
	v_rcp_f32_e32 v86, v75
	v_mul_f32_e32 v75, 0x3d372713, v81
	v_mul_f32_e32 v75, v81, v75
	v_fma_f32 v75, v81, v75, v81
	v_mul_f32_e32 v74, 0x3f4c422a, v74
	v_mul_f32_e32 v75, 0x3f4c422a, v75
	v_add_f32_e32 v74, v74, v74
	v_add_f32_e32 v75, v75, v75
	v_mul_f32_e32 v74, 0xbfb8aa3b, v74
	v_mul_f32_e32 v75, 0xbfb8aa3b, v75
	v_exp_f32_e32 v74, v74
	v_exp_f32_e32 v75, v75
	v_add_f32_e32 v74, 1.0, v74
	v_add_f32_e32 v75, 1.0, v75
	v_rcp_f32_e32 v74, v74
	v_rcp_f32_e32 v75, v75
	s_nop 0
	v_pk_mul_f32 v[80:81], v[80:81], v[74:75]
	v_mul_f32_e32 v74, 0x3d372713, v77
; DEVI float sigmoidf_(float x) { return __builtin_amdgcn_rcpf(1.f + __expf(-x)); }
; DEVI float siluf_(float x) { return x * __builtin_amdgcn_rcpf(1.f + __expf(-x)); }
; DEVI float logsigf_(float x) { return fminf(x, 0.f) - __logf(1.f + __expf(-fabsf(x))); }
	v_mul_f32_e32 v74, v77, v74
	v_fma_f32 v74, v77, v74, v77
	v_mul_f32_e32 v74, 0x3f4c422a, v74
	v_add_f32_e32 v74, v74, v74
	v_mul_f32_e32 v74, 0xbfb8aa3b, v74
	v_exp_f32_e32 v74, v74
	v_cvt_pk_bf16_f32 v75, v80, v81
	v_add_f32_e32 v74, 1.0, v74
	v_rcp_f32_e32 v87, v74
	v_cvt_pk_bf16_f32 v74, v78, v79
	v_lshl_add_u64 v[78:79], v[82:83], 0, v[122:123]
	v_pk_mul_f32 v[86:87], v[76:77], v[86:87]
	v_cvt_pk_bf16_f32 v76, v84, v85
	v_cvt_pk_bf16_f32 v77, v86, v87
	global_store_dwordx4 v[78:79], v[74:77], off
	s_nop 1
	v_mul_f32_e32 v75, 0x3d372713, v66
	v_mul_f32_e32 v75, v66, v75
	v_fma_f32 v75, v66, v75, v66
	v_mul_f32_e32 v75, 0x3f4c422a, v75
	v_add_f32_e32 v75, v75, v75
	v_mul_f32_e32 v75, 0xbfb8aa3b, v75
	v_exp_f32_e32 v75, v75
	v_mul_f32_e32 v74, 0x3d372713, v70
	v_mul_f32_e32 v74, v70, v74
	v_fma_f32 v74, v70, v74, v70
	v_add_f32_e32 v75, 1.0, v75
	v_rcp_f32_e32 v76, v75
	v_mul_f32_e32 v75, 0x3d372713, v71
	v_mul_f32_e32 v75, v71, v75
	v_fma_f32 v75, v71, v75, v71
	v_mul_f32_e32 v74, 0x3f4c422a, v74
	v_mul_f32_e32 v75, 0x3f4c422a, v75
	v_add_f32_e32 v74, v74, v74
	v_add_f32_e32 v75, v75, v75
	v_mul_f32_e32 v74, 0xbfb8aa3b, v74
	v_mul_f32_e32 v75, 0xbfb8aa3b, v75
	v_exp_f32_e32 v74, v74
	v_exp_f32_e32 v75, v75
	v_add_f32_e32 v74, 1.0, v74
	v_add_f32_e32 v75, 1.0, v75
	v_rcp_f32_e32 v74, v74
	v_rcp_f32_e32 v75, v75
	s_nop 0
	v_pk_mul_f32 v[70:71], v[70:71], v[74:75]
	v_mul_f32_e32 v74, 0x3d372713, v67
	v_mul_f32_e32 v74, v67, v74
	v_fma_f32 v74, v67, v74, v67
	v_mul_f32_e32 v74, 0x3f4c422a, v74
	v_add_f32_e32 v74, v74, v74
	v_mul_f32_e32 v74, 0xbfb8aa3b, v74
	v_exp_f32_e32 v74, v74
	s_nop 0
	v_add_f32_e32 v74, 1.0, v74
	v_rcp_f32_e32 v77, v74
	s_nop 0
	v_pk_mul_f32 v[74:75], v[66:67], v[76:77]
	v_mul_f32_e32 v67, 0x3d372713, v68
	v_mul_f32_e32 v67, v68, v67
	v_fma_f32 v67, v68, v67, v68
	v_mul_f32_e32 v67, 0x3f4c422a, v67
	v_add_f32_e32 v67, v67, v67
	v_mul_f32_e32 v67, 0xbfb8aa3b, v67
	v_exp_f32_e32 v67, v67
	v_mul_f32_e32 v66, 0x3d372713, v72
	v_mul_f32_e32 v66, v72, v66
	v_fma_f32 v66, v72, v66, v72
	v_add_f32_e32 v67, 1.0, v67
	v_rcp_f32_e32 v76, v67
	v_mul_f32_e32 v67, 0x3d372713, v73
	v_mul_f32_e32 v67, v73, v67
	v_fma_f32 v67, v73, v67, v73
	v_mul_f32_e32 v66, 0x3f4c422a, v66
	v_mul_f32_e32 v67, 0x3f4c422a, v67
	v_add_f32_e32 v66, v66, v66
	v_add_f32_e32 v67, v67, v67
	v_mul_f32_e32 v66, 0xbfb8aa3b, v66
	v_mul_f32_e32 v67, 0xbfb8aa3b, v67
	v_exp_f32_e32 v66, v66
	v_exp_f32_e32 v67, v67
	v_add_f32_e32 v66, 1.0, v66
	v_add_f32_e32 v67, 1.0, v67
	v_rcp_f32_e32 v66, v66
	v_rcp_f32_e32 v67, v67
	s_nop 0
	v_pk_mul_f32 v[72:73], v[72:73], v[66:67]
	v_mul_f32_e32 v66, 0x3d372713, v69
	v_mul_f32_e32 v66, v69, v66
	v_fma_f32 v66, v69, v66, v69
	v_mul_f32_e32 v66, 0x3f4c422a, v66
	v_add_f32_e32 v66, v66, v66
	v_mul_f32_e32 v66, 0xbfb8aa3b, v66
	v_exp_f32_e32 v66, v66
	v_cvt_pk_bf16_f32 v67, v72, v73
	v_add_f32_e32 v66, 1.0, v66
	v_rcp_f32_e32 v77, v66
	v_cvt_pk_bf16_f32 v66, v70, v71
	v_lshl_add_u64 v[70:71], v[82:83], 0, v[114:115]
	v_pk_mul_f32 v[76:77], v[68:69], v[76:77]
	v_cvt_pk_bf16_f32 v68, v74, v75
	v_cvt_pk_bf16_f32 v69, v76, v77
	global_store_dwordx4 v[70:71], v[66:69], off
	s_nop 1
	v_mul_f32_e32 v69, 0x3d372713, v58
	v_mul_f32_e32 v69, v58, v69
	v_fma_f32 v69, v58, v69, v58
	v_mul_f32_e32 v69, 0x3f4c422a, v69
	v_add_f32_e32 v69, v69, v69
	v_mul_f32_e32 v69, 0xbfb8aa3b, v69
	v_exp_f32_e32 v69, v69
	v_mul_f32_e32 v68, 0x3d372713, v62
	v_mul_f32_e32 v68, v62, v68
	v_fma_f32 v68, v62, v68, v62
	v_add_f32_e32 v69, 1.0, v69
	v_rcp_f32_e32 v70, v69
	v_mul_f32_e32 v69, 0x3d372713, v63
	v_mul_f32_e32 v69, v63, v69
	v_fma_f32 v69, v63, v69, v63
	v_mul_f32_e32 v68, 0x3f4c422a, v68
	v_mul_f32_e32 v69, 0x3f4c422a, v69
	v_add_f32_e32 v68, v68, v68
	v_add_f32_e32 v69, v69, v69
	v_mul_f32_e32 v68, 0xbfb8aa3b, v68
	v_mul_f32_e32 v69, 0xbfb8aa3b, v69
	v_exp_f32_e32 v68, v68
	v_exp_f32_e32 v69, v69
	v_lshl_add_u64 v[66:67], v[142:143], 0, s[0:1]
	s_mov_b64 s[0:1], 0x900000
	v_add_f32_e32 v68, 1.0, v68
	v_add_f32_e32 v69, 1.0, v69
	v_rcp_f32_e32 v68, v68
	v_rcp_f32_e32 v69, v69
	s_nop 0
	v_pk_mul_f32 v[62:63], v[62:63], v[68:69]
	v_mul_f32_e32 v68, 0x3d372713, v59
	v_mul_f32_e32 v68, v59, v68
	v_fma_f32 v68, v59, v68, v59
	v_mul_f32_e32 v68, 0x3f4c422a, v68
	v_add_f32_e32 v68, v68, v68
	v_mul_f32_e32 v68, 0xbfb8aa3b, v68
	v_exp_f32_e32 v68, v68
	s_nop 0
	v_add_f32_e32 v68, 1.0, v68
	v_rcp_f32_e32 v71, v68
	s_nop 0
	v_pk_mul_f32 v[68:69], v[58:59], v[70:71]
	v_mul_f32_e32 v59, 0x3d372713, v60
	v_mul_f32_e32 v59, v60, v59
	v_fma_f32 v59, v60, v59, v60
	v_mul_f32_e32 v59, 0x3f4c422a, v59
	v_add_f32_e32 v59, v59, v59
	v_mul_f32_e32 v59, 0xbfb8aa3b, v59
	v_exp_f32_e32 v59, v59
	v_mul_f32_e32 v58, 0x3d372713, v64
	v_mul_f32_e32 v58, v64, v58
	v_fma_f32 v58, v64, v58, v64
	v_add_f32_e32 v59, 1.0, v59
	v_rcp_f32_e32 v70, v59
	v_mul_f32_e32 v59, 0x3d372713, v65
	v_mul_f32_e32 v59, v65, v59
	v_fma_f32 v59, v65, v59, v65
	v_mul_f32_e32 v58, 0x3f4c422a, v58
	v_mul_f32_e32 v59, 0x3f4c422a, v59
	v_add_f32_e32 v58, v58, v58
	v_add_f32_e32 v59, v59, v59
	v_mul_f32_e32 v58, 0xbfb8aa3b, v58
	v_mul_f32_e32 v59, 0xbfb8aa3b, v59
	v_exp_f32_e32 v58, v58
	v_exp_f32_e32 v59, v59
	v_add_f32_e32 v58, 1.0, v58
	v_add_f32_e32 v59, 1.0, v59
	v_rcp_f32_e32 v58, v58
	v_rcp_f32_e32 v59, v59
	s_nop 0
	v_pk_mul_f32 v[64:65], v[64:65], v[58:59]
	v_mul_f32_e32 v58, 0x3d372713, v61
	v_mul_f32_e32 v58, v61, v58
	v_fma_f32 v58, v61, v58, v61
	v_mul_f32_e32 v58, 0x3f4c422a, v58
	v_add_f32_e32 v58, v58, v58
	v_mul_f32_e32 v58, 0xbfb8aa3b, v58
	v_exp_f32_e32 v58, v58
	v_cvt_pk_bf16_f32 v59, v64, v65
	v_add_f32_e32 v58, 1.0, v58
	v_rcp_f32_e32 v71, v58
	v_cvt_pk_bf16_f32 v58, v62, v63
; DEVI float sigmoidf_(float x) { return __builtin_amdgcn_rcpf(1.f + __expf(-x)); }
; DEVI float siluf_(float x) { return x * __builtin_amdgcn_rcpf(1.f + __expf(-x)); }
; DEVI float logsigf_(float x) { return fminf(x, 0.f) - __logf(1.f + __expf(-fabsf(x))); }
	v_lshl_add_u64 v[62:63], v[66:67], 0, v[122:123]
	v_pk_mul_f32 v[70:71], v[60:61], v[70:71]
	v_cvt_pk_bf16_f32 v60, v68, v69
	v_cvt_pk_bf16_f32 v61, v70, v71
	global_store_dwordx4 v[62:63], v[58:61], off
	s_nop 1
	v_mul_f32_e32 v59, 0x3d372713, v50
	v_mul_f32_e32 v59, v50, v59
	v_fma_f32 v59, v50, v59, v50
	v_mul_f32_e32 v59, 0x3f4c422a, v59
	v_add_f32_e32 v59, v59, v59
	v_mul_f32_e32 v59, 0xbfb8aa3b, v59
	v_exp_f32_e32 v59, v59
	v_mul_f32_e32 v58, 0x3d372713, v54
	v_mul_f32_e32 v58, v54, v58
	v_fma_f32 v58, v54, v58, v54
	v_add_f32_e32 v59, 1.0, v59
	v_rcp_f32_e32 v60, v59
	v_mul_f32_e32 v59, 0x3d372713, v55
	v_mul_f32_e32 v59, v55, v59
	v_fma_f32 v59, v55, v59, v55
	v_mul_f32_e32 v58, 0x3f4c422a, v58
	v_mul_f32_e32 v59, 0x3f4c422a, v59
	v_add_f32_e32 v58, v58, v58
	v_add_f32_e32 v59, v59, v59
	v_mul_f32_e32 v58, 0xbfb8aa3b, v58
	v_mul_f32_e32 v59, 0xbfb8aa3b, v59
	v_exp_f32_e32 v58, v58
	v_exp_f32_e32 v59, v59
	v_add_f32_e32 v58, 1.0, v58
	v_add_f32_e32 v59, 1.0, v59
	v_rcp_f32_e32 v58, v58
	v_rcp_f32_e32 v59, v59
	s_nop 0
	v_pk_mul_f32 v[54:55], v[54:55], v[58:59]
	v_mul_f32_e32 v58, 0x3d372713, v51
	v_mul_f32_e32 v58, v51, v58
	v_fma_f32 v58, v51, v58, v51
	v_mul_f32_e32 v58, 0x3f4c422a, v58
	v_add_f32_e32 v58, v58, v58
	v_mul_f32_e32 v58, 0xbfb8aa3b, v58
	v_exp_f32_e32 v58, v58
	s_nop 0
	v_add_f32_e32 v58, 1.0, v58
	v_rcp_f32_e32 v61, v58
	s_nop 0
	v_pk_mul_f32 v[58:59], v[50:51], v[60:61]
	v_mul_f32_e32 v51, 0x3d372713, v52
	v_mul_f32_e32 v51, v52, v51
	v_fma_f32 v51, v52, v51, v52
	v_mul_f32_e32 v51, 0x3f4c422a, v51
	v_add_f32_e32 v51, v51, v51
	v_mul_f32_e32 v51, 0xbfb8aa3b, v51
	v_exp_f32_e32 v51, v51
	v_mul_f32_e32 v50, 0x3d372713, v56
	v_mul_f32_e32 v50, v56, v50
	v_fma_f32 v50, v56, v50, v56
	v_add_f32_e32 v51, 1.0, v51
	v_rcp_f32_e32 v60, v51
	v_mul_f32_e32 v51, 0x3d372713, v57
	v_mul_f32_e32 v51, v57, v51
	v_fma_f32 v51, v57, v51, v57
	v_mul_f32_e32 v50, 0x3f4c422a, v50
	v_mul_f32_e32 v51, 0x3f4c422a, v51
	v_add_f32_e32 v50, v50, v50
	v_add_f32_e32 v51, v51, v51
	v_mul_f32_e32 v50, 0xbfb8aa3b, v50
	v_mul_f32_e32 v51, 0xbfb8aa3b, v51
	v_exp_f32_e32 v50, v50
	v_exp_f32_e32 v51, v51
	v_add_f32_e32 v50, 1.0, v50
	v_add_f32_e32 v51, 1.0, v51
	v_rcp_f32_e32 v50, v50
	v_rcp_f32_e32 v51, v51
	s_nop 0
	v_pk_mul_f32 v[56:57], v[56:57], v[50:51]
	v_mul_f32_e32 v50, 0x3d372713, v53
	v_mul_f32_e32 v50, v53, v50
	v_fma_f32 v50, v53, v50, v53
	v_mul_f32_e32 v50, 0x3f4c422a, v50
	v_add_f32_e32 v50, v50, v50
	v_mul_f32_e32 v50, 0xbfb8aa3b, v50
	v_exp_f32_e32 v50, v50
	v_cvt_pk_bf16_f32 v51, v56, v57
	v_add_f32_e32 v50, 1.0, v50
	v_rcp_f32_e32 v61, v50
	v_cvt_pk_bf16_f32 v50, v54, v55
	v_lshl_add_u64 v[54:55], v[66:67], 0, v[114:115]
	v_pk_mul_f32 v[60:61], v[52:53], v[60:61]
	v_cvt_pk_bf16_f32 v52, v58, v59
	v_cvt_pk_bf16_f32 v53, v60, v61
	global_store_dwordx4 v[54:55], v[50:53], off
	s_nop 1
	v_mul_f32_e32 v53, 0x3d372713, v42
	v_mul_f32_e32 v53, v42, v53
	v_fma_f32 v53, v42, v53, v42
	v_mul_f32_e32 v53, 0x3f4c422a, v53
	v_add_f32_e32 v53, v53, v53
	v_mul_f32_e32 v53, 0xbfb8aa3b, v53
	v_exp_f32_e32 v53, v53
	v_mul_f32_e32 v52, 0x3d372713, v46
	v_mul_f32_e32 v52, v46, v52
	v_fma_f32 v52, v46, v52, v46
	v_add_f32_e32 v53, 1.0, v53
	v_rcp_f32_e32 v54, v53
	v_mul_f32_e32 v53, 0x3d372713, v47
	v_mul_f32_e32 v53, v47, v53
	v_fma_f32 v53, v47, v53, v47
	v_mul_f32_e32 v52, 0x3f4c422a, v52
	v_mul_f32_e32 v53, 0x3f4c422a, v53
	v_add_f32_e32 v52, v52, v52
	v_add_f32_e32 v53, v53, v53
	v_mul_f32_e32 v52, 0xbfb8aa3b, v52
	v_mul_f32_e32 v53, 0xbfb8aa3b, v53
	v_exp_f32_e32 v52, v52
	v_exp_f32_e32 v53, v53
	v_lshl_add_u64 v[50:51], v[142:143], 0, s[0:1]
	s_mov_b64 s[0:1], 0xa00000
	v_add_f32_e32 v52, 1.0, v52
	v_add_f32_e32 v53, 1.0, v53
	v_rcp_f32_e32 v52, v52
	v_rcp_f32_e32 v53, v53
	s_nop 0
	v_pk_mul_f32 v[46:47], v[46:47], v[52:53]
	v_mul_f32_e32 v52, 0x3d372713, v43
	v_mul_f32_e32 v52, v43, v52
	v_fma_f32 v52, v43, v52, v43
	v_mul_f32_e32 v52, 0x3f4c422a, v52
	v_add_f32_e32 v52, v52, v52
	v_mul_f32_e32 v52, 0xbfb8aa3b, v52
	v_exp_f32_e32 v52, v52
	s_nop 0
	v_add_f32_e32 v52, 1.0, v52
	v_rcp_f32_e32 v55, v52
	s_nop 0
	v_pk_mul_f32 v[52:53], v[42:43], v[54:55]
	v_mul_f32_e32 v43, 0x3d372713, v44
	v_mul_f32_e32 v43, v44, v43
	v_fma_f32 v43, v44, v43, v44
	v_mul_f32_e32 v43, 0x3f4c422a, v43
	v_add_f32_e32 v43, v43, v43
	v_mul_f32_e32 v43, 0xbfb8aa3b, v43
	v_exp_f32_e32 v43, v43
	v_mul_f32_e32 v42, 0x3d372713, v48
	v_mul_f32_e32 v42, v48, v42
	v_fma_f32 v42, v48, v42, v48
	v_add_f32_e32 v43, 1.0, v43
	v_rcp_f32_e32 v54, v43
	v_mul_f32_e32 v43, 0x3d372713, v49
	v_mul_f32_e32 v43, v49, v43
	v_fma_f32 v43, v49, v43, v49
	v_mul_f32_e32 v42, 0x3f4c422a, v42
	v_mul_f32_e32 v43, 0x3f4c422a, v43
	v_add_f32_e32 v42, v42, v42
	v_add_f32_e32 v43, v43, v43
	v_mul_f32_e32 v42, 0xbfb8aa3b, v42
	v_mul_f32_e32 v43, 0xbfb8aa3b, v43
	v_exp_f32_e32 v42, v42
	v_exp_f32_e32 v43, v43
	v_add_f32_e32 v42, 1.0, v42
	v_add_f32_e32 v43, 1.0, v43
	v_rcp_f32_e32 v42, v42
	v_rcp_f32_e32 v43, v43
	s_nop 0
	v_pk_mul_f32 v[48:49], v[48:49], v[42:43]
	v_mul_f32_e32 v42, 0x3d372713, v45
	v_mul_f32_e32 v42, v45, v42
	v_fma_f32 v42, v45, v42, v45
	v_mul_f32_e32 v42, 0x3f4c422a, v42
	v_add_f32_e32 v42, v42, v42
	v_mul_f32_e32 v42, 0xbfb8aa3b, v42
	v_exp_f32_e32 v42, v42
	v_cvt_pk_bf16_f32 v43, v48, v49
	v_add_f32_e32 v42, 1.0, v42
	v_rcp_f32_e32 v55, v42
	v_cvt_pk_bf16_f32 v42, v46, v47
	v_lshl_add_u64 v[46:47], v[50:51], 0, v[122:123]
	v_pk_mul_f32 v[54:55], v[44:45], v[54:55]
	v_cvt_pk_bf16_f32 v44, v52, v53
	v_cvt_pk_bf16_f32 v45, v54, v55
	global_store_dwordx4 v[46:47], v[42:45], off
	s_nop 1
	v_mul_f32_e32 v43, 0x3d372713, v34
	v_mul_f32_e32 v43, v34, v43
	v_fma_f32 v43, v34, v43, v34
; DEVI float sigmoidf_(float x) { return __builtin_amdgcn_rcpf(1.f + __expf(-x)); }
; DEVI float siluf_(float x) { return x * __builtin_amdgcn_rcpf(1.f + __expf(-x)); }
; DEVI float logsigf_(float x) { return fminf(x, 0.f) - __logf(1.f + __expf(-fabsf(x))); }
	v_mul_f32_e32 v43, 0x3f4c422a, v43
	v_add_f32_e32 v43, v43, v43
	v_mul_f32_e32 v43, 0xbfb8aa3b, v43
	v_exp_f32_e32 v43, v43
	v_mul_f32_e32 v42, 0x3d372713, v38
	v_mul_f32_e32 v42, v38, v42
	v_fma_f32 v42, v38, v42, v38
	v_add_f32_e32 v43, 1.0, v43
	v_rcp_f32_e32 v44, v43
	v_mul_f32_e32 v43, 0x3d372713, v39
	v_mul_f32_e32 v43, v39, v43
	v_fma_f32 v43, v39, v43, v39
	v_mul_f32_e32 v42, 0x3f4c422a, v42
	v_mul_f32_e32 v43, 0x3f4c422a, v43
	v_add_f32_e32 v42, v42, v42
	v_add_f32_e32 v43, v43, v43
	v_mul_f32_e32 v42, 0xbfb8aa3b, v42
	v_mul_f32_e32 v43, 0xbfb8aa3b, v43
	v_exp_f32_e32 v42, v42
	v_exp_f32_e32 v43, v43
	v_add_f32_e32 v42, 1.0, v42
	v_add_f32_e32 v43, 1.0, v43
	v_rcp_f32_e32 v42, v42
	v_rcp_f32_e32 v43, v43
	s_nop 0
	v_pk_mul_f32 v[38:39], v[38:39], v[42:43]
	v_mul_f32_e32 v42, 0x3d372713, v35
	v_mul_f32_e32 v42, v35, v42
	v_fma_f32 v42, v35, v42, v35
	v_mul_f32_e32 v42, 0x3f4c422a, v42
	v_add_f32_e32 v42, v42, v42
	v_mul_f32_e32 v42, 0xbfb8aa3b, v42
	v_exp_f32_e32 v42, v42
	s_nop 0
	v_add_f32_e32 v42, 1.0, v42
	v_rcp_f32_e32 v45, v42
	s_nop 0
	v_pk_mul_f32 v[42:43], v[34:35], v[44:45]
	v_mul_f32_e32 v35, 0x3d372713, v36
	v_mul_f32_e32 v35, v36, v35
	v_fma_f32 v35, v36, v35, v36
	v_mul_f32_e32 v35, 0x3f4c422a, v35
	v_add_f32_e32 v35, v35, v35
	v_mul_f32_e32 v35, 0xbfb8aa3b, v35
	v_exp_f32_e32 v35, v35
	v_mul_f32_e32 v34, 0x3d372713, v40
	v_mul_f32_e32 v34, v40, v34
	v_fma_f32 v34, v40, v34, v40
	v_add_f32_e32 v35, 1.0, v35
	v_rcp_f32_e32 v44, v35
	v_mul_f32_e32 v35, 0x3d372713, v41
	v_mul_f32_e32 v35, v41, v35
	v_fma_f32 v35, v41, v35, v41
	v_mul_f32_e32 v34, 0x3f4c422a, v34
	v_mul_f32_e32 v35, 0x3f4c422a, v35
	v_add_f32_e32 v34, v34, v34
	v_add_f32_e32 v35, v35, v35
	v_mul_f32_e32 v34, 0xbfb8aa3b, v34
	v_mul_f32_e32 v35, 0xbfb8aa3b, v35
	v_exp_f32_e32 v34, v34
	v_exp_f32_e32 v35, v35
	v_add_f32_e32 v34, 1.0, v34
	v_add_f32_e32 v35, 1.0, v35
	v_rcp_f32_e32 v34, v34
	v_rcp_f32_e32 v35, v35
	s_nop 0
	v_pk_mul_f32 v[40:41], v[40:41], v[34:35]
	v_mul_f32_e32 v34, 0x3d372713, v37
	v_mul_f32_e32 v34, v37, v34
	v_fma_f32 v34, v37, v34, v37
	v_mul_f32_e32 v34, 0x3f4c422a, v34
	v_add_f32_e32 v34, v34, v34
	v_mul_f32_e32 v34, 0xbfb8aa3b, v34
	v_exp_f32_e32 v34, v34
	v_cvt_pk_bf16_f32 v35, v40, v41
	v_add_f32_e32 v34, 1.0, v34
	v_rcp_f32_e32 v45, v34
	v_cvt_pk_bf16_f32 v34, v38, v39
	v_lshl_add_u64 v[38:39], v[50:51], 0, v[114:115]
	v_pk_mul_f32 v[44:45], v[36:37], v[44:45]
	v_cvt_pk_bf16_f32 v36, v42, v43
	v_cvt_pk_bf16_f32 v37, v44, v45
	global_store_dwordx4 v[38:39], v[34:37], off
	s_nop 1
	v_mul_f32_e32 v37, 0x3d372713, v26
	v_mul_f32_e32 v37, v26, v37
	v_fma_f32 v37, v26, v37, v26
	v_mul_f32_e32 v37, 0x3f4c422a, v37
	v_add_f32_e32 v37, v37, v37
	v_mul_f32_e32 v37, 0xbfb8aa3b, v37
	v_exp_f32_e32 v37, v37
	v_mul_f32_e32 v36, 0x3d372713, v30
	v_mul_f32_e32 v36, v30, v36
	v_fma_f32 v36, v30, v36, v30
	v_add_f32_e32 v37, 1.0, v37
	v_rcp_f32_e32 v38, v37
	v_mul_f32_e32 v37, 0x3d372713, v31
	v_mul_f32_e32 v37, v31, v37
	v_fma_f32 v37, v31, v37, v31
	v_mul_f32_e32 v36, 0x3f4c422a, v36
	v_mul_f32_e32 v37, 0x3f4c422a, v37
	v_add_f32_e32 v36, v36, v36
	v_add_f32_e32 v37, v37, v37
	v_mul_f32_e32 v36, 0xbfb8aa3b, v36
	v_mul_f32_e32 v37, 0xbfb8aa3b, v37
	v_exp_f32_e32 v36, v36
	v_exp_f32_e32 v37, v37
	v_lshl_add_u64 v[34:35], v[142:143], 0, s[0:1]
	s_mov_b64 s[0:1], 0xb00000
	v_add_f32_e32 v36, 1.0, v36
	v_add_f32_e32 v37, 1.0, v37
	v_rcp_f32_e32 v36, v36
	v_rcp_f32_e32 v37, v37
	s_nop 0
	v_pk_mul_f32 v[30:31], v[30:31], v[36:37]
	v_mul_f32_e32 v36, 0x3d372713, v27
	v_mul_f32_e32 v36, v27, v36
	v_fma_f32 v36, v27, v36, v27
	v_mul_f32_e32 v36, 0x3f4c422a, v36
	v_add_f32_e32 v36, v36, v36
	v_mul_f32_e32 v36, 0xbfb8aa3b, v36
	v_exp_f32_e32 v36, v36
	s_nop 0
	v_add_f32_e32 v36, 1.0, v36
	v_rcp_f32_e32 v39, v36
	s_nop 0
	v_pk_mul_f32 v[36:37], v[26:27], v[38:39]
	v_mul_f32_e32 v27, 0x3d372713, v28
	v_mul_f32_e32 v27, v28, v27
	v_fma_f32 v27, v28, v27, v28
	v_mul_f32_e32 v27, 0x3f4c422a, v27
	v_add_f32_e32 v27, v27, v27
	v_mul_f32_e32 v27, 0xbfb8aa3b, v27
	v_exp_f32_e32 v27, v27
	v_mul_f32_e32 v26, 0x3d372713, v32
	v_mul_f32_e32 v26, v32, v26
	v_fma_f32 v26, v32, v26, v32
	v_add_f32_e32 v27, 1.0, v27
	v_rcp_f32_e32 v38, v27
	v_mul_f32_e32 v27, 0x3d372713, v33
	v_mul_f32_e32 v27, v33, v27
	v_fma_f32 v27, v33, v27, v33
	v_mul_f32_e32 v26, 0x3f4c422a, v26
	v_mul_f32_e32 v27, 0x3f4c422a, v27
	v_add_f32_e32 v26, v26, v26
	v_add_f32_e32 v27, v27, v27
	v_mul_f32_e32 v26, 0xbfb8aa3b, v26
	v_mul_f32_e32 v27, 0xbfb8aa3b, v27
	v_exp_f32_e32 v26, v26
	v_exp_f32_e32 v27, v27
	v_add_f32_e32 v26, 1.0, v26
	v_add_f32_e32 v27, 1.0, v27
	v_rcp_f32_e32 v26, v26
	v_rcp_f32_e32 v27, v27
	s_nop 0
	v_pk_mul_f32 v[32:33], v[32:33], v[26:27]
	v_mul_f32_e32 v26, 0x3d372713, v29
	v_mul_f32_e32 v26, v29, v26
	v_fma_f32 v26, v29, v26, v29
	v_mul_f32_e32 v26, 0x3f4c422a, v26
	v_add_f32_e32 v26, v26, v26
	v_mul_f32_e32 v26, 0xbfb8aa3b, v26
	v_exp_f32_e32 v26, v26
	v_cvt_pk_bf16_f32 v27, v32, v33
	v_add_f32_e32 v26, 1.0, v26
	v_rcp_f32_e32 v39, v26
	v_cvt_pk_bf16_f32 v26, v30, v31
	v_lshl_add_u64 v[30:31], v[34:35], 0, v[122:123]
	v_pk_mul_f32 v[38:39], v[28:29], v[38:39]
	v_cvt_pk_bf16_f32 v28, v36, v37
	v_cvt_pk_bf16_f32 v29, v38, v39
	global_store_dwordx4 v[30:31], v[26:29], off
	s_nop 1
	v_mul_f32_e32 v27, 0x3d372713, v18
	v_mul_f32_e32 v27, v18, v27
	v_fma_f32 v27, v18, v27, v18
	v_mul_f32_e32 v27, 0x3f4c422a, v27
	v_add_f32_e32 v27, v27, v27
	v_mul_f32_e32 v27, 0xbfb8aa3b, v27
	v_exp_f32_e32 v27, v27
	v_mul_f32_e32 v26, 0x3d372713, v22
	v_mul_f32_e32 v26, v22, v26
	v_fma_f32 v26, v22, v26, v22
	v_add_f32_e32 v27, 1.0, v27
	v_rcp_f32_e32 v28, v27
	v_mul_f32_e32 v27, 0x3d372713, v23
; DEVI float sigmoidf_(float x) { return __builtin_amdgcn_rcpf(1.f + __expf(-x)); }
; DEVI float siluf_(float x) { return x * __builtin_amdgcn_rcpf(1.f + __expf(-x)); }
; DEVI float logsigf_(float x) { return fminf(x, 0.f) - __logf(1.f + __expf(-fabsf(x))); }
	v_mul_f32_e32 v27, v23, v27
	v_fma_f32 v27, v23, v27, v23
	v_mul_f32_e32 v26, 0x3f4c422a, v26
	v_mul_f32_e32 v27, 0x3f4c422a, v27
	v_add_f32_e32 v26, v26, v26
	v_add_f32_e32 v27, v27, v27
	v_mul_f32_e32 v26, 0xbfb8aa3b, v26
	v_mul_f32_e32 v27, 0xbfb8aa3b, v27
	v_exp_f32_e32 v26, v26
	v_exp_f32_e32 v27, v27
	v_add_f32_e32 v26, 1.0, v26
	v_add_f32_e32 v27, 1.0, v27
	v_rcp_f32_e32 v26, v26
	v_rcp_f32_e32 v27, v27
	s_nop 0
	v_pk_mul_f32 v[22:23], v[22:23], v[26:27]
	v_mul_f32_e32 v26, 0x3d372713, v19
	v_mul_f32_e32 v26, v19, v26
	v_fma_f32 v26, v19, v26, v19
	v_mul_f32_e32 v26, 0x3f4c422a, v26
	v_add_f32_e32 v26, v26, v26
	v_mul_f32_e32 v26, 0xbfb8aa3b, v26
	v_exp_f32_e32 v26, v26
	s_nop 0
	v_add_f32_e32 v26, 1.0, v26
	v_rcp_f32_e32 v29, v26
	s_nop 0
	v_pk_mul_f32 v[26:27], v[18:19], v[28:29]
	v_mul_f32_e32 v19, 0x3d372713, v20
	v_mul_f32_e32 v19, v20, v19
	v_fma_f32 v19, v20, v19, v20
	v_mul_f32_e32 v19, 0x3f4c422a, v19
	v_add_f32_e32 v19, v19, v19
	v_mul_f32_e32 v19, 0xbfb8aa3b, v19
	v_exp_f32_e32 v19, v19
	v_mul_f32_e32 v18, 0x3d372713, v24
	v_mul_f32_e32 v18, v24, v18
	v_fma_f32 v18, v24, v18, v24
	v_add_f32_e32 v19, 1.0, v19
	v_rcp_f32_e32 v28, v19
	v_mul_f32_e32 v19, 0x3d372713, v25
	v_mul_f32_e32 v19, v25, v19
	v_fma_f32 v19, v25, v19, v25
	v_mul_f32_e32 v18, 0x3f4c422a, v18
	v_mul_f32_e32 v19, 0x3f4c422a, v19
	v_add_f32_e32 v18, v18, v18
	v_add_f32_e32 v19, v19, v19
	v_mul_f32_e32 v18, 0xbfb8aa3b, v18
	v_mul_f32_e32 v19, 0xbfb8aa3b, v19
	v_exp_f32_e32 v18, v18
	v_exp_f32_e32 v19, v19
	v_add_f32_e32 v18, 1.0, v18
	v_add_f32_e32 v19, 1.0, v19
	v_rcp_f32_e32 v18, v18
	v_rcp_f32_e32 v19, v19
	s_nop 0
	v_pk_mul_f32 v[24:25], v[24:25], v[18:19]
	v_mul_f32_e32 v18, 0x3d372713, v21
	v_mul_f32_e32 v18, v21, v18
	v_fma_f32 v18, v21, v18, v21
	v_mul_f32_e32 v18, 0x3f4c422a, v18
	v_add_f32_e32 v18, v18, v18
	v_mul_f32_e32 v18, 0xbfb8aa3b, v18
	v_exp_f32_e32 v18, v18
	v_cvt_pk_bf16_f32 v19, v24, v25
	v_add_f32_e32 v18, 1.0, v18
	v_rcp_f32_e32 v29, v18
	v_cvt_pk_bf16_f32 v18, v22, v23
	v_lshl_add_u64 v[22:23], v[34:35], 0, v[114:115]
	v_pk_mul_f32 v[28:29], v[20:21], v[28:29]
	v_cvt_pk_bf16_f32 v20, v26, v27
	v_cvt_pk_bf16_f32 v21, v28, v29
	global_store_dwordx4 v[22:23], v[18:21], off
	s_nop 1
	v_mul_f32_e32 v21, 0x3d372713, v10
	v_mul_f32_e32 v21, v10, v21
	v_fma_f32 v21, v10, v21, v10
	v_mul_f32_e32 v21, 0x3f4c422a, v21
	v_add_f32_e32 v21, v21, v21
	v_mul_f32_e32 v21, 0xbfb8aa3b, v21
	v_exp_f32_e32 v21, v21
	v_mul_f32_e32 v20, 0x3d372713, v14
	v_mul_f32_e32 v20, v14, v20
	v_fma_f32 v20, v14, v20, v14
	v_add_f32_e32 v21, 1.0, v21
	v_rcp_f32_e32 v22, v21
	v_mul_f32_e32 v21, 0x3d372713, v15
	v_mul_f32_e32 v21, v15, v21
	v_fma_f32 v21, v15, v21, v15
	v_mul_f32_e32 v20, 0x3f4c422a, v20
	v_mul_f32_e32 v21, 0x3f4c422a, v21
	v_add_f32_e32 v20, v20, v20
	v_add_f32_e32 v21, v21, v21
	v_mul_f32_e32 v20, 0xbfb8aa3b, v20
	v_mul_f32_e32 v21, 0xbfb8aa3b, v21
	v_exp_f32_e32 v20, v20
	v_exp_f32_e32 v21, v21
	v_lshl_add_u64 v[18:19], v[142:143], 0, s[0:1]
	s_mov_b32 s0, s8
	v_add_f32_e32 v20, 1.0, v20
	v_add_f32_e32 v21, 1.0, v21
	v_rcp_f32_e32 v20, v20
	v_rcp_f32_e32 v21, v21
	s_mov_b32 s1, s9
	v_pk_mul_f32 v[14:15], v[14:15], v[20:21]
	v_mul_f32_e32 v20, 0x3d372713, v11
	v_mul_f32_e32 v20, v11, v20
	v_fma_f32 v20, v11, v20, v11
	v_mul_f32_e32 v20, 0x3f4c422a, v20
	v_add_f32_e32 v20, v20, v20
	v_mul_f32_e32 v20, 0xbfb8aa3b, v20
	v_exp_f32_e32 v20, v20
	s_nop 0
	v_add_f32_e32 v20, 1.0, v20
	v_rcp_f32_e32 v23, v20
	s_nop 0
	v_pk_mul_f32 v[20:21], v[10:11], v[22:23]
	v_mul_f32_e32 v11, 0x3d372713, v12
	v_mul_f32_e32 v11, v12, v11
	v_fma_f32 v11, v12, v11, v12
	v_mul_f32_e32 v11, 0x3f4c422a, v11
	v_add_f32_e32 v11, v11, v11
	v_mul_f32_e32 v11, 0xbfb8aa3b, v11
	v_exp_f32_e32 v11, v11
	v_mul_f32_e32 v10, 0x3d372713, v16
; #define PG8_WAIT_V(n) asm volatile("s_waitcnt vmcnt(" #n ")" ::: "memory")
; #define PG8_BAR __builtin_amdgcn_s_barrier()
; template <class Epi>
; DEVI void gemm_phase(LAS unsigned char* lds, const Gemm g, const Epi& E) {
;     ...
;         if (!has_next) break;
; #pragma unroll
;         for (int a = 0; a < 2; ++a)
; #pragma unroll
;             for (int b = 0; b < 2; ++b)
; #pragma unroll
;                 for (int m = 0; m < 4; ++m)
; #pragma unroll
;                     for (int n = 0; n < 2; ++n) acc[a][b][m][n] = (f32x4){0.f, 0.f, 0.f, 0.f};
;         cur = nxt; cA = nA; cB = nB; ++ui;
;     }
;     PG8_WAIT_V(0);
;     if (wr == 0) PG8_BAR;
;     PG8_BAR;
	v_mul_f32_e32 v10, v16, v10
	v_fma_f32 v10, v16, v10, v16
	v_add_f32_e32 v11, 1.0, v11
	v_rcp_f32_e32 v22, v11
	v_mul_f32_e32 v11, 0x3d372713, v17
	v_mul_f32_e32 v11, v17, v11
	v_fma_f32 v11, v17, v11, v17
	v_mul_f32_e32 v10, 0x3f4c422a, v10
	v_mul_f32_e32 v11, 0x3f4c422a, v11
	v_add_f32_e32 v10, v10, v10
	v_add_f32_e32 v11, v11, v11
	v_mul_f32_e32 v10, 0xbfb8aa3b, v10
	v_mul_f32_e32 v11, 0xbfb8aa3b, v11
	v_exp_f32_e32 v10, v10
	v_exp_f32_e32 v11, v11
	v_add_f32_e32 v10, 1.0, v10
	v_add_f32_e32 v11, 1.0, v11
	v_rcp_f32_e32 v10, v10
	v_rcp_f32_e32 v11, v11
	s_nop 0
	v_pk_mul_f32 v[16:17], v[16:17], v[10:11]
	v_mul_f32_e32 v10, 0x3d372713, v13
	v_mul_f32_e32 v10, v13, v10
	v_fma_f32 v10, v13, v10, v13
	v_mul_f32_e32 v10, 0x3f4c422a, v10
	v_add_f32_e32 v10, v10, v10
	v_mul_f32_e32 v10, 0xbfb8aa3b, v10
	v_exp_f32_e32 v10, v10
	v_cvt_pk_bf16_f32 v11, v16, v17
	v_add_f32_e32 v10, 1.0, v10
	v_rcp_f32_e32 v23, v10
	v_cvt_pk_bf16_f32 v10, v14, v15
	v_lshl_add_u64 v[14:15], v[18:19], 0, v[122:123]
	v_pk_mul_f32 v[22:23], v[12:13], v[22:23]
	v_cvt_pk_bf16_f32 v12, v20, v21
	v_cvt_pk_bf16_f32 v13, v22, v23
	global_store_dwordx4 v[14:15], v[10:13], off
	s_nop 1
	v_mul_f32_e32 v11, 0x3d372713, v0
	v_mul_f32_e32 v11, v0, v11
	v_fma_f32 v11, v0, v11, v0
	v_mul_f32_e32 v11, 0x3f4c422a, v11
	v_add_f32_e32 v11, v11, v11
	v_mul_f32_e32 v11, 0xbfb8aa3b, v11
	v_exp_f32_e32 v11, v11
	v_mul_f32_e32 v10, 0x3d372713, v4
	v_mul_f32_e32 v10, v4, v10
	v_fma_f32 v10, v4, v10, v4
	v_add_f32_e32 v11, 1.0, v11
	v_rcp_f32_e32 v12, v11
	v_mul_f32_e32 v11, 0x3d372713, v5
	v_mul_f32_e32 v11, v5, v11
	v_fma_f32 v11, v5, v11, v5
	v_mul_f32_e32 v10, 0x3f4c422a, v10
	v_mul_f32_e32 v11, 0x3f4c422a, v11
	v_add_f32_e32 v10, v10, v10
	v_add_f32_e32 v11, v11, v11
	v_mul_f32_e32 v10, 0xbfb8aa3b, v10
	v_mul_f32_e32 v11, 0xbfb8aa3b, v11
	v_exp_f32_e32 v10, v10
	v_exp_f32_e32 v11, v11
	v_add_f32_e32 v10, 1.0, v10
	v_add_f32_e32 v11, 1.0, v11
	v_rcp_f32_e32 v10, v10
	v_rcp_f32_e32 v11, v11
	s_nop 0
	v_pk_mul_f32 v[4:5], v[4:5], v[10:11]
	v_mul_f32_e32 v10, 0x3d372713, v1
	v_mul_f32_e32 v10, v1, v10
	v_fma_f32 v10, v1, v10, v1
	v_mul_f32_e32 v10, 0x3f4c422a, v10
	v_add_f32_e32 v10, v10, v10
	v_mul_f32_e32 v10, 0xbfb8aa3b, v10
	v_exp_f32_e32 v10, v10
	s_nop 0
	v_add_f32_e32 v10, 1.0, v10
	v_rcp_f32_e32 v13, v10
	s_nop 0
	v_pk_mul_f32 v[10:11], v[0:1], v[12:13]
	v_mul_f32_e32 v1, 0x3d372713, v2
	v_mul_f32_e32 v1, v2, v1
	v_fma_f32 v1, v2, v1, v2
	v_mul_f32_e32 v1, 0x3f4c422a, v1
	v_add_f32_e32 v1, v1, v1
	v_mul_f32_e32 v1, 0xbfb8aa3b, v1
	v_exp_f32_e32 v1, v1
	v_mul_f32_e32 v0, 0x3d372713, v6
	v_mul_f32_e32 v0, v6, v0
	v_fma_f32 v0, v6, v0, v6
	v_add_f32_e32 v1, 1.0, v1
	v_rcp_f32_e32 v12, v1
	v_mul_f32_e32 v1, 0x3d372713, v7
	v_mul_f32_e32 v1, v7, v1
	v_fma_f32 v1, v7, v1, v7
	v_mul_f32_e32 v0, 0x3f4c422a, v0
	v_mul_f32_e32 v1, 0x3f4c422a, v1
	v_add_f32_e32 v0, v0, v0
	v_add_f32_e32 v1, v1, v1
	v_mul_f32_e32 v0, 0xbfb8aa3b, v0
	v_mul_f32_e32 v1, 0xbfb8aa3b, v1
	v_exp_f32_e32 v0, v0
	v_exp_f32_e32 v1, v1
	v_add_f32_e32 v0, 1.0, v0
	v_add_f32_e32 v1, 1.0, v1
	v_rcp_f32_e32 v0, v0
	v_rcp_f32_e32 v1, v1
	s_nop 0
	v_pk_mul_f32 v[6:7], v[6:7], v[0:1]
	v_mul_f32_e32 v0, 0x3d372713, v3
	v_mul_f32_e32 v0, v3, v0
	v_fma_f32 v0, v3, v0, v3
	v_mul_f32_e32 v0, 0x3f4c422a, v0
	v_add_f32_e32 v0, v0, v0
	v_mul_f32_e32 v0, 0xbfb8aa3b, v0
	v_exp_f32_e32 v0, v0
	v_cvt_pk_bf16_f32 v1, v6, v7
	v_add_f32_e32 v0, 1.0, v0
	v_rcp_f32_e32 v13, v0
	v_cvt_pk_bf16_f32 v0, v4, v5
	v_lshl_add_u64 v[4:5], v[18:19], 0, v[114:115]
	v_pk_mul_f32 v[12:13], v[2:3], v[12:13]
	v_cvt_pk_bf16_f32 v2, v10, v11
	v_cvt_pk_bf16_f32 v3, v12, v13
	global_store_dwordx4 v[4:5], v[0:3], off
	s_cbranch_vccz .LBB0_1271
	s_waitcnt vmcnt(0)
	s_cmpk_gt_u32 s36, 0xff
	s_cbranch_scc1 .LBB0_1282
	s_barrier

; #define PG8_STAGE(bufoff, gbase, voff) do { _Pragma("unroll") for (int _i = 0; _i < 2; ++_i) \
;         __builtin_amdgcn_global_load_lds((const unsigned*)((const char*)(gbase) + (voff)[_i]), (LAS unsigned*)(lds + (bufoff) + ldsw + _i * 8192), 16, 0, 0); } while (0)
; #define PG8_LDA(dst, b, h) do { _Pragma("unroll") for (int m = 0; m < 4; ++m) _Pragma("unroll") for (int k = 0; k < 2; ++k) dst[m][k] = *(const LAS bf16x8*)(lds + PG8_SA(b, h) + aoff + m * 2048 + k * 1024); } while (0)
; #define PG8_LDB(dst, b, h) do { _Pragma("unroll") for (int n = 0; n < 2; ++n) _Pragma("unroll") for (int k = 0; k < 2; ++k) dst[n][k] = *(const LAS bf16x8*)(lds + PG8_SB(b, h) + boff + n * 2048 + k * 1024); } while (0)
; #define PG8_MMA(ai, bj, At, Bt) do { __builtin_amdgcn_s_setprio(1); _Pragma("unroll") for (int m = 0; m < 4; ++m) _Pragma("unroll") for (int n = 0; n < 2; ++n) _Pragma("unroll") for (int k = 0; k < 2; ++k) \
;         acc[ai][bj][m][n] = __builtin_amdgcn_mfma_f32_16x16x32_bf16(Bt[n][k], At[m][k], acc[ai][bj][m][n], 0, 0, 0); __builtin_amdgcn_s_setprio(0); } while (0)
; template <class Epi>
; DEVI void gemm_phase(LAS unsigned char* lds, const Gemm g, const Epi& E) {
;     ...
;         for (int t = 0; t < nt; t += 2) {
;             const bool last = (t == nt - 2);
;             const char* a1 = cA + (size_t)(t + 1) * kstep;
;             const char* a2 = last ? nA : cA + (size_t)(t + 2) * kstep; const char* b2 = last ? nB : cB + (size_t)(t + 2) * kstep;
;             const char* a3 = a2 + kstep; const char* b3 = b2 + kstep;
;             PG8_LDB(B0, 0, 0); PG8_SCHED; PG8_LDA(At, 0, 0); PG8_STAGE(PG8_SA(1, 1), a1 + hstepA, voffA);
;             PG8_WAIT_L(8); PG8_BAR; PG8_WAIT_L(0); PG8_MMA(0, 0, At, B0); PG8_BAR; PG8_SCHED;
;             PG8_LDB(B1, 0, 1); PG8_STAGE(PG8_SB(0, 0), b2, voffB);
;             PG8_BAR; PG8_WAIT_L(0); PG8_MMA(0, 1, At, B1); PG8_BAR;
;             PG8_LDA(At, 0, 1); PG8_STAGE(PG8_SA(0, 0), a2, voffA);
;             PG8_BAR; PG8_WAIT_L(0); PG8_MMA(1, 0, At, B0); PG8_BAR; PG8_SCHED;
;             PG8_STAGE(PG8_SB(0, 1), b2 + hstepB, voffB);
;             PG8_WAIT_V(6); PG8_BAR; PG8_MMA(1, 1, At, B1); PG8_BAR;
;             PG8_LDB(B0, 1, 0); PG8_SCHED; PG8_LDA(At, 1, 0); PG8_STAGE(PG8_SA(0, 1), a2 + hstepA, voffA);
;             PG8_WAIT_L(8); PG8_BAR; PG8_WAIT_L(0); PG8_MMA(0, 0, At, B0); PG8_BAR; PG8_SCHED;
.LBB0_1346:
	s_add_u32 s14, s12, 0xfffc0080
	s_addc_u32 s15, s13, -1
	s_add_i32 s38, 0, 0x10000
	v_add_u32_e32 v152, s38, v185
	ds_read_b128 v[114:117], v152
	ds_read_b128 v[126:129], v152 offset:1024
	ds_read_b128 v[130:133], v152 offset:2048
	ds_read_b128 v[176:179], v152 offset:3072
	s_cmp_eq_u32 s27, 12
	s_cselect_b32 s17, s1, s15
	s_cselect_b32 s16, s3, s14
	s_cselect_b32 s15, s5, s26
	s_cselect_b32 s14, s18, s19
	v_lshl_add_u64 v[152:153], s[12:13], 0, v[148:149]
	s_add_i32 m0, s11, 0xc000
	ds_read_b128 v[180:183], v187
	ds_read_b128 v[188:191], v187 offset:1024
	ds_read_b128 v[192:195], v187 offset:2048
	ds_read_b128 v[196:199], v187 offset:3072
	ds_read_b128 v[200:203], v187 offset:4096
	ds_read_b128 v[204:207], v187 offset:5120
	ds_read_b128 v[214:217], v187 offset:6144
	ds_read_b128 v[218:221], v187 offset:7168
	global_load_lds_dwordx4 v[152:153], off
	v_lshl_add_u64 v[152:153], s[12:13], 0, v[150:151]
	s_add_i32 m0, s11, 0xe000
	s_nop 0
	global_load_lds_dwordx4 v[152:153], off
	s_waitcnt lgkmcnt(8)
	s_barrier
	s_waitcnt lgkmcnt(0)
	v_mfma_f32_16x16x32_bf16 v[138:141], v[114:117], v[180:183], v[138:141]
	v_mfma_f32_16x16x32_bf16 v[134:137], v[130:133], v[180:183], v[134:137]
	v_mfma_f32_16x16x32_bf16 v[110:113], v[114:117], v[192:195], v[110:113]
	v_mfma_f32_16x16x32_bf16 v[106:109], v[130:133], v[192:195], v[106:109]
	v_mfma_f32_16x16x32_bf16 v[94:97], v[114:117], v[200:203], v[94:97]
	v_mfma_f32_16x16x32_bf16 v[90:93], v[130:133], v[200:203], v[90:93]
	v_mfma_f32_16x16x32_bf16 v[78:81], v[114:117], v[214:217], v[78:81]
	v_mfma_f32_16x16x32_bf16 v[74:77], v[130:133], v[214:217], v[74:77]
	v_mfma_f32_16x16x32_bf16 v[138:141], v[126:129], v[188:191], v[138:141]
	v_mfma_f32_16x16x32_bf16 v[134:137], v[176:179], v[188:191], v[134:137]
	v_mfma_f32_16x16x32_bf16 v[110:113], v[126:129], v[196:199], v[110:113]
	v_mfma_f32_16x16x32_bf16 v[106:109], v[176:179], v[196:199], v[106:109]
	v_mfma_f32_16x16x32_bf16 v[94:97], v[126:129], v[204:207], v[94:97]
	v_mfma_f32_16x16x32_bf16 v[90:93], v[176:179], v[204:207], v[90:93]
	v_mfma_f32_16x16x32_bf16 v[78:81], v[126:129], v[218:221], v[78:81]
	v_mfma_f32_16x16x32_bf16 v[74:77], v[176:179], v[218:221], v[74:77]
	s_barrier
	s_add_i32 s40, 0, 0x14000
	v_add_u32_e32 v152, s40, v185
	s_add_i32 s38, s38, s47
	ds_read_b128 v[222:225], v152
	ds_read_b128 v[226:229], v152 offset:1024
	ds_read_b128 v[230:233], v152 offset:2048
	ds_read_b128 v[234:237], v152 offset:3072
	v_lshl_add_u64 v[152:153], s[14:15], 0, v[8:9]
	s_mov_b32 m0, s38
	v_lshl_add_u64 v[162:163], s[14:15], 0, v[146:147]
	global_load_lds_dwordx4 v[152:153], off
	s_add_i32 m0, s38, 0x2000
	s_nop 0
	global_load_lds_dwordx4 v[162:163], off
	s_barrier
	s_waitcnt lgkmcnt(0)
	v_mfma_f32_16x16x32_bf16 v[122:125], v[222:225], v[180:183], v[122:125]
	v_mfma_f32_16x16x32_bf16 v[118:121], v[230:233], v[180:183], v[118:121]
	v_mfma_f32_16x16x32_bf16 v[102:105], v[222:225], v[192:195], v[102:105]
	v_mfma_f32_16x16x32_bf16 v[98:101], v[230:233], v[192:195], v[98:101]
	v_mfma_f32_16x16x32_bf16 v[86:89], v[222:225], v[200:203], v[86:89]
	v_mfma_f32_16x16x32_bf16 v[82:85], v[230:233], v[200:203], v[82:85]
	v_mfma_f32_16x16x32_bf16 v[70:73], v[222:225], v[214:217], v[70:73]
	v_mfma_f32_16x16x32_bf16 v[66:69], v[230:233], v[214:217], v[66:69]
	v_mfma_f32_16x16x32_bf16 v[122:125], v[226:229], v[188:191], v[122:125]
	v_mfma_f32_16x16x32_bf16 v[118:121], v[234:237], v[188:191], v[118:121]
	v_mfma_f32_16x16x32_bf16 v[102:105], v[226:229], v[196:199], v[102:105]
	v_mfma_f32_16x16x32_bf16 v[98:101], v[234:237], v[196:199], v[98:101]
	v_mfma_f32_16x16x32_bf16 v[86:89], v[226:229], v[204:207], v[86:89]
	v_mfma_f32_16x16x32_bf16 v[82:85], v[234:237], v[204:207], v[82:85]
	v_mfma_f32_16x16x32_bf16 v[70:73], v[226:229], v[218:221], v[70:73]
	v_mfma_f32_16x16x32_bf16 v[66:69], v[234:237], v[218:221], v[66:69]
	s_mov_b32 m0, s11
	v_lshl_add_u64 v[164:165], s[16:17], 0, v[142:143]
	s_barrier
	ds_read_b128 v[180:183], v187 offset:16384
	ds_read_b128 v[188:191], v187 offset:17408
	ds_read_b128 v[192:195], v187 offset:18432
	ds_read_b128 v[196:199], v187 offset:19456
	ds_read_b128 v[200:203], v187 offset:20480
	ds_read_b128 v[204:207], v187 offset:21504
	ds_read_b128 v[214:217], v187 offset:22528
	ds_read_b128 v[218:221], v187 offset:23552
	global_load_lds_dwordx4 v[164:165], off
	v_lshl_add_u64 v[208:209], s[16:17], 0, v[144:145]
	s_mov_b32 m0, s66
	s_nop 0
	global_load_lds_dwordx4 v[208:209], off
	s_barrier
	s_waitcnt lgkmcnt(0)
	v_mfma_f32_16x16x32_bf16 v[62:65], v[114:117], v[180:183], v[62:65]
	v_mfma_f32_16x16x32_bf16 v[58:61], v[130:133], v[180:183], v[58:61]
	v_mfma_f32_16x16x32_bf16 v[46:49], v[114:117], v[192:195], v[46:49]
	v_mfma_f32_16x16x32_bf16 v[42:45], v[130:133], v[192:195], v[42:45]
	v_mfma_f32_16x16x32_bf16 v[30:33], v[114:117], v[200:203], v[30:33]
	v_mfma_f32_16x16x32_bf16 v[26:29], v[130:133], v[200:203], v[26:29]
	v_mfma_f32_16x16x32_bf16 v[14:17], v[114:117], v[214:217], v[14:17]
	v_mfma_f32_16x16x32_bf16 v[10:13], v[130:133], v[214:217], v[10:13]
	v_mfma_f32_16x16x32_bf16 v[62:65], v[126:129], v[188:191], v[62:65]
	v_mfma_f32_16x16x32_bf16 v[58:61], v[176:179], v[188:191], v[58:61]
	v_mfma_f32_16x16x32_bf16 v[46:49], v[126:129], v[196:199], v[46:49]
	v_mfma_f32_16x16x32_bf16 v[42:45], v[176:179], v[196:199], v[42:45]
	v_mfma_f32_16x16x32_bf16 v[30:33], v[126:129], v[204:207], v[30:33]
	v_mfma_f32_16x16x32_bf16 v[26:29], v[176:179], v[204:207], v[26:29]
	v_mfma_f32_16x16x32_bf16 v[14:17], v[126:129], v[218:221], v[14:17]
	v_mfma_f32_16x16x32_bf16 v[10:13], v[176:179], v[218:221], v[10:13]
	s_barrier
; #define PG8_STAGE(bufoff, gbase, voff) do { _Pragma("unroll") for (int _i = 0; _i < 2; ++_i) \
;         __builtin_amdgcn_global_load_lds((const unsigned*)((const char*)(gbase) + (voff)[_i]), (LAS unsigned*)(lds + (bufoff) + ldsw + _i * 8192), 16, 0, 0); } while (0)
; #define PG8_LDA(dst, b, h) do { _Pragma("unroll") for (int m = 0; m < 4; ++m) _Pragma("unroll") for (int k = 0; k < 2; ++k) dst[m][k] = *(const LAS bf16x8*)(lds + PG8_SA(b, h) + aoff + m * 2048 + k * 1024); } while (0)
; #define PG8_LDB(dst, b, h) do { _Pragma("unroll") for (int n = 0; n < 2; ++n) _Pragma("unroll") for (int k = 0; k < 2; ++k) dst[n][k] = *(const LAS bf16x8*)(lds + PG8_SB(b, h) + boff + n * 2048 + k * 1024); } while (0)
; #define PG8_MMA(ai, bj, At, Bt) do { __builtin_amdgcn_s_setprio(1); _Pragma("unroll") for (int m = 0; m < 4; ++m) _Pragma("unroll") for (int n = 0; n < 2; ++n) _Pragma("unroll") for (int k = 0; k < 2; ++k) \
;         acc[ai][bj][m][n] = __builtin_amdgcn_mfma_f32_16x16x32_bf16(Bt[n][k], At[m][k], acc[ai][bj][m][n], 0, 0, 0); __builtin_amdgcn_s_setprio(0); } while (0)
; #define PG8_WAIT_V(n) asm volatile("s_waitcnt vmcnt(" #n ")" ::: "memory")
; #define PG8_WAIT_L(n) asm volatile("s_waitcnt lgkmcnt(" #n ")" ::: "memory")
; #define PG8_BAR __builtin_amdgcn_s_barrier()
; #define PG8_SCHED __builtin_amdgcn_sched_barrier(0)
; template <class Epi>
; DEVI void gemm_phase(LAS unsigned char* lds, const Gemm g, const Epi& E) {
;     ...
;             PG8_STAGE(PG8_SB(0, 1), b2 + hstepB, voffB);
;             PG8_WAIT_V(6); PG8_BAR; PG8_MMA(1, 1, At, B1); PG8_BAR;
;             PG8_LDB(B0, 1, 0); PG8_SCHED; PG8_LDA(At, 1, 0); PG8_STAGE(PG8_SA(0, 1), a2 + hstepA, voffA);
;             PG8_WAIT_L(8); PG8_BAR; PG8_WAIT_L(0); PG8_MMA(0, 0, At, B0); PG8_BAR; PG8_SCHED;
;             PG8_LDB(B1, 1, 1); PG8_STAGE(PG8_SB(1, 0), b3, voffB);
;             PG8_BAR; PG8_WAIT_L(0); PG8_MMA(0, 1, At, B1); PG8_BAR;
;             PG8_LDA(At, 1, 1); PG8_STAGE(PG8_SA(1, 0), a3, voffA);
	s_add_u32 s38, s14, 0x40000
	s_addc_u32 s39, s15, 0
	s_add_i32 s40, s40, s47
	v_lshl_add_u64 v[114:115], s[38:39], 0, v[8:9]
	s_mov_b32 m0, s40
	s_nop 0
	global_load_lds_dwordx4 v[114:115], off
	v_lshl_add_u64 v[114:115], s[38:39], 0, v[146:147]
	s_add_i32 m0, s40, 0x2000
	s_nop 0
	global_load_lds_dwordx4 v[114:115], off
	s_waitcnt vmcnt(6)
	s_barrier
	v_mfma_f32_16x16x32_bf16 v[54:57], v[222:225], v[180:183], v[54:57]
	v_mfma_f32_16x16x32_bf16 v[50:53], v[230:233], v[180:183], v[50:53]
	v_mfma_f32_16x16x32_bf16 v[38:41], v[222:225], v[192:195], v[38:41]
	v_mfma_f32_16x16x32_bf16 v[34:37], v[230:233], v[192:195], v[34:37]
	v_mfma_f32_16x16x32_bf16 v[22:25], v[222:225], v[200:203], v[22:25]
	v_mfma_f32_16x16x32_bf16 v[18:21], v[230:233], v[200:203], v[18:21]
	v_mfma_f32_16x16x32_bf16 v[4:7], v[222:225], v[214:217], v[4:7]
	v_mfma_f32_16x16x32_bf16 v[0:3], v[230:233], v[214:217], v[0:3]
	v_mfma_f32_16x16x32_bf16 v[54:57], v[226:229], v[188:191], v[54:57]
	v_mfma_f32_16x16x32_bf16 v[50:53], v[234:237], v[188:191], v[50:53]
	v_mfma_f32_16x16x32_bf16 v[38:41], v[226:229], v[196:199], v[38:41]
	v_mfma_f32_16x16x32_bf16 v[34:37], v[234:237], v[196:199], v[34:37]
	v_mfma_f32_16x16x32_bf16 v[22:25], v[226:229], v[204:207], v[22:25]
	v_mfma_f32_16x16x32_bf16 v[18:21], v[234:237], v[204:207], v[18:21]
	v_mfma_f32_16x16x32_bf16 v[4:7], v[226:229], v[218:221], v[4:7]
	v_mfma_f32_16x16x32_bf16 v[0:3], v[234:237], v[218:221], v[0:3]
	s_add_i32 s38, 0, 0x18000
	v_add_u32_e32 v176, s38, v185
	s_barrier
	ds_read_b128 v[114:117], v176
	ds_read_b128 v[126:129], v176 offset:1024
	ds_read_b128 v[130:133], v176 offset:2048
	ds_read_b128 v[176:179], v176 offset:3072
	s_add_u32 s16, s16, 0x40000
	s_addc_u32 s17, s17, 0
	s_mov_b32 m0, s68
	v_lshl_add_u64 v[222:223], s[16:17], 0, v[142:143]
	ds_read_b128 v[180:183], v187 offset:32768
	ds_read_b128 v[188:191], v187 offset:33792
	ds_read_b128 v[192:195], v187 offset:34816
	ds_read_b128 v[196:199], v187 offset:35840
	ds_read_b128 v[200:203], v187 offset:36864
	ds_read_b128 v[204:207], v187 offset:37888
	ds_read_b128 v[214:217], v187 offset:38912
	ds_read_b128 v[218:221], v187 offset:39936
	global_load_lds_dwordx4 v[222:223], off
	v_lshl_add_u64 v[222:223], s[16:17], 0, v[144:145]
	s_mov_b32 m0, s69
	s_nop 0
	global_load_lds_dwordx4 v[222:223], off
	s_waitcnt lgkmcnt(8)
	s_barrier
	s_waitcnt lgkmcnt(0)
	v_mfma_f32_16x16x32_bf16 v[138:141], v[114:117], v[180:183], v[138:141]
	v_mfma_f32_16x16x32_bf16 v[134:137], v[130:133], v[180:183], v[134:137]
	v_mfma_f32_16x16x32_bf16 v[110:113], v[114:117], v[192:195], v[110:113]
	v_mfma_f32_16x16x32_bf16 v[106:109], v[130:133], v[192:195], v[106:109]
	v_mfma_f32_16x16x32_bf16 v[94:97], v[114:117], v[200:203], v[94:97]
	v_mfma_f32_16x16x32_bf16 v[90:93], v[130:133], v[200:203], v[90:93]
	v_mfma_f32_16x16x32_bf16 v[78:81], v[114:117], v[214:217], v[78:81]
	v_mfma_f32_16x16x32_bf16 v[74:77], v[130:133], v[214:217], v[74:77]
	v_mfma_f32_16x16x32_bf16 v[138:141], v[126:129], v[188:191], v[138:141]
	v_mfma_f32_16x16x32_bf16 v[134:137], v[176:179], v[188:191], v[134:137]
	v_mfma_f32_16x16x32_bf16 v[110:113], v[126:129], v[196:199], v[110:113]
	v_mfma_f32_16x16x32_bf16 v[106:109], v[176:179], v[196:199], v[106:109]
	v_mfma_f32_16x16x32_bf16 v[94:97], v[126:129], v[204:207], v[94:97]
	v_mfma_f32_16x16x32_bf16 v[90:93], v[176:179], v[204:207], v[90:93]
	v_mfma_f32_16x16x32_bf16 v[78:81], v[126:129], v[218:221], v[78:81]
	v_mfma_f32_16x16x32_bf16 v[74:77], v[176:179], v[218:221], v[74:77]
	s_barrier
	s_add_i32 s16, 0, 0x1c000
	s_add_i32 s17, s38, s47
	v_add_u32_e32 v213, s16, v185
	v_lshl_add_u64 v[152:153], v[152:153], 0, s[70:71]
	s_mov_b32 m0, s17
	ds_read_b128 v[222:225], v213
	ds_read_b128 v[226:229], v213 offset:1024
	ds_read_b128 v[230:233], v213 offset:2048
	ds_read_b128 v[234:237], v213 offset:3072
	global_load_lds_dwordx4 v[152:153], off
	v_lshl_add_u64 v[152:153], v[162:163], 0, s[70:71]
	s_add_i32 m0, s17, 0x2000
	s_nop 0
	global_load_lds_dwordx4 v[152:153], off
	s_barrier
	s_waitcnt lgkmcnt(0)
	v_mfma_f32_16x16x32_bf16 v[122:125], v[222:225], v[180:183], v[122:125]
	v_mfma_f32_16x16x32_bf16 v[118:121], v[230:233], v[180:183], v[118:121]
	v_mfma_f32_16x16x32_bf16 v[102:105], v[222:225], v[192:195], v[102:105]
	v_mfma_f32_16x16x32_bf16 v[98:101], v[230:233], v[192:195], v[98:101]
	v_mfma_f32_16x16x32_bf16 v[86:89], v[222:225], v[200:203], v[86:89]
	v_mfma_f32_16x16x32_bf16 v[82:85], v[230:233], v[200:203], v[82:85]
	v_mfma_f32_16x16x32_bf16 v[70:73], v[222:225], v[214:217], v[70:73]
	v_mfma_f32_16x16x32_bf16 v[66:69], v[230:233], v[214:217], v[66:69]
	v_mfma_f32_16x16x32_bf16 v[122:125], v[226:229], v[188:191], v[122:125]
	v_mfma_f32_16x16x32_bf16 v[118:121], v[234:237], v[188:191], v[118:121]
	v_mfma_f32_16x16x32_bf16 v[102:105], v[226:229], v[196:199], v[102:105]
	v_mfma_f32_16x16x32_bf16 v[98:101], v[234:237], v[196:199], v[98:101]
	v_mfma_f32_16x16x32_bf16 v[86:89], v[226:229], v[204:207], v[86:89]
	v_mfma_f32_16x16x32_bf16 v[82:85], v[234:237], v[204:207], v[82:85]
	v_mfma_f32_16x16x32_bf16 v[70:73], v[226:229], v[218:221], v[70:73]
	v_mfma_f32_16x16x32_bf16 v[66:69], v[234:237], v[218:221], v[66:69]
	s_mov_b32 m0, s80
	v_lshl_add_u64 v[152:153], v[164:165], 0, s[70:71]
	s_barrier
	ds_read_b128 v[180:183], v187 offset:49152
	ds_read_b128 v[188:191], v187 offset:50176
	ds_read_b128 v[192:195], v187 offset:51200
	ds_read_b128 v[196:199], v187 offset:52224
	ds_read_b128 v[200:203], v187 offset:53248
	ds_read_b128 v[204:207], v187 offset:54272
	ds_read_b128 v[214:217], v187 offset:55296
	ds_read_b128 v[218:221], v187 offset:56320
	global_load_lds_dwordx4 v[152:153], off
	v_lshl_add_u64 v[152:153], v[208:209], 0, s[70:71]
	s_mov_b32 m0, s81
	s_nop 0
	global_load_lds_dwordx4 v[152:153], off
	s_barrier
; #define PG8_STAGE(bufoff, gbase, voff) do { _Pragma("unroll") for (int _i = 0; _i < 2; ++_i) \
;         __builtin_amdgcn_global_load_lds((const unsigned*)((const char*)(gbase) + (voff)[_i]), (LAS unsigned*)(lds + (bufoff) + ldsw + _i * 8192), 16, 0, 0); } while (0)
; #define PG8_MMA(ai, bj, At, Bt) do { __builtin_amdgcn_s_setprio(1); _Pragma("unroll") for (int m = 0; m < 4; ++m) _Pragma("unroll") for (int n = 0; n < 2; ++n) _Pragma("unroll") for (int k = 0; k < 2; ++k) \
;         acc[ai][bj][m][n] = __builtin_amdgcn_mfma_f32_16x16x32_bf16(Bt[n][k], At[m][k], acc[ai][bj][m][n], 0, 0, 0); __builtin_amdgcn_s_setprio(0); } while (0)
; #define PG8_WAIT_V(n) asm volatile("s_waitcnt vmcnt(" #n ")" ::: "memory")
; #define PG8_WAIT_L(n) asm volatile("s_waitcnt lgkmcnt(" #n ")" ::: "memory")
; #define PG8_BAR __builtin_amdgcn_s_barrier()
; #define PG8_SCHED __builtin_amdgcn_sched_barrier(0)
;     DEVI f32x4 load(int r, int c) const { const bf16x4 y = *(const bf16x4*)(Y + (size_t)r * DM + c); return (f32x4){bf2f((u16)y[0]), bf2f((u16)y[1]), bf2f((u16)y[2]), bf2f((u16)y[3])}; }
; template <class Epi>
; DEVI void gemm_phase(LAS unsigned char* lds, const Gemm g, const Epi& E) {
;     ...
;             PG8_BAR; PG8_WAIT_L(0); PG8_MMA(1, 0, At, B0); PG8_BAR; PG8_SCHED;
;             PG8_STAGE(PG8_SB(1, 1), b3 + hstepB, voffB);
;             PG8_WAIT_V(6); PG8_BAR; PG8_MMA(1, 1, At, B1); PG8_BAR;
;         }
;     ...
;             for (int am = 0; am < 4; ++am) {
;                 const int ai = am >> 1, m0 = (am & 1) * 2;
;                 f32x4 pre[2][2][2];
;                 if constexpr (Epi::PRE) {
; #pragma unroll
;                     for (int m = 0; m < 2; ++m)
; #pragma unroll
;                         for (int bj = 0; bj < 2; ++bj)
; #pragma unroll
;                             for (int n = 0; n < 2; ++n) pre[m][bj][n] = E.load(row0 + ai * HALF + (m0 + m) * 16, col0 + bj * HALF + n * NST);
	s_waitcnt lgkmcnt(0)
	v_mfma_f32_16x16x32_bf16 v[62:65], v[114:117], v[180:183], v[62:65]
	v_mfma_f32_16x16x32_bf16 v[58:61], v[130:133], v[180:183], v[58:61]
	v_mfma_f32_16x16x32_bf16 v[46:49], v[114:117], v[192:195], v[46:49]
	v_mfma_f32_16x16x32_bf16 v[42:45], v[130:133], v[192:195], v[42:45]
	v_mfma_f32_16x16x32_bf16 v[30:33], v[114:117], v[200:203], v[30:33]
	v_mfma_f32_16x16x32_bf16 v[26:29], v[130:133], v[200:203], v[26:29]
	v_mfma_f32_16x16x32_bf16 v[14:17], v[114:117], v[214:217], v[14:17]
	v_mfma_f32_16x16x32_bf16 v[10:13], v[130:133], v[214:217], v[10:13]
	v_mfma_f32_16x16x32_bf16 v[62:65], v[126:129], v[188:191], v[62:65]
	v_mfma_f32_16x16x32_bf16 v[58:61], v[176:179], v[188:191], v[58:61]
	v_mfma_f32_16x16x32_bf16 v[46:49], v[126:129], v[196:199], v[46:49]
	v_mfma_f32_16x16x32_bf16 v[42:45], v[176:179], v[196:199], v[42:45]
	v_mfma_f32_16x16x32_bf16 v[30:33], v[126:129], v[204:207], v[30:33]
	v_mfma_f32_16x16x32_bf16 v[26:29], v[176:179], v[204:207], v[26:29]
	v_mfma_f32_16x16x32_bf16 v[14:17], v[126:129], v[218:221], v[14:17]
	v_mfma_f32_16x16x32_bf16 v[10:13], v[176:179], v[218:221], v[10:13]
	s_barrier
	s_add_u32 s14, s14, 0x40080
	s_addc_u32 s15, s15, 0
	s_add_i32 s16, s16, s47
	v_lshl_add_u64 v[114:115], s[14:15], 0, v[8:9]
	s_mov_b32 m0, s16
	s_nop 0
	global_load_lds_dwordx4 v[114:115], off
	v_lshl_add_u64 v[114:115], s[14:15], 0, v[146:147]
	s_add_i32 m0, s16, 0x2000
	s_nop 0
	global_load_lds_dwordx4 v[114:115], off
	s_waitcnt vmcnt(6)
	s_barrier
	v_mfma_f32_16x16x32_bf16 v[54:57], v[222:225], v[180:183], v[54:57]
	v_mfma_f32_16x16x32_bf16 v[50:53], v[230:233], v[180:183], v[50:53]
	v_mfma_f32_16x16x32_bf16 v[38:41], v[222:225], v[192:195], v[38:41]
	v_mfma_f32_16x16x32_bf16 v[34:37], v[230:233], v[192:195], v[34:37]
	v_mfma_f32_16x16x32_bf16 v[22:25], v[222:225], v[200:203], v[22:25]
	v_mfma_f32_16x16x32_bf16 v[18:21], v[230:233], v[200:203], v[18:21]
	v_mfma_f32_16x16x32_bf16 v[4:7], v[222:225], v[214:217], v[4:7]
	v_mfma_f32_16x16x32_bf16 v[0:3], v[230:233], v[214:217], v[0:3]
	v_mfma_f32_16x16x32_bf16 v[54:57], v[226:229], v[188:191], v[54:57]
	v_mfma_f32_16x16x32_bf16 v[50:53], v[234:237], v[188:191], v[50:53]
	v_mfma_f32_16x16x32_bf16 v[38:41], v[226:229], v[196:199], v[38:41]
	v_mfma_f32_16x16x32_bf16 v[34:37], v[234:237], v[196:199], v[34:37]
	v_mfma_f32_16x16x32_bf16 v[22:25], v[226:229], v[204:207], v[22:25]
	v_mfma_f32_16x16x32_bf16 v[18:21], v[234:237], v[204:207], v[18:21]
	v_mfma_f32_16x16x32_bf16 v[4:7], v[226:229], v[218:221], v[4:7]
	v_mfma_f32_16x16x32_bf16 v[0:3], v[234:237], v[218:221], v[0:3]
	s_add_i32 s27, s27, 2
	s_add_u32 s12, s12, 0x100
	s_addc_u32 s13, s13, 0
	s_add_u32 s19, s19, 0x100
	s_addc_u32 s26, s26, 0
	s_cmp_gt_u32 s27, 13
	s_barrier
	s_cbranch_scc0 .LBB0_1346
	s_setprio 0
	v_lshl_add_u32 v180, s10, 8, v184
	v_lshl_or_b32 v152, s0, 8, v186
	v_ashrrev_i32_e32 v181, 31, v180
	v_lshlrev_b64 v[178:179], 11, v[180:181]
	v_ashrrev_i32_e32 v153, 31, v152
	v_lshl_add_u64 v[114:115], s[24:25], 0, v[178:179]
	v_lshlrev_b64 v[176:177], 1, v[152:153]
	v_lshl_add_u64 v[114:115], v[114:115], 0, v[176:177]
	global_load_dwordx4 v[188:191], v[114:115], off
	global_load_dwordx4 v[130:133], v[114:115], off offset:256
	v_or_b32_e32 v114, 16, v180
	v_ashrrev_i32_e32 v115, 31, v114
	v_lshlrev_b64 v[182:183], 11, v[114:115]
	v_readlane_b32 s48, v251, 40
	v_lshl_add_u64 v[114:115], s[24:25], 0, v[182:183]
	v_readlane_b32 s54, v251, 46
	v_readlane_b32 s55, v251, 47
	v_lshl_add_u64 v[114:115], v[114:115], 0, v[176:177]
	global_load_dwordx4 v[126:129], v[114:115], off
	s_nop 0
	global_load_dwordx4 v[114:117], v[114:115], off offset:256
	v_lshl_add_u64 v[152:153], v[152:153], 2, s[54:55]
	global_load_dwordx4 v[214:217], v[152:153], off
	global_load_dwordx4 v[218:221], v[152:153], off offset:16
	global_load_dwordx4 v[222:225], v[152:153], off offset:512
	global_load_dwordx4 v[226:229], v[152:153], off offset:528
	s_mov_b64 s[0:1], 0x40000
	v_readlane_b32 s52, v251, 44
	v_readlane_b32 s56, v251, 48
	v_readlane_b32 s57, v251, 49
	v_readlane_b32 s58, v251, 50
	v_readlane_b32 s59, v251, 51
	v_readlane_b32 s60, v251, 52
	v_readlane_b32 s61, v251, 53
	v_readlane_b32 s62, v251, 54
	v_readlane_b32 s63, v251, 55
	s_and_b64 vcc, exec, s[36:37]
	s_mov_b32 s10, s2
	s_mov_b64 s[14:15], s[8:9]
	s_mov_b64 s[12:13], s[6:7]
	s_mov_b64 s[56:57], s[42:43]
	s_mov_b64 s[58:59], s[44:45]
	s_mov_b32 s60, s41
	s_mov_b32 s61, s83
	s_mov_b32 s62, s84
	s_mov_b32 s63, s85
	v_readlane_b32 s55, v254, 0
	s_movk_i32 s52, 0x110
	v_readlane_b32 s49, v251, 41
	v_readlane_b32 s50, v251, 42
	v_readlane_b32 s51, v251, 43
	v_readlane_b32 s53, v251, 45
	v_readlane_b32 s40, v254, 1
	s_waitcnt vmcnt(0)
;     DEVI f32x4 load(int r, int c) const { const bf16x4 y = *(const bf16x4*)(Y + (size_t)r * DM + c); return (f32x4){bf2f((u16)y[0]), bf2f((u16)y[1]), bf2f((u16)y[2]), bf2f((u16)y[3])}; }
; template <class Epi>
; DEVI void gemm_phase(LAS unsigned char* lds, const Gemm g, const Epi& E) {
;     ...
;             for (int am = 0; am < 4; ++am) {
;                 const int ai = am >> 1, m0 = (am & 1) * 2;
;                 f32x4 pre[2][2][2];
;                 if constexpr (Epi::PRE) {
; #pragma unroll
;                     for (int m = 0; m < 2; ++m)
; #pragma unroll
;                         for (int bj = 0; bj < 2; ++bj)
; #pragma unroll
;                             for (int n = 0; n < 2; ++n) pre[m][bj][n] = E.load(row0 + ai * HALF + (m0 + m) * 16, col0 + bj * HALF + n * NST);
;                 }
; #pragma unroll
;                 for (int mm = 0; mm < 2; ++mm) {
;                     const int m = m0 + mm;
;                     const int r = row0 + ai * HALF + m * 16; float rs = 1.f, part = 0.f;
;                     if constexpr (Epi::RS) rs = rsv[ai * 4 + m];
;                     if constexpr (Epi::PAIR) E.pair8(cur.b, r, cur.pn * HALF + wc * 32 + 8 * fq, acc[ai][0][m][0] * rs, acc[ai][0][m][1] * rs, acc[ai][1][m][0] * rs, acc[ai][1][m][1] * rs);
;                     else
; #pragma unroll
;                     for (int bj = 0; bj < 2; ++bj) {
;                         const int c = col0 + bj * HALF; f32x4 v0 = acc[ai][bj][m][0], v1 = acc[ai][bj][m][1];
;                         if constexpr (Epi::RS) { v0 = v0 * rs; v1 = v1 * rs; }
;                         if constexpr (Epi::PRE) part += E.frag_pre8(cur.b, r, c, v0, v1, pre[mm][bj][0], pre[mm][bj][1]);
;                         else if constexpr (Epi::PERM) E.frag8(cur.b, r, c, v0, v1);
;                         else { E.frag(cur.b, r, c, v0); E.frag(cur.b, r, c + 16, v1); }
	v_and_b32_e32 v163, 0xffff0000, v188
	v_lshlrev_b32_e32 v162, 16, v188
	v_add_f32_e32 v134, v134, v218
	v_add_f32_e32 v138, v138, v214
	v_add_f32_e32 v139, v139, v215
	v_mul_f32_e32 v138, 0xbfb8aa3b, v138
	v_mul_f32_e32 v139, 0xbfb8aa3b, v139
	v_add_f32_e32 v135, v135, v219
	v_exp_f32_e32 v138, v138
	v_mul_f32_e32 v134, 0xbfb8aa3b, v134
	v_exp_f32_e32 v139, v139
	v_mul_f32_e32 v135, 0xbfb8aa3b, v135
	v_exp_f32_e32 v134, v134
	v_exp_f32_e32 v135, v135
	v_add_f32_e32 v138, 1.0, v138
	v_add_f32_e32 v139, 1.0, v139
	v_rcp_f32_e32 v138, v138
	v_add_f32_e32 v134, 1.0, v134
	v_rcp_f32_e32 v139, v139
	v_add_f32_e32 v135, 1.0, v135
	v_rcp_f32_e32 v134, v134
	v_rcp_f32_e32 v135, v135
	v_pk_mul_f32 v[138:139], v[138:139], v[162:163]
	v_and_b32_e32 v163, 0xffff0000, v190
	v_lshlrev_b32_e32 v162, 16, v190
	v_pk_mul_f32 v[162:163], v[134:135], v[162:163]
	v_add_f32_e32 v135, v136, v220
	v_mul_f32_e32 v135, 0xbfb8aa3b, v135
	v_exp_f32_e32 v135, v135
	v_add_f32_e32 v134, v140, v216
	v_mul_f32_e32 v134, 0xbfb8aa3b, v134
	v_exp_f32_e32 v134, v134
	v_add_f32_e32 v135, 1.0, v135
	v_rcp_f32_e32 v136, v135
	v_add_f32_e32 v135, v141, v217
	v_mul_f32_e32 v135, 0xbfb8aa3b, v135
	v_exp_f32_e32 v135, v135
	v_add_f32_e32 v134, 1.0, v134
	v_rcp_f32_e32 v134, v134
	v_and_b32_e32 v141, 0xffff0000, v189
	v_add_f32_e32 v135, 1.0, v135
	v_rcp_f32_e32 v135, v135
	v_lshlrev_b32_e32 v140, 16, v189
	v_pk_mul_f32 v[140:141], v[134:135], v[140:141]
	v_add_f32_e32 v134, v137, v221
	v_mul_f32_e32 v134, 0xbfb8aa3b, v134
	v_exp_f32_e32 v134, v134
	v_and_b32_e32 v135, 0xffff0000, v191
	v_add_f32_e32 v134, 1.0, v134
	v_rcp_f32_e32 v137, v134
	v_lshlrev_b32_e32 v134, 16, v191
	v_pk_mul_f32 v[164:165], v[136:137], v[134:135]
	v_cvt_pk_bf16_f32 v134, v138, v139
	v_lshl_add_u64 v[138:139], s[64:65], 0, v[178:179]
	v_cvt_pk_bf16_f32 v135, v140, v141
	v_cvt_pk_bf16_f32 v136, v162, v163
	v_cvt_pk_bf16_f32 v137, v164, v165
	v_lshl_add_u64 v[138:139], v[138:139], 0, v[176:177]
	global_store_dwordx4 v[138:139], v[134:137], off
	s_nop 0
	v_and_b32_e32 v141, 0xffff0000, v130
	v_lshlrev_b32_e32 v140, 16, v130
	v_lshlrev_b32_e32 v130, 16, v133
	v_add_f32_e32 v118, v118, v226
	v_add_f32_e32 v119, v119, v227
	v_add_f32_e32 v122, v122, v222
	v_mul_f32_e32 v118, 0xbfb8aa3b, v118
	v_add_f32_e32 v123, v123, v223
	v_mul_f32_e32 v119, 0xbfb8aa3b, v119
	v_add_f32_e32 v124, v124, v224
	v_add_f32_e32 v120, v120, v228
	v_add_f32_e32 v125, v125, v225
	v_add_f32_e32 v121, v121, v229
	v_mul_f32_e32 v122, 0xbfb8aa3b, v122
	v_exp_f32_e32 v118, v118
	v_mul_f32_e32 v123, 0xbfb8aa3b, v123
	v_exp_f32_e32 v119, v119
	v_mul_f32_e32 v124, 0xbfb8aa3b, v124
	v_mul_f32_e32 v120, 0xbfb8aa3b, v120
	v_mul_f32_e32 v125, 0xbfb8aa3b, v125
	v_mul_f32_e32 v121, 0xbfb8aa3b, v121
	v_exp_f32_e32 v122, v122
	v_exp_f32_e32 v123, v123
	v_exp_f32_e32 v124, v124
	v_exp_f32_e32 v120, v120
	v_exp_f32_e32 v125, v125
	v_exp_f32_e32 v121, v121
	v_add_f32_e32 v118, 1.0, v118
	v_add_f32_e32 v119, 1.0, v119
	v_add_f32_e32 v122, 1.0, v122
	v_rcp_f32_e32 v118, v118
	v_add_f32_e32 v123, 1.0, v123
	v_rcp_f32_e32 v119, v119
	v_add_f32_e32 v124, 1.0, v124
	v_add_f32_e32 v120, 1.0, v120
	v_add_f32_e32 v125, 1.0, v125
	v_add_f32_e32 v121, 1.0, v121
	v_rcp_f32_e32 v122, v122
	v_rcp_f32_e32 v123, v123
	v_rcp_f32_e32 v124, v124
	v_rcp_f32_e32 v120, v120
	v_rcp_f32_e32 v125, v125
	v_rcp_f32_e32 v121, v121
	v_and_b32_e32 v135, 0xffff0000, v132
	v_lshlrev_b32_e32 v134, 16, v132
	v_pk_mul_f32 v[118:119], v[118:119], v[134:135]
	v_and_b32_e32 v135, 0xffff0000, v131
	v_lshlrev_b32_e32 v134, 16, v131
	v_and_b32_e32 v131, 0xffff0000, v133
	v_pk_mul_f32 v[122:123], v[122:123], v[140:141]
	v_pk_mul_f32 v[124:125], v[124:125], v[134:135]
	v_pk_mul_f32 v[130:131], v[120:121], v[130:131]
	v_cvt_pk_bf16_f32 v120, v122, v123
	v_cvt_pk_bf16_f32 v121, v124, v125
	v_cvt_pk_bf16_f32 v122, v118, v119
	v_cvt_pk_bf16_f32 v123, v130, v131
	global_store_dwordx4 v[138:139], v[120:123], off offset:256
	s_nop 0
	v_add_f32_e32 v106, v106, v218
	v_add_f32_e32 v107, v107, v219
	v_mul_f32_e32 v106, 0xbfb8aa3b, v106
	v_mul_f32_e32 v107, 0xbfb8aa3b, v107
	v_exp_f32_e32 v106, v106
	v_exp_f32_e32 v107, v107
	v_and_b32_e32 v119, 0xffff0000, v128
	v_lshlrev_b32_e32 v118, 16, v128
	v_add_f32_e32 v106, 1.0, v106
	v_add_f32_e32 v107, 1.0, v107
	v_rcp_f32_e32 v106, v106
	v_rcp_f32_e32 v107, v107
	v_add_f32_e32 v110, v110, v214
	v_add_f32_e32 v111, v111, v215
	v_mul_f32_e32 v110, 0xbfb8aa3b, v110
	v_pk_mul_f32 v[118:119], v[106:107], v[118:119]
	v_add_f32_e32 v107, v108, v220
	v_mul_f32_e32 v107, 0xbfb8aa3b, v107
	v_exp_f32_e32 v107, v107
	v_add_f32_e32 v106, v112, v216
	v_mul_f32_e32 v106, 0xbfb8aa3b, v106
	v_exp_f32_e32 v106, v106
	v_add_f32_e32 v107, 1.0, v107
	v_rcp_f32_e32 v108, v107
	v_add_f32_e32 v107, v113, v217
	v_mul_f32_e32 v107, 0xbfb8aa3b, v107
	v_exp_f32_e32 v107, v107
	v_add_f32_e32 v106, 1.0, v106
	v_rcp_f32_e32 v106, v106
	v_and_b32_e32 v113, 0xffff0000, v127
	v_add_f32_e32 v107, 1.0, v107
	v_rcp_f32_e32 v107, v107
	v_lshlrev_b32_e32 v112, 16, v127
	v_mul_f32_e32 v111, 0xbfb8aa3b, v111
	v_exp_f32_e32 v110, v110
	v_pk_mul_f32 v[112:113], v[106:107], v[112:113]
	v_add_f32_e32 v106, v109, v221
	v_exp_f32_e32 v111, v111
	v_mul_f32_e32 v106, 0xbfb8aa3b, v106
	v_exp_f32_e32 v106, v106
	v_add_f32_e32 v110, 1.0, v110
	v_add_f32_e32 v111, 1.0, v111
	v_rcp_f32_e32 v110, v110
	v_rcp_f32_e32 v111, v111
	v_add_f32_e32 v106, 1.0, v106
	v_rcp_f32_e32 v109, v106
	v_and_b32_e32 v123, 0xffff0000, v126
	v_lshlrev_b32_e32 v122, 16, v126
	v_pk_mul_f32 v[110:111], v[110:111], v[122:123]
	v_and_b32_e32 v107, 0xffff0000, v129
	v_lshlrev_b32_e32 v106, 16, v129
	v_pk_mul_f32 v[120:121], v[108:109], v[106:107]
;     DEVI f32x4 load(int r, int c) const { const bf16x4 y = *(const bf16x4*)(Y + (size_t)r * DM + c); return (f32x4){bf2f((u16)y[0]), bf2f((u16)y[1]), bf2f((u16)y[2]), bf2f((u16)y[3])}; }
; template <class Epi>
; DEVI void gemm_phase(LAS unsigned char* lds, const Gemm g, const Epi& E) {
;     ...
;             for (int am = 0; am < 4; ++am) {
;                 const int ai = am >> 1, m0 = (am & 1) * 2;
;                 f32x4 pre[2][2][2];
;                 if constexpr (Epi::PRE) {
; #pragma unroll
;                     for (int m = 0; m < 2; ++m)
; #pragma unroll
;                         for (int bj = 0; bj < 2; ++bj)
; #pragma unroll
;                             for (int n = 0; n < 2; ++n) pre[m][bj][n] = E.load(row0 + ai * HALF + (m0 + m) * 16, col0 + bj * HALF + n * NST);
;                 }
; #pragma unroll
;                 for (int mm = 0; mm < 2; ++mm) {
;                     const int m = m0 + mm;
;                     const int r = row0 + ai * HALF + m * 16; float rs = 1.f, part = 0.f;
;                     if constexpr (Epi::RS) rs = rsv[ai * 4 + m];
;                     if constexpr (Epi::PAIR) E.pair8(cur.b, r, cur.pn * HALF + wc * 32 + 8 * fq, acc[ai][0][m][0] * rs, acc[ai][0][m][1] * rs, acc[ai][1][m][0] * rs, acc[ai][1][m][1] * rs);
;                     else
; #pragma unroll
;                     for (int bj = 0; bj < 2; ++bj) {
;                         const int c = col0 + bj * HALF; f32x4 v0 = acc[ai][bj][m][0], v1 = acc[ai][bj][m][1];
;                         if constexpr (Epi::RS) { v0 = v0 * rs; v1 = v1 * rs; }
;                         if constexpr (Epi::PRE) part += E.frag_pre8(cur.b, r, c, v0, v1, pre[mm][bj][0], pre[mm][bj][1]);
;                         else if constexpr (Epi::PERM) E.frag8(cur.b, r, c, v0, v1);
;                         else { E.frag(cur.b, r, c, v0); E.frag(cur.b, r, c + 16, v1); }
	v_cvt_pk_bf16_f32 v106, v110, v111
	v_lshl_add_u64 v[110:111], s[64:65], 0, v[182:183]
	v_cvt_pk_bf16_f32 v107, v112, v113
	v_cvt_pk_bf16_f32 v108, v118, v119
	v_cvt_pk_bf16_f32 v109, v120, v121
	v_lshl_add_u64 v[110:111], v[110:111], 0, v[176:177]
	global_store_dwordx4 v[110:111], v[106:109], off
	s_nop 0
	v_and_b32_e32 v113, 0xffff0000, v114
	v_lshlrev_b32_e32 v112, 16, v114
	v_add_f32_e32 v98, v98, v226
	v_add_f32_e32 v99, v99, v227
	v_mul_f32_e32 v98, 0xbfb8aa3b, v98
	v_mul_f32_e32 v99, 0xbfb8aa3b, v99
	v_exp_f32_e32 v98, v98
	v_exp_f32_e32 v99, v99
	v_and_b32_e32 v107, 0xffff0000, v116
	v_lshlrev_b32_e32 v106, 16, v116
	v_add_f32_e32 v98, 1.0, v98
	v_add_f32_e32 v99, 1.0, v99
	v_rcp_f32_e32 v98, v98
	v_rcp_f32_e32 v99, v99
	v_add_f32_e32 v102, v102, v222
	v_add_f32_e32 v103, v103, v223
	v_mul_f32_e32 v102, 0xbfb8aa3b, v102
	v_pk_mul_f32 v[106:107], v[98:99], v[106:107]
	v_add_f32_e32 v99, v100, v228
	v_mul_f32_e32 v99, 0xbfb8aa3b, v99
	v_exp_f32_e32 v99, v99
	v_add_f32_e32 v98, v104, v224
	v_mul_f32_e32 v98, 0xbfb8aa3b, v98
	v_exp_f32_e32 v98, v98
	v_add_f32_e32 v99, 1.0, v99
	v_rcp_f32_e32 v100, v99
	v_add_f32_e32 v99, v105, v225
	v_mul_f32_e32 v99, 0xbfb8aa3b, v99
	v_exp_f32_e32 v99, v99
	v_add_f32_e32 v98, 1.0, v98
	v_rcp_f32_e32 v98, v98
	v_and_b32_e32 v105, 0xffff0000, v115
	v_add_f32_e32 v99, 1.0, v99
	v_rcp_f32_e32 v99, v99
	v_lshlrev_b32_e32 v104, 16, v115
	v_mul_f32_e32 v103, 0xbfb8aa3b, v103
	v_exp_f32_e32 v102, v102
	v_pk_mul_f32 v[104:105], v[98:99], v[104:105]
	v_add_f32_e32 v98, v101, v229
	v_mul_f32_e32 v98, 0xbfb8aa3b, v98
	v_exp_f32_e32 v103, v103
	v_exp_f32_e32 v98, v98
	v_add_f32_e32 v102, 1.0, v102
	v_rcp_f32_e32 v102, v102
	v_add_f32_e32 v103, 1.0, v103
	v_add_f32_e32 v98, 1.0, v98
	v_rcp_f32_e32 v103, v103
	v_rcp_f32_e32 v101, v98
	v_and_b32_e32 v99, 0xffff0000, v117
	v_lshlrev_b32_e32 v98, 16, v117
	v_pk_mul_f32 v[102:103], v[102:103], v[112:113]
	v_pk_mul_f32 v[108:109], v[100:101], v[98:99]
	v_cvt_pk_bf16_f32 v98, v102, v103
	v_cvt_pk_bf16_f32 v99, v104, v105
	v_cvt_pk_bf16_f32 v100, v106, v107
	v_cvt_pk_bf16_f32 v101, v108, v109
	global_store_dwordx4 v[110:111], v[98:101], off offset:256
	s_nop 1
	v_or_b32_e32 v98, 32, v180
	v_ashrrev_i32_e32 v99, 31, v98
	v_lshlrev_b64 v[120:121], 11, v[98:99]
	v_lshl_add_u64 v[98:99], s[24:25], 0, v[120:121]
	v_lshl_add_u64 v[98:99], v[98:99], 0, v[176:177]
	global_load_dwordx4 v[110:113], v[98:99], off
	global_load_dwordx4 v[106:109], v[98:99], off offset:256
	v_or_b32_e32 v98, 48, v180
	v_ashrrev_i32_e32 v99, 31, v98
	v_lshlrev_b64 v[118:119], 11, v[98:99]
	v_lshl_add_u64 v[98:99], s[24:25], 0, v[118:119]
	v_lshl_add_u64 v[98:99], v[98:99], 0, v[176:177]
	global_load_dwordx4 v[102:105], v[98:99], off
	s_nop 0
	global_load_dwordx4 v[98:101], v[98:99], off offset:256
	s_nop 0
	s_waitcnt vmcnt(0)
	v_add_f32_e32 v90, v90, v218
	v_add_f32_e32 v91, v91, v219
	v_mul_f32_e32 v90, 0xbfb8aa3b, v90
	v_mul_f32_e32 v91, 0xbfb8aa3b, v91
	v_exp_f32_e32 v90, v90
	v_exp_f32_e32 v91, v91
	v_and_b32_e32 v115, 0xffff0000, v112
	v_lshlrev_b32_e32 v114, 16, v112
	v_add_f32_e32 v90, 1.0, v90
	v_add_f32_e32 v91, 1.0, v91
	v_rcp_f32_e32 v90, v90
	v_rcp_f32_e32 v91, v91
	v_add_f32_e32 v94, v94, v214
	v_add_f32_e32 v95, v95, v215
	v_mul_f32_e32 v94, 0xbfb8aa3b, v94
	v_pk_mul_f32 v[114:115], v[90:91], v[114:115]
	v_add_f32_e32 v91, v92, v220
	v_mul_f32_e32 v91, 0xbfb8aa3b, v91
	v_exp_f32_e32 v91, v91
	v_add_f32_e32 v90, v96, v216
	v_mul_f32_e32 v90, 0xbfb8aa3b, v90
	v_exp_f32_e32 v90, v90
	v_add_f32_e32 v91, 1.0, v91
	v_rcp_f32_e32 v92, v91
	v_add_f32_e32 v91, v97, v217
	v_mul_f32_e32 v91, 0xbfb8aa3b, v91
	v_exp_f32_e32 v91, v91
	v_add_f32_e32 v90, 1.0, v90
	v_rcp_f32_e32 v90, v90
	v_and_b32_e32 v97, 0xffff0000, v111
	v_add_f32_e32 v91, 1.0, v91
	v_rcp_f32_e32 v91, v91
	v_lshlrev_b32_e32 v96, 16, v111
	v_mul_f32_e32 v95, 0xbfb8aa3b, v95
	v_exp_f32_e32 v94, v94
	v_pk_mul_f32 v[96:97], v[90:91], v[96:97]
	v_add_f32_e32 v90, v93, v221
	v_exp_f32_e32 v95, v95
	v_mul_f32_e32 v90, 0xbfb8aa3b, v90
	v_exp_f32_e32 v90, v90
	v_add_f32_e32 v94, 1.0, v94
	v_add_f32_e32 v95, 1.0, v95
	v_rcp_f32_e32 v94, v94
	v_rcp_f32_e32 v95, v95
	v_add_f32_e32 v90, 1.0, v90
	v_rcp_f32_e32 v93, v90
	v_and_b32_e32 v123, 0xffff0000, v110
	v_lshlrev_b32_e32 v122, 16, v110
	v_pk_mul_f32 v[94:95], v[94:95], v[122:123]
	v_and_b32_e32 v91, 0xffff0000, v113
	v_lshlrev_b32_e32 v90, 16, v113
	v_pk_mul_f32 v[110:111], v[92:93], v[90:91]
	v_cvt_pk_bf16_f32 v90, v94, v95
	v_lshl_add_u64 v[94:95], s[64:65], 0, v[120:121]
	v_cvt_pk_bf16_f32 v91, v96, v97
	v_cvt_pk_bf16_f32 v92, v114, v115
	v_cvt_pk_bf16_f32 v93, v110, v111
	v_lshl_add_u64 v[94:95], v[94:95], 0, v[176:177]
	global_store_dwordx4 v[94:95], v[90:93], off
	s_nop 0
	v_and_b32_e32 v97, 0xffff0000, v106
	v_lshlrev_b32_e32 v96, 16, v106
	v_add_f32_e32 v82, v82, v226
	v_add_f32_e32 v83, v83, v227
	v_mul_f32_e32 v82, 0xbfb8aa3b, v82
	v_mul_f32_e32 v83, 0xbfb8aa3b, v83
	v_add_f32_e32 v88, v88, v224
	v_add_f32_e32 v89, v89, v225
	v_add_f32_e32 v86, v86, v222
	v_exp_f32_e32 v82, v82
	v_add_f32_e32 v87, v87, v223
	v_exp_f32_e32 v83, v83
	v_mul_f32_e32 v88, 0xbfb8aa3b, v88
	v_add_f32_e32 v84, v84, v228
	v_mul_f32_e32 v89, 0xbfb8aa3b, v89
	v_add_f32_e32 v85, v85, v229
	v_mul_f32_e32 v86, 0xbfb8aa3b, v86
	v_mul_f32_e32 v87, 0xbfb8aa3b, v87
	v_exp_f32_e32 v88, v88
	v_mul_f32_e32 v84, 0xbfb8aa3b, v84
	v_exp_f32_e32 v89, v89
	v_mul_f32_e32 v85, 0xbfb8aa3b, v85
	v_exp_f32_e32 v86, v86
	v_exp_f32_e32 v87, v87
	v_exp_f32_e32 v84, v84
	v_exp_f32_e32 v85, v85
	v_add_f32_e32 v82, 1.0, v82
	v_add_f32_e32 v83, 1.0, v83
	v_rcp_f32_e32 v82, v82
	v_rcp_f32_e32 v83, v83
	v_add_f32_e32 v88, 1.0, v88
;     DEVI f32x4 load(int r, int c) const { const bf16x4 y = *(const bf16x4*)(Y + (size_t)r * DM + c); return (f32x4){bf2f((u16)y[0]), bf2f((u16)y[1]), bf2f((u16)y[2]), bf2f((u16)y[3])}; }
; template <class Epi>
; DEVI void gemm_phase(LAS unsigned char* lds, const Gemm g, const Epi& E) {
;     ...
;             for (int am = 0; am < 4; ++am) {
;                 const int ai = am >> 1, m0 = (am & 1) * 2;
;                 f32x4 pre[2][2][2];
;                 if constexpr (Epi::PRE) {
; #pragma unroll
;                     for (int m = 0; m < 2; ++m)
; #pragma unroll
;                         for (int bj = 0; bj < 2; ++bj)
; #pragma unroll
;                             for (int n = 0; n < 2; ++n) pre[m][bj][n] = E.load(row0 + ai * HALF + (m0 + m) * 16, col0 + bj * HALF + n * NST);
;                 }
; #pragma unroll
;                 for (int mm = 0; mm < 2; ++mm) {
;                     const int m = m0 + mm;
;                     const int r = row0 + ai * HALF + m * 16; float rs = 1.f, part = 0.f;
;                     if constexpr (Epi::RS) rs = rsv[ai * 4 + m];
;                     if constexpr (Epi::PAIR) E.pair8(cur.b, r, cur.pn * HALF + wc * 32 + 8 * fq, acc[ai][0][m][0] * rs, acc[ai][0][m][1] * rs, acc[ai][1][m][0] * rs, acc[ai][1][m][1] * rs);
;                     else
; #pragma unroll
;                     for (int bj = 0; bj < 2; ++bj) {
;                         const int c = col0 + bj * HALF; f32x4 v0 = acc[ai][bj][m][0], v1 = acc[ai][bj][m][1];
;                         if constexpr (Epi::RS) { v0 = v0 * rs; v1 = v1 * rs; }
;                         if constexpr (Epi::PRE) part += E.frag_pre8(cur.b, r, c, v0, v1, pre[mm][bj][0], pre[mm][bj][1]);
;                         else if constexpr (Epi::PERM) E.frag8(cur.b, r, c, v0, v1);
;                         else { E.frag(cur.b, r, c, v0); E.frag(cur.b, r, c + 16, v1); }
	v_add_f32_e32 v89, 1.0, v89
	v_add_f32_e32 v86, 1.0, v86
	v_add_f32_e32 v87, 1.0, v87
	v_rcp_f32_e32 v88, v88
	v_add_f32_e32 v84, 1.0, v84
	v_rcp_f32_e32 v89, v89
	v_add_f32_e32 v85, 1.0, v85
	v_rcp_f32_e32 v86, v86
	v_rcp_f32_e32 v87, v87
	v_rcp_f32_e32 v84, v84
	v_rcp_f32_e32 v85, v85
	v_and_b32_e32 v91, 0xffff0000, v108
	v_lshlrev_b32_e32 v90, 16, v108
	v_pk_mul_f32 v[82:83], v[82:83], v[90:91]
	v_and_b32_e32 v91, 0xffff0000, v107
	v_lshlrev_b32_e32 v90, 16, v107
	v_pk_mul_f32 v[88:89], v[88:89], v[90:91]
	v_and_b32_e32 v91, 0xffff0000, v109
	v_lshlrev_b32_e32 v90, 16, v109
	v_pk_mul_f32 v[86:87], v[86:87], v[96:97]
	v_pk_mul_f32 v[90:91], v[84:85], v[90:91]
	v_cvt_pk_bf16_f32 v84, v86, v87
	v_cvt_pk_bf16_f32 v85, v88, v89
	v_cvt_pk_bf16_f32 v86, v82, v83
	v_cvt_pk_bf16_f32 v87, v90, v91
	global_store_dwordx4 v[94:95], v[84:87], off offset:256
	s_nop 0
	v_add_f32_e32 v74, v74, v218
	v_add_f32_e32 v75, v75, v219
	v_mul_f32_e32 v74, 0xbfb8aa3b, v74
	v_mul_f32_e32 v75, 0xbfb8aa3b, v75
	v_exp_f32_e32 v74, v74
	v_exp_f32_e32 v75, v75
	v_and_b32_e32 v83, 0xffff0000, v104
	v_lshlrev_b32_e32 v82, 16, v104
	v_add_f32_e32 v74, 1.0, v74
	v_add_f32_e32 v75, 1.0, v75
	v_rcp_f32_e32 v74, v74
	v_rcp_f32_e32 v75, v75
	v_add_f32_e32 v78, v78, v214
	v_add_f32_e32 v79, v79, v215
	v_mul_f32_e32 v78, 0xbfb8aa3b, v78
	v_pk_mul_f32 v[82:83], v[74:75], v[82:83]
	v_add_f32_e32 v75, v76, v220
	v_mul_f32_e32 v75, 0xbfb8aa3b, v75
	v_exp_f32_e32 v75, v75
	v_add_f32_e32 v74, v80, v216
	v_mul_f32_e32 v74, 0xbfb8aa3b, v74
	v_exp_f32_e32 v74, v74
	v_add_f32_e32 v75, 1.0, v75
	v_rcp_f32_e32 v76, v75
	v_add_f32_e32 v75, v81, v217
	v_mul_f32_e32 v75, 0xbfb8aa3b, v75
	v_exp_f32_e32 v75, v75
	v_add_f32_e32 v74, 1.0, v74
	v_rcp_f32_e32 v74, v74
	v_and_b32_e32 v81, 0xffff0000, v103
	v_add_f32_e32 v75, 1.0, v75
	v_rcp_f32_e32 v75, v75
	v_lshlrev_b32_e32 v80, 16, v103
	v_mul_f32_e32 v79, 0xbfb8aa3b, v79
	v_exp_f32_e32 v78, v78
	v_pk_mul_f32 v[80:81], v[74:75], v[80:81]
	v_add_f32_e32 v74, v77, v221
	v_exp_f32_e32 v79, v79
	v_mul_f32_e32 v74, 0xbfb8aa3b, v74
	v_exp_f32_e32 v74, v74
	v_add_f32_e32 v78, 1.0, v78
	v_add_f32_e32 v79, 1.0, v79
	v_rcp_f32_e32 v78, v78
	v_rcp_f32_e32 v79, v79
	v_add_f32_e32 v74, 1.0, v74
	v_rcp_f32_e32 v77, v74
	v_and_b32_e32 v87, 0xffff0000, v102
	v_lshlrev_b32_e32 v86, 16, v102
	v_pk_mul_f32 v[78:79], v[78:79], v[86:87]
	v_and_b32_e32 v75, 0xffff0000, v105
	v_lshlrev_b32_e32 v74, 16, v105
	v_pk_mul_f32 v[84:85], v[76:77], v[74:75]
	v_cvt_pk_bf16_f32 v74, v78, v79
	v_lshl_add_u64 v[78:79], s[64:65], 0, v[118:119]
	v_cvt_pk_bf16_f32 v75, v80, v81
	v_cvt_pk_bf16_f32 v76, v82, v83
	v_cvt_pk_bf16_f32 v77, v84, v85
	v_lshl_add_u64 v[78:79], v[78:79], 0, v[176:177]
	global_store_dwordx4 v[78:79], v[74:77], off
	s_nop 0
	v_lshl_add_u64 v[88:89], v[178:179], 0, s[0:1]
	s_mov_b64 s[0:1], 0x48000
	v_lshl_add_u64 v[86:87], v[178:179], 0, s[0:1]
	s_mov_b64 s[0:1], 0x50000
	v_add_f32_e32 v66, v66, v226
	v_add_f32_e32 v67, v67, v227
	v_mul_f32_e32 v66, 0xbfb8aa3b, v66
	v_mul_f32_e32 v67, 0xbfb8aa3b, v67
	v_exp_f32_e32 v66, v66
	v_exp_f32_e32 v67, v67
	v_and_b32_e32 v75, 0xffff0000, v100
	v_lshlrev_b32_e32 v74, 16, v100
	v_add_f32_e32 v66, 1.0, v66
	v_add_f32_e32 v67, 1.0, v67
	v_rcp_f32_e32 v66, v66
	v_rcp_f32_e32 v67, v67
	v_add_f32_e32 v70, v70, v222
	v_add_f32_e32 v71, v71, v223
	v_mul_f32_e32 v70, 0xbfb8aa3b, v70
	v_pk_mul_f32 v[74:75], v[66:67], v[74:75]
	v_add_f32_e32 v67, v68, v228
	v_mul_f32_e32 v67, 0xbfb8aa3b, v67
	v_exp_f32_e32 v67, v67
	v_add_f32_e32 v66, v72, v224
	v_mul_f32_e32 v66, 0xbfb8aa3b, v66
	v_exp_f32_e32 v66, v66
	v_add_f32_e32 v67, 1.0, v67
	v_rcp_f32_e32 v68, v67
	v_add_f32_e32 v67, v73, v225
	v_mul_f32_e32 v67, 0xbfb8aa3b, v67
	v_exp_f32_e32 v67, v67
	v_add_f32_e32 v66, 1.0, v66
	v_rcp_f32_e32 v66, v66
	v_and_b32_e32 v73, 0xffff0000, v99
	v_add_f32_e32 v67, 1.0, v67
	v_rcp_f32_e32 v67, v67
	v_lshlrev_b32_e32 v72, 16, v99
	v_mul_f32_e32 v71, 0xbfb8aa3b, v71
	v_exp_f32_e32 v70, v70
	v_pk_mul_f32 v[72:73], v[66:67], v[72:73]
	v_add_f32_e32 v66, v69, v229
	v_mul_f32_e32 v66, 0xbfb8aa3b, v66
	v_exp_f32_e32 v71, v71
	v_exp_f32_e32 v66, v66
	v_add_f32_e32 v70, 1.0, v70
	v_rcp_f32_e32 v70, v70
	v_add_f32_e32 v71, 1.0, v71
	v_add_f32_e32 v66, 1.0, v66
	v_rcp_f32_e32 v71, v71
	v_rcp_f32_e32 v69, v66
	v_and_b32_e32 v81, 0xffff0000, v98
	v_lshlrev_b32_e32 v80, 16, v98
	v_and_b32_e32 v67, 0xffff0000, v101
	v_lshlrev_b32_e32 v66, 16, v101
	v_pk_mul_f32 v[70:71], v[70:71], v[80:81]
	v_pk_mul_f32 v[76:77], v[68:69], v[66:67]
	v_cvt_pk_bf16_f32 v66, v70, v71
	v_cvt_pk_bf16_f32 v67, v72, v73
	v_cvt_pk_bf16_f32 v68, v74, v75
	v_cvt_pk_bf16_f32 v69, v76, v77
	global_store_dwordx4 v[78:79], v[66:69], off offset:256
	s_nop 1
	v_lshl_add_u64 v[66:67], s[24:25], 0, v[88:89]
	v_lshl_add_u64 v[66:67], v[66:67], 0, v[176:177]
	global_load_dwordx4 v[78:81], v[66:67], off
	global_load_dwordx4 v[74:77], v[66:67], off offset:256
	v_lshl_add_u64 v[66:67], s[24:25], 0, v[86:87]
	v_lshl_add_u64 v[66:67], v[66:67], 0, v[176:177]
	global_load_dwordx4 v[70:73], v[66:67], off
	s_nop 0
	global_load_dwordx4 v[66:69], v[66:67], off offset:256
	s_nop 0
	s_waitcnt vmcnt(0)
;     DEVI f32x4 load(int r, int c) const { const bf16x4 y = *(const bf16x4*)(Y + (size_t)r * DM + c); return (f32x4){bf2f((u16)y[0]), bf2f((u16)y[1]), bf2f((u16)y[2]), bf2f((u16)y[3])}; }
; template <class Epi>
; DEVI void gemm_phase(LAS unsigned char* lds, const Gemm g, const Epi& E) {
;     ...
;             for (int am = 0; am < 4; ++am) {
;                 const int ai = am >> 1, m0 = (am & 1) * 2;
;                 f32x4 pre[2][2][2];
;                 if constexpr (Epi::PRE) {
; #pragma unroll
;                     for (int m = 0; m < 2; ++m)
; #pragma unroll
;                         for (int bj = 0; bj < 2; ++bj)
; #pragma unroll
;                             for (int n = 0; n < 2; ++n) pre[m][bj][n] = E.load(row0 + ai * HALF + (m0 + m) * 16, col0 + bj * HALF + n * NST);
;                 }
; #pragma unroll
;                 for (int mm = 0; mm < 2; ++mm) {
;                     const int m = m0 + mm;
;                     const int r = row0 + ai * HALF + m * 16; float rs = 1.f, part = 0.f;
;                     if constexpr (Epi::RS) rs = rsv[ai * 4 + m];
;                     if constexpr (Epi::PAIR) E.pair8(cur.b, r, cur.pn * HALF + wc * 32 + 8 * fq, acc[ai][0][m][0] * rs, acc[ai][0][m][1] * rs, acc[ai][1][m][0] * rs, acc[ai][1][m][1] * rs);
;                     else
; #pragma unroll
;                     for (int bj = 0; bj < 2; ++bj) {
;                         const int c = col0 + bj * HALF; f32x4 v0 = acc[ai][bj][m][0], v1 = acc[ai][bj][m][1];
;                         if constexpr (Epi::RS) { v0 = v0 * rs; v1 = v1 * rs; }
;                         if constexpr (Epi::PRE) part += E.frag_pre8(cur.b, r, c, v0, v1, pre[mm][bj][0], pre[mm][bj][1]);
;                         else if constexpr (Epi::PERM) E.frag8(cur.b, r, c, v0, v1);
;                         else { E.frag(cur.b, r, c, v0); E.frag(cur.b, r, c + 16, v1); }
	v_add_f32_e32 v58, v58, v218
	v_add_f32_e32 v59, v59, v219
	v_mul_f32_e32 v58, 0xbfb8aa3b, v58
	v_mul_f32_e32 v59, 0xbfb8aa3b, v59
	v_exp_f32_e32 v58, v58
	v_exp_f32_e32 v59, v59
	v_and_b32_e32 v83, 0xffff0000, v80
	v_lshlrev_b32_e32 v82, 16, v80
	v_add_f32_e32 v58, 1.0, v58
	v_add_f32_e32 v59, 1.0, v59
	v_rcp_f32_e32 v58, v58
	v_rcp_f32_e32 v59, v59
	v_add_f32_e32 v62, v62, v214
	v_add_f32_e32 v63, v63, v215
	v_mul_f32_e32 v62, 0xbfb8aa3b, v62
	v_pk_mul_f32 v[82:83], v[58:59], v[82:83]
	v_add_f32_e32 v59, v60, v220
	v_mul_f32_e32 v59, 0xbfb8aa3b, v59
	v_exp_f32_e32 v59, v59
	v_add_f32_e32 v58, v64, v216
	v_mul_f32_e32 v58, 0xbfb8aa3b, v58
	v_exp_f32_e32 v58, v58
	v_add_f32_e32 v59, 1.0, v59
	v_rcp_f32_e32 v60, v59
	v_add_f32_e32 v59, v65, v217
	v_mul_f32_e32 v59, 0xbfb8aa3b, v59
	v_exp_f32_e32 v59, v59
	v_add_f32_e32 v58, 1.0, v58
	v_rcp_f32_e32 v58, v58
	v_and_b32_e32 v65, 0xffff0000, v79
	v_add_f32_e32 v59, 1.0, v59
	v_rcp_f32_e32 v59, v59
	v_lshlrev_b32_e32 v64, 16, v79
	v_mul_f32_e32 v63, 0xbfb8aa3b, v63
	v_exp_f32_e32 v62, v62
	v_pk_mul_f32 v[64:65], v[58:59], v[64:65]
	v_add_f32_e32 v58, v61, v221
	v_exp_f32_e32 v63, v63
	v_mul_f32_e32 v58, 0xbfb8aa3b, v58
	v_exp_f32_e32 v58, v58
	v_add_f32_e32 v62, 1.0, v62
	v_add_f32_e32 v63, 1.0, v63
	v_rcp_f32_e32 v62, v62
	v_rcp_f32_e32 v63, v63
	v_add_f32_e32 v58, 1.0, v58
	v_rcp_f32_e32 v61, v58
	v_and_b32_e32 v91, 0xffff0000, v78
	v_lshlrev_b32_e32 v90, 16, v78
	v_pk_mul_f32 v[62:63], v[62:63], v[90:91]
	v_and_b32_e32 v59, 0xffff0000, v81
	v_lshlrev_b32_e32 v58, 16, v81
	v_pk_mul_f32 v[78:79], v[60:61], v[58:59]
	v_cvt_pk_bf16_f32 v58, v62, v63
	v_lshl_add_u64 v[62:63], s[64:65], 0, v[88:89]
	v_cvt_pk_bf16_f32 v59, v64, v65
	v_cvt_pk_bf16_f32 v60, v82, v83
	v_cvt_pk_bf16_f32 v61, v78, v79
	v_lshl_add_u64 v[62:63], v[62:63], 0, v[176:177]
	global_store_dwordx4 v[62:63], v[58:61], off
	s_nop 0
	v_and_b32_e32 v65, 0xffff0000, v74
	v_lshlrev_b32_e32 v64, 16, v74
	v_add_f32_e32 v50, v50, v226
	v_add_f32_e32 v51, v51, v227
	v_mul_f32_e32 v50, 0xbfb8aa3b, v50
	v_mul_f32_e32 v51, 0xbfb8aa3b, v51
	v_add_f32_e32 v56, v56, v224
	v_add_f32_e32 v57, v57, v225
	v_add_f32_e32 v54, v54, v222
	v_exp_f32_e32 v50, v50
	v_add_f32_e32 v55, v55, v223
	v_exp_f32_e32 v51, v51
	v_mul_f32_e32 v56, 0xbfb8aa3b, v56
	v_add_f32_e32 v52, v52, v228
	v_mul_f32_e32 v57, 0xbfb8aa3b, v57
	v_add_f32_e32 v53, v53, v229
	v_mul_f32_e32 v54, 0xbfb8aa3b, v54
	v_mul_f32_e32 v55, 0xbfb8aa3b, v55
	v_exp_f32_e32 v56, v56
	v_mul_f32_e32 v52, 0xbfb8aa3b, v52
	v_exp_f32_e32 v57, v57
	v_mul_f32_e32 v53, 0xbfb8aa3b, v53
	v_exp_f32_e32 v54, v54
	v_exp_f32_e32 v55, v55
	v_exp_f32_e32 v52, v52
	v_exp_f32_e32 v53, v53
	v_add_f32_e32 v50, 1.0, v50
	v_add_f32_e32 v51, 1.0, v51
	v_rcp_f32_e32 v50, v50
	v_rcp_f32_e32 v51, v51
	v_add_f32_e32 v56, 1.0, v56
	v_add_f32_e32 v57, 1.0, v57
	v_add_f32_e32 v54, 1.0, v54
	v_add_f32_e32 v55, 1.0, v55
	v_rcp_f32_e32 v56, v56
	v_add_f32_e32 v52, 1.0, v52
	v_rcp_f32_e32 v57, v57
	v_add_f32_e32 v53, 1.0, v53
	v_rcp_f32_e32 v54, v54
	v_rcp_f32_e32 v55, v55
	v_rcp_f32_e32 v52, v52
	v_rcp_f32_e32 v53, v53
	v_and_b32_e32 v59, 0xffff0000, v76
	v_lshlrev_b32_e32 v58, 16, v76
	v_pk_mul_f32 v[50:51], v[50:51], v[58:59]
	v_and_b32_e32 v59, 0xffff0000, v75
	v_lshlrev_b32_e32 v58, 16, v75
	v_pk_mul_f32 v[56:57], v[56:57], v[58:59]
	v_and_b32_e32 v59, 0xffff0000, v77
	v_lshlrev_b32_e32 v58, 16, v77
	v_pk_mul_f32 v[54:55], v[54:55], v[64:65]
	v_pk_mul_f32 v[58:59], v[52:53], v[58:59]
	v_cvt_pk_bf16_f32 v52, v54, v55
	v_cvt_pk_bf16_f32 v53, v56, v57
	v_cvt_pk_bf16_f32 v54, v50, v51
	v_cvt_pk_bf16_f32 v55, v58, v59
	global_store_dwordx4 v[62:63], v[52:55], off offset:256
	s_nop 0
	v_add_f32_e32 v42, v42, v218
	v_add_f32_e32 v43, v43, v219
	v_mul_f32_e32 v42, 0xbfb8aa3b, v42
	v_mul_f32_e32 v43, 0xbfb8aa3b, v43
	v_exp_f32_e32 v42, v42
	v_exp_f32_e32 v43, v43
	v_and_b32_e32 v51, 0xffff0000, v72
	v_lshlrev_b32_e32 v50, 16, v72
	v_add_f32_e32 v42, 1.0, v42
	v_add_f32_e32 v43, 1.0, v43
	v_rcp_f32_e32 v42, v42
	v_rcp_f32_e32 v43, v43
	v_add_f32_e32 v46, v46, v214
	v_add_f32_e32 v47, v47, v215
	v_mul_f32_e32 v46, 0xbfb8aa3b, v46
	v_pk_mul_f32 v[50:51], v[42:43], v[50:51]
	v_add_f32_e32 v43, v44, v220
	v_mul_f32_e32 v43, 0xbfb8aa3b, v43
	v_exp_f32_e32 v43, v43
	v_add_f32_e32 v42, v48, v216
	v_mul_f32_e32 v42, 0xbfb8aa3b, v42
	v_exp_f32_e32 v42, v42
	v_add_f32_e32 v43, 1.0, v43
	v_rcp_f32_e32 v44, v43
	v_add_f32_e32 v43, v49, v217
	v_mul_f32_e32 v43, 0xbfb8aa3b, v43
	v_exp_f32_e32 v43, v43
	v_add_f32_e32 v42, 1.0, v42
	v_rcp_f32_e32 v42, v42
	v_and_b32_e32 v49, 0xffff0000, v71
	v_add_f32_e32 v43, 1.0, v43
	v_rcp_f32_e32 v43, v43
	v_lshlrev_b32_e32 v48, 16, v71
	v_mul_f32_e32 v47, 0xbfb8aa3b, v47
	v_exp_f32_e32 v46, v46
	v_pk_mul_f32 v[48:49], v[42:43], v[48:49]
	v_add_f32_e32 v42, v45, v221
	v_exp_f32_e32 v47, v47
	v_mul_f32_e32 v42, 0xbfb8aa3b, v42
	v_exp_f32_e32 v42, v42
	v_add_f32_e32 v46, 1.0, v46
	v_add_f32_e32 v47, 1.0, v47
	v_rcp_f32_e32 v46, v46
	v_rcp_f32_e32 v47, v47
	v_add_f32_e32 v42, 1.0, v42
	v_rcp_f32_e32 v45, v42
	v_and_b32_e32 v55, 0xffff0000, v70
	v_lshlrev_b32_e32 v54, 16, v70
	v_pk_mul_f32 v[46:47], v[46:47], v[54:55]
	v_and_b32_e32 v43, 0xffff0000, v73
	v_lshlrev_b32_e32 v42, 16, v73
	v_pk_mul_f32 v[52:53], v[44:45], v[42:43]
	v_cvt_pk_bf16_f32 v42, v46, v47
	v_lshl_add_u64 v[46:47], s[64:65], 0, v[86:87]
	v_cvt_pk_bf16_f32 v43, v48, v49
	v_cvt_pk_bf16_f32 v44, v50, v51
	v_cvt_pk_bf16_f32 v45, v52, v53
	v_lshl_add_u64 v[46:47], v[46:47], 0, v[176:177]
	global_store_dwordx4 v[46:47], v[42:45], off
	s_nop 0
	v_lshl_add_u64 v[56:57], v[178:179], 0, s[0:1]
	s_mov_b64 s[0:1], 0x58000
	v_lshl_add_u64 v[54:55], v[178:179], 0, s[0:1]
;     DEVI f32x4 load(int r, int c) const { const bf16x4 y = *(const bf16x4*)(Y + (size_t)r * DM + c); return (f32x4){bf2f((u16)y[0]), bf2f((u16)y[1]), bf2f((u16)y[2]), bf2f((u16)y[3])}; }
; template <class Epi>
; DEVI void gemm_phase(LAS unsigned char* lds, const Gemm g, const Epi& E) {
;     ...
;             for (int am = 0; am < 4; ++am) {
;                 const int ai = am >> 1, m0 = (am & 1) * 2;
;                 f32x4 pre[2][2][2];
;                 if constexpr (Epi::PRE) {
; #pragma unroll
;                     for (int m = 0; m < 2; ++m)
; #pragma unroll
;                         for (int bj = 0; bj < 2; ++bj)
; #pragma unroll
;                             for (int n = 0; n < 2; ++n) pre[m][bj][n] = E.load(row0 + ai * HALF + (m0 + m) * 16, col0 + bj * HALF + n * NST);
;                 }
; #pragma unroll
;                 for (int mm = 0; mm < 2; ++mm) {
;                     const int m = m0 + mm;
;                     const int r = row0 + ai * HALF + m * 16; float rs = 1.f, part = 0.f;
;                     if constexpr (Epi::RS) rs = rsv[ai * 4 + m];
;                     if constexpr (Epi::PAIR) E.pair8(cur.b, r, cur.pn * HALF + wc * 32 + 8 * fq, acc[ai][0][m][0] * rs, acc[ai][0][m][1] * rs, acc[ai][1][m][0] * rs, acc[ai][1][m][1] * rs);
;                     else
; #pragma unroll
;                     for (int bj = 0; bj < 2; ++bj) {
;                         const int c = col0 + bj * HALF; f32x4 v0 = acc[ai][bj][m][0], v1 = acc[ai][bj][m][1];
;                         if constexpr (Epi::RS) { v0 = v0 * rs; v1 = v1 * rs; }
;                         if constexpr (Epi::PRE) part += E.frag_pre8(cur.b, r, c, v0, v1, pre[mm][bj][0], pre[mm][bj][1]);
;                         else if constexpr (Epi::PERM) E.frag8(cur.b, r, c, v0, v1);
;                         else { E.frag(cur.b, r, c, v0); E.frag(cur.b, r, c + 16, v1); }
	s_mov_b32 s0, s4
	v_add_f32_e32 v34, v34, v226
	v_add_f32_e32 v35, v35, v227
	v_mul_f32_e32 v34, 0xbfb8aa3b, v34
	v_mul_f32_e32 v35, 0xbfb8aa3b, v35
	v_exp_f32_e32 v34, v34
	v_exp_f32_e32 v35, v35
	v_and_b32_e32 v43, 0xffff0000, v68
	v_lshlrev_b32_e32 v42, 16, v68
	v_add_f32_e32 v34, 1.0, v34
	v_add_f32_e32 v35, 1.0, v35
	v_rcp_f32_e32 v34, v34
	v_rcp_f32_e32 v35, v35
	v_add_f32_e32 v38, v38, v222
	v_add_f32_e32 v39, v39, v223
	v_mul_f32_e32 v38, 0xbfb8aa3b, v38
	v_pk_mul_f32 v[42:43], v[34:35], v[42:43]
	v_add_f32_e32 v35, v36, v228
	v_mul_f32_e32 v35, 0xbfb8aa3b, v35
	v_exp_f32_e32 v35, v35
	v_add_f32_e32 v34, v40, v224
	v_mul_f32_e32 v34, 0xbfb8aa3b, v34
	v_exp_f32_e32 v34, v34
	v_add_f32_e32 v35, 1.0, v35
	v_rcp_f32_e32 v36, v35
	v_add_f32_e32 v35, v41, v225
	v_mul_f32_e32 v35, 0xbfb8aa3b, v35
	v_exp_f32_e32 v35, v35
	v_add_f32_e32 v34, 1.0, v34
	v_rcp_f32_e32 v34, v34
	v_and_b32_e32 v41, 0xffff0000, v67
	v_add_f32_e32 v35, 1.0, v35
	v_rcp_f32_e32 v35, v35
	v_lshlrev_b32_e32 v40, 16, v67
	v_mul_f32_e32 v39, 0xbfb8aa3b, v39
	v_exp_f32_e32 v38, v38
	v_pk_mul_f32 v[40:41], v[34:35], v[40:41]
	v_add_f32_e32 v34, v37, v229
	v_mul_f32_e32 v34, 0xbfb8aa3b, v34
	v_exp_f32_e32 v39, v39
	v_exp_f32_e32 v34, v34
	v_add_f32_e32 v38, 1.0, v38
	v_rcp_f32_e32 v38, v38
	v_add_f32_e32 v39, 1.0, v39
	v_add_f32_e32 v34, 1.0, v34
	v_rcp_f32_e32 v39, v39
	v_rcp_f32_e32 v37, v34
	v_and_b32_e32 v49, 0xffff0000, v66
	v_lshlrev_b32_e32 v48, 16, v66
	v_and_b32_e32 v35, 0xffff0000, v69
	v_lshlrev_b32_e32 v34, 16, v69
	v_pk_mul_f32 v[38:39], v[38:39], v[48:49]
	v_pk_mul_f32 v[44:45], v[36:37], v[34:35]
	v_cvt_pk_bf16_f32 v34, v38, v39
	v_cvt_pk_bf16_f32 v35, v40, v41
	v_cvt_pk_bf16_f32 v36, v42, v43
	v_cvt_pk_bf16_f32 v37, v44, v45
	global_store_dwordx4 v[46:47], v[34:37], off offset:256
	s_nop 1
	v_lshl_add_u64 v[34:35], s[24:25], 0, v[56:57]
	v_lshl_add_u64 v[34:35], v[34:35], 0, v[176:177]
	global_load_dwordx4 v[46:49], v[34:35], off
	global_load_dwordx4 v[42:45], v[34:35], off offset:256
	v_lshl_add_u64 v[34:35], s[24:25], 0, v[54:55]
	v_lshl_add_u64 v[34:35], v[34:35], 0, v[176:177]
	global_load_dwordx4 v[38:41], v[34:35], off
	s_nop 0
	global_load_dwordx4 v[34:37], v[34:35], off offset:256
	s_nop 0
	s_waitcnt vmcnt(0)
	v_add_f32_e32 v26, v26, v218
	v_add_f32_e32 v27, v27, v219
	v_mul_f32_e32 v26, 0xbfb8aa3b, v26
	v_mul_f32_e32 v27, 0xbfb8aa3b, v27
	v_exp_f32_e32 v26, v26
	v_exp_f32_e32 v27, v27
	v_and_b32_e32 v51, 0xffff0000, v48
	v_lshlrev_b32_e32 v50, 16, v48
	v_add_f32_e32 v26, 1.0, v26
	v_add_f32_e32 v27, 1.0, v27
	v_rcp_f32_e32 v26, v26
	v_rcp_f32_e32 v27, v27
	v_add_f32_e32 v30, v30, v214
	v_add_f32_e32 v31, v31, v215
	v_mul_f32_e32 v30, 0xbfb8aa3b, v30
	v_pk_mul_f32 v[50:51], v[26:27], v[50:51]
	v_add_f32_e32 v27, v28, v220
	v_mul_f32_e32 v27, 0xbfb8aa3b, v27
	v_exp_f32_e32 v27, v27
	v_add_f32_e32 v26, v32, v216
	v_mul_f32_e32 v26, 0xbfb8aa3b, v26
	v_exp_f32_e32 v26, v26
	v_add_f32_e32 v27, 1.0, v27
	v_rcp_f32_e32 v28, v27
	v_add_f32_e32 v27, v33, v217
	v_mul_f32_e32 v27, 0xbfb8aa3b, v27
	v_exp_f32_e32 v27, v27
	v_add_f32_e32 v26, 1.0, v26
	v_rcp_f32_e32 v26, v26
	v_and_b32_e32 v33, 0xffff0000, v47
	v_add_f32_e32 v27, 1.0, v27
	v_rcp_f32_e32 v27, v27
	v_lshlrev_b32_e32 v32, 16, v47
	v_mul_f32_e32 v31, 0xbfb8aa3b, v31
	v_exp_f32_e32 v30, v30
	v_pk_mul_f32 v[32:33], v[26:27], v[32:33]
	v_add_f32_e32 v26, v29, v221
	v_exp_f32_e32 v31, v31
	v_mul_f32_e32 v26, 0xbfb8aa3b, v26
	v_exp_f32_e32 v26, v26
	v_add_f32_e32 v30, 1.0, v30
	v_add_f32_e32 v31, 1.0, v31
	v_rcp_f32_e32 v30, v30
	v_rcp_f32_e32 v31, v31
	v_add_f32_e32 v26, 1.0, v26
	v_rcp_f32_e32 v29, v26
	v_and_b32_e32 v59, 0xffff0000, v46
	v_lshlrev_b32_e32 v58, 16, v46
	v_pk_mul_f32 v[30:31], v[30:31], v[58:59]
	v_and_b32_e32 v27, 0xffff0000, v49
	v_lshlrev_b32_e32 v26, 16, v49
	v_pk_mul_f32 v[46:47], v[28:29], v[26:27]
	v_cvt_pk_bf16_f32 v26, v30, v31
	v_lshl_add_u64 v[30:31], s[64:65], 0, v[56:57]
	v_cvt_pk_bf16_f32 v27, v32, v33
	v_cvt_pk_bf16_f32 v28, v50, v51
	v_cvt_pk_bf16_f32 v29, v46, v47
	v_lshl_add_u64 v[30:31], v[30:31], 0, v[176:177]
	global_store_dwordx4 v[30:31], v[26:29], off
	s_nop 0
	v_and_b32_e32 v33, 0xffff0000, v42
	v_lshlrev_b32_e32 v32, 16, v42
	v_add_f32_e32 v18, v18, v226
	v_add_f32_e32 v19, v19, v227
	v_mul_f32_e32 v18, 0xbfb8aa3b, v18
	v_mul_f32_e32 v19, 0xbfb8aa3b, v19
	v_add_f32_e32 v24, v24, v224
	v_add_f32_e32 v25, v25, v225
	v_add_f32_e32 v22, v22, v222
	v_exp_f32_e32 v18, v18
	v_add_f32_e32 v23, v23, v223
	v_exp_f32_e32 v19, v19
	v_mul_f32_e32 v24, 0xbfb8aa3b, v24
	v_add_f32_e32 v20, v20, v228
	v_mul_f32_e32 v25, 0xbfb8aa3b, v25
	v_add_f32_e32 v21, v21, v229
	v_mul_f32_e32 v22, 0xbfb8aa3b, v22
	v_mul_f32_e32 v23, 0xbfb8aa3b, v23
	v_exp_f32_e32 v24, v24
	v_mul_f32_e32 v20, 0xbfb8aa3b, v20
	v_exp_f32_e32 v25, v25
; #define PG8_WAIT_V(n) asm volatile("s_waitcnt vmcnt(" #n ")" ::: "memory")
; #define PG8_BAR __builtin_amdgcn_s_barrier()
; template <class Epi>
; DEVI void gemm_phase(LAS unsigned char* lds, const Gemm g, const Epi& E) {
;     ...
;             for (int am = 0; am < 4; ++am) {
;                 const int ai = am >> 1, m0 = (am & 1) * 2;
;                 f32x4 pre[2][2][2];
;                 if constexpr (Epi::PRE) {
; #pragma unroll
;                     for (int m = 0; m < 2; ++m)
; #pragma unroll
;                         for (int bj = 0; bj < 2; ++bj)
; #pragma unroll
;                             for (int n = 0; n < 2; ++n) pre[m][bj][n] = E.load(row0 + ai * HALF + (m0 + m) * 16, col0 + bj * HALF + n * NST);
;                 }
; #pragma unroll
;                 for (int mm = 0; mm < 2; ++mm) {
;                     const int m = m0 + mm;
;                     const int r = row0 + ai * HALF + m * 16; float rs = 1.f, part = 0.f;
;                     if constexpr (Epi::RS) rs = rsv[ai * 4 + m];
;                     if constexpr (Epi::PAIR) E.pair8(cur.b, r, cur.pn * HALF + wc * 32 + 8 * fq, acc[ai][0][m][0] * rs, acc[ai][0][m][1] * rs, acc[ai][1][m][0] * rs, acc[ai][1][m][1] * rs);
;                     else
; #pragma unroll
;                     for (int bj = 0; bj < 2; ++bj) {
;                         const int c = col0 + bj * HALF; f32x4 v0 = acc[ai][bj][m][0], v1 = acc[ai][bj][m][1];
;                         if constexpr (Epi::RS) { v0 = v0 * rs; v1 = v1 * rs; }
;                         if constexpr (Epi::PRE) part += E.frag_pre8(cur.b, r, c, v0, v1, pre[mm][bj][0], pre[mm][bj][1]);
;                         else if constexpr (Epi::PERM) E.frag8(cur.b, r, c, v0, v1);
;                         else { E.frag(cur.b, r, c, v0); E.frag(cur.b, r, c + 16, v1); }
;     ...
;         if (!has_next) break;
; #pragma unroll
;         for (int a = 0; a < 2; ++a)
; #pragma unroll
;             for (int b = 0; b < 2; ++b)
; #pragma unroll
;                 for (int m = 0; m < 4; ++m)
; #pragma unroll
;                     for (int n = 0; n < 2; ++n) acc[a][b][m][n] = (f32x4){0.f, 0.f, 0.f, 0.f};
;         cur = nxt; cA = nA; cB = nB; ++ui;
;     }
;     PG8_WAIT_V(0);
;     if (wr == 0) PG8_BAR;
;     PG8_BAR;
	v_mul_f32_e32 v21, 0xbfb8aa3b, v21
	v_exp_f32_e32 v22, v22
	v_exp_f32_e32 v23, v23
	v_exp_f32_e32 v20, v20
	v_exp_f32_e32 v21, v21
	v_add_f32_e32 v18, 1.0, v18
	v_add_f32_e32 v19, 1.0, v19
	v_rcp_f32_e32 v18, v18
	v_rcp_f32_e32 v19, v19
	v_add_f32_e32 v24, 1.0, v24
	v_add_f32_e32 v25, 1.0, v25
	v_add_f32_e32 v22, 1.0, v22
	v_add_f32_e32 v23, 1.0, v23
	v_rcp_f32_e32 v24, v24
	v_add_f32_e32 v20, 1.0, v20
	v_rcp_f32_e32 v25, v25
	v_add_f32_e32 v21, 1.0, v21
	v_rcp_f32_e32 v22, v22
	v_rcp_f32_e32 v23, v23
	v_rcp_f32_e32 v20, v20
	v_rcp_f32_e32 v21, v21
	v_and_b32_e32 v27, 0xffff0000, v44
	v_lshlrev_b32_e32 v26, 16, v44
	v_pk_mul_f32 v[18:19], v[18:19], v[26:27]
	v_and_b32_e32 v27, 0xffff0000, v43
	v_lshlrev_b32_e32 v26, 16, v43
	v_pk_mul_f32 v[24:25], v[24:25], v[26:27]
	v_and_b32_e32 v27, 0xffff0000, v45
	v_lshlrev_b32_e32 v26, 16, v45
	v_pk_mul_f32 v[22:23], v[22:23], v[32:33]
	v_pk_mul_f32 v[26:27], v[20:21], v[26:27]
	v_cvt_pk_bf16_f32 v20, v22, v23
	v_cvt_pk_bf16_f32 v21, v24, v25
	v_cvt_pk_bf16_f32 v22, v18, v19
	v_cvt_pk_bf16_f32 v23, v26, v27
	global_store_dwordx4 v[30:31], v[20:23], off offset:256
	s_nop 0
	v_add_f32_e32 v10, v10, v218
	v_add_f32_e32 v11, v11, v219
	v_mul_f32_e32 v10, 0xbfb8aa3b, v10
	v_mul_f32_e32 v11, 0xbfb8aa3b, v11
	v_exp_f32_e32 v10, v10
	v_exp_f32_e32 v11, v11
	v_and_b32_e32 v19, 0xffff0000, v40
	v_lshlrev_b32_e32 v18, 16, v40
	v_add_f32_e32 v10, 1.0, v10
	v_add_f32_e32 v11, 1.0, v11
	v_rcp_f32_e32 v10, v10
	v_rcp_f32_e32 v11, v11
	v_add_f32_e32 v14, v14, v214
	v_add_f32_e32 v15, v15, v215
	v_mul_f32_e32 v14, 0xbfb8aa3b, v14
	v_pk_mul_f32 v[18:19], v[10:11], v[18:19]
	v_add_f32_e32 v11, v12, v220
	v_mul_f32_e32 v11, 0xbfb8aa3b, v11
	v_exp_f32_e32 v11, v11
	v_add_f32_e32 v10, v16, v216
	v_mul_f32_e32 v10, 0xbfb8aa3b, v10
	v_exp_f32_e32 v10, v10
	v_add_f32_e32 v11, 1.0, v11
	v_rcp_f32_e32 v12, v11
	v_add_f32_e32 v11, v17, v217
	v_mul_f32_e32 v11, 0xbfb8aa3b, v11
	v_exp_f32_e32 v11, v11
	v_add_f32_e32 v10, 1.0, v10
	v_rcp_f32_e32 v10, v10
	v_and_b32_e32 v17, 0xffff0000, v39
	v_add_f32_e32 v11, 1.0, v11
	v_rcp_f32_e32 v11, v11
	v_lshlrev_b32_e32 v16, 16, v39
	v_mul_f32_e32 v15, 0xbfb8aa3b, v15
	v_exp_f32_e32 v14, v14
	v_pk_mul_f32 v[16:17], v[10:11], v[16:17]
	v_add_f32_e32 v10, v13, v221
	v_exp_f32_e32 v15, v15
	v_mul_f32_e32 v10, 0xbfb8aa3b, v10
	v_exp_f32_e32 v10, v10
	v_add_f32_e32 v14, 1.0, v14
	v_add_f32_e32 v15, 1.0, v15
	v_rcp_f32_e32 v14, v14
	v_rcp_f32_e32 v15, v15
	v_add_f32_e32 v10, 1.0, v10
	v_rcp_f32_e32 v13, v10
	v_and_b32_e32 v23, 0xffff0000, v38
	v_lshlrev_b32_e32 v22, 16, v38
	v_pk_mul_f32 v[14:15], v[14:15], v[22:23]
	v_and_b32_e32 v11, 0xffff0000, v41
	v_lshlrev_b32_e32 v10, 16, v41
	v_pk_mul_f32 v[20:21], v[12:13], v[10:11]
	v_cvt_pk_bf16_f32 v10, v14, v15
	v_lshl_add_u64 v[14:15], s[64:65], 0, v[54:55]
	v_cvt_pk_bf16_f32 v11, v16, v17
	v_cvt_pk_bf16_f32 v12, v18, v19
	v_cvt_pk_bf16_f32 v13, v20, v21
	v_lshl_add_u64 v[14:15], v[14:15], 0, v[176:177]
	global_store_dwordx4 v[14:15], v[10:13], off
	s_nop 0
	v_add_f32_e32 v0, v0, v226
	v_add_f32_e32 v1, v1, v227
	v_mul_f32_e32 v0, 0xbfb8aa3b, v0
	v_mul_f32_e32 v1, 0xbfb8aa3b, v1
	v_exp_f32_e32 v0, v0
	v_exp_f32_e32 v1, v1
	v_and_b32_e32 v11, 0xffff0000, v36
	v_lshlrev_b32_e32 v10, 16, v36
	v_add_f32_e32 v0, 1.0, v0
	v_add_f32_e32 v1, 1.0, v1
	v_rcp_f32_e32 v0, v0
	v_rcp_f32_e32 v1, v1
	v_add_f32_e32 v4, v4, v222
	v_add_f32_e32 v5, v5, v223
	v_mul_f32_e32 v4, 0xbfb8aa3b, v4
	v_pk_mul_f32 v[10:11], v[0:1], v[10:11]
	v_add_f32_e32 v1, v2, v228
	v_mul_f32_e32 v1, 0xbfb8aa3b, v1
	v_exp_f32_e32 v1, v1
	v_add_f32_e32 v0, v6, v224
	v_mul_f32_e32 v0, 0xbfb8aa3b, v0
	v_exp_f32_e32 v0, v0
	v_add_f32_e32 v1, 1.0, v1
	v_rcp_f32_e32 v2, v1
	v_add_f32_e32 v1, v7, v225
	v_mul_f32_e32 v1, 0xbfb8aa3b, v1
	v_exp_f32_e32 v1, v1
	v_add_f32_e32 v0, 1.0, v0
	v_rcp_f32_e32 v0, v0
	v_and_b32_e32 v7, 0xffff0000, v35
	v_add_f32_e32 v1, 1.0, v1
	v_rcp_f32_e32 v1, v1
	v_lshlrev_b32_e32 v6, 16, v35
	v_mul_f32_e32 v5, 0xbfb8aa3b, v5
	v_exp_f32_e32 v4, v4
	v_pk_mul_f32 v[6:7], v[0:1], v[6:7]
	v_add_f32_e32 v0, v3, v229
	v_mul_f32_e32 v0, 0xbfb8aa3b, v0
	v_exp_f32_e32 v5, v5
	v_exp_f32_e32 v0, v0
	v_add_f32_e32 v4, 1.0, v4
	v_rcp_f32_e32 v4, v4
	v_add_f32_e32 v5, 1.0, v5
	v_add_f32_e32 v0, 1.0, v0
	v_rcp_f32_e32 v5, v5
	v_rcp_f32_e32 v3, v0
	v_and_b32_e32 v17, 0xffff0000, v34
	v_lshlrev_b32_e32 v16, 16, v34
	v_and_b32_e32 v1, 0xffff0000, v37
	v_lshlrev_b32_e32 v0, 16, v37
	v_pk_mul_f32 v[4:5], v[4:5], v[16:17]
	v_pk_mul_f32 v[12:13], v[2:3], v[0:1]
	v_cvt_pk_bf16_f32 v0, v4, v5
	v_cvt_pk_bf16_f32 v1, v6, v7
	v_cvt_pk_bf16_f32 v2, v10, v11
	v_cvt_pk_bf16_f32 v3, v12, v13
	global_store_dwordx4 v[14:15], v[0:3], off offset:256
	s_cbranch_vccz .LBB0_1339
	s_waitcnt vmcnt(0)
	s_cmpk_gt_u32 s46, 0xff
	s_cbranch_scc1 .LBB0_1350
	s_barrier

; #define PG8_STAGE(bufoff, gbase, voff) do { _Pragma("unroll") for (int _i = 0; _i < 2; ++_i) \
;         __builtin_amdgcn_global_load_lds((const unsigned*)((const char*)(gbase) + (voff)[_i]), (LAS unsigned*)(lds + (bufoff) + ldsw + _i * 8192), 16, 0, 0); } while (0)
; #define PG8_LDA(dst, b, h) do { _Pragma("unroll") for (int m = 0; m < 4; ++m) _Pragma("unroll") for (int k = 0; k < 2; ++k) dst[m][k] = *(const LAS bf16x8*)(lds + PG8_SA(b, h) + aoff + m * 2048 + k * 1024); } while (0)
; #define PG8_LDB(dst, b, h) do { _Pragma("unroll") for (int n = 0; n < 2; ++n) _Pragma("unroll") for (int k = 0; k < 2; ++k) dst[n][k] = *(const LAS bf16x8*)(lds + PG8_SB(b, h) + boff + n * 2048 + k * 1024); } while (0)
; #define PG8_MMA(ai, bj, At, Bt) do { __builtin_amdgcn_s_setprio(1); _Pragma("unroll") for (int m = 0; m < 4; ++m) _Pragma("unroll") for (int n = 0; n < 2; ++n) _Pragma("unroll") for (int k = 0; k < 2; ++k) \
;         acc[ai][bj][m][n] = __builtin_amdgcn_mfma_f32_16x16x32_bf16(Bt[n][k], At[m][k], acc[ai][bj][m][n], 0, 0, 0); __builtin_amdgcn_s_setprio(0); } while (0)
; template <class Epi>
; DEVI void gemm_phase(LAS unsigned char* lds, const Gemm g, const Epi& E) {
;     ...
;         for (int t = 0; t < nt; t += 2) {
;             const bool last = (t == nt - 2);
;             const char* a1 = cA + (size_t)(t + 1) * kstep;
;             const char* a2 = last ? nA : cA + (size_t)(t + 2) * kstep; const char* b2 = last ? nB : cB + (size_t)(t + 2) * kstep;
;             const char* a3 = a2 + kstep; const char* b3 = b2 + kstep;
;             PG8_LDB(B0, 0, 0); PG8_SCHED; PG8_LDA(At, 0, 0); PG8_STAGE(PG8_SA(1, 1), a1 + hstepA, voffA);
;             PG8_WAIT_L(8); PG8_BAR; PG8_WAIT_L(0); PG8_MMA(0, 0, At, B0); PG8_BAR; PG8_SCHED;
;             PG8_LDB(B1, 0, 1); PG8_STAGE(PG8_SB(0, 0), b2, voffB);
;             PG8_BAR; PG8_WAIT_L(0); PG8_MMA(0, 1, At, B1); PG8_BAR;
;             PG8_LDA(At, 0, 1); PG8_STAGE(PG8_SA(0, 0), a2, voffA);
;             PG8_BAR; PG8_WAIT_L(0); PG8_MMA(1, 0, At, B0); PG8_BAR; PG8_SCHED;
;             PG8_STAGE(PG8_SB(0, 1), b2 + hstepB, voffB);
;             PG8_WAIT_V(6); PG8_BAR; PG8_MMA(1, 1, At, B1); PG8_BAR;
;             PG8_LDB(B0, 1, 0); PG8_SCHED; PG8_LDA(At, 1, 0); PG8_STAGE(PG8_SA(0, 1), a2 + hstepA, voffA);
;             PG8_WAIT_L(8); PG8_BAR; PG8_WAIT_L(0); PG8_MMA(0, 0, At, B0); PG8_BAR; PG8_SCHED;
.LBB0_1507:
	s_add_u32 s19, s6, 0xfffc0080
	s_addc_u32 s26, s7, -1
	s_add_i32 s27, 0, 0x10000
	v_add_u32_e32 v142, s27, v199
	ds_read_b128 v[130:133], v142
	ds_read_b128 v[134:137], v142 offset:1024
	ds_read_b128 v[138:141], v142 offset:2048
	ds_read_b128 v[142:145], v142 offset:3072
	s_cmp_eq_u32 s18, 12
	s_cselect_b32 s79, s0, s26
	s_cselect_b32 s78, s1, s19
	s_cselect_b32 s69, s15, s13
	s_cselect_b32 s68, s14, s11
	v_lshl_add_u64 v[162:163], s[6:7], 0, v[182:183]
	s_add_i32 m0, s37, 0xc000
	ds_read_b128 v[146:149], v202
	ds_read_b128 v[150:153], v202 offset:1024
	ds_read_b128 v[186:189], v202 offset:2048
	ds_read_b128 v[190:193], v202 offset:3072
	ds_read_b128 v[194:197], v202 offset:4096
	ds_read_b128 v[204:207], v202 offset:5120
	ds_read_b128 v[214:217], v202 offset:6144
	ds_read_b128 v[218:221], v202 offset:7168
	global_load_lds_dwordx4 v[162:163], off
	v_lshl_add_u64 v[162:163], s[6:7], 0, v[184:185]
	s_add_i32 m0, s37, 0xe000
	s_nop 0
	global_load_lds_dwordx4 v[162:163], off
	s_waitcnt lgkmcnt(8)
	s_barrier
	s_waitcnt lgkmcnt(0)
	v_mfma_f32_16x16x32_bf16 v[126:129], v[130:133], v[146:149], v[126:129]
	v_mfma_f32_16x16x32_bf16 v[122:125], v[138:141], v[146:149], v[122:125]
	v_mfma_f32_16x16x32_bf16 v[110:113], v[130:133], v[186:189], v[110:113]
	v_mfma_f32_16x16x32_bf16 v[106:109], v[138:141], v[186:189], v[106:109]
	v_mfma_f32_16x16x32_bf16 v[94:97], v[130:133], v[194:197], v[94:97]
	v_mfma_f32_16x16x32_bf16 v[90:93], v[138:141], v[194:197], v[90:93]
	v_mfma_f32_16x16x32_bf16 v[78:81], v[130:133], v[214:217], v[78:81]
	v_mfma_f32_16x16x32_bf16 v[74:77], v[138:141], v[214:217], v[74:77]
	v_mfma_f32_16x16x32_bf16 v[126:129], v[134:137], v[150:153], v[126:129]
	v_mfma_f32_16x16x32_bf16 v[122:125], v[142:145], v[150:153], v[122:125]
	v_mfma_f32_16x16x32_bf16 v[110:113], v[134:137], v[190:193], v[110:113]
	v_mfma_f32_16x16x32_bf16 v[106:109], v[142:145], v[190:193], v[106:109]
	v_mfma_f32_16x16x32_bf16 v[94:97], v[134:137], v[204:207], v[94:97]
	v_mfma_f32_16x16x32_bf16 v[90:93], v[142:145], v[204:207], v[90:93]
	v_mfma_f32_16x16x32_bf16 v[78:81], v[134:137], v[218:221], v[78:81]
	v_mfma_f32_16x16x32_bf16 v[74:77], v[142:145], v[218:221], v[74:77]
	s_barrier
	s_add_i32 s19, 0, 0x14000
	v_add_u32_e32 v162, s19, v199
	s_add_i32 s26, s27, s80
	ds_read_b128 v[222:225], v162
	ds_read_b128 v[226:229], v162 offset:1024
	ds_read_b128 v[230:233], v162 offset:2048
	ds_read_b128 v[234:237], v162 offset:3072
	v_lshl_add_u64 v[162:163], s[68:69], 0, v[8:9]
	s_mov_b32 m0, s26
	v_lshl_add_u64 v[164:165], s[68:69], 0, v[180:181]
	global_load_lds_dwordx4 v[162:163], off
	s_add_i32 m0, s26, 0x2000
	s_nop 0
	global_load_lds_dwordx4 v[164:165], off
	s_barrier
	s_waitcnt lgkmcnt(0)
	v_mfma_f32_16x16x32_bf16 v[118:121], v[222:225], v[146:149], v[118:121]
	v_mfma_f32_16x16x32_bf16 v[114:117], v[230:233], v[146:149], v[114:117]
	v_mfma_f32_16x16x32_bf16 v[102:105], v[222:225], v[186:189], v[102:105]
	v_mfma_f32_16x16x32_bf16 v[98:101], v[230:233], v[186:189], v[98:101]
	v_mfma_f32_16x16x32_bf16 v[86:89], v[222:225], v[194:197], v[86:89]
	v_mfma_f32_16x16x32_bf16 v[82:85], v[230:233], v[194:197], v[82:85]
	v_mfma_f32_16x16x32_bf16 v[70:73], v[222:225], v[214:217], v[70:73]
	v_mfma_f32_16x16x32_bf16 v[62:65], v[230:233], v[214:217], v[62:65]
	v_mfma_f32_16x16x32_bf16 v[118:121], v[226:229], v[150:153], v[118:121]
	v_mfma_f32_16x16x32_bf16 v[114:117], v[234:237], v[150:153], v[114:117]
	v_mfma_f32_16x16x32_bf16 v[102:105], v[226:229], v[190:193], v[102:105]
	v_mfma_f32_16x16x32_bf16 v[98:101], v[234:237], v[190:193], v[98:101]
	v_mfma_f32_16x16x32_bf16 v[86:89], v[226:229], v[204:207], v[86:89]
	v_mfma_f32_16x16x32_bf16 v[82:85], v[234:237], v[204:207], v[82:85]
	v_mfma_f32_16x16x32_bf16 v[70:73], v[226:229], v[218:221], v[70:73]
	v_mfma_f32_16x16x32_bf16 v[62:65], v[234:237], v[218:221], v[62:65]
	s_mov_b32 m0, s37
	v_lshl_add_u64 v[208:209], s[78:79], 0, v[176:177]
	s_barrier
	ds_read_b128 v[146:149], v202 offset:16384
	ds_read_b128 v[150:153], v202 offset:17408
	ds_read_b128 v[186:189], v202 offset:18432
	ds_read_b128 v[190:193], v202 offset:19456
	ds_read_b128 v[194:197], v202 offset:20480
	ds_read_b128 v[204:207], v202 offset:21504
	ds_read_b128 v[214:217], v202 offset:22528
	ds_read_b128 v[218:221], v202 offset:23552
	global_load_lds_dwordx4 v[208:209], off
	v_lshl_add_u64 v[238:239], s[78:79], 0, v[178:179]
	s_mov_b32 m0, s47
	s_nop 0
	global_load_lds_dwordx4 v[238:239], off
	s_barrier
	s_waitcnt lgkmcnt(0)
	v_mfma_f32_16x16x32_bf16 v[66:69], v[130:133], v[146:149], v[66:69]
	v_mfma_f32_16x16x32_bf16 v[54:57], v[138:141], v[146:149], v[54:57]
	v_mfma_f32_16x16x32_bf16 v[46:49], v[130:133], v[186:189], v[46:49]
	v_mfma_f32_16x16x32_bf16 v[38:41], v[138:141], v[186:189], v[38:41]
	v_mfma_f32_16x16x32_bf16 v[30:33], v[130:133], v[194:197], v[30:33]
	v_mfma_f32_16x16x32_bf16 v[22:25], v[138:141], v[194:197], v[22:25]
	v_mfma_f32_16x16x32_bf16 v[14:17], v[130:133], v[214:217], v[14:17]
	v_mfma_f32_16x16x32_bf16 v[4:7], v[138:141], v[214:217], v[4:7]
	v_mfma_f32_16x16x32_bf16 v[66:69], v[134:137], v[150:153], v[66:69]
	v_mfma_f32_16x16x32_bf16 v[54:57], v[142:145], v[150:153], v[54:57]
	v_mfma_f32_16x16x32_bf16 v[46:49], v[134:137], v[190:193], v[46:49]
	v_mfma_f32_16x16x32_bf16 v[38:41], v[142:145], v[190:193], v[38:41]
	v_mfma_f32_16x16x32_bf16 v[30:33], v[134:137], v[204:207], v[30:33]
	v_mfma_f32_16x16x32_bf16 v[22:25], v[142:145], v[204:207], v[22:25]
	v_mfma_f32_16x16x32_bf16 v[14:17], v[134:137], v[218:221], v[14:17]
	v_mfma_f32_16x16x32_bf16 v[4:7], v[142:145], v[218:221], v[4:7]
	s_barrier
; #define PG8_STAGE(bufoff, gbase, voff) do { _Pragma("unroll") for (int _i = 0; _i < 2; ++_i) \
;         __builtin_amdgcn_global_load_lds((const unsigned*)((const char*)(gbase) + (voff)[_i]), (LAS unsigned*)(lds + (bufoff) + ldsw + _i * 8192), 16, 0, 0); } while (0)
; #define PG8_LDA(dst, b, h) do { _Pragma("unroll") for (int m = 0; m < 4; ++m) _Pragma("unroll") for (int k = 0; k < 2; ++k) dst[m][k] = *(const LAS bf16x8*)(lds + PG8_SA(b, h) + aoff + m * 2048 + k * 1024); } while (0)
; #define PG8_LDB(dst, b, h) do { _Pragma("unroll") for (int n = 0; n < 2; ++n) _Pragma("unroll") for (int k = 0; k < 2; ++k) dst[n][k] = *(const LAS bf16x8*)(lds + PG8_SB(b, h) + boff + n * 2048 + k * 1024); } while (0)
; #define PG8_MMA(ai, bj, At, Bt) do { __builtin_amdgcn_s_setprio(1); _Pragma("unroll") for (int m = 0; m < 4; ++m) _Pragma("unroll") for (int n = 0; n < 2; ++n) _Pragma("unroll") for (int k = 0; k < 2; ++k) \
;         acc[ai][bj][m][n] = __builtin_amdgcn_mfma_f32_16x16x32_bf16(Bt[n][k], At[m][k], acc[ai][bj][m][n], 0, 0, 0); __builtin_amdgcn_s_setprio(0); } while (0)
; #define PG8_WAIT_V(n) asm volatile("s_waitcnt vmcnt(" #n ")" ::: "memory")
; #define PG8_WAIT_L(n) asm volatile("s_waitcnt lgkmcnt(" #n ")" ::: "memory")
; #define PG8_BAR __builtin_amdgcn_s_barrier()
; #define PG8_SCHED __builtin_amdgcn_sched_barrier(0)
; template <class Epi>
; DEVI void gemm_phase(LAS unsigned char* lds, const Gemm g, const Epi& E) {
;     ...
;             PG8_STAGE(PG8_SB(0, 1), b2 + hstepB, voffB);
;             PG8_WAIT_V(6); PG8_BAR; PG8_MMA(1, 1, At, B1); PG8_BAR;
;             PG8_LDB(B0, 1, 0); PG8_SCHED; PG8_LDA(At, 1, 0); PG8_STAGE(PG8_SA(0, 1), a2 + hstepA, voffA);
;             PG8_WAIT_L(8); PG8_BAR; PG8_WAIT_L(0); PG8_MMA(0, 0, At, B0); PG8_BAR; PG8_SCHED;
;             PG8_LDB(B1, 1, 1); PG8_STAGE(PG8_SB(1, 0), b3, voffB);
;             PG8_BAR; PG8_WAIT_L(0); PG8_MMA(0, 1, At, B1); PG8_BAR;
;             PG8_LDA(At, 1, 1); PG8_STAGE(PG8_SA(1, 0), a3, voffA);
	s_add_u32 s26, s68, 0x40000
	s_addc_u32 s27, s69, 0
	s_add_i32 s19, s19, s80
	v_lshl_add_u64 v[130:131], s[26:27], 0, v[8:9]
	s_mov_b32 m0, s19
	s_nop 0
	global_load_lds_dwordx4 v[130:131], off
	v_lshl_add_u64 v[130:131], s[26:27], 0, v[180:181]
	s_add_i32 m0, s19, 0x2000
	s_nop 0
	global_load_lds_dwordx4 v[130:131], off
	s_waitcnt vmcnt(6)
	s_barrier
	v_mfma_f32_16x16x32_bf16 v[58:61], v[222:225], v[146:149], v[58:61]
	v_mfma_f32_16x16x32_bf16 v[50:53], v[230:233], v[146:149], v[50:53]
	v_mfma_f32_16x16x32_bf16 v[42:45], v[222:225], v[186:189], v[42:45]
	v_mfma_f32_16x16x32_bf16 v[34:37], v[230:233], v[186:189], v[34:37]
	v_mfma_f32_16x16x32_bf16 v[26:29], v[222:225], v[194:197], v[26:29]
	v_mfma_f32_16x16x32_bf16 v[18:21], v[230:233], v[194:197], v[18:21]
	v_mfma_f32_16x16x32_bf16 v[10:13], v[222:225], v[214:217], v[10:13]
	v_mfma_f32_16x16x32_bf16 v[0:3], v[230:233], v[214:217], v[0:3]
	v_mfma_f32_16x16x32_bf16 v[58:61], v[226:229], v[150:153], v[58:61]
	v_mfma_f32_16x16x32_bf16 v[50:53], v[234:237], v[150:153], v[50:53]
	v_mfma_f32_16x16x32_bf16 v[42:45], v[226:229], v[190:193], v[42:45]
	v_mfma_f32_16x16x32_bf16 v[34:37], v[234:237], v[190:193], v[34:37]
	v_mfma_f32_16x16x32_bf16 v[26:29], v[226:229], v[204:207], v[26:29]
	v_mfma_f32_16x16x32_bf16 v[18:21], v[234:237], v[204:207], v[18:21]
	v_mfma_f32_16x16x32_bf16 v[10:13], v[226:229], v[218:221], v[10:13]
	v_mfma_f32_16x16x32_bf16 v[0:3], v[234:237], v[218:221], v[0:3]
	s_add_i32 s19, 0, 0x18000
	v_add_u32_e32 v142, s19, v199
	s_barrier
	ds_read_b128 v[130:133], v142
	ds_read_b128 v[134:137], v142 offset:1024
	ds_read_b128 v[138:141], v142 offset:2048
	ds_read_b128 v[142:145], v142 offset:3072
	s_add_u32 s26, s78, 0x40000
	s_addc_u32 s27, s79, 0
	s_mov_b32 m0, s81
	v_lshl_add_u64 v[222:223], s[26:27], 0, v[176:177]
	ds_read_b128 v[146:149], v202 offset:32768
	ds_read_b128 v[150:153], v202 offset:33792
	ds_read_b128 v[186:189], v202 offset:34816
	ds_read_b128 v[190:193], v202 offset:35840
	ds_read_b128 v[194:197], v202 offset:36864
	ds_read_b128 v[204:207], v202 offset:37888
	ds_read_b128 v[214:217], v202 offset:38912
	ds_read_b128 v[218:221], v202 offset:39936
	global_load_lds_dwordx4 v[222:223], off
	v_lshl_add_u64 v[222:223], s[26:27], 0, v[178:179]
	s_mov_b32 m0, s82
	s_nop 0
	global_load_lds_dwordx4 v[222:223], off
	s_waitcnt lgkmcnt(8)
	s_barrier
	s_waitcnt lgkmcnt(0)
	v_mfma_f32_16x16x32_bf16 v[126:129], v[130:133], v[146:149], v[126:129]
	v_mfma_f32_16x16x32_bf16 v[122:125], v[138:141], v[146:149], v[122:125]
	v_mfma_f32_16x16x32_bf16 v[110:113], v[130:133], v[186:189], v[110:113]
	v_mfma_f32_16x16x32_bf16 v[106:109], v[138:141], v[186:189], v[106:109]
	v_mfma_f32_16x16x32_bf16 v[94:97], v[130:133], v[194:197], v[94:97]
	v_mfma_f32_16x16x32_bf16 v[90:93], v[138:141], v[194:197], v[90:93]
	v_mfma_f32_16x16x32_bf16 v[78:81], v[130:133], v[214:217], v[78:81]
	v_mfma_f32_16x16x32_bf16 v[74:77], v[138:141], v[214:217], v[74:77]
	v_mfma_f32_16x16x32_bf16 v[126:129], v[134:137], v[150:153], v[126:129]
	v_mfma_f32_16x16x32_bf16 v[122:125], v[142:145], v[150:153], v[122:125]
	v_mfma_f32_16x16x32_bf16 v[110:113], v[134:137], v[190:193], v[110:113]
	v_mfma_f32_16x16x32_bf16 v[106:109], v[142:145], v[190:193], v[106:109]
	v_mfma_f32_16x16x32_bf16 v[94:97], v[134:137], v[204:207], v[94:97]
	v_mfma_f32_16x16x32_bf16 v[90:93], v[142:145], v[204:207], v[90:93]
	v_mfma_f32_16x16x32_bf16 v[78:81], v[134:137], v[218:221], v[78:81]
	v_mfma_f32_16x16x32_bf16 v[74:77], v[142:145], v[218:221], v[74:77]
	s_barrier
	s_add_i32 s38, 0, 0x1c000
	s_add_i32 s19, s19, s80
	v_add_u32_e32 v213, s38, v199
	v_lshl_add_u64 v[162:163], v[162:163], 0, s[70:71]
	s_mov_b32 m0, s19
	ds_read_b128 v[222:225], v213
	ds_read_b128 v[226:229], v213 offset:1024
	ds_read_b128 v[230:233], v213 offset:2048
	ds_read_b128 v[234:237], v213 offset:3072
	global_load_lds_dwordx4 v[162:163], off
	v_lshl_add_u64 v[162:163], v[164:165], 0, s[70:71]
	s_add_i32 m0, s19, 0x2000
	s_nop 0
	global_load_lds_dwordx4 v[162:163], off
	s_barrier
	s_waitcnt lgkmcnt(0)
	v_mfma_f32_16x16x32_bf16 v[118:121], v[222:225], v[146:149], v[118:121]
	v_mfma_f32_16x16x32_bf16 v[114:117], v[230:233], v[146:149], v[114:117]
	v_mfma_f32_16x16x32_bf16 v[102:105], v[222:225], v[186:189], v[102:105]
	v_mfma_f32_16x16x32_bf16 v[98:101], v[230:233], v[186:189], v[98:101]
	v_mfma_f32_16x16x32_bf16 v[86:89], v[222:225], v[194:197], v[86:89]
	v_mfma_f32_16x16x32_bf16 v[82:85], v[230:233], v[194:197], v[82:85]
	v_mfma_f32_16x16x32_bf16 v[70:73], v[222:225], v[214:217], v[70:73]
	v_mfma_f32_16x16x32_bf16 v[62:65], v[230:233], v[214:217], v[62:65]
	v_mfma_f32_16x16x32_bf16 v[118:121], v[226:229], v[150:153], v[118:121]
	v_mfma_f32_16x16x32_bf16 v[114:117], v[234:237], v[150:153], v[114:117]
	v_mfma_f32_16x16x32_bf16 v[102:105], v[226:229], v[190:193], v[102:105]
	v_mfma_f32_16x16x32_bf16 v[98:101], v[234:237], v[190:193], v[98:101]
	v_mfma_f32_16x16x32_bf16 v[86:89], v[226:229], v[204:207], v[86:89]
	v_mfma_f32_16x16x32_bf16 v[82:85], v[234:237], v[204:207], v[82:85]
	v_mfma_f32_16x16x32_bf16 v[70:73], v[226:229], v[218:221], v[70:73]
	v_mfma_f32_16x16x32_bf16 v[62:65], v[234:237], v[218:221], v[62:65]
	s_mov_b32 m0, s83
	v_lshl_add_u64 v[162:163], v[208:209], 0, s[70:71]
	s_barrier
	ds_read_b128 v[146:149], v202 offset:49152
	ds_read_b128 v[150:153], v202 offset:50176
	ds_read_b128 v[186:189], v202 offset:51200
	ds_read_b128 v[190:193], v202 offset:52224
	ds_read_b128 v[194:197], v202 offset:53248
	ds_read_b128 v[204:207], v202 offset:54272
	ds_read_b128 v[214:217], v202 offset:55296
	ds_read_b128 v[218:221], v202 offset:56320
	global_load_lds_dwordx4 v[162:163], off
	v_lshl_add_u64 v[162:163], v[238:239], 0, s[70:71]
	s_mov_b32 m0, s84
	s_nop 0
	global_load_lds_dwordx4 v[162:163], off
	s_barrier
; #define PG8_STAGE(bufoff, gbase, voff) do { _Pragma("unroll") for (int _i = 0; _i < 2; ++_i) \
;         __builtin_amdgcn_global_load_lds((const unsigned*)((const char*)(gbase) + (voff)[_i]), (LAS unsigned*)(lds + (bufoff) + ldsw + _i * 8192), 16, 0, 0); } while (0)
; #define PG8_MMA(ai, bj, At, Bt) do { __builtin_amdgcn_s_setprio(1); _Pragma("unroll") for (int m = 0; m < 4; ++m) _Pragma("unroll") for (int n = 0; n < 2; ++n) _Pragma("unroll") for (int k = 0; k < 2; ++k) \
;         acc[ai][bj][m][n] = __builtin_amdgcn_mfma_f32_16x16x32_bf16(Bt[n][k], At[m][k], acc[ai][bj][m][n], 0, 0, 0); __builtin_amdgcn_s_setprio(0); } while (0)
; #define PG8_WAIT_V(n) asm volatile("s_waitcnt vmcnt(" #n ")" ::: "memory")
; #define PG8_WAIT_L(n) asm volatile("s_waitcnt lgkmcnt(" #n ")" ::: "memory")
; #define PG8_BAR __builtin_amdgcn_s_barrier()
; #define PG8_SCHED __builtin_amdgcn_sched_barrier(0)
; template <class Epi>
; DEVI void gemm_phase(LAS unsigned char* lds, const Gemm g, const Epi& E) {
;     ...
;             PG8_BAR; PG8_WAIT_L(0); PG8_MMA(1, 0, At, B0); PG8_BAR; PG8_SCHED;
;             PG8_STAGE(PG8_SB(1, 1), b3 + hstepB, voffB);
;             PG8_WAIT_V(6); PG8_BAR; PG8_MMA(1, 1, At, B1); PG8_BAR;
;         }
	s_waitcnt lgkmcnt(0)
	v_mfma_f32_16x16x32_bf16 v[66:69], v[130:133], v[146:149], v[66:69]
	v_mfma_f32_16x16x32_bf16 v[54:57], v[138:141], v[146:149], v[54:57]
	v_mfma_f32_16x16x32_bf16 v[46:49], v[130:133], v[186:189], v[46:49]
	v_mfma_f32_16x16x32_bf16 v[38:41], v[138:141], v[186:189], v[38:41]
	v_mfma_f32_16x16x32_bf16 v[30:33], v[130:133], v[194:197], v[30:33]
	v_mfma_f32_16x16x32_bf16 v[22:25], v[138:141], v[194:197], v[22:25]
	v_mfma_f32_16x16x32_bf16 v[14:17], v[130:133], v[214:217], v[14:17]
	v_mfma_f32_16x16x32_bf16 v[4:7], v[138:141], v[214:217], v[4:7]
	v_mfma_f32_16x16x32_bf16 v[66:69], v[134:137], v[150:153], v[66:69]
	v_mfma_f32_16x16x32_bf16 v[54:57], v[142:145], v[150:153], v[54:57]
	v_mfma_f32_16x16x32_bf16 v[46:49], v[134:137], v[190:193], v[46:49]
	v_mfma_f32_16x16x32_bf16 v[38:41], v[142:145], v[190:193], v[38:41]
	v_mfma_f32_16x16x32_bf16 v[30:33], v[134:137], v[204:207], v[30:33]
	v_mfma_f32_16x16x32_bf16 v[22:25], v[142:145], v[204:207], v[22:25]
	v_mfma_f32_16x16x32_bf16 v[14:17], v[134:137], v[218:221], v[14:17]
	v_mfma_f32_16x16x32_bf16 v[4:7], v[142:145], v[218:221], v[4:7]
	s_barrier
	s_add_u32 s26, s68, 0x40080
	s_addc_u32 s27, s69, 0
	s_add_i32 s19, s38, s80
	v_lshl_add_u64 v[130:131], s[26:27], 0, v[8:9]
	s_mov_b32 m0, s19
	s_nop 0
	global_load_lds_dwordx4 v[130:131], off
	v_lshl_add_u64 v[130:131], s[26:27], 0, v[180:181]
	s_add_i32 m0, s19, 0x2000
	s_nop 0
	global_load_lds_dwordx4 v[130:131], off
	s_waitcnt vmcnt(6)
	s_barrier
	v_mfma_f32_16x16x32_bf16 v[58:61], v[222:225], v[146:149], v[58:61]
	v_mfma_f32_16x16x32_bf16 v[50:53], v[230:233], v[146:149], v[50:53]
	v_mfma_f32_16x16x32_bf16 v[42:45], v[222:225], v[186:189], v[42:45]
	v_mfma_f32_16x16x32_bf16 v[34:37], v[230:233], v[186:189], v[34:37]
	v_mfma_f32_16x16x32_bf16 v[26:29], v[222:225], v[194:197], v[26:29]
	v_mfma_f32_16x16x32_bf16 v[18:21], v[230:233], v[194:197], v[18:21]
	v_mfma_f32_16x16x32_bf16 v[10:13], v[222:225], v[214:217], v[10:13]
	v_mfma_f32_16x16x32_bf16 v[0:3], v[230:233], v[214:217], v[0:3]
	v_mfma_f32_16x16x32_bf16 v[58:61], v[226:229], v[150:153], v[58:61]
	v_mfma_f32_16x16x32_bf16 v[50:53], v[234:237], v[150:153], v[50:53]
	v_mfma_f32_16x16x32_bf16 v[42:45], v[226:229], v[190:193], v[42:45]
	v_mfma_f32_16x16x32_bf16 v[34:37], v[234:237], v[190:193], v[34:37]
	v_mfma_f32_16x16x32_bf16 v[26:29], v[226:229], v[204:207], v[26:29]
	v_mfma_f32_16x16x32_bf16 v[18:21], v[234:237], v[204:207], v[18:21]
	v_mfma_f32_16x16x32_bf16 v[10:13], v[226:229], v[218:221], v[10:13]
	v_mfma_f32_16x16x32_bf16 v[0:3], v[234:237], v[218:221], v[0:3]
	s_add_i32 s18, s18, 2
	s_add_u32 s6, s6, 0x100
	s_addc_u32 s7, s7, 0
	s_add_u32 s11, s11, 0x100
	s_addc_u32 s13, s13, 0
	s_cmp_gt_u32 s18, 13
	s_barrier
	s_cbranch_scc0 .LBB0_1507
; #define LAS __attribute__((address_space(3)))
; template <class Epi>
; DEVI void gemm_phase(LAS unsigned char* lds, const Gemm g, const Epi& E) {
;     ...
;             const int row0 = cur.pm * BM + wr * 64 + fr, col0 = cur.pn * BM + wc * 32 + (Epi::PERM ? 8 : 4) * fq; constexpr int NST = Epi::PERM ? 4 : 16;
;             float rsv[8];
;             if constexpr (Epi::RS) { f32x4 q4[8];
; #pragma unroll
;                 for (int i = 0; i < 8; ++i) q4[i] = *(const f32x4*)(E.ssq_in + (size_t)(row0 + (i >> 2) * HALF + (i & 3) * 16) * 4);
; #pragma unroll
;                 for (int i = 0; i < 8; ++i) rsv[i] = rsqrtf((((q4[i][0] + q4[i][1]) + q4[i][2]) + q4[i][3]) * (1.f / DM) + 1e-6f); }
;             if constexpr (Epi::SOFTMAX) {
;                 LAS float* red = (LAS float*)(lds + 131072);
; #pragma unroll
;                 for (int ai = 0; ai < 2; ++ai)
; #pragma unroll
;                     for (int m = 0; m < 4; ++m) { const float sc = rsv[ai * 4 + m] * 0.0625f; float part = 0.f;
; #pragma unroll
;                         for (int bj = 0; bj < 2; ++bj)
; #pragma unroll
;                             for (int n = 0; n < 2; ++n)
; #pragma unroll
;                                 for (int j = 0; j < 4; ++j) { const float e = __expf(fmaxf(fminf(acc[ai][bj][m][n][j] * sc, 80.f), -80.f)); acc[ai][bj][m][n][j] = e; part += e; }
;                         part += __shfl_xor(part, 16); part += __shfl_xor(part, 32);
;                         if (fq == 0) red[(wr * 4 + wc) * 128 + ai * 64 + m * 16 + fr] = part; }
	s_setprio 0
	v_lshl_add_u32 v194, s46, 8, v198
	v_or_b32_e32 v192, 16, v194
	v_ashrrev_i32_e32 v195, 31, v194
	v_ashrrev_i32_e32 v193, 31, v192
	v_lshl_add_u64 v[130:131], v[194:195], 4, s[8:9]
	v_lshl_add_u64 v[134:135], v[192:193], 4, s[8:9]
	global_load_dwordx4 v[130:133], v[130:131], off
	v_and_b32_e32 v139, 64, v155
	global_load_dwordx4 v[134:137], v[134:135], off
	v_add_u32_e32 v138, 0x90, v194
	v_add_u32_e32 v140, 0xa0, v194
	v_add_u32_e32 v205, 64, v139
	v_ashrrev_i32_e32 v139, 31, v138
	v_ashrrev_i32_e32 v141, 31, v140
	v_lshl_add_u64 v[164:165], v[138:139], 4, s[8:9]
	v_lshl_add_u64 v[206:207], v[140:141], 4, s[8:9]
	v_xor_b32_e32 v144, 16, v155
	v_or_b32_e32 v190, 32, v194
	v_or_b32_e32 v188, 48, v194
	v_add_u32_e32 v186, 0x80, v194
	v_cmp_lt_i32_e32 vcc, v144, v205
	v_add_u32_e32 v142, 0xb0, v194
	v_ashrrev_i32_e32 v191, 31, v190
	v_ashrrev_i32_e32 v189, 31, v188
	v_ashrrev_i32_e32 v187, 31, v186
	v_cndmask_b32_e32 v146, v155, v144, vcc
	v_ashrrev_i32_e32 v143, 31, v142
	v_lshl_add_u64 v[144:145], v[190:191], 4, s[8:9]
	v_lshl_add_u64 v[150:151], v[188:189], 4, s[8:9]
	v_lshl_add_u64 v[162:163], v[186:187], 4, s[8:9]
	v_lshl_add_u64 v[208:209], v[142:143], 4, s[8:9]
	v_lshlrev_b32_e32 v204, 2, v146
	global_load_dwordx4 v[146:149], v[144:145], off
	s_nop 0
	global_load_dwordx4 v[150:153], v[150:151], off
	s_waitcnt vmcnt(0)
	v_mov_b32_e32 v139, v130
	v_mov_b32_e32 v141, v132
	v_mov_b32_e32 v138, v134
	v_mov_b32_e32 v130, v135
	v_mov_b32_e32 v140, v136
	v_pk_add_f32 v[130:131], v[138:139], v[130:131]
	v_mov_b32_e32 v132, v137
	v_pk_add_f32 v[130:131], v[140:141], v[130:131]
	s_nop 0
	v_pk_add_f32 v[130:131], v[132:133], v[130:131]
	s_nop 0
	v_pk_fma_f32 v[196:197], v[130:131], s[72:73], v[160:161] op_sel_hi:[1,0,0]
	s_nop 0
	v_mul_f32_e32 v130, 0x4b800000, v197
	v_cmp_gt_f32_e32 vcc, s94, v197
	s_nop 1
	v_cndmask_b32_e32 v130, v197, v130, vcc
	v_rsq_f32_e32 v197, v130
	global_load_dwordx4 v[138:141], v[162:163], off
	global_load_dwordx4 v[142:145], v[164:165], off
	global_load_dwordx4 v[130:133], v[206:207], off
	global_load_dwordx4 v[134:137], v[208:209], off
	v_mul_f32_e32 v162, 0x45800000, v197
	v_cndmask_b32_e32 v162, v197, v162, vcc
	v_mul_f32_e32 v162, 0x3d800000, v162
	v_mul_f32_e32 v126, v126, v162
	v_mul_f32_e32 v127, v127, v162
	v_mul_f32_e32 v124, v124, v162
	v_min_f32_e32 v126, 0x42a00000, v126
	v_mul_f32_e32 v128, v128, v162
	v_mul_f32_e32 v125, v125, v162
	v_min_f32_e32 v127, 0x42a00000, v127
	v_min_f32_e32 v124, 0x42a00000, v124
	v_max_f32_e32 v126, 0xc2a00000, v126
	v_mul_f32_e32 v129, v129, v162
	v_min_f32_e32 v128, 0x42a00000, v128
	v_min_f32_e32 v125, 0x42a00000, v125
	v_max_f32_e32 v127, 0xc2a00000, v127
	v_max_f32_e32 v124, 0xc2a00000, v124
	v_mul_f32_e32 v126, 0x3fb8aa3b, v126
	v_mul_f32_e32 v122, v122, v162
	v_min_f32_e32 v129, 0x42a00000, v129
	v_max_f32_e32 v128, 0xc2a00000, v128
	v_max_f32_e32 v125, 0xc2a00000, v125
	v_mul_f32_e32 v127, 0x3fb8aa3b, v127
	v_mul_f32_e32 v163, 0x3fb8aa3b, v124
	v_exp_f32_e32 v124, v126
	v_mul_f32_e32 v123, v123, v162
	v_min_f32_e32 v122, 0x42a00000, v122
	v_max_f32_e32 v129, 0xc2a00000, v129
	v_mul_f32_e32 v128, 0x3fb8aa3b, v128
	v_mul_f32_e32 v164, 0x3fb8aa3b, v125
	v_exp_f32_e32 v125, v127
	v_min_f32_e32 v123, 0x42a00000, v123
	v_max_f32_e32 v122, 0xc2a00000, v122
	v_mul_f32_e32 v129, 0x3fb8aa3b, v129
	v_exp_f32_e32 v128, v128
	v_max_f32_e32 v123, 0xc2a00000, v123
	v_mul_f32_e32 v122, 0x3fb8aa3b, v122
	v_exp_f32_e32 v129, v129
	v_mul_f32_e32 v118, v118, v162
	v_mul_f32_e32 v123, 0x3fb8aa3b, v123
	v_exp_f32_e32 v122, v122
	v_exp_f32_e32 v126, v163
	v_add_f32_e32 v163, 0, v124
	v_mul_f32_e32 v119, v119, v162
	v_min_f32_e32 v118, 0x42a00000, v118
	v_exp_f32_e32 v123, v123
	v_add_f32_e32 v163, v125, v163
	v_mul_f32_e32 v120, v120, v162
	v_min_f32_e32 v119, 0x42a00000, v119
	v_max_f32_e32 v118, 0xc2a00000, v118
	v_add_f32_e32 v163, v128, v163
	v_max_f32_e32 v119, 0xc2a00000, v119
	v_mul_f32_e32 v118, 0x3fb8aa3b, v118
	v_exp_f32_e32 v127, v164
	v_add_f32_e32 v163, v129, v163
	v_min_f32_e32 v120, 0x42a00000, v120
	v_mul_f32_e32 v121, v121, v162
	v_mul_f32_e32 v119, 0x3fb8aa3b, v119
	v_exp_f32_e32 v118, v118
	v_add_f32_e32 v163, v122, v163
	v_max_f32_e32 v120, 0xc2a00000, v120
	v_min_f32_e32 v121, 0x42a00000, v121
	v_mul_f32_e32 v114, v114, v162
	v_exp_f32_e32 v119, v119
	v_add_f32_e32 v163, v123, v163
	v_mul_f32_e32 v120, 0x3fb8aa3b, v120
	v_max_f32_e32 v121, 0xc2a00000, v121
	v_min_f32_e32 v114, 0x42a00000, v114
	v_mul_f32_e32 v115, v115, v162
	v_add_f32_e32 v163, v126, v163
	v_exp_f32_e32 v120, v120
	v_mul_f32_e32 v121, 0x3fb8aa3b, v121
	v_max_f32_e32 v114, 0xc2a00000, v114
	v_min_f32_e32 v115, 0x42a00000, v115
	v_mul_f32_e32 v116, v116, v162
	v_add_f32_e32 v163, v127, v163
	v_exp_f32_e32 v121, v121
	v_mul_f32_e32 v114, 0x3fb8aa3b, v114
	v_max_f32_e32 v115, 0xc2a00000, v115
	v_min_f32_e32 v116, 0x42a00000, v116
	v_mul_f32_e32 v117, v117, v162
	v_add_f32_e32 v163, v118, v163
	v_exp_f32_e32 v114, v114
	v_mul_f32_e32 v115, 0x3fb8aa3b, v115
	v_max_f32_e32 v116, 0xc2a00000, v116
	v_min_f32_e32 v117, 0x42a00000, v117
	v_add_f32_e32 v163, v119, v163
	v_exp_f32_e32 v115, v115
	v_mul_f32_e32 v116, 0x3fb8aa3b, v116
	v_max_f32_e32 v117, 0xc2a00000, v117
	v_add_f32_e32 v163, v120, v163
	v_exp_f32_e32 v116, v116
	v_mul_f32_e32 v117, 0x3fb8aa3b, v117
	v_add_f32_e32 v163, v121, v163
	v_exp_f32_e32 v117, v117
	v_add_f32_e32 v162, v114, v163
	v_add_f32_e32 v162, v115, v162
	v_add_f32_e32 v162, v116, v162
	v_add_f32_e32 v162, v117, v162
	ds_bpermute_b32 v163, v204, v162
	v_xor_b32_e32 v164, 32, v155
	v_cmp_lt_i32_e32 vcc, v164, v205
	s_waitcnt lgkmcnt(0)
	v_add_f32_e32 v205, v162, v163
	v_cndmask_b32_e32 v164, v155, v164, vcc
	v_lshlrev_b32_e32 v197, 2, v164
	ds_bpermute_b32 v206, v197, v205
	v_cmp_gt_f32_e32 vcc, s94, v196
	s_and_saveexec_b64 s[6:7], s[2:3]
	s_cbranch_execz .LBB0_1510
	s_waitcnt lgkmcnt(0)
	v_add_f32_e32 v162, v205, v206
	ds_write_b32 v201, v162

; #define PG8_STAGE(bufoff, gbase, voff) do { _Pragma("unroll") for (int _i = 0; _i < 2; ++_i) \
;         __builtin_amdgcn_global_load_lds((const unsigned*)((const char*)(gbase) + (voff)[_i]), (LAS unsigned*)(lds + (bufoff) + ldsw + _i * 8192), 16, 0, 0); } while (0)
; #define PG8_LDA(dst, b, h) do { _Pragma("unroll") for (int m = 0; m < 4; ++m) _Pragma("unroll") for (int k = 0; k < 2; ++k) dst[m][k] = *(const LAS bf16x8*)(lds + PG8_SA(b, h) + aoff + m * 2048 + k * 1024); } while (0)
; #define PG8_LDB(dst, b, h) do { _Pragma("unroll") for (int n = 0; n < 2; ++n) _Pragma("unroll") for (int k = 0; k < 2; ++k) dst[n][k] = *(const LAS bf16x8*)(lds + PG8_SB(b, h) + boff + n * 2048 + k * 1024); } while (0)
; #define PG8_MMA(ai, bj, At, Bt) do { __builtin_amdgcn_s_setprio(1); _Pragma("unroll") for (int m = 0; m < 4; ++m) _Pragma("unroll") for (int n = 0; n < 2; ++n) _Pragma("unroll") for (int k = 0; k < 2; ++k) \
;         acc[ai][bj][m][n] = __builtin_amdgcn_mfma_f32_16x16x32_bf16(Bt[n][k], At[m][k], acc[ai][bj][m][n], 0, 0, 0); __builtin_amdgcn_s_setprio(0); } while (0)
; template <class Epi>
; DEVI void gemm_phase(LAS unsigned char* lds, const Gemm g, const Epi& E) {
;     ...
;         for (int t = 0; t < nt; t += 2) {
;             const bool last = (t == nt - 2);
;             const char* a1 = cA + (size_t)(t + 1) * kstep;
;             const char* a2 = last ? nA : cA + (size_t)(t + 2) * kstep; const char* b2 = last ? nB : cB + (size_t)(t + 2) * kstep;
;             const char* a3 = a2 + kstep; const char* b3 = b2 + kstep;
;             PG8_LDB(B0, 0, 0); PG8_SCHED; PG8_LDA(At, 0, 0); PG8_STAGE(PG8_SA(1, 1), a1 + hstepA, voffA);
;             PG8_WAIT_L(8); PG8_BAR; PG8_WAIT_L(0); PG8_MMA(0, 0, At, B0); PG8_BAR; PG8_SCHED;
;             PG8_LDB(B1, 0, 1); PG8_STAGE(PG8_SB(0, 0), b2, voffB);
;             PG8_BAR; PG8_WAIT_L(0); PG8_MMA(0, 1, At, B1); PG8_BAR;
;             PG8_LDA(At, 0, 1); PG8_STAGE(PG8_SA(0, 0), a2, voffA);
;             PG8_BAR; PG8_WAIT_L(0); PG8_MMA(1, 0, At, B0); PG8_BAR; PG8_SCHED;
;             PG8_STAGE(PG8_SB(0, 1), b2 + hstepB, voffB);
;             PG8_WAIT_V(6); PG8_BAR; PG8_MMA(1, 1, At, B1); PG8_BAR;
;             PG8_LDB(B0, 1, 0); PG8_SCHED; PG8_LDA(At, 1, 0); PG8_STAGE(PG8_SA(0, 1), a2 + hstepA, voffA);
;             PG8_WAIT_L(8); PG8_BAR; PG8_WAIT_L(0); PG8_MMA(0, 0, At, B0); PG8_BAR; PG8_SCHED;
.LBB0_1595:
	s_add_u32 s18, s8, 0xfffc0080
	s_addc_u32 s19, s9, -1
	s_add_i32 s26, 0, 0x10000
	v_add_u32_e32 v142, s26, v191
	ds_read_b128 v[130:133], v142
	ds_read_b128 v[134:137], v142 offset:1024
	ds_read_b128 v[138:141], v142 offset:2048
	ds_read_b128 v[142:145], v142 offset:3072
	s_cmp_eq_u32 s17, 12
	s_cselect_b32 s81, s0, s19
	s_cselect_b32 s80, s1, s18
	s_cselect_b32 s79, s37, s15
	s_cselect_b32 s78, s36, s13
	v_lshl_add_u64 v[162:163], s[8:9], 0, v[152:153]
	s_add_i32 m0, s69, 0xc000
	ds_read_b128 v[178:181], v196
	ds_read_b128 v[182:185], v196 offset:1024
	ds_read_b128 v[186:189], v196 offset:2048
	ds_read_b128 v[198:201], v196 offset:3072
	ds_read_b128 v[202:205], v196 offset:4096
	ds_read_b128 v[206:209], v196 offset:5120
	ds_read_b128 v[214:217], v196 offset:6144
	ds_read_b128 v[218:221], v196 offset:7168
	global_load_lds_dwordx4 v[162:163], off
	v_lshl_add_u64 v[162:163], s[8:9], 0, v[176:177]
	s_add_i32 m0, s69, 0xe000
	s_nop 0
	global_load_lds_dwordx4 v[162:163], off
	s_waitcnt lgkmcnt(8)
	s_barrier
	s_waitcnt lgkmcnt(0)
	v_mfma_f32_16x16x32_bf16 v[126:129], v[130:133], v[178:181], v[126:129]
	v_mfma_f32_16x16x32_bf16 v[122:125], v[138:141], v[178:181], v[122:125]
	v_mfma_f32_16x16x32_bf16 v[110:113], v[130:133], v[186:189], v[110:113]
	v_mfma_f32_16x16x32_bf16 v[106:109], v[138:141], v[186:189], v[106:109]
	v_mfma_f32_16x16x32_bf16 v[94:97], v[130:133], v[202:205], v[94:97]
	v_mfma_f32_16x16x32_bf16 v[90:93], v[138:141], v[202:205], v[90:93]
	v_mfma_f32_16x16x32_bf16 v[78:81], v[130:133], v[214:217], v[78:81]
	v_mfma_f32_16x16x32_bf16 v[74:77], v[138:141], v[214:217], v[74:77]
	v_mfma_f32_16x16x32_bf16 v[126:129], v[134:137], v[182:185], v[126:129]
	v_mfma_f32_16x16x32_bf16 v[122:125], v[142:145], v[182:185], v[122:125]
	v_mfma_f32_16x16x32_bf16 v[110:113], v[134:137], v[198:201], v[110:113]
	v_mfma_f32_16x16x32_bf16 v[106:109], v[142:145], v[198:201], v[106:109]
	v_mfma_f32_16x16x32_bf16 v[94:97], v[134:137], v[206:209], v[94:97]
	v_mfma_f32_16x16x32_bf16 v[90:93], v[142:145], v[206:209], v[90:93]
	v_mfma_f32_16x16x32_bf16 v[78:81], v[134:137], v[218:221], v[78:81]
	v_mfma_f32_16x16x32_bf16 v[74:77], v[142:145], v[218:221], v[74:77]
	s_barrier
	s_add_i32 s27, 0, 0x14000
	v_add_u32_e32 v162, s27, v191
	s_add_i32 s18, s26, s82
	ds_read_b128 v[222:225], v162
	ds_read_b128 v[226:229], v162 offset:1024
	ds_read_b128 v[230:233], v162 offset:2048
	ds_read_b128 v[234:237], v162 offset:3072
	v_lshl_add_u64 v[162:163], s[78:79], 0, v[8:9]
	s_mov_b32 m0, s18
	v_lshl_add_u64 v[164:165], s[78:79], 0, v[150:151]
	global_load_lds_dwordx4 v[162:163], off
	s_add_i32 m0, s18, 0x2000
	s_nop 0
	global_load_lds_dwordx4 v[164:165], off
	s_barrier
	s_waitcnt lgkmcnt(0)
	v_mfma_f32_16x16x32_bf16 v[118:121], v[222:225], v[178:181], v[118:121]
	v_mfma_f32_16x16x32_bf16 v[114:117], v[230:233], v[178:181], v[114:117]
	v_mfma_f32_16x16x32_bf16 v[102:105], v[222:225], v[186:189], v[102:105]
	v_mfma_f32_16x16x32_bf16 v[98:101], v[230:233], v[186:189], v[98:101]
	v_mfma_f32_16x16x32_bf16 v[86:89], v[222:225], v[202:205], v[86:89]
	v_mfma_f32_16x16x32_bf16 v[82:85], v[230:233], v[202:205], v[82:85]
	v_mfma_f32_16x16x32_bf16 v[70:73], v[222:225], v[214:217], v[70:73]
	v_mfma_f32_16x16x32_bf16 v[66:69], v[230:233], v[214:217], v[66:69]
	v_mfma_f32_16x16x32_bf16 v[118:121], v[226:229], v[182:185], v[118:121]
	v_mfma_f32_16x16x32_bf16 v[114:117], v[234:237], v[182:185], v[114:117]
	v_mfma_f32_16x16x32_bf16 v[102:105], v[226:229], v[198:201], v[102:105]
	v_mfma_f32_16x16x32_bf16 v[98:101], v[234:237], v[198:201], v[98:101]
	v_mfma_f32_16x16x32_bf16 v[86:89], v[226:229], v[206:209], v[86:89]
	v_mfma_f32_16x16x32_bf16 v[82:85], v[234:237], v[206:209], v[82:85]
	v_mfma_f32_16x16x32_bf16 v[70:73], v[226:229], v[218:221], v[70:73]
	v_mfma_f32_16x16x32_bf16 v[66:69], v[234:237], v[218:221], v[66:69]
	s_mov_b32 m0, s69
	v_lshl_add_u64 v[238:239], s[80:81], 0, v[146:147]
	s_barrier
	ds_read_b128 v[178:181], v196 offset:16384
	ds_read_b128 v[182:185], v196 offset:17408
	ds_read_b128 v[186:189], v196 offset:18432
	ds_read_b128 v[198:201], v196 offset:19456
	ds_read_b128 v[202:205], v196 offset:20480
	ds_read_b128 v[206:209], v196 offset:21504
	ds_read_b128 v[214:217], v196 offset:22528
	ds_read_b128 v[218:221], v196 offset:23552
	global_load_lds_dwordx4 v[238:239], off
	v_lshl_add_u64 v[240:241], s[80:81], 0, v[148:149]
	s_mov_b32 m0, s83
	s_nop 0
	global_load_lds_dwordx4 v[240:241], off
	s_barrier
	s_waitcnt lgkmcnt(0)
	v_mfma_f32_16x16x32_bf16 v[62:65], v[130:133], v[178:181], v[62:65]
	v_mfma_f32_16x16x32_bf16 v[58:61], v[138:141], v[178:181], v[58:61]
	v_mfma_f32_16x16x32_bf16 v[46:49], v[130:133], v[186:189], v[46:49]
	v_mfma_f32_16x16x32_bf16 v[42:45], v[138:141], v[186:189], v[42:45]
	v_mfma_f32_16x16x32_bf16 v[30:33], v[130:133], v[202:205], v[30:33]
	v_mfma_f32_16x16x32_bf16 v[26:29], v[138:141], v[202:205], v[26:29]
	v_mfma_f32_16x16x32_bf16 v[14:17], v[130:133], v[214:217], v[14:17]
	v_mfma_f32_16x16x32_bf16 v[10:13], v[138:141], v[214:217], v[10:13]
	v_mfma_f32_16x16x32_bf16 v[62:65], v[134:137], v[182:185], v[62:65]
	v_mfma_f32_16x16x32_bf16 v[58:61], v[142:145], v[182:185], v[58:61]
	v_mfma_f32_16x16x32_bf16 v[46:49], v[134:137], v[198:201], v[46:49]
	v_mfma_f32_16x16x32_bf16 v[42:45], v[142:145], v[198:201], v[42:45]
	v_mfma_f32_16x16x32_bf16 v[30:33], v[134:137], v[206:209], v[30:33]
	v_mfma_f32_16x16x32_bf16 v[26:29], v[142:145], v[206:209], v[26:29]
	v_mfma_f32_16x16x32_bf16 v[14:17], v[134:137], v[218:221], v[14:17]
	v_mfma_f32_16x16x32_bf16 v[10:13], v[142:145], v[218:221], v[10:13]
	s_barrier
; #define PG8_STAGE(bufoff, gbase, voff) do { _Pragma("unroll") for (int _i = 0; _i < 2; ++_i) \
;         __builtin_amdgcn_global_load_lds((const unsigned*)((const char*)(gbase) + (voff)[_i]), (LAS unsigned*)(lds + (bufoff) + ldsw + _i * 8192), 16, 0, 0); } while (0)
; #define PG8_LDA(dst, b, h) do { _Pragma("unroll") for (int m = 0; m < 4; ++m) _Pragma("unroll") for (int k = 0; k < 2; ++k) dst[m][k] = *(const LAS bf16x8*)(lds + PG8_SA(b, h) + aoff + m * 2048 + k * 1024); } while (0)
; #define PG8_LDB(dst, b, h) do { _Pragma("unroll") for (int n = 0; n < 2; ++n) _Pragma("unroll") for (int k = 0; k < 2; ++k) dst[n][k] = *(const LAS bf16x8*)(lds + PG8_SB(b, h) + boff + n * 2048 + k * 1024); } while (0)
; #define PG8_MMA(ai, bj, At, Bt) do { __builtin_amdgcn_s_setprio(1); _Pragma("unroll") for (int m = 0; m < 4; ++m) _Pragma("unroll") for (int n = 0; n < 2; ++n) _Pragma("unroll") for (int k = 0; k < 2; ++k) \
;         acc[ai][bj][m][n] = __builtin_amdgcn_mfma_f32_16x16x32_bf16(Bt[n][k], At[m][k], acc[ai][bj][m][n], 0, 0, 0); __builtin_amdgcn_s_setprio(0); } while (0)
; #define PG8_WAIT_V(n) asm volatile("s_waitcnt vmcnt(" #n ")" ::: "memory")
; #define PG8_WAIT_L(n) asm volatile("s_waitcnt lgkmcnt(" #n ")" ::: "memory")
; #define PG8_BAR __builtin_amdgcn_s_barrier()
; #define PG8_SCHED __builtin_amdgcn_sched_barrier(0)
; template <class Epi>
; DEVI void gemm_phase(LAS unsigned char* lds, const Gemm g, const Epi& E) {
;     ...
;             PG8_STAGE(PG8_SB(0, 1), b2 + hstepB, voffB);
;             PG8_WAIT_V(6); PG8_BAR; PG8_MMA(1, 1, At, B1); PG8_BAR;
;             PG8_LDB(B0, 1, 0); PG8_SCHED; PG8_LDA(At, 1, 0); PG8_STAGE(PG8_SA(0, 1), a2 + hstepA, voffA);
;             PG8_WAIT_L(8); PG8_BAR; PG8_WAIT_L(0); PG8_MMA(0, 0, At, B0); PG8_BAR; PG8_SCHED;
;             PG8_LDB(B1, 1, 1); PG8_STAGE(PG8_SB(1, 0), b3, voffB);
;             PG8_BAR; PG8_WAIT_L(0); PG8_MMA(0, 1, At, B1); PG8_BAR;
;             PG8_LDA(At, 1, 1); PG8_STAGE(PG8_SA(1, 0), a3, voffA);
	s_add_u32 s18, s78, 0x40000
	s_addc_u32 s19, s79, 0
	s_add_i32 s26, s27, s82
	v_lshl_add_u64 v[130:131], s[18:19], 0, v[8:9]
	s_mov_b32 m0, s26
	s_nop 0
	global_load_lds_dwordx4 v[130:131], off
	v_lshl_add_u64 v[130:131], s[18:19], 0, v[150:151]
	s_add_i32 m0, s26, 0x2000
	s_nop 0
	global_load_lds_dwordx4 v[130:131], off
	s_waitcnt vmcnt(6)
	s_barrier
	v_mfma_f32_16x16x32_bf16 v[54:57], v[222:225], v[178:181], v[54:57]
	v_mfma_f32_16x16x32_bf16 v[50:53], v[230:233], v[178:181], v[50:53]
	v_mfma_f32_16x16x32_bf16 v[38:41], v[222:225], v[186:189], v[38:41]
	v_mfma_f32_16x16x32_bf16 v[34:37], v[230:233], v[186:189], v[34:37]
	v_mfma_f32_16x16x32_bf16 v[22:25], v[222:225], v[202:205], v[22:25]
	v_mfma_f32_16x16x32_bf16 v[18:21], v[230:233], v[202:205], v[18:21]
	v_mfma_f32_16x16x32_bf16 v[4:7], v[222:225], v[214:217], v[4:7]
	v_mfma_f32_16x16x32_bf16 v[0:3], v[230:233], v[214:217], v[0:3]
	v_mfma_f32_16x16x32_bf16 v[54:57], v[226:229], v[182:185], v[54:57]
	v_mfma_f32_16x16x32_bf16 v[50:53], v[234:237], v[182:185], v[50:53]
	v_mfma_f32_16x16x32_bf16 v[38:41], v[226:229], v[198:201], v[38:41]
	v_mfma_f32_16x16x32_bf16 v[34:37], v[234:237], v[198:201], v[34:37]
	v_mfma_f32_16x16x32_bf16 v[22:25], v[226:229], v[206:209], v[22:25]
	v_mfma_f32_16x16x32_bf16 v[18:21], v[234:237], v[206:209], v[18:21]
	v_mfma_f32_16x16x32_bf16 v[4:7], v[226:229], v[218:221], v[4:7]
	v_mfma_f32_16x16x32_bf16 v[0:3], v[234:237], v[218:221], v[0:3]
	s_add_i32 s26, 0, 0x18000
	v_add_u32_e32 v142, s26, v191
	s_barrier
	ds_read_b128 v[130:133], v142
	ds_read_b128 v[134:137], v142 offset:1024
	ds_read_b128 v[138:141], v142 offset:2048
	ds_read_b128 v[142:145], v142 offset:3072
	s_add_u32 s18, s80, 0x40000
	s_addc_u32 s19, s81, 0
	s_mov_b32 m0, s84
	v_lshl_add_u64 v[222:223], s[18:19], 0, v[146:147]
	ds_read_b128 v[178:181], v196 offset:32768
	ds_read_b128 v[182:185], v196 offset:33792
	ds_read_b128 v[186:189], v196 offset:34816
	ds_read_b128 v[198:201], v196 offset:35840
	ds_read_b128 v[202:205], v196 offset:36864
	ds_read_b128 v[206:209], v196 offset:37888
	ds_read_b128 v[214:217], v196 offset:38912
	ds_read_b128 v[218:221], v196 offset:39936
	global_load_lds_dwordx4 v[222:223], off
	v_lshl_add_u64 v[222:223], s[18:19], 0, v[148:149]
	s_mov_b32 m0, s85
	s_nop 0
	global_load_lds_dwordx4 v[222:223], off
	s_waitcnt lgkmcnt(8)
	s_barrier
	s_waitcnt lgkmcnt(0)
	v_mfma_f32_16x16x32_bf16 v[126:129], v[130:133], v[178:181], v[126:129]
	v_mfma_f32_16x16x32_bf16 v[122:125], v[138:141], v[178:181], v[122:125]
	v_mfma_f32_16x16x32_bf16 v[110:113], v[130:133], v[186:189], v[110:113]
	v_mfma_f32_16x16x32_bf16 v[106:109], v[138:141], v[186:189], v[106:109]
	v_mfma_f32_16x16x32_bf16 v[94:97], v[130:133], v[202:205], v[94:97]
	v_mfma_f32_16x16x32_bf16 v[90:93], v[138:141], v[202:205], v[90:93]
	v_mfma_f32_16x16x32_bf16 v[78:81], v[130:133], v[214:217], v[78:81]
	v_mfma_f32_16x16x32_bf16 v[74:77], v[138:141], v[214:217], v[74:77]
	v_mfma_f32_16x16x32_bf16 v[126:129], v[134:137], v[182:185], v[126:129]
	v_mfma_f32_16x16x32_bf16 v[122:125], v[142:145], v[182:185], v[122:125]
	v_mfma_f32_16x16x32_bf16 v[110:113], v[134:137], v[198:201], v[110:113]
	v_mfma_f32_16x16x32_bf16 v[106:109], v[142:145], v[198:201], v[106:109]
	v_mfma_f32_16x16x32_bf16 v[94:97], v[134:137], v[206:209], v[94:97]
	v_mfma_f32_16x16x32_bf16 v[90:93], v[142:145], v[206:209], v[90:93]
	v_mfma_f32_16x16x32_bf16 v[78:81], v[134:137], v[218:221], v[78:81]
	v_mfma_f32_16x16x32_bf16 v[74:77], v[142:145], v[218:221], v[74:77]
	s_barrier
	s_add_i32 s27, 0, 0x1c000
	s_add_i32 s18, s26, s82
	v_add_u32_e32 v197, s27, v191
	v_lshl_add_u64 v[162:163], v[162:163], 0, s[70:71]
	s_mov_b32 m0, s18
	ds_read_b128 v[222:225], v197
	ds_read_b128 v[226:229], v197 offset:1024
	ds_read_b128 v[230:233], v197 offset:2048
	ds_read_b128 v[234:237], v197 offset:3072
	global_load_lds_dwordx4 v[162:163], off
	v_lshl_add_u64 v[162:163], v[164:165], 0, s[70:71]
	s_add_i32 m0, s18, 0x2000
	s_nop 0
	global_load_lds_dwordx4 v[162:163], off
	s_barrier
	s_waitcnt lgkmcnt(0)
	v_mfma_f32_16x16x32_bf16 v[118:121], v[222:225], v[178:181], v[118:121]
	v_mfma_f32_16x16x32_bf16 v[114:117], v[230:233], v[178:181], v[114:117]
	v_mfma_f32_16x16x32_bf16 v[102:105], v[222:225], v[186:189], v[102:105]
	v_mfma_f32_16x16x32_bf16 v[98:101], v[230:233], v[186:189], v[98:101]
	v_mfma_f32_16x16x32_bf16 v[86:89], v[222:225], v[202:205], v[86:89]
	v_mfma_f32_16x16x32_bf16 v[82:85], v[230:233], v[202:205], v[82:85]
	v_mfma_f32_16x16x32_bf16 v[70:73], v[222:225], v[214:217], v[70:73]
	v_mfma_f32_16x16x32_bf16 v[66:69], v[230:233], v[214:217], v[66:69]
	v_mfma_f32_16x16x32_bf16 v[118:121], v[226:229], v[182:185], v[118:121]
	v_mfma_f32_16x16x32_bf16 v[114:117], v[234:237], v[182:185], v[114:117]
	v_mfma_f32_16x16x32_bf16 v[102:105], v[226:229], v[198:201], v[102:105]
	v_mfma_f32_16x16x32_bf16 v[98:101], v[234:237], v[198:201], v[98:101]
	v_mfma_f32_16x16x32_bf16 v[86:89], v[226:229], v[206:209], v[86:89]
	v_mfma_f32_16x16x32_bf16 v[82:85], v[234:237], v[206:209], v[82:85]
	v_mfma_f32_16x16x32_bf16 v[70:73], v[226:229], v[218:221], v[70:73]
	v_mfma_f32_16x16x32_bf16 v[66:69], v[234:237], v[218:221], v[66:69]
	s_mov_b32 m0, s86
	v_lshl_add_u64 v[162:163], v[238:239], 0, s[70:71]
	s_barrier
	ds_read_b128 v[178:181], v196 offset:49152
	ds_read_b128 v[182:185], v196 offset:50176
	ds_read_b128 v[186:189], v196 offset:51200
	ds_read_b128 v[198:201], v196 offset:52224
	ds_read_b128 v[202:205], v196 offset:53248
	ds_read_b128 v[206:209], v196 offset:54272
	ds_read_b128 v[214:217], v196 offset:55296
	ds_read_b128 v[218:221], v196 offset:56320
	global_load_lds_dwordx4 v[162:163], off
	v_lshl_add_u64 v[162:163], v[240:241], 0, s[70:71]
	s_mov_b32 m0, s87
	s_nop 0
	global_load_lds_dwordx4 v[162:163], off
	s_barrier
; #define LAS __attribute__((address_space(3)))
; #define PG8_WAIT_V(n) asm volatile("s_waitcnt vmcnt(" #n ")" ::: "memory")
; #define PG8_WAIT_L(n) asm volatile("s_waitcnt lgkmcnt(" #n ")" ::: "memory")
; #define PG8_BAR __builtin_amdgcn_s_barrier()
; template <class Epi>
; DEVI void gemm_phase(LAS unsigned char* lds, const Gemm g, const Epi& E) {
;     ...
;             PG8_BAR; PG8_WAIT_L(0); PG8_MMA(1, 0, At, B0); PG8_BAR; PG8_SCHED;
;             PG8_STAGE(PG8_SB(1, 1), b3 + hstepB, voffB);
;             PG8_WAIT_V(6); PG8_BAR; PG8_MMA(1, 1, At, B1); PG8_BAR;
;         }
;     ...
;             for (int am = 0; am < 4; ++am) {
;                 const int ai = am >> 1, m0 = (am & 1) * 2;
;                 f32x4 pre[2][2][2];
;                 if constexpr (Epi::PRE) {
; #pragma unroll
;                     for (int m = 0; m < 2; ++m)
; #pragma unroll
;                         for (int bj = 0; bj < 2; ++bj)
; #pragma unroll
;                             for (int n = 0; n < 2; ++n) pre[m][bj][n] = E.load(row0 + ai * HALF + (m0 + m) * 16, col0 + bj * HALF + n * NST);
;                 }
; #pragma unroll
;                 for (int mm = 0; mm < 2; ++mm) {
;                     const int m = m0 + mm;
;                     const int r = row0 + ai * HALF + m * 16; float rs = 1.f, part = 0.f;
;                     if constexpr (Epi::RS) rs = rsv[ai * 4 + m];
;                     if constexpr (Epi::PAIR) E.pair8(cur.b, r, cur.pn * HALF + wc * 32 + 8 * fq, acc[ai][0][m][0] * rs, acc[ai][0][m][1] * rs, acc[ai][1][m][0] * rs, acc[ai][1][m][1] * rs);
;                     else
; #pragma unroll
;                     for (int bj = 0; bj < 2; ++bj) {
;                         const int c = col0 + bj * HALF; f32x4 v0 = acc[ai][bj][m][0], v1 = acc[ai][bj][m][1];
;                         if constexpr (Epi::RS) { v0 = v0 * rs; v1 = v1 * rs; }
;                         if constexpr (Epi::PRE) part += E.frag_pre8(cur.b, r, c, v0, v1, pre[mm][bj][0], pre[mm][bj][1]);
;                         else if constexpr (Epi::PERM) E.frag8(cur.b, r, c, v0, v1);
;                         else { E.frag(cur.b, r, c, v0); E.frag(cur.b, r, c + 16, v1); }
;                     }
;                     if constexpr (Epi::SSQ) { part += __shfl_xor(part, 16); part += __shfl_xor(part, 32); if (fq == 0) ((LAS float*)(lds + 131072))[(wr * 4 + wc) * 128 + ai * 64 + m * 16 + fr] = part; }
	s_waitcnt lgkmcnt(0)
	v_mfma_f32_16x16x32_bf16 v[62:65], v[130:133], v[178:181], v[62:65]
	v_mfma_f32_16x16x32_bf16 v[58:61], v[138:141], v[178:181], v[58:61]
	v_mfma_f32_16x16x32_bf16 v[46:49], v[130:133], v[186:189], v[46:49]
	v_mfma_f32_16x16x32_bf16 v[42:45], v[138:141], v[186:189], v[42:45]
	v_mfma_f32_16x16x32_bf16 v[30:33], v[130:133], v[202:205], v[30:33]
	v_mfma_f32_16x16x32_bf16 v[26:29], v[138:141], v[202:205], v[26:29]
	v_mfma_f32_16x16x32_bf16 v[14:17], v[130:133], v[214:217], v[14:17]
	v_mfma_f32_16x16x32_bf16 v[10:13], v[138:141], v[214:217], v[10:13]
	v_mfma_f32_16x16x32_bf16 v[62:65], v[134:137], v[182:185], v[62:65]
	v_mfma_f32_16x16x32_bf16 v[58:61], v[142:145], v[182:185], v[58:61]
	v_mfma_f32_16x16x32_bf16 v[46:49], v[134:137], v[198:201], v[46:49]
	v_mfma_f32_16x16x32_bf16 v[42:45], v[142:145], v[198:201], v[42:45]
	v_mfma_f32_16x16x32_bf16 v[30:33], v[134:137], v[206:209], v[30:33]
	v_mfma_f32_16x16x32_bf16 v[26:29], v[142:145], v[206:209], v[26:29]
	v_mfma_f32_16x16x32_bf16 v[14:17], v[134:137], v[218:221], v[14:17]
	v_mfma_f32_16x16x32_bf16 v[10:13], v[142:145], v[218:221], v[10:13]
	s_barrier
	s_add_u32 s18, s78, 0x40080
	s_addc_u32 s19, s79, 0
	s_add_i32 s26, s27, s82
	v_lshl_add_u64 v[130:131], s[18:19], 0, v[8:9]
	s_mov_b32 m0, s26
	s_nop 0
	global_load_lds_dwordx4 v[130:131], off
	v_lshl_add_u64 v[130:131], s[18:19], 0, v[150:151]
	s_add_i32 m0, s26, 0x2000
	s_nop 0
	global_load_lds_dwordx4 v[130:131], off
	s_waitcnt vmcnt(6)
	s_barrier
	v_mfma_f32_16x16x32_bf16 v[54:57], v[222:225], v[178:181], v[54:57]
	v_mfma_f32_16x16x32_bf16 v[50:53], v[230:233], v[178:181], v[50:53]
	v_mfma_f32_16x16x32_bf16 v[38:41], v[222:225], v[186:189], v[38:41]
	v_mfma_f32_16x16x32_bf16 v[34:37], v[230:233], v[186:189], v[34:37]
	v_mfma_f32_16x16x32_bf16 v[22:25], v[222:225], v[202:205], v[22:25]
	v_mfma_f32_16x16x32_bf16 v[18:21], v[230:233], v[202:205], v[18:21]
	v_mfma_f32_16x16x32_bf16 v[4:7], v[222:225], v[214:217], v[4:7]
	v_mfma_f32_16x16x32_bf16 v[0:3], v[230:233], v[214:217], v[0:3]
	v_mfma_f32_16x16x32_bf16 v[54:57], v[226:229], v[182:185], v[54:57]
	v_mfma_f32_16x16x32_bf16 v[50:53], v[234:237], v[182:185], v[50:53]
	v_mfma_f32_16x16x32_bf16 v[38:41], v[226:229], v[198:201], v[38:41]
	v_mfma_f32_16x16x32_bf16 v[34:37], v[234:237], v[198:201], v[34:37]
	v_mfma_f32_16x16x32_bf16 v[22:25], v[226:229], v[206:209], v[22:25]
	v_mfma_f32_16x16x32_bf16 v[18:21], v[234:237], v[206:209], v[18:21]
	v_mfma_f32_16x16x32_bf16 v[4:7], v[226:229], v[218:221], v[4:7]
	v_mfma_f32_16x16x32_bf16 v[0:3], v[234:237], v[218:221], v[0:3]
	s_add_i32 s17, s17, 2
	s_add_u32 s8, s8, 0x100
	s_addc_u32 s9, s9, 0
	s_add_u32 s13, s13, 0x100
	s_addc_u32 s15, s15, 0
	s_cmp_gt_u32 s17, 13
	s_barrier
	s_cbranch_scc0 .LBB0_1595
	s_setprio 0
	s_lshl_b32 s0, s68, 8
	v_add_u32_e32 v182, s0, v190
	v_lshl_or_b32 v180, s12, 8, v195
	v_ashrrev_i32_e32 v183, 31, v182
	v_lshlrev_b64 v[130:131], 12, v[182:183]
	v_ashrrev_i32_e32 v181, 31, v180
	v_lshl_add_u64 v[130:131], s[30:31], 0, v[130:131]
	v_lshlrev_b64 v[184:185], 2, v[180:181]
	v_lshl_add_u64 v[162:163], v[130:131], 0, v[184:185]
	global_load_dwordx4 v[200:203], v[162:163], off
	global_load_dwordx4 v[204:207], v[162:163], off offset:16
	global_load_dwordx4 v[214:217], v[162:163], off offset:512
	global_load_dwordx4 v[218:221], v[162:163], off offset:528
	v_or_b32_e32 v188, 16, v182
	v_ashrrev_i32_e32 v189, 31, v188
	v_lshlrev_b64 v[130:131], 12, v[188:189]
	v_lshl_add_u64 v[130:131], s[30:31], 0, v[130:131]
	v_lshl_add_u64 v[186:187], v[130:131], 0, v[184:185]
	global_load_dwordx4 v[138:141], v[186:187], off offset:16
	global_load_dwordx4 v[142:145], v[186:187], off
	global_load_dwordx4 v[130:133], v[186:187], off offset:528
	global_load_dwordx4 v[134:137], v[186:187], off offset:512
	v_and_b32_e32 v165, 64, v155
	v_xor_b32_e32 v164, 16, v155
	v_add_u32_e32 v165, 64, v165
	v_xor_b32_e32 v179, 32, v155
	v_cmp_lt_i32_e32 vcc, v164, v165
	v_or_b32_e32 v178, 0x80, v180
	s_waitcnt vmcnt(0)
	v_pk_add_f32 v[128:129], v[128:129], v[202:203]
	v_cndmask_b32_e32 v164, v155, v164, vcc
	v_cmp_lt_i32_e32 vcc, v179, v165
	v_lshlrev_b32_e32 v198, 2, v164
	v_pk_add_f32 v[126:127], v[126:127], v[200:201]
	v_cndmask_b32_e32 v165, v155, v179, vcc
	v_lshlrev_b32_e32 v197, 2, v165
	v_lshlrev_b64 v[164:165], 10, v[182:183]
	v_pk_add_f32 v[124:125], v[124:125], v[206:207]
	v_pk_add_f32 v[122:123], v[122:123], v[204:205]
	v_pk_add_f32 v[120:121], v[120:121], v[216:217]
	v_pk_add_f32 v[118:119], v[118:119], v[214:215]
	v_pk_add_f32 v[202:203], v[116:117], v[220:221]
	v_pk_add_f32 v[200:201], v[114:115], v[218:219]
	v_lshl_add_u64 v[208:209], v[164:165], 0, v[180:181]
	global_store_dwordx4 v[162:163], v[126:129], off
	global_store_dwordx4 v[162:163], v[122:125], off offset:16
	v_cvt_pk_bf16_f32 v114, v126, v127
	v_cvt_pk_bf16_f32 v115, v128, v129
	v_cvt_pk_bf16_f32 v116, v122, v123
	v_cvt_pk_bf16_f32 v117, v124, v125
	v_mul_f32_e32 v127, v127, v127
	v_mul_f32_e32 v129, v129, v129
	v_mul_f32_e32 v123, v123, v123
	v_mul_f32_e32 v125, v125, v125
	v_mul_f32_e32 v183, v119, v119
	v_mul_f32_e32 v199, v121, v121
	v_mul_f32_e32 v204, v201, v201
	v_mul_f32_e32 v205, v203, v203
	v_lshl_add_u64 v[208:209], v[208:209], 1, s[24:25]
	v_fmac_f32_e32 v127, v126, v126
	v_fmac_f32_e32 v129, v128, v128
	v_fmac_f32_e32 v123, v122, v122
	v_fmac_f32_e32 v125, v124, v124
	v_fmac_f32_e32 v183, v118, v118
	v_fmac_f32_e32 v199, v120, v120
	v_fmac_f32_e32 v204, v200, v200
	v_fmac_f32_e32 v205, v202, v202
	global_store_dwordx4 v[208:209], v[114:117], off
	v_ashrrev_i32_e32 v179, 31, v178
	v_lshl_add_u64 v[164:165], v[164:165], 0, v[178:179]
	v_add_f32_e32 v114, v127, v129
	v_add_f32_e32 v115, v123, v125
	v_add_f32_e32 v116, v183, v199
	v_add_f32_e32 v117, v204, v205
	v_add_f32_e32 v114, v114, v115
	v_add_f32_e32 v115, v116, v117
	v_add_f32_e32 v114, v114, v115
	ds_bpermute_b32 v115, v198, v114
	global_store_dwordx4 v[162:163], v[118:121], off offset:512
	global_store_dwordx4 v[162:163], v[200:203], off offset:528
	v_cvt_pk_bf16_f32 v116, v118, v119
	v_cvt_pk_bf16_f32 v117, v120, v121
	v_cvt_pk_bf16_f32 v118, v200, v201
	s_waitcnt lgkmcnt(0)
	v_add_f32_e32 v114, v114, v115
	ds_bpermute_b32 v115, v197, v114
	v_cvt_pk_bf16_f32 v119, v202, v203
	v_lshl_add_u64 v[120:121], v[164:165], 1, s[24:25]
	global_store_dwordx4 v[120:121], v[116:119], off
	s_and_saveexec_b64 s[8:9], s[2:3]
	s_cbranch_execz .LBB0_1598
	s_waitcnt lgkmcnt(0)
	v_add_f32_e32 v114, v114, v115
	ds_write_b32 v192, v114

; #define PG8_STAGE(bufoff, gbase, voff) do { _Pragma("unroll") for (int _i = 0; _i < 2; ++_i) \
;         __builtin_amdgcn_global_load_lds((const unsigned*)((const char*)(gbase) + (voff)[_i]), (LAS unsigned*)(lds + (bufoff) + ldsw + _i * 8192), 16, 0, 0); } while (0)
; #define PG8_LDA(dst, b, h) do { _Pragma("unroll") for (int m = 0; m < 4; ++m) _Pragma("unroll") for (int k = 0; k < 2; ++k) dst[m][k] = *(const LAS bf16x8*)(lds + PG8_SA(b, h) + aoff + m * 2048 + k * 1024); } while (0)
; #define PG8_LDB(dst, b, h) do { _Pragma("unroll") for (int n = 0; n < 2; ++n) _Pragma("unroll") for (int k = 0; k < 2; ++k) dst[n][k] = *(const LAS bf16x8*)(lds + PG8_SB(b, h) + boff + n * 2048 + k * 1024); } while (0)
; #define PG8_MMA(ai, bj, At, Bt) do { __builtin_amdgcn_s_setprio(1); _Pragma("unroll") for (int m = 0; m < 4; ++m) _Pragma("unroll") for (int n = 0; n < 2; ++n) _Pragma("unroll") for (int k = 0; k < 2; ++k) \
;         acc[ai][bj][m][n] = __builtin_amdgcn_mfma_f32_16x16x32_bf16(Bt[n][k], At[m][k], acc[ai][bj][m][n], 0, 0, 0); __builtin_amdgcn_s_setprio(0); } while (0)
; template <class Epi>
; DEVI void gemm_phase(LAS unsigned char* lds, const Gemm g, const Epi& E) {
;     ...
;         for (int t = 0; t < nt; t += 2) {
;             const bool last = (t == nt - 2);
;             const char* a1 = cA + (size_t)(t + 1) * kstep;
;             const char* a2 = last ? nA : cA + (size_t)(t + 2) * kstep; const char* b2 = last ? nB : cB + (size_t)(t + 2) * kstep;
;             const char* a3 = a2 + kstep; const char* b3 = b2 + kstep;
;             PG8_LDB(B0, 0, 0); PG8_SCHED; PG8_LDA(At, 0, 0); PG8_STAGE(PG8_SA(1, 1), a1 + hstepA, voffA);
;             PG8_WAIT_L(8); PG8_BAR; PG8_WAIT_L(0); PG8_MMA(0, 0, At, B0); PG8_BAR; PG8_SCHED;
;             PG8_LDB(B1, 0, 1); PG8_STAGE(PG8_SB(0, 0), b2, voffB);
;             PG8_BAR; PG8_WAIT_L(0); PG8_MMA(0, 1, At, B1); PG8_BAR;
;             PG8_LDA(At, 0, 1); PG8_STAGE(PG8_SA(0, 0), a2, voffA);
;             PG8_BAR; PG8_WAIT_L(0); PG8_MMA(1, 0, At, B0); PG8_BAR; PG8_SCHED;
;             PG8_STAGE(PG8_SB(0, 1), b2 + hstepB, voffB);
;             PG8_WAIT_V(6); PG8_BAR; PG8_MMA(1, 1, At, B1); PG8_BAR;
;             PG8_LDB(B0, 1, 0); PG8_SCHED; PG8_LDA(At, 1, 0); PG8_STAGE(PG8_SA(0, 1), a2 + hstepA, voffA);
;             PG8_WAIT_L(8); PG8_BAR; PG8_WAIT_L(0); PG8_MMA(0, 0, At, B0); PG8_BAR; PG8_SCHED;
.LBB0_1672:
	s_add_u32 s26, s16, 0xfffc0080
	s_addc_u32 s27, s17, -1
	s_add_i32 s38, 0, 0x10000
	v_add_u32_e32 v142, s38, v197
	ds_read_b128 v[130:133], v142
	ds_read_b128 v[134:137], v142 offset:1024
	ds_read_b128 v[138:141], v142 offset:2048
	ds_read_b128 v[142:145], v142 offset:3072
	s_cmp_eq_u32 s19, 12
	s_cselect_b32 s47, s0, s27
	s_cselect_b32 s46, s1, s26
	s_cselect_b32 s37, s5, s18
	s_cselect_b32 s36, s7, s9
	v_lshl_add_u64 v[162:163], s[16:17], 0, v[152:153]
	s_add_i32 m0, s79, 0xc000
	ds_read_b128 v[178:181], v201
	ds_read_b128 v[182:185], v201 offset:1024
	ds_read_b128 v[186:189], v201 offset:2048
	ds_read_b128 v[202:205], v201 offset:3072
	ds_read_b128 v[206:209], v201 offset:4096
	ds_read_b128 v[214:217], v201 offset:5120
	ds_read_b128 v[218:221], v201 offset:6144
	ds_read_b128 v[222:225], v201 offset:7168
	global_load_lds_dwordx4 v[162:163], off
	v_lshl_add_u64 v[162:163], s[16:17], 0, v[176:177]
	s_add_i32 m0, s79, 0xe000
	s_nop 0
	global_load_lds_dwordx4 v[162:163], off
	s_waitcnt lgkmcnt(8)
	s_barrier
	s_waitcnt lgkmcnt(0)
	v_mfma_f32_16x16x32_bf16 v[126:129], v[130:133], v[178:181], v[126:129]
	v_mfma_f32_16x16x32_bf16 v[122:125], v[138:141], v[178:181], v[122:125]
	v_mfma_f32_16x16x32_bf16 v[110:113], v[130:133], v[186:189], v[110:113]
	v_mfma_f32_16x16x32_bf16 v[106:109], v[138:141], v[186:189], v[106:109]
	v_mfma_f32_16x16x32_bf16 v[94:97], v[130:133], v[206:209], v[94:97]
	v_mfma_f32_16x16x32_bf16 v[90:93], v[138:141], v[206:209], v[90:93]
	v_mfma_f32_16x16x32_bf16 v[78:81], v[130:133], v[218:221], v[78:81]
	v_mfma_f32_16x16x32_bf16 v[74:77], v[138:141], v[218:221], v[74:77]
	v_mfma_f32_16x16x32_bf16 v[126:129], v[134:137], v[182:185], v[126:129]
	v_mfma_f32_16x16x32_bf16 v[122:125], v[142:145], v[182:185], v[122:125]
	v_mfma_f32_16x16x32_bf16 v[110:113], v[134:137], v[202:205], v[110:113]
	v_mfma_f32_16x16x32_bf16 v[106:109], v[142:145], v[202:205], v[106:109]
	v_mfma_f32_16x16x32_bf16 v[94:97], v[134:137], v[214:217], v[94:97]
	v_mfma_f32_16x16x32_bf16 v[90:93], v[142:145], v[214:217], v[90:93]
	v_mfma_f32_16x16x32_bf16 v[78:81], v[134:137], v[222:225], v[78:81]
	v_mfma_f32_16x16x32_bf16 v[74:77], v[142:145], v[222:225], v[74:77]
	s_barrier
	s_add_i32 s39, 0, 0x14000
	v_add_u32_e32 v162, s39, v197
	s_add_i32 s26, s38, s78
	ds_read_b128 v[226:229], v162
	ds_read_b128 v[230:233], v162 offset:1024
	ds_read_b128 v[234:237], v162 offset:2048
	ds_read_b128 v[238:241], v162 offset:3072
	v_lshl_add_u64 v[162:163], s[36:37], 0, v[8:9]
	s_mov_b32 m0, s26
	v_lshl_add_u64 v[164:165], s[36:37], 0, v[146:147]
	global_load_lds_dwordx4 v[162:163], off
	s_add_i32 m0, s26, 0x2000
	s_nop 0
	global_load_lds_dwordx4 v[164:165], off
	s_barrier
	s_waitcnt lgkmcnt(0)
	v_mfma_f32_16x16x32_bf16 v[118:121], v[226:229], v[178:181], v[118:121]
	v_mfma_f32_16x16x32_bf16 v[114:117], v[234:237], v[178:181], v[114:117]
	v_mfma_f32_16x16x32_bf16 v[102:105], v[226:229], v[186:189], v[102:105]
	v_mfma_f32_16x16x32_bf16 v[98:101], v[234:237], v[186:189], v[98:101]
	v_mfma_f32_16x16x32_bf16 v[86:89], v[226:229], v[206:209], v[86:89]
	v_mfma_f32_16x16x32_bf16 v[82:85], v[234:237], v[206:209], v[82:85]
	v_mfma_f32_16x16x32_bf16 v[70:73], v[226:229], v[218:221], v[70:73]
	v_mfma_f32_16x16x32_bf16 v[66:69], v[234:237], v[218:221], v[66:69]
	v_mfma_f32_16x16x32_bf16 v[118:121], v[230:233], v[182:185], v[118:121]
	v_mfma_f32_16x16x32_bf16 v[114:117], v[238:241], v[182:185], v[114:117]
	v_mfma_f32_16x16x32_bf16 v[102:105], v[230:233], v[202:205], v[102:105]
	v_mfma_f32_16x16x32_bf16 v[98:101], v[238:241], v[202:205], v[98:101]
	v_mfma_f32_16x16x32_bf16 v[86:89], v[230:233], v[214:217], v[86:89]
	v_mfma_f32_16x16x32_bf16 v[82:85], v[238:241], v[214:217], v[82:85]
	v_mfma_f32_16x16x32_bf16 v[70:73], v[230:233], v[222:225], v[70:73]
	v_mfma_f32_16x16x32_bf16 v[66:69], v[238:241], v[222:225], v[66:69]
	s_mov_b32 m0, s79
	v_lshl_add_u64 v[190:191], s[46:47], 0, v[150:151]
	s_barrier
	ds_read_b128 v[178:181], v201 offset:16384
	ds_read_b128 v[182:185], v201 offset:17408
	ds_read_b128 v[186:189], v201 offset:18432
	ds_read_b128 v[202:205], v201 offset:19456
	ds_read_b128 v[206:209], v201 offset:20480
	ds_read_b128 v[214:217], v201 offset:21504
	ds_read_b128 v[218:221], v201 offset:22528
	ds_read_b128 v[222:225], v201 offset:23552
	global_load_lds_dwordx4 v[190:191], off
	v_lshl_add_u64 v[194:195], s[46:47], 0, v[148:149]
	s_mov_b32 m0, s80
	s_nop 0
	global_load_lds_dwordx4 v[194:195], off
	s_barrier
	s_waitcnt lgkmcnt(0)
	v_mfma_f32_16x16x32_bf16 v[50:53], v[130:133], v[178:181], v[50:53]
	v_mfma_f32_16x16x32_bf16 v[54:57], v[138:141], v[178:181], v[54:57]
	v_mfma_f32_16x16x32_bf16 v[34:37], v[130:133], v[186:189], v[34:37]
	v_mfma_f32_16x16x32_bf16 v[38:41], v[138:141], v[186:189], v[38:41]
	v_mfma_f32_16x16x32_bf16 v[18:21], v[130:133], v[206:209], v[18:21]
	v_mfma_f32_16x16x32_bf16 v[22:25], v[138:141], v[206:209], v[22:25]
	v_mfma_f32_16x16x32_bf16 v[0:3], v[130:133], v[218:221], v[0:3]
	v_mfma_f32_16x16x32_bf16 v[4:7], v[138:141], v[218:221], v[4:7]
	v_mfma_f32_16x16x32_bf16 v[50:53], v[134:137], v[182:185], v[50:53]
	v_mfma_f32_16x16x32_bf16 v[54:57], v[142:145], v[182:185], v[54:57]
	v_mfma_f32_16x16x32_bf16 v[34:37], v[134:137], v[202:205], v[34:37]
	v_mfma_f32_16x16x32_bf16 v[38:41], v[142:145], v[202:205], v[38:41]
	v_mfma_f32_16x16x32_bf16 v[18:21], v[134:137], v[214:217], v[18:21]
	v_mfma_f32_16x16x32_bf16 v[22:25], v[142:145], v[214:217], v[22:25]
	v_mfma_f32_16x16x32_bf16 v[0:3], v[134:137], v[222:225], v[0:3]
	v_mfma_f32_16x16x32_bf16 v[4:7], v[142:145], v[222:225], v[4:7]
	s_barrier
; #define PG8_STAGE(bufoff, gbase, voff) do { _Pragma("unroll") for (int _i = 0; _i < 2; ++_i) \
;         __builtin_amdgcn_global_load_lds((const unsigned*)((const char*)(gbase) + (voff)[_i]), (LAS unsigned*)(lds + (bufoff) + ldsw + _i * 8192), 16, 0, 0); } while (0)
; #define PG8_LDA(dst, b, h) do { _Pragma("unroll") for (int m = 0; m < 4; ++m) _Pragma("unroll") for (int k = 0; k < 2; ++k) dst[m][k] = *(const LAS bf16x8*)(lds + PG8_SA(b, h) + aoff + m * 2048 + k * 1024); } while (0)
; #define PG8_LDB(dst, b, h) do { _Pragma("unroll") for (int n = 0; n < 2; ++n) _Pragma("unroll") for (int k = 0; k < 2; ++k) dst[n][k] = *(const LAS bf16x8*)(lds + PG8_SB(b, h) + boff + n * 2048 + k * 1024); } while (0)
; #define PG8_MMA(ai, bj, At, Bt) do { __builtin_amdgcn_s_setprio(1); _Pragma("unroll") for (int m = 0; m < 4; ++m) _Pragma("unroll") for (int n = 0; n < 2; ++n) _Pragma("unroll") for (int k = 0; k < 2; ++k) \
;         acc[ai][bj][m][n] = __builtin_amdgcn_mfma_f32_16x16x32_bf16(Bt[n][k], At[m][k], acc[ai][bj][m][n], 0, 0, 0); __builtin_amdgcn_s_setprio(0); } while (0)
; #define PG8_WAIT_V(n) asm volatile("s_waitcnt vmcnt(" #n ")" ::: "memory")
; #define PG8_WAIT_L(n) asm volatile("s_waitcnt lgkmcnt(" #n ")" ::: "memory")
; #define PG8_BAR __builtin_amdgcn_s_barrier()
; #define PG8_SCHED __builtin_amdgcn_sched_barrier(0)
; template <class Epi>
; DEVI void gemm_phase(LAS unsigned char* lds, const Gemm g, const Epi& E) {
;     ...
;             PG8_STAGE(PG8_SB(0, 1), b2 + hstepB, voffB);
;             PG8_WAIT_V(6); PG8_BAR; PG8_MMA(1, 1, At, B1); PG8_BAR;
;             PG8_LDB(B0, 1, 0); PG8_SCHED; PG8_LDA(At, 1, 0); PG8_STAGE(PG8_SA(0, 1), a2 + hstepA, voffA);
;             PG8_WAIT_L(8); PG8_BAR; PG8_WAIT_L(0); PG8_MMA(0, 0, At, B0); PG8_BAR; PG8_SCHED;
;             PG8_LDB(B1, 1, 1); PG8_STAGE(PG8_SB(1, 0), b3, voffB);
;             PG8_BAR; PG8_WAIT_L(0); PG8_MMA(0, 1, At, B1); PG8_BAR;
;             PG8_LDA(At, 1, 1); PG8_STAGE(PG8_SA(1, 0), a3, voffA);
	s_add_u32 s26, s36, 0x40000
	s_addc_u32 s27, s37, 0
	s_add_i32 s38, s39, s78
	v_lshl_add_u64 v[130:131], s[26:27], 0, v[8:9]
	s_mov_b32 m0, s38
	s_nop 0
	global_load_lds_dwordx4 v[130:131], off
	v_lshl_add_u64 v[130:131], s[26:27], 0, v[146:147]
	s_add_i32 m0, s38, 0x2000
	s_nop 0
	global_load_lds_dwordx4 v[130:131], off
	s_waitcnt vmcnt(6)
	s_barrier
	v_mfma_f32_16x16x32_bf16 v[58:61], v[226:229], v[178:181], v[58:61]
	v_mfma_f32_16x16x32_bf16 v[62:65], v[234:237], v[178:181], v[62:65]
	v_mfma_f32_16x16x32_bf16 v[42:45], v[226:229], v[186:189], v[42:45]
	v_mfma_f32_16x16x32_bf16 v[46:49], v[234:237], v[186:189], v[46:49]
	v_mfma_f32_16x16x32_bf16 v[26:29], v[226:229], v[206:209], v[26:29]
	v_mfma_f32_16x16x32_bf16 v[30:33], v[234:237], v[206:209], v[30:33]
	v_mfma_f32_16x16x32_bf16 v[10:13], v[226:229], v[218:221], v[10:13]
	v_mfma_f32_16x16x32_bf16 v[14:17], v[234:237], v[218:221], v[14:17]
	v_mfma_f32_16x16x32_bf16 v[58:61], v[230:233], v[182:185], v[58:61]
	v_mfma_f32_16x16x32_bf16 v[62:65], v[238:241], v[182:185], v[62:65]
	v_mfma_f32_16x16x32_bf16 v[42:45], v[230:233], v[202:205], v[42:45]
	v_mfma_f32_16x16x32_bf16 v[46:49], v[238:241], v[202:205], v[46:49]
	v_mfma_f32_16x16x32_bf16 v[26:29], v[230:233], v[214:217], v[26:29]
	v_mfma_f32_16x16x32_bf16 v[30:33], v[238:241], v[214:217], v[30:33]
	v_mfma_f32_16x16x32_bf16 v[10:13], v[230:233], v[222:225], v[10:13]
	v_mfma_f32_16x16x32_bf16 v[14:17], v[238:241], v[222:225], v[14:17]
	s_add_i32 s38, 0, 0x18000
	v_add_u32_e32 v142, s38, v197
	s_barrier
	ds_read_b128 v[130:133], v142
	ds_read_b128 v[134:137], v142 offset:1024
	ds_read_b128 v[138:141], v142 offset:2048
	ds_read_b128 v[142:145], v142 offset:3072
	s_add_u32 s26, s46, 0x40000
	s_addc_u32 s27, s47, 0
	s_mov_b32 m0, s81
	v_lshl_add_u64 v[226:227], s[26:27], 0, v[150:151]
	ds_read_b128 v[178:181], v201 offset:32768
	ds_read_b128 v[182:185], v201 offset:33792
	ds_read_b128 v[186:189], v201 offset:34816
	ds_read_b128 v[202:205], v201 offset:35840
	ds_read_b128 v[206:209], v201 offset:36864
	ds_read_b128 v[214:217], v201 offset:37888
	ds_read_b128 v[218:221], v201 offset:38912
	ds_read_b128 v[222:225], v201 offset:39936
	global_load_lds_dwordx4 v[226:227], off
	v_lshl_add_u64 v[226:227], s[26:27], 0, v[148:149]
	s_mov_b32 m0, s82
	s_nop 0
	global_load_lds_dwordx4 v[226:227], off
	s_waitcnt lgkmcnt(8)
	s_barrier
	s_waitcnt lgkmcnt(0)
	v_mfma_f32_16x16x32_bf16 v[126:129], v[130:133], v[178:181], v[126:129]
	v_mfma_f32_16x16x32_bf16 v[122:125], v[138:141], v[178:181], v[122:125]
	v_mfma_f32_16x16x32_bf16 v[110:113], v[130:133], v[186:189], v[110:113]
	v_mfma_f32_16x16x32_bf16 v[106:109], v[138:141], v[186:189], v[106:109]
	v_mfma_f32_16x16x32_bf16 v[94:97], v[130:133], v[206:209], v[94:97]
	v_mfma_f32_16x16x32_bf16 v[90:93], v[138:141], v[206:209], v[90:93]
	v_mfma_f32_16x16x32_bf16 v[78:81], v[130:133], v[218:221], v[78:81]
	v_mfma_f32_16x16x32_bf16 v[74:77], v[138:141], v[218:221], v[74:77]
	v_mfma_f32_16x16x32_bf16 v[126:129], v[134:137], v[182:185], v[126:129]
	v_mfma_f32_16x16x32_bf16 v[122:125], v[142:145], v[182:185], v[122:125]
	v_mfma_f32_16x16x32_bf16 v[110:113], v[134:137], v[202:205], v[110:113]
	v_mfma_f32_16x16x32_bf16 v[106:109], v[142:145], v[202:205], v[106:109]
	v_mfma_f32_16x16x32_bf16 v[94:97], v[134:137], v[214:217], v[94:97]
	v_mfma_f32_16x16x32_bf16 v[90:93], v[142:145], v[214:217], v[90:93]
	v_mfma_f32_16x16x32_bf16 v[78:81], v[134:137], v[222:225], v[78:81]
	v_mfma_f32_16x16x32_bf16 v[74:77], v[142:145], v[222:225], v[74:77]
	s_barrier
	s_add_i32 s39, 0, 0x1c000
	s_add_i32 s26, s38, s78
	v_add_u32_e32 v192, s39, v197
	v_lshl_add_u64 v[162:163], v[162:163], 0, s[70:71]
	s_mov_b32 m0, s26
	ds_read_b128 v[226:229], v192
	ds_read_b128 v[230:233], v192 offset:1024
	ds_read_b128 v[234:237], v192 offset:2048
	ds_read_b128 v[238:241], v192 offset:3072
	global_load_lds_dwordx4 v[162:163], off
	v_lshl_add_u64 v[162:163], v[164:165], 0, s[70:71]
	s_add_i32 m0, s26, 0x2000
	s_nop 0
	global_load_lds_dwordx4 v[162:163], off
	s_barrier
	s_waitcnt lgkmcnt(0)
	v_mfma_f32_16x16x32_bf16 v[118:121], v[226:229], v[178:181], v[118:121]
	v_mfma_f32_16x16x32_bf16 v[114:117], v[234:237], v[178:181], v[114:117]
	v_mfma_f32_16x16x32_bf16 v[102:105], v[226:229], v[186:189], v[102:105]
	v_mfma_f32_16x16x32_bf16 v[98:101], v[234:237], v[186:189], v[98:101]
	v_mfma_f32_16x16x32_bf16 v[86:89], v[226:229], v[206:209], v[86:89]
	v_mfma_f32_16x16x32_bf16 v[82:85], v[234:237], v[206:209], v[82:85]
	v_mfma_f32_16x16x32_bf16 v[70:73], v[226:229], v[218:221], v[70:73]
	v_mfma_f32_16x16x32_bf16 v[66:69], v[234:237], v[218:221], v[66:69]
	v_mfma_f32_16x16x32_bf16 v[118:121], v[230:233], v[182:185], v[118:121]
	v_mfma_f32_16x16x32_bf16 v[114:117], v[238:241], v[182:185], v[114:117]
	v_mfma_f32_16x16x32_bf16 v[102:105], v[230:233], v[202:205], v[102:105]
	v_mfma_f32_16x16x32_bf16 v[98:101], v[238:241], v[202:205], v[98:101]
	v_mfma_f32_16x16x32_bf16 v[86:89], v[230:233], v[214:217], v[86:89]
	v_mfma_f32_16x16x32_bf16 v[82:85], v[238:241], v[214:217], v[82:85]
	v_mfma_f32_16x16x32_bf16 v[70:73], v[230:233], v[222:225], v[70:73]
	v_mfma_f32_16x16x32_bf16 v[66:69], v[238:241], v[222:225], v[66:69]
	s_mov_b32 m0, s83
	v_lshl_add_u64 v[162:163], v[190:191], 0, s[70:71]
	s_barrier
	ds_read_b128 v[178:181], v201 offset:49152
	ds_read_b128 v[182:185], v201 offset:50176
	ds_read_b128 v[186:189], v201 offset:51200
	ds_read_b128 v[202:205], v201 offset:52224
	ds_read_b128 v[206:209], v201 offset:53248
	ds_read_b128 v[214:217], v201 offset:54272
	ds_read_b128 v[218:221], v201 offset:55296
	ds_read_b128 v[222:225], v201 offset:56320
	global_load_lds_dwordx4 v[162:163], off
	v_lshl_add_u64 v[162:163], v[194:195], 0, s[70:71]
	s_mov_b32 m0, s84
	s_nop 0
	global_load_lds_dwordx4 v[162:163], off
	s_barrier
; #define PG8_STAGE(bufoff, gbase, voff) do { _Pragma("unroll") for (int _i = 0; _i < 2; ++_i) \
;         __builtin_amdgcn_global_load_lds((const unsigned*)((const char*)(gbase) + (voff)[_i]), (LAS unsigned*)(lds + (bufoff) + ldsw + _i * 8192), 16, 0, 0); } while (0)
; #define PG8_WAIT_V(n) asm volatile("s_waitcnt vmcnt(" #n ")" ::: "memory")
; #define PG8_WAIT_L(n) asm volatile("s_waitcnt lgkmcnt(" #n ")" ::: "memory")
; #define PG8_BAR __builtin_amdgcn_s_barrier()
; #define PG8_SCHED __builtin_amdgcn_sched_barrier(0)
; template <class Epi>
; DEVI void gemm_phase(LAS unsigned char* lds, const Gemm g, const Epi& E) {
;     ...
;             PG8_BAR; PG8_WAIT_L(0); PG8_MMA(1, 0, At, B0); PG8_BAR; PG8_SCHED;
;             PG8_STAGE(PG8_SB(1, 1), b3 + hstepB, voffB);
;             PG8_WAIT_V(6); PG8_BAR; PG8_MMA(1, 1, At, B1); PG8_BAR;
;         }
;     ...
;             const int row0 = cur.pm * BM + wr * 64 + fr, col0 = cur.pn * BM + wc * 32 + (Epi::PERM ? 8 : 4) * fq; constexpr int NST = Epi::PERM ? 4 : 16;
;             float rsv[8];
;             if constexpr (Epi::RS) { f32x4 q4[8];
; #pragma unroll
;                 for (int i = 0; i < 8; ++i) q4[i] = *(const f32x4*)(E.ssq_in + (size_t)(row0 + (i >> 2) * HALF + (i & 3) * 16) * 4);
; #pragma unroll
;                 for (int i = 0; i < 8; ++i) rsv[i] = rsqrtf((((q4[i][0] + q4[i][1]) + q4[i][2]) + q4[i][3]) * (1.f / DM) + 1e-6f); }
;     ...
;             for (int am = 0; am < 4; ++am) {
;                 const int ai = am >> 1, m0 = (am & 1) * 2;
;                 f32x4 pre[2][2][2];
;                 if constexpr (Epi::PRE) {
; #pragma unroll
;                     for (int m = 0; m < 2; ++m)
; #pragma unroll
;                         for (int bj = 0; bj < 2; ++bj)
; #pragma unroll
;                             for (int n = 0; n < 2; ++n) pre[m][bj][n] = E.load(row0 + ai * HALF + (m0 + m) * 16, col0 + bj * HALF + n * NST);
;                 }
; #pragma unroll
;                 for (int mm = 0; mm < 2; ++mm) {
;                     const int m = m0 + mm;
;                     const int r = row0 + ai * HALF + m * 16; float rs = 1.f, part = 0.f;
;                     if constexpr (Epi::RS) rs = rsv[ai * 4 + m];
;                     if constexpr (Epi::PAIR) E.pair8(cur.b, r, cur.pn * HALF + wc * 32 + 8 * fq, acc[ai][0][m][0] * rs, acc[ai][0][m][1] * rs, acc[ai][1][m][0] * rs, acc[ai][1][m][1] * rs);
	s_waitcnt lgkmcnt(0)
	v_mfma_f32_16x16x32_bf16 v[50:53], v[130:133], v[178:181], v[50:53]
	v_mfma_f32_16x16x32_bf16 v[54:57], v[138:141], v[178:181], v[54:57]
	v_mfma_f32_16x16x32_bf16 v[34:37], v[130:133], v[186:189], v[34:37]
	v_mfma_f32_16x16x32_bf16 v[38:41], v[138:141], v[186:189], v[38:41]
	v_mfma_f32_16x16x32_bf16 v[18:21], v[130:133], v[206:209], v[18:21]
	v_mfma_f32_16x16x32_bf16 v[22:25], v[138:141], v[206:209], v[22:25]
	v_mfma_f32_16x16x32_bf16 v[0:3], v[130:133], v[218:221], v[0:3]
	v_mfma_f32_16x16x32_bf16 v[4:7], v[138:141], v[218:221], v[4:7]
	v_mfma_f32_16x16x32_bf16 v[50:53], v[134:137], v[182:185], v[50:53]
	v_mfma_f32_16x16x32_bf16 v[54:57], v[142:145], v[182:185], v[54:57]
	v_mfma_f32_16x16x32_bf16 v[34:37], v[134:137], v[202:205], v[34:37]
	v_mfma_f32_16x16x32_bf16 v[38:41], v[142:145], v[202:205], v[38:41]
	v_mfma_f32_16x16x32_bf16 v[18:21], v[134:137], v[214:217], v[18:21]
	v_mfma_f32_16x16x32_bf16 v[22:25], v[142:145], v[214:217], v[22:25]
	v_mfma_f32_16x16x32_bf16 v[0:3], v[134:137], v[222:225], v[0:3]
	v_mfma_f32_16x16x32_bf16 v[4:7], v[142:145], v[222:225], v[4:7]
	s_barrier
	s_add_u32 s26, s36, 0x40080
	s_addc_u32 s27, s37, 0
	s_add_i32 s36, s39, s78
	v_lshl_add_u64 v[130:131], s[26:27], 0, v[8:9]
	s_mov_b32 m0, s36
	s_nop 0
	global_load_lds_dwordx4 v[130:131], off
	v_lshl_add_u64 v[130:131], s[26:27], 0, v[146:147]
	s_add_i32 m0, s36, 0x2000
	s_nop 0
	global_load_lds_dwordx4 v[130:131], off
	s_waitcnt vmcnt(6)
	s_barrier
	v_mfma_f32_16x16x32_bf16 v[58:61], v[226:229], v[178:181], v[58:61]
	v_mfma_f32_16x16x32_bf16 v[62:65], v[234:237], v[178:181], v[62:65]
	v_mfma_f32_16x16x32_bf16 v[42:45], v[226:229], v[186:189], v[42:45]
	v_mfma_f32_16x16x32_bf16 v[46:49], v[234:237], v[186:189], v[46:49]
	v_mfma_f32_16x16x32_bf16 v[26:29], v[226:229], v[206:209], v[26:29]
	v_mfma_f32_16x16x32_bf16 v[30:33], v[234:237], v[206:209], v[30:33]
	v_mfma_f32_16x16x32_bf16 v[10:13], v[226:229], v[218:221], v[10:13]
	v_mfma_f32_16x16x32_bf16 v[14:17], v[234:237], v[218:221], v[14:17]
	v_mfma_f32_16x16x32_bf16 v[58:61], v[230:233], v[182:185], v[58:61]
	v_mfma_f32_16x16x32_bf16 v[62:65], v[238:241], v[182:185], v[62:65]
	v_mfma_f32_16x16x32_bf16 v[42:45], v[230:233], v[202:205], v[42:45]
	v_mfma_f32_16x16x32_bf16 v[46:49], v[238:241], v[202:205], v[46:49]
	v_mfma_f32_16x16x32_bf16 v[26:29], v[230:233], v[214:217], v[26:29]
	v_mfma_f32_16x16x32_bf16 v[30:33], v[238:241], v[214:217], v[30:33]
	v_mfma_f32_16x16x32_bf16 v[10:13], v[230:233], v[222:225], v[10:13]
	v_mfma_f32_16x16x32_bf16 v[14:17], v[238:241], v[222:225], v[14:17]
	s_add_i32 s19, s19, 2
	s_add_u32 s16, s16, 0x100
	s_addc_u32 s17, s17, 0
	s_add_u32 s9, s9, 0x100
	s_addc_u32 s18, s18, 0
	s_cmp_gt_u32 s19, 13
	s_barrier
	s_cbranch_scc0 .LBB0_1672
	s_setprio 0
	v_lshl_add_u32 v194, s4, 8, v193
	v_add_u32_e32 v178, 0xb0, v194
	v_ashrrev_i32_e32 v195, 31, v194
	v_or_b32_e32 v190, 16, v194
	v_ashrrev_i32_e32 v179, 31, v178
	v_lshl_add_u64 v[130:131], v[194:195], 4, s[10:11]
	v_ashrrev_i32_e32 v191, 31, v190
	v_lshl_add_u64 v[134:135], v[178:179], 4, s[10:11]
	global_load_dwordx4 v[202:205], v[130:131], off
	v_or_b32_e32 v188, 32, v194
	global_load_dwordx4 v[134:137], v[134:135], off
	v_lshl_add_u64 v[130:131], v[190:191], 4, s[10:11]
	global_load_dwordx4 v[206:209], v[130:131], off
	v_ashrrev_i32_e32 v189, 31, v188
	v_or_b32_e32 v186, 48, v194
	v_lshl_add_u64 v[130:131], v[188:189], 4, s[10:11]
	v_ashrrev_i32_e32 v187, 31, v186
	global_load_dwordx4 v[214:217], v[130:131], off
	v_lshl_add_u64 v[130:131], v[186:187], 4, s[10:11]
	global_load_dwordx4 v[218:221], v[130:131], off
	v_add_u32_e32 v184, 0x80, v194
	v_ashrrev_i32_e32 v185, 31, v184
	v_add_u32_e32 v182, 0x90, v194
	v_lshl_add_u64 v[130:131], v[184:185], 4, s[10:11]
	v_ashrrev_i32_e32 v183, 31, v182
	global_load_dwordx4 v[138:141], v[130:131], off
	v_lshl_add_u64 v[130:131], v[182:183], 4, s[10:11]
	v_add_u32_e32 v180, 0xa0, v194
	global_load_dwordx4 v[142:145], v[130:131], off
	v_ashrrev_i32_e32 v181, 31, v180
	v_lshl_add_u64 v[130:131], v[180:181], 4, s[10:11]
	global_load_dwordx4 v[130:133], v[130:131], off
	s_mov_b32 s0, 0x358637bd
	s_mov_b64 s[36:37], s[14:15]
	s_mov_b64 s[16:17], s[12:13]
	s_waitcnt vmcnt(0)
	v_mov_b32_e32 v163, v202
	v_mov_b32_e32 v165, v204
	v_mov_b32_e32 v162, v206
	v_mov_b32_e32 v202, v207
	v_pk_add_f32 v[162:163], v[162:163], v[202:203]
	v_mov_b32_e32 v164, v208
	v_pk_add_f32 v[162:163], v[164:165], v[162:163]
	v_mov_b32_e32 v204, v209
	v_pk_add_f32 v[162:163], v[204:205], v[162:163]
	v_mov_b64_e32 v[202:203], s[0:1]
	v_pk_fma_f32 v[162:163], v[162:163], s[72:73], v[202:203] op_sel_hi:[1,0,0]
	v_mov_b32_e32 v165, v216
	v_mul_f32_e32 v164, 0x4b800000, v163
	v_cmp_gt_f32_e64 s[4:5], s94, v163
	v_cmp_gt_f32_e32 vcc, s94, v162
	v_mov_b32_e32 v216, v221
	v_cndmask_b32_e64 v163, v163, v164, s[4:5]
	v_rsq_f32_e32 v163, v163
	s_nop 0
	v_mul_f32_e32 v164, 0x45800000, v163
	v_cndmask_b32_e64 v200, v163, v164, s[4:5]
	v_mul_f32_e32 v163, 0x4b800000, v162
	v_cndmask_b32_e32 v162, v162, v163, vcc
	v_rsq_f32_e32 v162, v162
	v_mov_b32_e32 v164, v220
	v_pk_mul_f32 v[126:127], v[126:127], v[200:201] op_sel_hi:[1,0]
	v_pk_mul_f32 v[122:123], v[122:123], v[200:201] op_sel_hi:[1,0]
	v_mul_f32_e32 v163, 0x45800000, v162
	v_cndmask_b32_e32 v198, v162, v163, vcc
	v_mov_b32_e32 v162, v218
	v_mov_b32_e32 v163, v214
	v_mov_b32_e32 v214, v219
	v_pk_add_f32 v[162:163], v[162:163], v[214:215]
	v_pk_mul_f32 v[118:119], v[118:119], v[200:201] op_sel_hi:[1,0]
	v_pk_add_f32 v[162:163], v[164:165], v[162:163]
	v_pk_mul_f32 v[124:125], v[124:125], v[200:201] op_sel_hi:[1,0]
	v_pk_add_f32 v[162:163], v[216:217], v[162:163]
; template <class Epi>
; DEVI void gemm_phase(LAS unsigned char* lds, const Gemm g, const Epi& E) {
;     ...
;             const int row0 = cur.pm * BM + wr * 64 + fr, col0 = cur.pn * BM + wc * 32 + (Epi::PERM ? 8 : 4) * fq; constexpr int NST = Epi::PERM ? 4 : 16;
;             float rsv[8];
;             if constexpr (Epi::RS) { f32x4 q4[8];
; #pragma unroll
;                 for (int i = 0; i < 8; ++i) q4[i] = *(const f32x4*)(E.ssq_in + (size_t)(row0 + (i >> 2) * HALF + (i & 3) * 16) * 4);
; #pragma unroll
;                 for (int i = 0; i < 8; ++i) rsv[i] = rsqrtf((((q4[i][0] + q4[i][1]) + q4[i][2]) + q4[i][3]) * (1.f / DM) + 1e-6f); }
;     ...
;                 for (int mm = 0; mm < 2; ++mm) {
;                     const int m = m0 + mm;
;                     const int r = row0 + ai * HALF + m * 16; float rs = 1.f, part = 0.f;
;                     if constexpr (Epi::RS) rs = rsv[ai * 4 + m];
;                     if constexpr (Epi::PAIR) E.pair8(cur.b, r, cur.pn * HALF + wc * 32 + 8 * fq, acc[ai][0][m][0] * rs, acc[ai][0][m][1] * rs, acc[ai][1][m][0] * rs, acc[ai][1][m][1] * rs);
	v_pk_mul_f32 v[114:115], v[114:115], v[200:201] op_sel_hi:[1,0]
	v_pk_fma_f32 v[162:163], v[162:163], s[72:73], v[202:203] op_sel_hi:[1,0,0]
	v_pk_mul_f32 v[128:129], v[128:129], v[200:201] op_sel_hi:[1,0]
	v_mul_f32_e32 v164, 0x4b800000, v163
	v_cmp_gt_f32_e64 s[4:5], s94, v163
	v_cmp_gt_f32_e32 vcc, s94, v162
	v_pk_mul_f32 v[120:121], v[120:121], v[200:201] op_sel_hi:[1,0]
	v_cndmask_b32_e64 v163, v163, v164, s[4:5]
	v_rsq_f32_e32 v163, v163
	v_pk_mul_f32 v[116:117], v[116:117], v[200:201] op_sel_hi:[1,0]
	v_pk_mul_f32 v[106:107], v[106:107], v[198:199] op_sel_hi:[1,0]
	v_pk_mul_f32 v[110:111], v[110:111], v[198:199] op_sel_hi:[1,0]
	v_mul_f32_e32 v164, 0x45800000, v163
	v_cndmask_b32_e64 v196, v163, v164, s[4:5]
	v_mul_f32_e32 v163, 0x4b800000, v162
	v_cndmask_b32_e32 v162, v162, v163, vcc
	v_rsq_f32_e32 v162, v162
	v_pk_mul_f32 v[102:103], v[102:103], v[198:199] op_sel_hi:[1,0]
	v_pk_mul_f32 v[108:109], v[108:109], v[198:199] op_sel_hi:[1,0]
	v_pk_mul_f32 v[98:99], v[98:99], v[198:199] op_sel_hi:[1,0]
	v_mul_f32_e32 v163, 0x45800000, v162
	v_cndmask_b32_e32 v192, v162, v163, vcc
	v_mov_b32_e32 v162, v142
	v_mov_b32_e32 v163, v138
	v_mov_b32_e32 v138, v143
	v_pk_add_f32 v[138:139], v[162:163], v[138:139]
	v_mov_b32_e32 v142, v144
	v_mov_b32_e32 v143, v140
	v_pk_add_f32 v[138:139], v[142:143], v[138:139]
	v_mov_b32_e32 v142, v134
	v_mov_b32_e32 v143, v130
	v_mov_b32_e32 v130, v135
	v_pk_add_f32 v[130:131], v[142:143], v[130:131]
	v_mov_b32_e32 v134, v136
	v_mov_b32_e32 v135, v132
	v_pk_add_f32 v[130:131], v[134:135], v[130:131]
	v_mov_b32_e32 v132, v137
	v_pk_add_f32 v[130:131], v[132:133], v[130:131]
	v_mul_f32_e32 v133, 0xbfb8aa3b, v126
	v_exp_f32_e32 v133, v133
	v_mov_b32_e32 v140, v145
	v_pk_add_f32 v[138:139], v[140:141], v[138:139]
	v_pk_fma_f32 v[130:131], v[130:131], s[72:73], v[202:203] op_sel_hi:[1,0,0]
	v_add_f32_e32 v133, 1.0, v133
	v_rcp_f32_e32 v136, v133
	v_mul_f32_e32 v133, 0xbfb8aa3b, v122
	v_exp_f32_e32 v133, v133
	v_pk_fma_f32 v[138:139], v[138:139], s[72:73], v[202:203] op_sel_hi:[1,0,0]
	v_mul_f32_e32 v132, 0x4b800000, v131
	v_mul_f32_e32 v140, 0x4b800000, v139
	v_add_f32_e32 v133, 1.0, v133
	v_rcp_f32_e32 v142, v133
	v_mul_f32_e32 v133, 0xbfb8aa3b, v127
	v_exp_f32_e32 v133, v133
	v_cmp_gt_f32_e64 s[4:5], s94, v139
	v_cmp_gt_f32_e32 vcc, s94, v138
	v_pk_mul_f32 v[112:113], v[112:113], v[198:199] op_sel_hi:[1,0]
	v_add_f32_e32 v133, 1.0, v133
	v_rcp_f32_e32 v137, v133
	v_cndmask_b32_e64 v139, v139, v140, s[4:5]
	v_rsq_f32_e32 v139, v139
	v_pk_mul_f32 v[104:105], v[104:105], v[198:199] op_sel_hi:[1,0]
	v_pk_mul_f32 v[126:127], v[126:127], v[136:137]
	v_pk_mul_f32 v[100:101], v[100:101], v[198:199] op_sel_hi:[1,0]
	v_pk_mul_f32 v[118:119], v[118:119], v[126:127]
	v_mul_f32_e32 v126, 0xbfb8aa3b, v123
	v_exp_f32_e32 v126, v126
	v_mul_f32_e32 v140, 0x45800000, v139
	v_cndmask_b32_e64 v140, v139, v140, s[4:5]
	v_mul_f32_e32 v139, 0x4b800000, v138
	v_add_f32_e32 v126, 1.0, v126
	v_rcp_f32_e32 v143, v126
	v_cmp_gt_f32_e64 s[4:5], s94, v131
	v_cndmask_b32_e32 v138, v138, v139, vcc
	v_rsq_f32_e32 v138, v138
	v_pk_mul_f32 v[122:123], v[122:123], v[142:143]
	v_cndmask_b32_e64 v131, v131, v132, s[4:5]
	v_pk_mul_f32 v[122:123], v[114:115], v[122:123]
	v_mul_f32_e32 v115, 0xbfb8aa3b, v124
	v_exp_f32_e32 v115, v115
	v_mul_f32_e32 v114, 0xbfb8aa3b, v128
	v_exp_f32_e32 v114, v114
	v_rsq_f32_e32 v131, v131
	v_add_f32_e32 v115, 1.0, v115
	v_rcp_f32_e32 v126, v115
	v_mul_f32_e32 v115, 0xbfb8aa3b, v129
	v_exp_f32_e32 v115, v115
	v_add_f32_e32 v114, 1.0, v114
	v_rcp_f32_e32 v114, v114
	v_mul_f32_e32 v139, 0x45800000, v138
	v_add_f32_e32 v115, 1.0, v115
	v_rcp_f32_e32 v115, v115
	v_mul_f32_e32 v132, 0x45800000, v131
	v_cndmask_b32_e32 v138, v138, v139, vcc
	v_cmp_gt_f32_e32 vcc, s94, v130
	v_pk_mul_f32 v[114:115], v[128:129], v[114:115]
	v_cndmask_b32_e64 v134, v131, v132, s[4:5]
	v_pk_mul_f32 v[120:121], v[120:121], v[114:115]
	v_mul_f32_e32 v114, 0xbfb8aa3b, v125
	v_exp_f32_e32 v114, v114
	v_mul_f32_e32 v131, 0x4b800000, v130
	v_cndmask_b32_e32 v130, v130, v131, vcc
	v_rsq_f32_e32 v130, v130
	v_add_f32_e32 v114, 1.0, v114
	v_rcp_f32_e32 v127, v114
	v_pk_mul_f32 v[90:91], v[90:91], v[196:197] op_sel_hi:[1,0]
	v_mul_f32_e32 v131, 0x45800000, v130
	v_cndmask_b32_e32 v132, v130, v131, vcc
	v_lshl_or_b32 v130, s86, 7, v199
	v_ashrrev_i32_e32 v131, 31, v130
	v_pk_mul_f32 v[114:115], v[124:125], v[126:127]
	v_lshl_add_u64 v[130:131], v[130:131], 1, s[28:29]
	v_pk_mul_f32 v[124:125], v[116:117], v[114:115]
	v_cvt_pk_bf16_f32 v114, v118, v119
	v_cvt_pk_bf16_f32 v115, v120, v121
	v_cvt_pk_bf16_f32 v116, v122, v123
	v_cvt_pk_bf16_f32 v117, v124, v125
	v_mad_i64_i32 v[118:119], s[0:1], v194, s35, v[130:131]
	global_store_dwordx4 v[118:119], v[114:117], off
	v_pk_mul_f32 v[94:95], v[94:95], v[196:197] op_sel_hi:[1,0]
	v_pk_mul_f32 v[86:87], v[86:87], v[196:197] op_sel_hi:[1,0]
	v_mul_f32_e32 v115, 0xbfb8aa3b, v106
	v_exp_f32_e32 v115, v115
	v_mul_f32_e32 v114, 0xbfb8aa3b, v110
	v_exp_f32_e32 v114, v114
	v_pk_mul_f32 v[92:93], v[92:93], v[196:197] op_sel_hi:[1,0]
	v_add_f32_e32 v115, 1.0, v115
	v_rcp_f32_e32 v116, v115
	v_mul_f32_e32 v115, 0xbfb8aa3b, v111
	v_exp_f32_e32 v115, v115
	v_add_f32_e32 v114, 1.0, v114
	v_rcp_f32_e32 v114, v114
	v_pk_mul_f32 v[82:83], v[82:83], v[196:197] op_sel_hi:[1,0]
	v_add_f32_e32 v115, 1.0, v115
	v_rcp_f32_e32 v115, v115
	v_pk_mul_f32 v[96:97], v[96:97], v[196:197] op_sel_hi:[1,0]
	v_pk_mul_f32 v[88:89], v[88:89], v[196:197] op_sel_hi:[1,0]
	v_pk_mul_f32 v[84:85], v[84:85], v[196:197] op_sel_hi:[1,0]
	v_pk_mul_f32 v[110:111], v[110:111], v[114:115]
	v_pk_mul_f32 v[74:75], v[74:75], v[192:193] op_sel_hi:[1,0]
; template <class Epi>
; DEVI void gemm_phase(LAS unsigned char* lds, const Gemm g, const Epi& E) {
;     ...
;                 for (int mm = 0; mm < 2; ++mm) {
;                     const int m = m0 + mm;
;                     const int r = row0 + ai * HALF + m * 16; float rs = 1.f, part = 0.f;
;                     if constexpr (Epi::RS) rs = rsv[ai * 4 + m];
;                     if constexpr (Epi::PAIR) E.pair8(cur.b, r, cur.pn * HALF + wc * 32 + 8 * fq, acc[ai][0][m][0] * rs, acc[ai][0][m][1] * rs, acc[ai][1][m][0] * rs, acc[ai][1][m][1] * rs);
	v_pk_mul_f32 v[102:103], v[102:103], v[110:111]
	v_mul_f32_e32 v110, 0xbfb8aa3b, v107
	v_exp_f32_e32 v110, v110
	v_pk_mul_f32 v[78:79], v[78:79], v[192:193] op_sel_hi:[1,0]
	v_pk_mul_f32 v[70:71], v[70:71], v[192:193] op_sel_hi:[1,0]
	v_pk_mul_f32 v[76:77], v[76:77], v[192:193] op_sel_hi:[1,0]
	v_add_f32_e32 v110, 1.0, v110
	v_rcp_f32_e32 v117, v110
	v_pk_mul_f32 v[66:67], v[66:67], v[192:193] op_sel_hi:[1,0]
	v_pk_mul_f32 v[80:81], v[80:81], v[192:193] op_sel_hi:[1,0]
	v_pk_mul_f32 v[72:73], v[72:73], v[192:193] op_sel_hi:[1,0]
	v_pk_mul_f32 v[106:107], v[106:107], v[116:117]
	v_pk_mul_f32 v[68:69], v[68:69], v[192:193] op_sel_hi:[1,0]
	v_pk_mul_f32 v[106:107], v[98:99], v[106:107]
	v_mul_f32_e32 v99, 0xbfb8aa3b, v108
	v_exp_f32_e32 v99, v99
	v_mul_f32_e32 v98, 0xbfb8aa3b, v112
	v_exp_f32_e32 v98, v98
	v_pk_mul_f32 v[54:55], v[54:55], v[140:141] op_sel_hi:[1,0]
	v_add_f32_e32 v99, 1.0, v99
	v_rcp_f32_e32 v110, v99
	v_mul_f32_e32 v99, 0xbfb8aa3b, v113
	v_exp_f32_e32 v99, v99
	v_add_f32_e32 v98, 1.0, v98
	v_rcp_f32_e32 v98, v98
	v_pk_mul_f32 v[50:51], v[50:51], v[140:141] op_sel_hi:[1,0]
	v_add_f32_e32 v99, 1.0, v99
	v_rcp_f32_e32 v99, v99
	v_pk_mul_f32 v[58:59], v[58:59], v[140:141] op_sel_hi:[1,0]
	v_pk_mul_f32 v[56:57], v[56:57], v[140:141] op_sel_hi:[1,0]
	v_pk_mul_f32 v[52:53], v[52:53], v[140:141] op_sel_hi:[1,0]
	v_pk_mul_f32 v[98:99], v[112:113], v[98:99]
	v_pk_mul_f32 v[62:63], v[62:63], v[140:141] op_sel_hi:[1,0]
	v_pk_mul_f32 v[104:105], v[104:105], v[98:99]
	v_mul_f32_e32 v98, 0xbfb8aa3b, v109
	v_exp_f32_e32 v98, v98
	v_pk_mul_f32 v[60:61], v[60:61], v[140:141] op_sel_hi:[1,0]
	v_pk_mul_f32 v[64:65], v[64:65], v[140:141] op_sel_hi:[1,0]
	v_pk_mul_f32 v[38:39], v[38:39], v[138:139] op_sel_hi:[1,0]
	v_add_f32_e32 v98, 1.0, v98
	v_rcp_f32_e32 v111, v98
	v_pk_mul_f32 v[34:35], v[34:35], v[138:139] op_sel_hi:[1,0]
	v_pk_mul_f32 v[42:43], v[42:43], v[138:139] op_sel_hi:[1,0]
	v_pk_mul_f32 v[40:41], v[40:41], v[138:139] op_sel_hi:[1,0]
	v_pk_mul_f32 v[98:99], v[108:109], v[110:111]
	v_pk_mul_f32 v[36:37], v[36:37], v[138:139] op_sel_hi:[1,0]
	v_pk_mul_f32 v[108:109], v[100:101], v[98:99]
	v_cvt_pk_bf16_f32 v98, v102, v103
	v_cvt_pk_bf16_f32 v99, v104, v105
	v_cvt_pk_bf16_f32 v100, v106, v107
	v_cvt_pk_bf16_f32 v101, v108, v109
	v_mad_i64_i32 v[102:103], s[0:1], v190, s35, v[130:131]
	global_store_dwordx4 v[102:103], v[98:101], off
	v_pk_mul_f32 v[46:47], v[46:47], v[138:139] op_sel_hi:[1,0]
	v_pk_mul_f32 v[44:45], v[44:45], v[138:139] op_sel_hi:[1,0]
	v_mul_f32_e32 v99, 0xbfb8aa3b, v90
	v_exp_f32_e32 v99, v99
	v_mul_f32_e32 v98, 0xbfb8aa3b, v94
	v_exp_f32_e32 v98, v98
	v_pk_mul_f32 v[48:49], v[48:49], v[138:139] op_sel_hi:[1,0]
	v_add_f32_e32 v99, 1.0, v99
	v_rcp_f32_e32 v100, v99
	v_mul_f32_e32 v99, 0xbfb8aa3b, v95
	v_exp_f32_e32 v99, v99
	v_add_f32_e32 v98, 1.0, v98
	v_rcp_f32_e32 v98, v98
	v_pk_mul_f32 v[22:23], v[22:23], v[134:135] op_sel_hi:[1,0]
	v_add_f32_e32 v99, 1.0, v99
	v_rcp_f32_e32 v99, v99
	v_pk_mul_f32 v[18:19], v[18:19], v[134:135] op_sel_hi:[1,0]
	v_pk_mul_f32 v[26:27], v[26:27], v[134:135] op_sel_hi:[1,0]
	v_pk_mul_f32 v[24:25], v[24:25], v[134:135] op_sel_hi:[1,0]
	v_pk_mul_f32 v[94:95], v[94:95], v[98:99]
	v_pk_mul_f32 v[20:21], v[20:21], v[134:135] op_sel_hi:[1,0]
	v_pk_mul_f32 v[86:87], v[86:87], v[94:95]
	v_mul_f32_e32 v94, 0xbfb8aa3b, v91
	v_exp_f32_e32 v94, v94
	v_pk_mul_f32 v[30:31], v[30:31], v[134:135] op_sel_hi:[1,0]
	v_pk_mul_f32 v[28:29], v[28:29], v[134:135] op_sel_hi:[1,0]
	v_pk_mul_f32 v[32:33], v[32:33], v[134:135] op_sel_hi:[1,0]
	v_add_f32_e32 v94, 1.0, v94
	v_rcp_f32_e32 v101, v94
	v_pk_mul_f32 v[4:5], v[4:5], v[132:133] op_sel_hi:[1,0]
	v_pk_mul_f32 v[0:1], v[0:1], v[132:133] op_sel_hi:[1,0]
	v_pk_mul_f32 v[10:11], v[10:11], v[132:133] op_sel_hi:[1,0]
	v_pk_mul_f32 v[90:91], v[90:91], v[100:101]
	v_pk_mul_f32 v[6:7], v[6:7], v[132:133] op_sel_hi:[1,0]
	v_pk_mul_f32 v[90:91], v[82:83], v[90:91]
	v_mul_f32_e32 v83, 0xbfb8aa3b, v92
	v_exp_f32_e32 v83, v83
	v_mul_f32_e32 v82, 0xbfb8aa3b, v96
	v_exp_f32_e32 v82, v82
	v_pk_mul_f32 v[2:3], v[2:3], v[132:133] op_sel_hi:[1,0]
	v_add_f32_e32 v83, 1.0, v83
	v_rcp_f32_e32 v94, v83
	v_mul_f32_e32 v83, 0xbfb8aa3b, v97
	v_exp_f32_e32 v83, v83
	v_add_f32_e32 v82, 1.0, v82
	v_rcp_f32_e32 v82, v82
	v_pk_mul_f32 v[14:15], v[14:15], v[132:133] op_sel_hi:[1,0]
	v_add_f32_e32 v83, 1.0, v83
	v_rcp_f32_e32 v83, v83
	v_pk_mul_f32 v[12:13], v[12:13], v[132:133] op_sel_hi:[1,0]
	v_pk_mul_f32 v[16:17], v[16:17], v[132:133] op_sel_hi:[1,0]
	s_and_b64 vcc, exec, s[2:3]
	v_pk_mul_f32 v[82:83], v[96:97], v[82:83]
	s_mov_b32 s86, s8
	v_pk_mul_f32 v[88:89], v[88:89], v[82:83]
	v_mul_f32_e32 v82, 0xbfb8aa3b, v93
	v_exp_f32_e32 v82, v82
	s_mov_b32 s4, s6
	v_add_f32_e32 v82, 1.0, v82
	v_rcp_f32_e32 v95, v82
	s_nop 0
	v_pk_mul_f32 v[82:83], v[92:93], v[94:95]
	s_nop 0
	v_pk_mul_f32 v[92:93], v[84:85], v[82:83]
	v_cvt_pk_bf16_f32 v82, v86, v87
	v_cvt_pk_bf16_f32 v83, v88, v89
	v_cvt_pk_bf16_f32 v84, v90, v91
	v_cvt_pk_bf16_f32 v85, v92, v93
	v_mad_i64_i32 v[86:87], s[0:1], v188, s35, v[130:131]
	global_store_dwordx4 v[86:87], v[82:85], off
	s_nop 1
	v_mul_f32_e32 v83, 0xbfb8aa3b, v74
	v_exp_f32_e32 v83, v83
	v_mul_f32_e32 v82, 0xbfb8aa3b, v78
	v_exp_f32_e32 v82, v82
	v_add_f32_e32 v83, 1.0, v83
	v_rcp_f32_e32 v84, v83
	v_mul_f32_e32 v83, 0xbfb8aa3b, v79
	v_exp_f32_e32 v83, v83
	v_add_f32_e32 v82, 1.0, v82
	v_rcp_f32_e32 v82, v82
	v_add_f32_e32 v83, 1.0, v83
	v_rcp_f32_e32 v83, v83
	s_nop 0
	v_pk_mul_f32 v[78:79], v[78:79], v[82:83]
	s_nop 0
	v_pk_mul_f32 v[70:71], v[70:71], v[78:79]
	v_mul_f32_e32 v78, 0xbfb8aa3b, v75
	v_exp_f32_e32 v78, v78
	s_nop 0
	v_add_f32_e32 v78, 1.0, v78
; template <class Epi>
; DEVI void gemm_phase(LAS unsigned char* lds, const Gemm g, const Epi& E) {
;     ...
;                 for (int mm = 0; mm < 2; ++mm) {
;                     const int m = m0 + mm;
;                     const int r = row0 + ai * HALF + m * 16; float rs = 1.f, part = 0.f;
;                     if constexpr (Epi::RS) rs = rsv[ai * 4 + m];
;                     if constexpr (Epi::PAIR) E.pair8(cur.b, r, cur.pn * HALF + wc * 32 + 8 * fq, acc[ai][0][m][0] * rs, acc[ai][0][m][1] * rs, acc[ai][1][m][0] * rs, acc[ai][1][m][1] * rs);
	v_rcp_f32_e32 v85, v78
	s_nop 0
	v_pk_mul_f32 v[74:75], v[74:75], v[84:85]
	s_nop 0
	v_pk_mul_f32 v[74:75], v[66:67], v[74:75]
	v_mul_f32_e32 v67, 0xbfb8aa3b, v76
	v_exp_f32_e32 v67, v67
	v_mul_f32_e32 v66, 0xbfb8aa3b, v80
	v_exp_f32_e32 v66, v66
	v_add_f32_e32 v67, 1.0, v67
	v_rcp_f32_e32 v78, v67
	v_mul_f32_e32 v67, 0xbfb8aa3b, v81
	v_exp_f32_e32 v67, v67
	v_add_f32_e32 v66, 1.0, v66
	v_rcp_f32_e32 v66, v66
	v_add_f32_e32 v67, 1.0, v67
	v_rcp_f32_e32 v67, v67
	s_nop 0
	v_pk_mul_f32 v[66:67], v[80:81], v[66:67]
	s_nop 0
	v_pk_mul_f32 v[72:73], v[72:73], v[66:67]
	v_mul_f32_e32 v66, 0xbfb8aa3b, v77
	v_exp_f32_e32 v66, v66
	s_nop 0
	v_add_f32_e32 v66, 1.0, v66
	v_rcp_f32_e32 v79, v66
	s_nop 0
	v_pk_mul_f32 v[66:67], v[76:77], v[78:79]
	s_nop 0
	v_pk_mul_f32 v[76:77], v[68:69], v[66:67]
	v_cvt_pk_bf16_f32 v66, v70, v71
	v_cvt_pk_bf16_f32 v67, v72, v73
	v_cvt_pk_bf16_f32 v68, v74, v75
	v_cvt_pk_bf16_f32 v69, v76, v77
	v_mad_i64_i32 v[70:71], s[0:1], v186, s35, v[130:131]
	global_store_dwordx4 v[70:71], v[66:69], off
	s_nop 1
	v_mul_f32_e32 v67, 0xbfb8aa3b, v54
	v_exp_f32_e32 v67, v67
	v_mul_f32_e32 v66, 0xbfb8aa3b, v50
	v_exp_f32_e32 v66, v66
	v_add_f32_e32 v67, 1.0, v67
	v_rcp_f32_e32 v68, v67
	v_mul_f32_e32 v67, 0xbfb8aa3b, v51
	v_exp_f32_e32 v67, v67
	v_add_f32_e32 v66, 1.0, v66
	v_rcp_f32_e32 v66, v66
	v_add_f32_e32 v67, 1.0, v67
	v_rcp_f32_e32 v67, v67
	s_nop 0
	v_pk_mul_f32 v[50:51], v[50:51], v[66:67]
	s_nop 0
	v_pk_mul_f32 v[50:51], v[58:59], v[50:51]
	v_mul_f32_e32 v58, 0xbfb8aa3b, v55
	v_exp_f32_e32 v58, v58
	v_mul_f32_e32 v59, 0xbfb8aa3b, v56
	v_exp_f32_e32 v59, v59
	v_cvt_pk_bf16_f32 v50, v50, v51
	v_add_f32_e32 v58, 1.0, v58
	v_rcp_f32_e32 v69, v58
	v_add_f32_e32 v59, 1.0, v59
	v_mul_f32_e32 v58, 0xbfb8aa3b, v52
	v_exp_f32_e32 v58, v58
	v_pk_mul_f32 v[54:55], v[54:55], v[68:69]
	v_add_f32_e32 v58, 1.0, v58
	v_pk_mul_f32 v[54:55], v[62:63], v[54:55]
	v_rcp_f32_e32 v62, v59
	v_mul_f32_e32 v59, 0xbfb8aa3b, v53
	v_exp_f32_e32 v59, v59
	v_rcp_f32_e32 v58, v58
	v_add_f32_e32 v59, 1.0, v59
	v_rcp_f32_e32 v59, v59
	s_nop 0
	v_pk_mul_f32 v[52:53], v[52:53], v[58:59]
	v_mul_f32_e32 v58, 0xbfb8aa3b, v57
	v_exp_f32_e32 v58, v58
	v_pk_mul_f32 v[52:53], v[60:61], v[52:53]
	v_add_f32_e32 v58, 1.0, v58
	v_rcp_f32_e32 v63, v58
	v_cvt_pk_bf16_f32 v51, v52, v53
	v_cvt_pk_bf16_f32 v52, v54, v55
	v_mad_i64_i32 v[54:55], s[0:1], v184, s35, v[130:131]
	v_pk_mul_f32 v[56:57], v[56:57], v[62:63]
	s_nop 0
	v_pk_mul_f32 v[56:57], v[64:65], v[56:57]
	s_nop 0
	v_cvt_pk_bf16_f32 v53, v56, v57
	global_store_dwordx4 v[54:55], v[50:53], off
	s_nop 1
	v_mul_f32_e32 v51, 0xbfb8aa3b, v38
	v_exp_f32_e32 v51, v51
	v_mul_f32_e32 v50, 0xbfb8aa3b, v34
	v_exp_f32_e32 v50, v50
	v_add_f32_e32 v51, 1.0, v51
	v_rcp_f32_e32 v52, v51
	v_mul_f32_e32 v51, 0xbfb8aa3b, v35
	v_exp_f32_e32 v51, v51
	v_add_f32_e32 v50, 1.0, v50
	v_rcp_f32_e32 v50, v50
	v_add_f32_e32 v51, 1.0, v51
	v_rcp_f32_e32 v51, v51
	s_nop 0
	v_pk_mul_f32 v[34:35], v[34:35], v[50:51]
	s_nop 0
	v_pk_mul_f32 v[34:35], v[42:43], v[34:35]
	v_mul_f32_e32 v42, 0xbfb8aa3b, v39
	v_exp_f32_e32 v42, v42
	v_mul_f32_e32 v43, 0xbfb8aa3b, v40
	v_exp_f32_e32 v43, v43
	v_cvt_pk_bf16_f32 v34, v34, v35
	v_add_f32_e32 v42, 1.0, v42
	v_rcp_f32_e32 v53, v42
	v_add_f32_e32 v43, 1.0, v43
	v_mul_f32_e32 v42, 0xbfb8aa3b, v36
	v_exp_f32_e32 v42, v42
	v_pk_mul_f32 v[38:39], v[38:39], v[52:53]
	v_add_f32_e32 v42, 1.0, v42
	v_pk_mul_f32 v[38:39], v[46:47], v[38:39]
	v_rcp_f32_e32 v46, v43
	v_mul_f32_e32 v43, 0xbfb8aa3b, v37
	v_exp_f32_e32 v43, v43
	v_rcp_f32_e32 v42, v42
	v_add_f32_e32 v43, 1.0, v43
	v_rcp_f32_e32 v43, v43
	s_nop 0
; #define PG8_WAIT_V(n) asm volatile("s_waitcnt vmcnt(" #n ")" ::: "memory")
; #define PG8_BAR __builtin_amdgcn_s_barrier()
; template <class Epi>
; DEVI void gemm_phase(LAS unsigned char* lds, const Gemm g, const Epi& E) {
;     ...
;         if (!has_next) break;
; #pragma unroll
;         for (int a = 0; a < 2; ++a)
; #pragma unroll
;             for (int b = 0; b < 2; ++b)
; #pragma unroll
;                 for (int m = 0; m < 4; ++m)
; #pragma unroll
;                     for (int n = 0; n < 2; ++n) acc[a][b][m][n] = (f32x4){0.f, 0.f, 0.f, 0.f};
;         cur = nxt; cA = nA; cB = nB; ++ui;
;     }
;     PG8_WAIT_V(0);
;     if (wr == 0) PG8_BAR;
;     PG8_BAR;
	v_pk_mul_f32 v[36:37], v[36:37], v[42:43]
	v_mul_f32_e32 v42, 0xbfb8aa3b, v41
	v_exp_f32_e32 v42, v42
	v_pk_mul_f32 v[36:37], v[44:45], v[36:37]
	v_add_f32_e32 v42, 1.0, v42
	v_rcp_f32_e32 v47, v42
	v_cvt_pk_bf16_f32 v35, v36, v37
	v_cvt_pk_bf16_f32 v36, v38, v39
	v_mad_i64_i32 v[38:39], s[0:1], v182, s35, v[130:131]
	v_pk_mul_f32 v[40:41], v[40:41], v[46:47]
	s_nop 0
	v_pk_mul_f32 v[40:41], v[48:49], v[40:41]
	s_nop 0
	v_cvt_pk_bf16_f32 v37, v40, v41
	global_store_dwordx4 v[38:39], v[34:37], off
	s_nop 1
	v_mul_f32_e32 v35, 0xbfb8aa3b, v22
	v_exp_f32_e32 v35, v35
	v_mul_f32_e32 v34, 0xbfb8aa3b, v18
	v_exp_f32_e32 v34, v34
	v_add_f32_e32 v35, 1.0, v35
	v_rcp_f32_e32 v36, v35
	v_mul_f32_e32 v35, 0xbfb8aa3b, v19
	v_exp_f32_e32 v35, v35
	v_add_f32_e32 v34, 1.0, v34
	v_rcp_f32_e32 v34, v34
	v_add_f32_e32 v35, 1.0, v35
	v_rcp_f32_e32 v35, v35
	s_nop 0
	v_pk_mul_f32 v[18:19], v[18:19], v[34:35]
	s_nop 0
	v_pk_mul_f32 v[18:19], v[26:27], v[18:19]
	v_mul_f32_e32 v26, 0xbfb8aa3b, v23
	v_exp_f32_e32 v26, v26
	v_mul_f32_e32 v27, 0xbfb8aa3b, v24
	v_exp_f32_e32 v27, v27
	v_cvt_pk_bf16_f32 v18, v18, v19
	v_add_f32_e32 v26, 1.0, v26
	v_rcp_f32_e32 v37, v26
	v_add_f32_e32 v27, 1.0, v27
	v_mul_f32_e32 v26, 0xbfb8aa3b, v20
	v_exp_f32_e32 v26, v26
	v_pk_mul_f32 v[22:23], v[22:23], v[36:37]
	v_add_f32_e32 v26, 1.0, v26
	v_pk_mul_f32 v[22:23], v[30:31], v[22:23]
	v_rcp_f32_e32 v30, v27
	v_mul_f32_e32 v27, 0xbfb8aa3b, v21
	v_exp_f32_e32 v27, v27
	v_rcp_f32_e32 v26, v26
	v_add_f32_e32 v27, 1.0, v27
	v_rcp_f32_e32 v27, v27
	s_nop 0
	v_pk_mul_f32 v[20:21], v[20:21], v[26:27]
	v_mul_f32_e32 v26, 0xbfb8aa3b, v25
	v_exp_f32_e32 v26, v26
	v_pk_mul_f32 v[20:21], v[28:29], v[20:21]
	v_add_f32_e32 v26, 1.0, v26
	v_rcp_f32_e32 v31, v26
	v_cvt_pk_bf16_f32 v19, v20, v21
	v_cvt_pk_bf16_f32 v20, v22, v23
	v_mad_i64_i32 v[22:23], s[0:1], v180, s35, v[130:131]
	v_pk_mul_f32 v[24:25], v[24:25], v[30:31]
	s_nop 0
	v_pk_mul_f32 v[24:25], v[32:33], v[24:25]
	s_nop 0
	v_cvt_pk_bf16_f32 v21, v24, v25
	global_store_dwordx4 v[22:23], v[18:21], off
	s_nop 1
	v_mul_f32_e32 v19, 0xbfb8aa3b, v4
	v_exp_f32_e32 v19, v19
	v_mul_f32_e32 v18, 0xbfb8aa3b, v0
	v_exp_f32_e32 v18, v18
	v_add_f32_e32 v19, 1.0, v19
	v_rcp_f32_e32 v20, v19
	v_mul_f32_e32 v19, 0xbfb8aa3b, v1
	v_exp_f32_e32 v19, v19
	v_add_f32_e32 v18, 1.0, v18
	v_rcp_f32_e32 v18, v18
	v_add_f32_e32 v19, 1.0, v19
	v_rcp_f32_e32 v19, v19
	s_nop 0
	v_pk_mul_f32 v[0:1], v[0:1], v[18:19]
	s_nop 0
	v_pk_mul_f32 v[0:1], v[10:11], v[0:1]
	v_mul_f32_e32 v10, 0xbfb8aa3b, v5
	v_exp_f32_e32 v10, v10
	v_mul_f32_e32 v11, 0xbfb8aa3b, v6
	v_exp_f32_e32 v11, v11
	v_cvt_pk_bf16_f32 v0, v0, v1
	v_add_f32_e32 v10, 1.0, v10
	v_rcp_f32_e32 v21, v10
	v_add_f32_e32 v11, 1.0, v11
	v_mul_f32_e32 v10, 0xbfb8aa3b, v2
	v_exp_f32_e32 v10, v10
	v_pk_mul_f32 v[4:5], v[4:5], v[20:21]
	v_add_f32_e32 v10, 1.0, v10
	v_pk_mul_f32 v[4:5], v[14:15], v[4:5]
	v_rcp_f32_e32 v14, v11
	v_mul_f32_e32 v11, 0xbfb8aa3b, v3
	v_exp_f32_e32 v11, v11
	v_rcp_f32_e32 v10, v10
	v_add_f32_e32 v11, 1.0, v11
	v_rcp_f32_e32 v11, v11
	s_nop 0
	v_pk_mul_f32 v[2:3], v[2:3], v[10:11]
	v_mul_f32_e32 v10, 0xbfb8aa3b, v7
	v_exp_f32_e32 v10, v10
	v_pk_mul_f32 v[2:3], v[12:13], v[2:3]
	v_add_f32_e32 v10, 1.0, v10
	v_rcp_f32_e32 v15, v10
	v_cvt_pk_bf16_f32 v1, v2, v3
	v_cvt_pk_bf16_f32 v2, v4, v5
	v_mad_i64_i32 v[4:5], s[0:1], v178, s35, v[130:131]
	v_pk_mul_f32 v[6:7], v[6:7], v[14:15]
	s_nop 0
	v_pk_mul_f32 v[6:7], v[16:17], v[6:7]
	s_nop 0
	v_cvt_pk_bf16_f32 v3, v6, v7
	global_store_dwordx4 v[4:5], v[0:3], off
	s_cbranch_vccz .LBB0_1669
	s_waitcnt vmcnt(0)
	s_cmpk_gt_u32 s66, 0xff
	s_cbranch_scc1 .LBB0_1676
	s_barrier

; #define PG8_STAGE(bufoff, gbase, voff) do { _Pragma("unroll") for (int _i = 0; _i < 2; ++_i) \
;         __builtin_amdgcn_global_load_lds((const unsigned*)((const char*)(gbase) + (voff)[_i]), (LAS unsigned*)(lds + (bufoff) + ldsw + _i * 8192), 16, 0, 0); } while (0)
; #define PG8_LDA(dst, b, h) do { _Pragma("unroll") for (int m = 0; m < 4; ++m) _Pragma("unroll") for (int k = 0; k < 2; ++k) dst[m][k] = *(const LAS bf16x8*)(lds + PG8_SA(b, h) + aoff + m * 2048 + k * 1024); } while (0)
; #define PG8_LDB(dst, b, h) do { _Pragma("unroll") for (int n = 0; n < 2; ++n) _Pragma("unroll") for (int k = 0; k < 2; ++k) dst[n][k] = *(const LAS bf16x8*)(lds + PG8_SB(b, h) + boff + n * 2048 + k * 1024); } while (0)
; #define PG8_MMA(ai, bj, At, Bt) do { __builtin_amdgcn_s_setprio(1); _Pragma("unroll") for (int m = 0; m < 4; ++m) _Pragma("unroll") for (int n = 0; n < 2; ++n) _Pragma("unroll") for (int k = 0; k < 2; ++k) \
;         acc[ai][bj][m][n] = __builtin_amdgcn_mfma_f32_16x16x32_bf16(Bt[n][k], At[m][k], acc[ai][bj][m][n], 0, 0, 0); __builtin_amdgcn_s_setprio(0); } while (0)
; #define PG8_WAIT_V(n) asm volatile("s_waitcnt vmcnt(" #n ")" ::: "memory")
; #define PG8_WAIT_L(n) asm volatile("s_waitcnt lgkmcnt(" #n ")" ::: "memory")
; #define PG8_BAR __builtin_amdgcn_s_barrier()
; #define PG8_SCHED __builtin_amdgcn_sched_barrier(0)
; template <class Epi>
; DEVI void gemm_phase(LAS unsigned char* lds, const Gemm g, const Epi& E) {
;     ...
;             PG8_LDB(B0, 0, 0); PG8_SCHED; PG8_LDA(At, 0, 0); PG8_STAGE(PG8_SA(1, 1), a1 + hstepA, voffA);
;             PG8_WAIT_L(8); PG8_BAR; PG8_WAIT_L(0); PG8_MMA(0, 0, At, B0); PG8_BAR; PG8_SCHED;
;             PG8_LDB(B1, 0, 1); PG8_STAGE(PG8_SB(0, 0), b2, voffB);
;             PG8_BAR; PG8_WAIT_L(0); PG8_MMA(0, 1, At, B1); PG8_BAR;
;             PG8_LDA(At, 0, 1); PG8_STAGE(PG8_SA(0, 0), a2, voffA);
;             PG8_BAR; PG8_WAIT_L(0); PG8_MMA(1, 0, At, B0); PG8_BAR; PG8_SCHED;
;             PG8_STAGE(PG8_SB(0, 1), b2 + hstepB, voffB);
;             PG8_WAIT_V(6); PG8_BAR; PG8_MMA(1, 1, At, B1); PG8_BAR;
.LBB0_1747:
	s_add_u32 s36, s16, 0x100
	s_addc_u32 s37, s17, 0
	s_add_i32 s19, 0, 0x10000
	v_add_u32_e32 v142, s19, v191
	ds_read_b128 v[130:133], v142
	ds_read_b128 v[134:137], v142 offset:1024
	ds_read_b128 v[138:141], v142 offset:2048
	ds_read_b128 v[142:145], v142 offset:3072
	s_cmp_eq_u32 s18, 40
	s_cselect_b32 s69, s9, s37
	s_cselect_b32 s68, s8, s36
	s_cselect_b32 s47, s11, s13
	s_cselect_b32 s46, s10, s1
	v_lshl_add_u64 v[162:163], s[16:17], 0, v[152:153]
	s_add_i32 m0, s81, 0xc000
	ds_read_b128 v[178:181], v196
	ds_read_b128 v[182:185], v196 offset:1024
	ds_read_b128 v[186:189], v196 offset:2048
	ds_read_b128 v[198:201], v196 offset:3072
	ds_read_b128 v[202:205], v196 offset:4096
	ds_read_b128 v[206:209], v196 offset:5120
	ds_read_b128 v[214:217], v196 offset:6144
	ds_read_b128 v[218:221], v196 offset:7168
	global_load_lds_dwordx4 v[162:163], off
	v_lshl_add_u64 v[162:163], s[16:17], 0, v[176:177]
	s_add_i32 m0, s81, 0xe000
	s_nop 0
	global_load_lds_dwordx4 v[162:163], off
	s_waitcnt lgkmcnt(8)
	s_barrier
	s_waitcnt lgkmcnt(0)
	v_mfma_f32_16x16x32_bf16 v[126:129], v[130:133], v[178:181], v[126:129]
	v_mfma_f32_16x16x32_bf16 v[122:125], v[138:141], v[178:181], v[122:125]
	v_mfma_f32_16x16x32_bf16 v[110:113], v[130:133], v[186:189], v[110:113]
	v_mfma_f32_16x16x32_bf16 v[106:109], v[138:141], v[186:189], v[106:109]
	v_mfma_f32_16x16x32_bf16 v[94:97], v[130:133], v[202:205], v[94:97]
	v_mfma_f32_16x16x32_bf16 v[90:93], v[138:141], v[202:205], v[90:93]
	v_mfma_f32_16x16x32_bf16 v[78:81], v[130:133], v[214:217], v[78:81]
	v_mfma_f32_16x16x32_bf16 v[74:77], v[138:141], v[214:217], v[74:77]
	v_mfma_f32_16x16x32_bf16 v[126:129], v[134:137], v[182:185], v[126:129]
	v_mfma_f32_16x16x32_bf16 v[122:125], v[142:145], v[182:185], v[122:125]
	v_mfma_f32_16x16x32_bf16 v[110:113], v[134:137], v[198:201], v[110:113]
	v_mfma_f32_16x16x32_bf16 v[106:109], v[142:145], v[198:201], v[106:109]
	v_mfma_f32_16x16x32_bf16 v[94:97], v[134:137], v[206:209], v[94:97]
	v_mfma_f32_16x16x32_bf16 v[90:93], v[142:145], v[206:209], v[90:93]
	v_mfma_f32_16x16x32_bf16 v[78:81], v[134:137], v[218:221], v[78:81]
	v_mfma_f32_16x16x32_bf16 v[74:77], v[142:145], v[218:221], v[74:77]
	s_barrier
	s_add_i32 s26, 0, 0x14000
	v_add_u32_e32 v162, s26, v191
	s_add_i32 s16, s19, s80
	ds_read_b128 v[222:225], v162
	ds_read_b128 v[226:229], v162 offset:1024
	ds_read_b128 v[230:233], v162 offset:2048
	ds_read_b128 v[234:237], v162 offset:3072
	v_lshl_add_u64 v[162:163], s[46:47], 0, v[8:9]
	s_mov_b32 m0, s16
	v_lshl_add_u64 v[164:165], s[46:47], 0, v[150:151]
	global_load_lds_dwordx4 v[162:163], off
	s_add_i32 m0, s16, 0x2000
	s_nop 0
	global_load_lds_dwordx4 v[164:165], off
	s_barrier
	s_waitcnt lgkmcnt(0)
	v_mfma_f32_16x16x32_bf16 v[118:121], v[222:225], v[178:181], v[118:121]
	v_mfma_f32_16x16x32_bf16 v[114:117], v[230:233], v[178:181], v[114:117]
	v_mfma_f32_16x16x32_bf16 v[102:105], v[222:225], v[186:189], v[102:105]
	v_mfma_f32_16x16x32_bf16 v[98:101], v[230:233], v[186:189], v[98:101]
	v_mfma_f32_16x16x32_bf16 v[86:89], v[222:225], v[202:205], v[86:89]
	v_mfma_f32_16x16x32_bf16 v[82:85], v[230:233], v[202:205], v[82:85]
	v_mfma_f32_16x16x32_bf16 v[70:73], v[222:225], v[214:217], v[70:73]
	v_mfma_f32_16x16x32_bf16 v[66:69], v[230:233], v[214:217], v[66:69]
	v_mfma_f32_16x16x32_bf16 v[118:121], v[226:229], v[182:185], v[118:121]
	v_mfma_f32_16x16x32_bf16 v[114:117], v[234:237], v[182:185], v[114:117]
	v_mfma_f32_16x16x32_bf16 v[102:105], v[226:229], v[198:201], v[102:105]
	v_mfma_f32_16x16x32_bf16 v[98:101], v[234:237], v[198:201], v[98:101]
	v_mfma_f32_16x16x32_bf16 v[86:89], v[226:229], v[206:209], v[86:89]
	v_mfma_f32_16x16x32_bf16 v[82:85], v[234:237], v[206:209], v[82:85]
	v_mfma_f32_16x16x32_bf16 v[70:73], v[226:229], v[218:221], v[70:73]
	v_mfma_f32_16x16x32_bf16 v[66:69], v[234:237], v[218:221], v[66:69]
	s_mov_b32 m0, s81
	v_lshl_add_u64 v[238:239], s[68:69], 0, v[146:147]
	s_barrier
	ds_read_b128 v[178:181], v196 offset:16384
	ds_read_b128 v[182:185], v196 offset:17408
	ds_read_b128 v[186:189], v196 offset:18432
	ds_read_b128 v[198:201], v196 offset:19456
	ds_read_b128 v[202:205], v196 offset:20480
	ds_read_b128 v[206:209], v196 offset:21504
	ds_read_b128 v[214:217], v196 offset:22528
	ds_read_b128 v[218:221], v196 offset:23552
	global_load_lds_dwordx4 v[238:239], off
	v_lshl_add_u64 v[240:241], s[68:69], 0, v[148:149]
	s_mov_b32 m0, s82
	s_nop 0
	global_load_lds_dwordx4 v[240:241], off
	s_barrier
	s_waitcnt lgkmcnt(0)
	v_mfma_f32_16x16x32_bf16 v[62:65], v[130:133], v[178:181], v[62:65]
	v_mfma_f32_16x16x32_bf16 v[58:61], v[138:141], v[178:181], v[58:61]
	v_mfma_f32_16x16x32_bf16 v[46:49], v[130:133], v[186:189], v[46:49]
	v_mfma_f32_16x16x32_bf16 v[42:45], v[138:141], v[186:189], v[42:45]
	v_mfma_f32_16x16x32_bf16 v[30:33], v[130:133], v[202:205], v[30:33]
	v_mfma_f32_16x16x32_bf16 v[26:29], v[138:141], v[202:205], v[26:29]
	v_mfma_f32_16x16x32_bf16 v[14:17], v[130:133], v[214:217], v[14:17]
	v_mfma_f32_16x16x32_bf16 v[10:13], v[138:141], v[214:217], v[10:13]
	v_mfma_f32_16x16x32_bf16 v[62:65], v[134:137], v[182:185], v[62:65]
	v_mfma_f32_16x16x32_bf16 v[58:61], v[142:145], v[182:185], v[58:61]
	v_mfma_f32_16x16x32_bf16 v[46:49], v[134:137], v[198:201], v[46:49]
	v_mfma_f32_16x16x32_bf16 v[42:45], v[142:145], v[198:201], v[42:45]
	v_mfma_f32_16x16x32_bf16 v[30:33], v[134:137], v[206:209], v[30:33]
	v_mfma_f32_16x16x32_bf16 v[26:29], v[142:145], v[206:209], v[26:29]
	v_mfma_f32_16x16x32_bf16 v[14:17], v[134:137], v[218:221], v[14:17]
	v_mfma_f32_16x16x32_bf16 v[10:13], v[142:145], v[218:221], v[10:13]
	s_barrier
; #define PG8_STAGE(bufoff, gbase, voff) do { _Pragma("unroll") for (int _i = 0; _i < 2; ++_i) \
;         __builtin_amdgcn_global_load_lds((const unsigned*)((const char*)(gbase) + (voff)[_i]), (LAS unsigned*)(lds + (bufoff) + ldsw + _i * 8192), 16, 0, 0); } while (0)
; #define PG8_LDA(dst, b, h) do { _Pragma("unroll") for (int m = 0; m < 4; ++m) _Pragma("unroll") for (int k = 0; k < 2; ++k) dst[m][k] = *(const LAS bf16x8*)(lds + PG8_SA(b, h) + aoff + m * 2048 + k * 1024); } while (0)
; #define PG8_LDB(dst, b, h) do { _Pragma("unroll") for (int n = 0; n < 2; ++n) _Pragma("unroll") for (int k = 0; k < 2; ++k) dst[n][k] = *(const LAS bf16x8*)(lds + PG8_SB(b, h) + boff + n * 2048 + k * 1024); } while (0)
; #define PG8_MMA(ai, bj, At, Bt) do { __builtin_amdgcn_s_setprio(1); _Pragma("unroll") for (int m = 0; m < 4; ++m) _Pragma("unroll") for (int n = 0; n < 2; ++n) _Pragma("unroll") for (int k = 0; k < 2; ++k) \
;         acc[ai][bj][m][n] = __builtin_amdgcn_mfma_f32_16x16x32_bf16(Bt[n][k], At[m][k], acc[ai][bj][m][n], 0, 0, 0); __builtin_amdgcn_s_setprio(0); } while (0)
; #define PG8_WAIT_V(n) asm volatile("s_waitcnt vmcnt(" #n ")" ::: "memory")
; #define PG8_WAIT_L(n) asm volatile("s_waitcnt lgkmcnt(" #n ")" ::: "memory")
; #define PG8_BAR __builtin_amdgcn_s_barrier()
; #define PG8_SCHED __builtin_amdgcn_sched_barrier(0)
; template <class Epi>
; DEVI void gemm_phase(LAS unsigned char* lds, const Gemm g, const Epi& E) {
;     ...
;             PG8_WAIT_V(6); PG8_BAR; PG8_MMA(1, 1, At, B1); PG8_BAR;
;             PG8_LDB(B0, 1, 0); PG8_SCHED; PG8_LDA(At, 1, 0); PG8_STAGE(PG8_SA(0, 1), a2 + hstepA, voffA);
;             PG8_WAIT_L(8); PG8_BAR; PG8_WAIT_L(0); PG8_MMA(0, 0, At, B0); PG8_BAR; PG8_SCHED;
;             PG8_LDB(B1, 1, 1); PG8_STAGE(PG8_SB(1, 0), b3, voffB);
;             PG8_BAR; PG8_WAIT_L(0); PG8_MMA(0, 1, At, B1); PG8_BAR;
;             PG8_LDA(At, 1, 1); PG8_STAGE(PG8_SA(1, 0), a3, voffA);
;             PG8_BAR; PG8_WAIT_L(0); PG8_MMA(1, 0, At, B0); PG8_BAR; PG8_SCHED;
	s_add_u32 s16, s46, 0xb0000
	s_addc_u32 s17, s47, 0
	s_add_i32 s19, s26, s80
	v_lshl_add_u64 v[130:131], s[16:17], 0, v[8:9]
	s_mov_b32 m0, s19
	s_nop 0
	global_load_lds_dwordx4 v[130:131], off
	v_lshl_add_u64 v[130:131], s[16:17], 0, v[150:151]
	s_add_i32 m0, s19, 0x2000
	s_nop 0
	global_load_lds_dwordx4 v[130:131], off
	s_waitcnt vmcnt(6)
	s_barrier
	v_mfma_f32_16x16x32_bf16 v[54:57], v[222:225], v[178:181], v[54:57]
	v_mfma_f32_16x16x32_bf16 v[50:53], v[230:233], v[178:181], v[50:53]
	v_mfma_f32_16x16x32_bf16 v[38:41], v[222:225], v[186:189], v[38:41]
	v_mfma_f32_16x16x32_bf16 v[34:37], v[230:233], v[186:189], v[34:37]
	v_mfma_f32_16x16x32_bf16 v[22:25], v[222:225], v[202:205], v[22:25]
	v_mfma_f32_16x16x32_bf16 v[18:21], v[230:233], v[202:205], v[18:21]
	v_mfma_f32_16x16x32_bf16 v[4:7], v[222:225], v[214:217], v[4:7]
	v_mfma_f32_16x16x32_bf16 v[0:3], v[230:233], v[214:217], v[0:3]
	v_mfma_f32_16x16x32_bf16 v[54:57], v[226:229], v[182:185], v[54:57]
	v_mfma_f32_16x16x32_bf16 v[50:53], v[234:237], v[182:185], v[50:53]
	v_mfma_f32_16x16x32_bf16 v[38:41], v[226:229], v[198:201], v[38:41]
	v_mfma_f32_16x16x32_bf16 v[34:37], v[234:237], v[198:201], v[34:37]
	v_mfma_f32_16x16x32_bf16 v[22:25], v[226:229], v[206:209], v[22:25]
	v_mfma_f32_16x16x32_bf16 v[18:21], v[234:237], v[206:209], v[18:21]
	v_mfma_f32_16x16x32_bf16 v[4:7], v[226:229], v[218:221], v[4:7]
	v_mfma_f32_16x16x32_bf16 v[0:3], v[234:237], v[218:221], v[0:3]
	s_add_i32 s19, 0, 0x18000
	v_add_u32_e32 v142, s19, v191
	s_barrier
	ds_read_b128 v[130:133], v142
	ds_read_b128 v[134:137], v142 offset:1024
	ds_read_b128 v[138:141], v142 offset:2048
	ds_read_b128 v[142:145], v142 offset:3072
	s_add_u32 s16, s68, 0xb0000
	s_addc_u32 s17, s69, 0
	s_mov_b32 m0, s83
	v_lshl_add_u64 v[222:223], s[16:17], 0, v[146:147]
	ds_read_b128 v[178:181], v196 offset:32768
	ds_read_b128 v[182:185], v196 offset:33792
	ds_read_b128 v[186:189], v196 offset:34816
	ds_read_b128 v[198:201], v196 offset:35840
	ds_read_b128 v[202:205], v196 offset:36864
	ds_read_b128 v[206:209], v196 offset:37888
	ds_read_b128 v[214:217], v196 offset:38912
	ds_read_b128 v[218:221], v196 offset:39936
	global_load_lds_dwordx4 v[222:223], off
	v_lshl_add_u64 v[222:223], s[16:17], 0, v[148:149]
	s_mov_b32 m0, s84
	s_nop 0
	global_load_lds_dwordx4 v[222:223], off
	s_waitcnt lgkmcnt(8)
	s_barrier
	s_waitcnt lgkmcnt(0)
	v_mfma_f32_16x16x32_bf16 v[126:129], v[130:133], v[178:181], v[126:129]
	v_mfma_f32_16x16x32_bf16 v[122:125], v[138:141], v[178:181], v[122:125]
	v_mfma_f32_16x16x32_bf16 v[110:113], v[130:133], v[186:189], v[110:113]
	v_mfma_f32_16x16x32_bf16 v[106:109], v[138:141], v[186:189], v[106:109]
	v_mfma_f32_16x16x32_bf16 v[94:97], v[130:133], v[202:205], v[94:97]
	v_mfma_f32_16x16x32_bf16 v[90:93], v[138:141], v[202:205], v[90:93]
	v_mfma_f32_16x16x32_bf16 v[78:81], v[130:133], v[214:217], v[78:81]
	v_mfma_f32_16x16x32_bf16 v[74:77], v[138:141], v[214:217], v[74:77]
	v_mfma_f32_16x16x32_bf16 v[126:129], v[134:137], v[182:185], v[126:129]
	v_mfma_f32_16x16x32_bf16 v[122:125], v[142:145], v[182:185], v[122:125]
	v_mfma_f32_16x16x32_bf16 v[110:113], v[134:137], v[198:201], v[110:113]
	v_mfma_f32_16x16x32_bf16 v[106:109], v[142:145], v[198:201], v[106:109]
	v_mfma_f32_16x16x32_bf16 v[94:97], v[134:137], v[206:209], v[94:97]
	v_mfma_f32_16x16x32_bf16 v[90:93], v[142:145], v[206:209], v[90:93]
	v_mfma_f32_16x16x32_bf16 v[78:81], v[134:137], v[218:221], v[78:81]
	v_mfma_f32_16x16x32_bf16 v[74:77], v[142:145], v[218:221], v[74:77]
	s_barrier
	s_add_i32 s26, 0, 0x1c000
	s_add_i32 s16, s19, s80
	v_add_u32_e32 v197, s26, v191
	v_lshl_add_u64 v[162:163], v[162:163], 0, s[70:71]
	s_mov_b32 m0, s16
	ds_read_b128 v[222:225], v197
	ds_read_b128 v[226:229], v197 offset:1024
	ds_read_b128 v[230:233], v197 offset:2048
	ds_read_b128 v[234:237], v197 offset:3072
	global_load_lds_dwordx4 v[162:163], off
	v_lshl_add_u64 v[162:163], v[164:165], 0, s[70:71]
	s_add_i32 m0, s16, 0x2000
	s_nop 0
	global_load_lds_dwordx4 v[162:163], off
	s_barrier
	s_waitcnt lgkmcnt(0)
	v_mfma_f32_16x16x32_bf16 v[118:121], v[222:225], v[178:181], v[118:121]
	v_mfma_f32_16x16x32_bf16 v[114:117], v[230:233], v[178:181], v[114:117]
	v_mfma_f32_16x16x32_bf16 v[102:105], v[222:225], v[186:189], v[102:105]
	v_mfma_f32_16x16x32_bf16 v[98:101], v[230:233], v[186:189], v[98:101]
	v_mfma_f32_16x16x32_bf16 v[86:89], v[222:225], v[202:205], v[86:89]
	v_mfma_f32_16x16x32_bf16 v[82:85], v[230:233], v[202:205], v[82:85]
	v_mfma_f32_16x16x32_bf16 v[70:73], v[222:225], v[214:217], v[70:73]
	v_mfma_f32_16x16x32_bf16 v[66:69], v[230:233], v[214:217], v[66:69]
	v_mfma_f32_16x16x32_bf16 v[118:121], v[226:229], v[182:185], v[118:121]
	v_mfma_f32_16x16x32_bf16 v[114:117], v[234:237], v[182:185], v[114:117]
	v_mfma_f32_16x16x32_bf16 v[102:105], v[226:229], v[198:201], v[102:105]
	v_mfma_f32_16x16x32_bf16 v[98:101], v[234:237], v[198:201], v[98:101]
	v_mfma_f32_16x16x32_bf16 v[86:89], v[226:229], v[206:209], v[86:89]
	v_mfma_f32_16x16x32_bf16 v[82:85], v[234:237], v[206:209], v[82:85]
	v_mfma_f32_16x16x32_bf16 v[70:73], v[226:229], v[218:221], v[70:73]
	v_mfma_f32_16x16x32_bf16 v[66:69], v[234:237], v[218:221], v[66:69]
	s_mov_b32 m0, s76
	v_lshl_add_u64 v[162:163], v[238:239], 0, s[70:71]
	s_barrier
	ds_read_b128 v[178:181], v196 offset:49152
	ds_read_b128 v[182:185], v196 offset:50176
	ds_read_b128 v[186:189], v196 offset:51200
	ds_read_b128 v[198:201], v196 offset:52224
	ds_read_b128 v[202:205], v196 offset:53248
	ds_read_b128 v[206:209], v196 offset:54272
	ds_read_b128 v[214:217], v196 offset:55296
	ds_read_b128 v[218:221], v196 offset:56320
	global_load_lds_dwordx4 v[162:163], off
	v_lshl_add_u64 v[162:163], v[240:241], 0, s[70:71]
	s_mov_b32 m0, s77
	s_nop 0
	global_load_lds_dwordx4 v[162:163], off
	s_barrier
; #define LAS __attribute__((address_space(3)))
; #define PG8_WAIT_V(n) asm volatile("s_waitcnt vmcnt(" #n ")" ::: "memory")
; #define PG8_WAIT_L(n) asm volatile("s_waitcnt lgkmcnt(" #n ")" ::: "memory")
; #define PG8_BAR __builtin_amdgcn_s_barrier()
; template <class Epi>
; DEVI void gemm_phase(LAS unsigned char* lds, const Gemm g, const Epi& E) {
;     ...
;             PG8_BAR; PG8_WAIT_L(0); PG8_MMA(1, 0, At, B0); PG8_BAR; PG8_SCHED;
;             PG8_STAGE(PG8_SB(1, 1), b3 + hstepB, voffB);
;             PG8_WAIT_V(6); PG8_BAR; PG8_MMA(1, 1, At, B1); PG8_BAR;
;         }
;     ...
;             for (int am = 0; am < 4; ++am) {
;                 const int ai = am >> 1, m0 = (am & 1) * 2;
;                 f32x4 pre[2][2][2];
;                 if constexpr (Epi::PRE) {
; #pragma unroll
;                     for (int m = 0; m < 2; ++m)
; #pragma unroll
;                         for (int bj = 0; bj < 2; ++bj)
; #pragma unroll
;                             for (int n = 0; n < 2; ++n) pre[m][bj][n] = E.load(row0 + ai * HALF + (m0 + m) * 16, col0 + bj * HALF + n * NST);
;                 }
; #pragma unroll
;                 for (int mm = 0; mm < 2; ++mm) {
;                     const int m = m0 + mm;
;                     const int r = row0 + ai * HALF + m * 16; float rs = 1.f, part = 0.f;
;                     if constexpr (Epi::RS) rs = rsv[ai * 4 + m];
;                     if constexpr (Epi::PAIR) E.pair8(cur.b, r, cur.pn * HALF + wc * 32 + 8 * fq, acc[ai][0][m][0] * rs, acc[ai][0][m][1] * rs, acc[ai][1][m][0] * rs, acc[ai][1][m][1] * rs);
;                     else
; #pragma unroll
;                     for (int bj = 0; bj < 2; ++bj) {
;                         const int c = col0 + bj * HALF; f32x4 v0 = acc[ai][bj][m][0], v1 = acc[ai][bj][m][1];
;                         if constexpr (Epi::RS) { v0 = v0 * rs; v1 = v1 * rs; }
;                         if constexpr (Epi::PRE) part += E.frag_pre8(cur.b, r, c, v0, v1, pre[mm][bj][0], pre[mm][bj][1]);
;                         else if constexpr (Epi::PERM) E.frag8(cur.b, r, c, v0, v1);
;                         else { E.frag(cur.b, r, c, v0); E.frag(cur.b, r, c + 16, v1); }
;                     }
;                     if constexpr (Epi::SSQ) { part += __shfl_xor(part, 16); part += __shfl_xor(part, 32); if (fq == 0) ((LAS float*)(lds + 131072))[(wr * 4 + wc) * 128 + ai * 64 + m * 16 + fr] = part; }
	s_waitcnt lgkmcnt(0)
	v_mfma_f32_16x16x32_bf16 v[62:65], v[130:133], v[178:181], v[62:65]
	v_mfma_f32_16x16x32_bf16 v[58:61], v[138:141], v[178:181], v[58:61]
	v_mfma_f32_16x16x32_bf16 v[46:49], v[130:133], v[186:189], v[46:49]
	v_mfma_f32_16x16x32_bf16 v[42:45], v[138:141], v[186:189], v[42:45]
	v_mfma_f32_16x16x32_bf16 v[30:33], v[130:133], v[202:205], v[30:33]
	v_mfma_f32_16x16x32_bf16 v[26:29], v[138:141], v[202:205], v[26:29]
	v_mfma_f32_16x16x32_bf16 v[14:17], v[130:133], v[214:217], v[14:17]
	v_mfma_f32_16x16x32_bf16 v[10:13], v[138:141], v[214:217], v[10:13]
	v_mfma_f32_16x16x32_bf16 v[62:65], v[134:137], v[182:185], v[62:65]
	v_mfma_f32_16x16x32_bf16 v[58:61], v[142:145], v[182:185], v[58:61]
	v_mfma_f32_16x16x32_bf16 v[46:49], v[134:137], v[198:201], v[46:49]
	v_mfma_f32_16x16x32_bf16 v[42:45], v[142:145], v[198:201], v[42:45]
	v_mfma_f32_16x16x32_bf16 v[30:33], v[134:137], v[206:209], v[30:33]
	v_mfma_f32_16x16x32_bf16 v[26:29], v[142:145], v[206:209], v[26:29]
	v_mfma_f32_16x16x32_bf16 v[14:17], v[134:137], v[218:221], v[14:17]
	v_mfma_f32_16x16x32_bf16 v[10:13], v[142:145], v[218:221], v[10:13]
	s_barrier
	s_add_u32 s16, s46, 0xb0080
	s_addc_u32 s17, s47, 0
	s_add_i32 s19, s26, s80
	v_lshl_add_u64 v[130:131], s[16:17], 0, v[8:9]
	s_mov_b32 m0, s19
	s_nop 0
	global_load_lds_dwordx4 v[130:131], off
	v_lshl_add_u64 v[130:131], s[16:17], 0, v[150:151]
	s_add_i32 m0, s19, 0x2000
	s_nop 0
	global_load_lds_dwordx4 v[130:131], off
	s_waitcnt vmcnt(6)
	s_barrier
	v_mfma_f32_16x16x32_bf16 v[54:57], v[222:225], v[178:181], v[54:57]
	v_mfma_f32_16x16x32_bf16 v[50:53], v[230:233], v[178:181], v[50:53]
	v_mfma_f32_16x16x32_bf16 v[38:41], v[222:225], v[186:189], v[38:41]
	v_mfma_f32_16x16x32_bf16 v[34:37], v[230:233], v[186:189], v[34:37]
	v_mfma_f32_16x16x32_bf16 v[22:25], v[222:225], v[202:205], v[22:25]
	v_mfma_f32_16x16x32_bf16 v[18:21], v[230:233], v[202:205], v[18:21]
	v_mfma_f32_16x16x32_bf16 v[4:7], v[222:225], v[214:217], v[4:7]
	v_mfma_f32_16x16x32_bf16 v[0:3], v[230:233], v[214:217], v[0:3]
	v_mfma_f32_16x16x32_bf16 v[54:57], v[226:229], v[182:185], v[54:57]
	v_mfma_f32_16x16x32_bf16 v[50:53], v[234:237], v[182:185], v[50:53]
	v_mfma_f32_16x16x32_bf16 v[38:41], v[226:229], v[198:201], v[38:41]
	v_mfma_f32_16x16x32_bf16 v[34:37], v[234:237], v[198:201], v[34:37]
	v_mfma_f32_16x16x32_bf16 v[22:25], v[226:229], v[206:209], v[22:25]
	v_mfma_f32_16x16x32_bf16 v[18:21], v[234:237], v[206:209], v[18:21]
	v_mfma_f32_16x16x32_bf16 v[4:7], v[226:229], v[218:221], v[4:7]
	v_mfma_f32_16x16x32_bf16 v[0:3], v[234:237], v[218:221], v[0:3]
	s_add_i32 s18, s18, 2
	s_add_u32 s1, s1, 0x100
	s_addc_u32 s13, s13, 0
	s_cmp_gt_u32 s18, 41
	s_mov_b64 s[16:17], s[36:37]
	s_barrier
	s_cbranch_scc0 .LBB0_1747
	s_setprio 0
	s_lshl_b32 s0, s0, 8
	v_add_u32_e32 v182, s0, v190
	v_lshl_or_b32 v180, s12, 8, v195
	v_ashrrev_i32_e32 v183, 31, v182
	v_lshlrev_b64 v[130:131], 12, v[182:183]
	v_ashrrev_i32_e32 v181, 31, v180
	v_lshl_add_u64 v[130:131], s[30:31], 0, v[130:131]
	v_lshlrev_b64 v[184:185], 2, v[180:181]
	v_lshl_add_u64 v[162:163], v[130:131], 0, v[184:185]
	global_load_dwordx4 v[200:203], v[162:163], off
	global_load_dwordx4 v[204:207], v[162:163], off offset:16
	global_load_dwordx4 v[214:217], v[162:163], off offset:512
	global_load_dwordx4 v[218:221], v[162:163], off offset:528
	v_or_b32_e32 v188, 16, v182
	v_ashrrev_i32_e32 v189, 31, v188
	v_lshlrev_b64 v[130:131], 12, v[188:189]
	v_lshl_add_u64 v[130:131], s[30:31], 0, v[130:131]
	v_lshl_add_u64 v[186:187], v[130:131], 0, v[184:185]
	global_load_dwordx4 v[138:141], v[186:187], off offset:16
	global_load_dwordx4 v[142:145], v[186:187], off
	global_load_dwordx4 v[130:133], v[186:187], off offset:528
	global_load_dwordx4 v[134:137], v[186:187], off offset:512
	v_and_b32_e32 v165, 64, v155
	v_xor_b32_e32 v164, 16, v155
	v_add_u32_e32 v165, 64, v165
	v_xor_b32_e32 v179, 32, v155
	v_cmp_lt_i32_e32 vcc, v164, v165
	v_or_b32_e32 v178, 0x80, v180
	s_waitcnt vmcnt(0)
	v_pk_add_f32 v[128:129], v[128:129], v[202:203]
	v_cndmask_b32_e32 v164, v155, v164, vcc
	v_cmp_lt_i32_e32 vcc, v179, v165
	v_lshlrev_b32_e32 v198, 2, v164
	v_pk_add_f32 v[126:127], v[126:127], v[200:201]
	v_cndmask_b32_e32 v165, v155, v179, vcc
	v_lshlrev_b32_e32 v197, 2, v165
	v_lshlrev_b64 v[164:165], 10, v[182:183]
	v_pk_add_f32 v[124:125], v[124:125], v[206:207]
	v_pk_add_f32 v[122:123], v[122:123], v[204:205]
	v_pk_add_f32 v[120:121], v[120:121], v[216:217]
	v_pk_add_f32 v[118:119], v[118:119], v[214:215]
	v_pk_add_f32 v[202:203], v[116:117], v[220:221]
	v_pk_add_f32 v[200:201], v[114:115], v[218:219]
	v_lshl_add_u64 v[208:209], v[164:165], 0, v[180:181]
	global_store_dwordx4 v[162:163], v[126:129], off
	global_store_dwordx4 v[162:163], v[122:125], off offset:16
	v_cvt_pk_bf16_f32 v114, v126, v127
	v_cvt_pk_bf16_f32 v115, v128, v129
	v_cvt_pk_bf16_f32 v116, v122, v123
	v_cvt_pk_bf16_f32 v117, v124, v125
	v_mul_f32_e32 v127, v127, v127
	v_mul_f32_e32 v129, v129, v129
	v_mul_f32_e32 v123, v123, v123
	v_mul_f32_e32 v125, v125, v125
	v_mul_f32_e32 v183, v119, v119
	v_mul_f32_e32 v199, v121, v121
	v_mul_f32_e32 v204, v201, v201
	v_mul_f32_e32 v205, v203, v203
	v_lshl_add_u64 v[208:209], v[208:209], 1, s[24:25]
	v_fmac_f32_e32 v127, v126, v126
	v_fmac_f32_e32 v129, v128, v128
	v_fmac_f32_e32 v123, v122, v122
	v_fmac_f32_e32 v125, v124, v124
	v_fmac_f32_e32 v183, v118, v118
	v_fmac_f32_e32 v199, v120, v120
	v_fmac_f32_e32 v204, v200, v200
	v_fmac_f32_e32 v205, v202, v202
	global_store_dwordx4 v[208:209], v[114:117], off
	v_ashrrev_i32_e32 v179, 31, v178
	v_lshl_add_u64 v[164:165], v[164:165], 0, v[178:179]
	v_add_f32_e32 v114, v127, v129
	v_add_f32_e32 v115, v123, v125
	v_add_f32_e32 v116, v183, v199
	v_add_f32_e32 v117, v204, v205
	v_add_f32_e32 v114, v114, v115
	v_add_f32_e32 v115, v116, v117
	v_add_f32_e32 v114, v114, v115
	ds_bpermute_b32 v115, v198, v114
	global_store_dwordx4 v[162:163], v[118:121], off offset:512
	global_store_dwordx4 v[162:163], v[200:203], off offset:528
	v_cvt_pk_bf16_f32 v116, v118, v119
	v_cvt_pk_bf16_f32 v117, v120, v121
	v_cvt_pk_bf16_f32 v118, v200, v201
	s_waitcnt lgkmcnt(0)
	v_add_f32_e32 v114, v114, v115
	ds_bpermute_b32 v115, v197, v114
	v_cvt_pk_bf16_f32 v119, v202, v203
	v_lshl_add_u64 v[120:121], v[164:165], 1, s[24:25]
	global_store_dwordx4 v[120:121], v[116:119], off
	s_and_saveexec_b64 s[16:17], s[2:3]
	s_cbranch_execz .LBB0_1750
	s_waitcnt lgkmcnt(0)
	v_add_f32_e32 v114, v114, v115
	ds_write_b32 v192, v114
